# K-loop LDS read rebalancing: the 4 B0 fragment reads of each K-tile moved from the 12-read load parts (P1/P5) one phase earlier into the read-free ones (P8/P4), published by extra counted vmcnt(10) wa
# speedup vs baseline: 1.0347x; 1.0090x over previous
.LBB0_286:
	s_ashr_i32 s45, s44, 31
	s_lshl_b64 s[0:1], s[44:45], 19
	v_mov_b64_e32 v[2:3], 0x16b0
	s_add_u32 s48, s20, s0
	v_cmp_lt_i64_e32 vcc, s[26:27], v[2:3]
	s_addc_u32 s49, s21, s1
	s_and_b64 s[0:1], vcc, exec
	s_cselect_b32 s18, s49, s23
	s_cselect_b32 s19, s48, s22
	s_ashr_i32 s47, s46, 31
	s_lshl_b64 s[0:1], s[46:47], 19
	s_add_u32 s50, s36, s0
	s_addc_u32 s51, s37, s1
	s_and_b64 s[0:1], vcc, exec
	s_cselect_b32 s45, s51, s25
	s_cselect_b32 s47, s50, s24
	s_add_u32 s22, s22, 0x40080
	s_addc_u32 s23, s23, 0
	s_add_u32 s59, s24, 0x100
	v_mov_b32_e32 v2, 0
	s_addc_u32 s68, s25, 0
	s_mov_b32 s69, -2
	v_mov_b32_e32 v3, v2
	v_mov_b32_e32 v4, v2
	v_mov_b32_e32 v5, v2
	v_mov_b32_e32 v6, v2
	v_mov_b32_e32 v7, v2
	v_mov_b32_e32 v8, v2
	v_mov_b32_e32 v9, v2
	v_mov_b32_e32 v18, v2
	v_mov_b32_e32 v19, v2
	v_mov_b32_e32 v20, v2
	v_mov_b32_e32 v21, v2
	v_mov_b32_e32 v22, v2
	v_mov_b32_e32 v23, v2
	v_mov_b32_e32 v24, v2
	v_mov_b32_e32 v25, v2
	s_waitcnt vmcnt(0)
	v_mov_b32_e32 v36, v2
	v_mov_b32_e32 v37, v2
	v_mov_b32_e32 v38, v2
	v_mov_b32_e32 v39, v2
	v_mov_b32_e32 v40, v2
	v_mov_b32_e32 v41, v2
	v_mov_b32_e32 v42, v2
	v_mov_b32_e32 v43, v2
	v_mov_b32_e32 v52, v2
	v_mov_b32_e32 v53, v2
	v_mov_b32_e32 v54, v2
	v_mov_b32_e32 v55, v2
	v_mov_b32_e32 v56, v2
	v_mov_b32_e32 v57, v2
	v_mov_b32_e32 v58, v2
	v_mov_b32_e32 v59, v2
	v_mov_b32_e32 v10, v2
	v_mov_b32_e32 v11, v2
	v_mov_b32_e32 v12, v2
	v_mov_b32_e32 v13, v2
	v_mov_b32_e32 v14, v2
	v_mov_b32_e32 v15, v2
	v_mov_b32_e32 v16, v2
	v_mov_b32_e32 v17, v2
	v_mov_b32_e32 v28, v2
	v_mov_b32_e32 v29, v2
	v_mov_b32_e32 v30, v2
	v_mov_b32_e32 v31, v2
	v_mov_b32_e32 v32, v2
	v_mov_b32_e32 v33, v2
	v_mov_b32_e32 v34, v2
	v_mov_b32_e32 v35, v2
	v_mov_b32_e32 v44, v2
	v_mov_b32_e32 v45, v2
	v_mov_b32_e32 v46, v2
	v_mov_b32_e32 v47, v2
	v_mov_b32_e32 v48, v2
	v_mov_b32_e32 v49, v2
	v_mov_b32_e32 v50, v2
	v_mov_b32_e32 v51, v2
	v_mov_b32_e32 v60, v2
	v_mov_b32_e32 v61, v2
	v_mov_b32_e32 v62, v2
	v_mov_b32_e32 v63, v2
	v_mov_b32_e32 v64, v2
	v_mov_b32_e32 v65, v2
	v_mov_b32_e32 v66, v2
	v_mov_b32_e32 v67, v2
	v_mov_b32_e32 v84, v2
	v_mov_b32_e32 v85, v2
	v_mov_b32_e32 v86, v2
	v_mov_b32_e32 v87, v2
	v_mov_b32_e32 v88, v2
	v_mov_b32_e32 v89, v2
	v_mov_b32_e32 v90, v2
	v_mov_b32_e32 v91, v2
	v_mov_b32_e32 v100, v2
	v_mov_b32_e32 v101, v2
	v_mov_b32_e32 v102, v2
	v_mov_b32_e32 v103, v2
	v_mov_b32_e32 v104, v2
	v_mov_b32_e32 v105, v2
	v_mov_b32_e32 v106, v2
	v_mov_b32_e32 v107, v2
	v_mov_b32_e32 v116, v2
	v_mov_b32_e32 v117, v2
	v_mov_b32_e32 v118, v2
	v_mov_b32_e32 v119, v2
	v_mov_b32_e32 v120, v2
	v_mov_b32_e32 v121, v2
	v_mov_b32_e32 v122, v2
	v_mov_b32_e32 v123, v2
	v_mov_b32_e32 v132, v2
	v_mov_b32_e32 v133, v2
	v_mov_b32_e32 v134, v2
	v_mov_b32_e32 v135, v2
	v_mov_b32_e32 v136, v2
	v_mov_b32_e32 v137, v2
	v_mov_b32_e32 v138, v2
	v_mov_b32_e32 v139, v2
	v_mov_b32_e32 v92, v2
	v_mov_b32_e32 v93, v2
	v_mov_b32_e32 v94, v2
	v_mov_b32_e32 v95, v2
	v_mov_b32_e32 v96, v2
	v_mov_b32_e32 v97, v2
	v_mov_b32_e32 v98, v2
	v_mov_b32_e32 v99, v2
	v_mov_b32_e32 v108, v2
	v_mov_b32_e32 v109, v2
	v_mov_b32_e32 v110, v2
	v_mov_b32_e32 v111, v2
	v_mov_b32_e32 v112, v2
	v_mov_b32_e32 v113, v2
	v_mov_b32_e32 v114, v2
	v_mov_b32_e32 v115, v2
	v_mov_b32_e32 v124, v2
	v_mov_b32_e32 v125, v2
	v_mov_b32_e32 v126, v2
	v_mov_b32_e32 v127, v2
	v_mov_b32_e32 v128, v2
	v_mov_b32_e32 v129, v2
	v_mov_b32_e32 v130, v2
	v_mov_b32_e32 v131, v2
	v_mov_b32_e32 v140, v2
	v_mov_b32_e32 v141, v2
	v_mov_b32_e32 v142, v2
	v_mov_b32_e32 v143, v2
	v_mov_b32_e32 v144, v2
	v_mov_b32_e32 v145, v2
	v_mov_b32_e32 v146, v2
	v_mov_b32_e32 v147, v2
	v_add_u32_e32 v80, 0x10000, v163
	ds_read_b128 v[68:71], v80
	ds_read_b128 v[72:75], v80 offset:1024
	ds_read_b128 v[76:79], v80 offset:2048
	ds_read_b128 v[80:83], v80 offset:3072
.LBB0_287:
	s_add_u32 s0, s22, 0xfffc0080
	s_addc_u32 s1, s23, -1
	s_add_i32 s72, 0, 0x10000
	s_cmp_eq_u32 s69, 12
	s_cselect_b32 s27, s18, s1
	s_cselect_b32 s26, s19, s0
	s_cselect_b32 s25, s45, s68
	s_cselect_b32 s24, s47, s59
	v_lshl_add_u64 v[202:203], s[22:23], 0, v[154:155]
	s_add_i32 m0, s53, 0xc000
	ds_read_b128 v[158:161], v165
	ds_read_b128 v[174:177], v165 offset:1024
	ds_read_b128 v[178:181], v165 offset:2048
	ds_read_b128 v[182:185], v165 offset:3072
	ds_read_b128 v[186:189], v165 offset:4096
	ds_read_b128 v[190:193], v165 offset:5120
	ds_read_b128 v[194:197], v165 offset:6144
	ds_read_b128 v[198:201], v165 offset:7168
	global_load_lds_dwordx4 v[202:203], off
	v_lshl_add_u64 v[202:203], s[22:23], 0, v[156:157]
	s_add_i32 m0, s53, 0xe000
	s_nop 0
	global_load_lds_dwordx4 v[202:203], off
	s_waitcnt vmcnt(10) lgkmcnt(8)
	s_setprio 1
	s_barrier
	s_waitcnt lgkmcnt(0)
	v_mfma_f32_16x16x32_bf16 v[144:147], v[68:71], v[158:161], v[144:147]
	v_mfma_f32_16x16x32_bf16 v[140:143], v[76:79], v[158:161], v[140:143]
	v_mfma_f32_16x16x32_bf16 v[128:131], v[68:71], v[178:181], v[128:131]
	v_mfma_f32_16x16x32_bf16 v[124:127], v[76:79], v[178:181], v[124:127]
	v_mfma_f32_16x16x32_bf16 v[112:115], v[68:71], v[186:189], v[112:115]
	v_mfma_f32_16x16x32_bf16 v[108:111], v[76:79], v[186:189], v[108:111]
	v_mfma_f32_16x16x32_bf16 v[96:99], v[68:71], v[194:197], v[96:99]
	v_mfma_f32_16x16x32_bf16 v[92:95], v[76:79], v[194:197], v[92:95]
	v_mfma_f32_16x16x32_bf16 v[144:147], v[72:75], v[174:177], v[144:147]
	v_mfma_f32_16x16x32_bf16 v[140:143], v[80:83], v[174:177], v[140:143]
	v_mfma_f32_16x16x32_bf16 v[128:131], v[72:75], v[182:185], v[128:131]
	v_mfma_f32_16x16x32_bf16 v[124:127], v[80:83], v[182:185], v[124:127]
	v_mfma_f32_16x16x32_bf16 v[112:115], v[72:75], v[190:193], v[112:115]
	v_mfma_f32_16x16x32_bf16 v[108:111], v[80:83], v[190:193], v[108:111]
	v_mfma_f32_16x16x32_bf16 v[96:99], v[72:75], v[198:201], v[96:99]
	v_mfma_f32_16x16x32_bf16 v[92:95], v[80:83], v[198:201], v[92:95]
	s_barrier
	s_setprio 0
	s_add_i32 s73, 0, 0x14000
	s_add_i32 s0, s72, s52
	v_add_u32_e32 v166, s73, v163
	v_lshl_add_u64 v[218:219], s[24:25], 0, v[26:27]
	s_mov_b32 m0, s0
	ds_read_b128 v[202:205], v166
	ds_read_b128 v[206:209], v166 offset:1024
	ds_read_b128 v[210:213], v166 offset:2048
	ds_read_b128 v[214:217], v166 offset:3072
	global_load_lds_dwordx4 v[218:219], off
	v_lshl_add_u64 v[220:221], s[24:25], 0, v[148:149]
	s_add_i32 m0, s0, 0x2000
	s_nop 0
	global_load_lds_dwordx4 v[220:221], off
	s_waitcnt vmcnt(10)
	s_setprio 1
	s_barrier
	s_waitcnt lgkmcnt(0)
	v_mfma_f32_16x16x32_bf16 v[136:139], v[202:205], v[158:161], v[136:139]
	v_mfma_f32_16x16x32_bf16 v[132:135], v[210:213], v[158:161], v[132:135]
	v_mfma_f32_16x16x32_bf16 v[120:123], v[202:205], v[178:181], v[120:123]
	v_mfma_f32_16x16x32_bf16 v[116:119], v[210:213], v[178:181], v[116:119]
	v_mfma_f32_16x16x32_bf16 v[104:107], v[202:205], v[186:189], v[104:107]
	v_mfma_f32_16x16x32_bf16 v[100:103], v[210:213], v[186:189], v[100:103]
	v_mfma_f32_16x16x32_bf16 v[88:91], v[202:205], v[194:197], v[88:91]
	v_mfma_f32_16x16x32_bf16 v[84:87], v[210:213], v[194:197], v[84:87]
	v_mfma_f32_16x16x32_bf16 v[136:139], v[206:209], v[174:177], v[136:139]
	v_mfma_f32_16x16x32_bf16 v[132:135], v[214:217], v[174:177], v[132:135]
	v_mfma_f32_16x16x32_bf16 v[120:123], v[206:209], v[182:185], v[120:123]
	v_mfma_f32_16x16x32_bf16 v[116:119], v[214:217], v[182:185], v[116:119]
	v_mfma_f32_16x16x32_bf16 v[104:107], v[206:209], v[190:193], v[104:107]
	v_mfma_f32_16x16x32_bf16 v[100:103], v[214:217], v[190:193], v[100:103]
	v_mfma_f32_16x16x32_bf16 v[88:91], v[206:209], v[198:201], v[88:91]
	v_mfma_f32_16x16x32_bf16 v[84:87], v[214:217], v[198:201], v[84:87]
	s_barrier
	s_setprio 0
	s_mov_b32 m0, s53
	v_lshl_add_u64 v[222:223], s[26:27], 0, v[152:153]
	ds_read_b128 v[158:161], v165 offset:16384
	ds_read_b128 v[174:177], v165 offset:17408
	ds_read_b128 v[178:181], v165 offset:18432
	ds_read_b128 v[182:185], v165 offset:19456
	ds_read_b128 v[186:189], v165 offset:20480
	ds_read_b128 v[190:193], v165 offset:21504
	ds_read_b128 v[194:197], v165 offset:22528
	ds_read_b128 v[198:201], v165 offset:23552
	global_load_lds_dwordx4 v[222:223], off
	v_lshl_add_u64 v[224:225], s[26:27], 0, v[150:151]
	s_mov_b32 m0, s54
	s_nop 0
	global_load_lds_dwordx4 v[224:225], off
	s_waitcnt vmcnt(10)
	s_setprio 1
	s_barrier
	s_waitcnt lgkmcnt(0)
	v_mfma_f32_16x16x32_bf16 v[64:67], v[68:71], v[158:161], v[64:67]
	v_mfma_f32_16x16x32_bf16 v[60:63], v[76:79], v[158:161], v[60:63]
	v_mfma_f32_16x16x32_bf16 v[48:51], v[68:71], v[178:181], v[48:51]
	v_mfma_f32_16x16x32_bf16 v[44:47], v[76:79], v[178:181], v[44:47]
	v_mfma_f32_16x16x32_bf16 v[32:35], v[68:71], v[186:189], v[32:35]
	v_mfma_f32_16x16x32_bf16 v[28:31], v[76:79], v[186:189], v[28:31]
	v_mfma_f32_16x16x32_bf16 v[14:17], v[68:71], v[194:197], v[14:17]
	v_mfma_f32_16x16x32_bf16 v[10:13], v[76:79], v[194:197], v[10:13]
	v_mfma_f32_16x16x32_bf16 v[64:67], v[72:75], v[174:177], v[64:67]
	v_mfma_f32_16x16x32_bf16 v[60:63], v[80:83], v[174:177], v[60:63]
	v_mfma_f32_16x16x32_bf16 v[48:51], v[72:75], v[182:185], v[48:51]
	v_mfma_f32_16x16x32_bf16 v[44:47], v[80:83], v[182:185], v[44:47]
	v_mfma_f32_16x16x32_bf16 v[32:35], v[72:75], v[190:193], v[32:35]
	v_mfma_f32_16x16x32_bf16 v[28:31], v[80:83], v[190:193], v[28:31]
	v_mfma_f32_16x16x32_bf16 v[14:17], v[72:75], v[198:201], v[14:17]
	v_mfma_f32_16x16x32_bf16 v[10:13], v[80:83], v[198:201], v[10:13]
	s_barrier
	s_setprio 0
	s_add_u32 s0, s24, 0x40000
	s_addc_u32 s1, s25, 0
	s_add_i32 s72, s73, s52
	v_lshl_add_u64 v[68:69], s[0:1], 0, v[26:27]
	s_mov_b32 m0, s72
	s_nop 0
	global_load_lds_dwordx4 v[68:69], off
	v_lshl_add_u64 v[68:69], s[0:1], 0, v[148:149]
	s_add_i32 m0, s72, 0x2000
	s_nop 0
	global_load_lds_dwordx4 v[68:69], off
	v_add_u32_e32 v80, 0x18000, v163
	ds_read_b128 v[68:71], v80
	ds_read_b128 v[72:75], v80 offset:1024
	ds_read_b128 v[76:79], v80 offset:2048
	ds_read_b128 v[80:83], v80 offset:3072
	s_waitcnt vmcnt(10)
	s_setprio 1
	s_barrier
	v_mfma_f32_16x16x32_bf16 v[56:59], v[202:205], v[158:161], v[56:59]
	v_mfma_f32_16x16x32_bf16 v[52:55], v[210:213], v[158:161], v[52:55]
	v_mfma_f32_16x16x32_bf16 v[40:43], v[202:205], v[178:181], v[40:43]
	v_mfma_f32_16x16x32_bf16 v[36:39], v[210:213], v[178:181], v[36:39]
	v_mfma_f32_16x16x32_bf16 v[22:25], v[202:205], v[186:189], v[22:25]
	v_mfma_f32_16x16x32_bf16 v[18:21], v[210:213], v[186:189], v[18:21]
	v_mfma_f32_16x16x32_bf16 v[6:9], v[202:205], v[194:197], v[6:9]
	v_mfma_f32_16x16x32_bf16 v[2:5], v[210:213], v[194:197], v[2:5]
	v_mfma_f32_16x16x32_bf16 v[56:59], v[206:209], v[174:177], v[56:59]
	v_mfma_f32_16x16x32_bf16 v[52:55], v[214:217], v[174:177], v[52:55]
	v_mfma_f32_16x16x32_bf16 v[40:43], v[206:209], v[182:185], v[40:43]
	v_mfma_f32_16x16x32_bf16 v[36:39], v[214:217], v[182:185], v[36:39]
	v_mfma_f32_16x16x32_bf16 v[22:25], v[206:209], v[190:193], v[22:25]
	v_mfma_f32_16x16x32_bf16 v[18:21], v[214:217], v[190:193], v[18:21]
	v_mfma_f32_16x16x32_bf16 v[6:9], v[206:209], v[198:201], v[6:9]
	v_mfma_f32_16x16x32_bf16 v[2:5], v[214:217], v[198:201], v[2:5]
	s_barrier
	s_setprio 0
	s_add_i32 s72, 0, 0x18000
	s_add_u32 s0, s26, 0x40000
	s_addc_u32 s1, s27, 0
	s_mov_b32 m0, s55
	v_lshl_add_u64 v[202:203], s[0:1], 0, v[152:153]
	ds_read_b128 v[158:161], v165 offset:32768
	ds_read_b128 v[174:177], v165 offset:33792
	ds_read_b128 v[178:181], v165 offset:34816
	ds_read_b128 v[182:185], v165 offset:35840
	ds_read_b128 v[186:189], v165 offset:36864
	ds_read_b128 v[190:193], v165 offset:37888
	ds_read_b128 v[194:197], v165 offset:38912
	ds_read_b128 v[198:201], v165 offset:39936
	global_load_lds_dwordx4 v[202:203], off
	v_lshl_add_u64 v[202:203], s[0:1], 0, v[150:151]
	s_mov_b32 m0, s56
	s_nop 0
	global_load_lds_dwordx4 v[202:203], off
	s_waitcnt vmcnt(10) lgkmcnt(8)
	s_setprio 1
	s_barrier
	s_waitcnt lgkmcnt(0)
	v_mfma_f32_16x16x32_bf16 v[144:147], v[68:71], v[158:161], v[144:147]
	v_mfma_f32_16x16x32_bf16 v[140:143], v[76:79], v[158:161], v[140:143]
	v_mfma_f32_16x16x32_bf16 v[128:131], v[68:71], v[178:181], v[128:131]
	v_mfma_f32_16x16x32_bf16 v[124:127], v[76:79], v[178:181], v[124:127]
	v_mfma_f32_16x16x32_bf16 v[112:115], v[68:71], v[186:189], v[112:115]
	v_mfma_f32_16x16x32_bf16 v[108:111], v[76:79], v[186:189], v[108:111]
	v_mfma_f32_16x16x32_bf16 v[96:99], v[68:71], v[194:197], v[96:99]
	v_mfma_f32_16x16x32_bf16 v[92:95], v[76:79], v[194:197], v[92:95]
	v_mfma_f32_16x16x32_bf16 v[144:147], v[72:75], v[174:177], v[144:147]
	v_mfma_f32_16x16x32_bf16 v[140:143], v[80:83], v[174:177], v[140:143]
	v_mfma_f32_16x16x32_bf16 v[128:131], v[72:75], v[182:185], v[128:131]
	v_mfma_f32_16x16x32_bf16 v[124:127], v[80:83], v[182:185], v[124:127]
	v_mfma_f32_16x16x32_bf16 v[112:115], v[72:75], v[190:193], v[112:115]
	v_mfma_f32_16x16x32_bf16 v[108:111], v[80:83], v[190:193], v[108:111]
	v_mfma_f32_16x16x32_bf16 v[96:99], v[72:75], v[198:201], v[96:99]
	v_mfma_f32_16x16x32_bf16 v[92:95], v[80:83], v[198:201], v[92:95]
	s_barrier
	s_setprio 0
	s_add_i32 s26, 0, 0x1c000
	s_add_i32 s0, s72, s52
	v_add_u32_e32 v166, s26, v163
	v_lshl_add_u64 v[218:219], v[218:219], 0, s[12:13]
	s_mov_b32 m0, s0
	ds_read_b128 v[202:205], v166
	ds_read_b128 v[206:209], v166 offset:1024
	ds_read_b128 v[210:213], v166 offset:2048
	ds_read_b128 v[214:217], v166 offset:3072
	global_load_lds_dwordx4 v[218:219], off
	v_lshl_add_u64 v[218:219], v[220:221], 0, s[12:13]
	s_add_i32 m0, s0, 0x2000
	s_nop 0
	global_load_lds_dwordx4 v[218:219], off
	s_waitcnt vmcnt(10)
	s_setprio 1
	s_barrier
	s_waitcnt lgkmcnt(0)
	v_mfma_f32_16x16x32_bf16 v[136:139], v[202:205], v[158:161], v[136:139]
	v_mfma_f32_16x16x32_bf16 v[132:135], v[210:213], v[158:161], v[132:135]
	v_mfma_f32_16x16x32_bf16 v[120:123], v[202:205], v[178:181], v[120:123]
	v_mfma_f32_16x16x32_bf16 v[116:119], v[210:213], v[178:181], v[116:119]
	v_mfma_f32_16x16x32_bf16 v[104:107], v[202:205], v[186:189], v[104:107]
	v_mfma_f32_16x16x32_bf16 v[100:103], v[210:213], v[186:189], v[100:103]
	v_mfma_f32_16x16x32_bf16 v[88:91], v[202:205], v[194:197], v[88:91]
	v_mfma_f32_16x16x32_bf16 v[84:87], v[210:213], v[194:197], v[84:87]
	v_mfma_f32_16x16x32_bf16 v[136:139], v[206:209], v[174:177], v[136:139]
	v_mfma_f32_16x16x32_bf16 v[132:135], v[214:217], v[174:177], v[132:135]
	v_mfma_f32_16x16x32_bf16 v[120:123], v[206:209], v[182:185], v[120:123]
	v_mfma_f32_16x16x32_bf16 v[116:119], v[214:217], v[182:185], v[116:119]
	v_mfma_f32_16x16x32_bf16 v[104:107], v[206:209], v[190:193], v[104:107]
	v_mfma_f32_16x16x32_bf16 v[100:103], v[214:217], v[190:193], v[100:103]
	v_mfma_f32_16x16x32_bf16 v[88:91], v[206:209], v[198:201], v[88:91]
	v_mfma_f32_16x16x32_bf16 v[84:87], v[214:217], v[198:201], v[84:87]
	s_barrier
	s_setprio 0
	s_mov_b32 m0, s30
	v_lshl_add_u64 v[218:219], v[222:223], 0, s[12:13]
	ds_read_b128 v[158:161], v165 offset:49152
	ds_read_b128 v[174:177], v165 offset:50176
	ds_read_b128 v[178:181], v165 offset:51200
	ds_read_b128 v[182:185], v165 offset:52224
	ds_read_b128 v[186:189], v165 offset:53248
	ds_read_b128 v[190:193], v165 offset:54272
	ds_read_b128 v[194:197], v165 offset:55296
	ds_read_b128 v[198:201], v165 offset:56320
	global_load_lds_dwordx4 v[218:219], off
	v_lshl_add_u64 v[218:219], v[224:225], 0, s[12:13]
	s_mov_b32 m0, s31
	s_nop 0
	global_load_lds_dwordx4 v[218:219], off
	s_waitcnt vmcnt(10)
	s_setprio 1
	s_barrier
	s_waitcnt lgkmcnt(0)
	v_mfma_f32_16x16x32_bf16 v[64:67], v[68:71], v[158:161], v[64:67]
	v_mfma_f32_16x16x32_bf16 v[60:63], v[76:79], v[158:161], v[60:63]
	v_mfma_f32_16x16x32_bf16 v[48:51], v[68:71], v[178:181], v[48:51]
	v_mfma_f32_16x16x32_bf16 v[44:47], v[76:79], v[178:181], v[44:47]
	v_mfma_f32_16x16x32_bf16 v[32:35], v[68:71], v[186:189], v[32:35]
	v_mfma_f32_16x16x32_bf16 v[28:31], v[76:79], v[186:189], v[28:31]
	v_mfma_f32_16x16x32_bf16 v[14:17], v[68:71], v[194:197], v[14:17]
	v_mfma_f32_16x16x32_bf16 v[10:13], v[76:79], v[194:197], v[10:13]
	v_mfma_f32_16x16x32_bf16 v[64:67], v[72:75], v[174:177], v[64:67]
	v_mfma_f32_16x16x32_bf16 v[60:63], v[80:83], v[174:177], v[60:63]
	v_mfma_f32_16x16x32_bf16 v[48:51], v[72:75], v[182:185], v[48:51]
	v_mfma_f32_16x16x32_bf16 v[44:47], v[80:83], v[182:185], v[44:47]
	v_mfma_f32_16x16x32_bf16 v[32:35], v[72:75], v[190:193], v[32:35]
	v_mfma_f32_16x16x32_bf16 v[28:31], v[80:83], v[190:193], v[28:31]
	v_mfma_f32_16x16x32_bf16 v[14:17], v[72:75], v[198:201], v[14:17]
	v_mfma_f32_16x16x32_bf16 v[10:13], v[80:83], v[198:201], v[10:13]
	s_barrier
	s_setprio 0
	s_add_u32 s0, s24, 0x40080
	s_addc_u32 s1, s25, 0
	s_add_i32 s24, s26, s52
	v_lshl_add_u64 v[68:69], s[0:1], 0, v[26:27]
	s_mov_b32 m0, s24
	s_nop 0
	global_load_lds_dwordx4 v[68:69], off
	v_lshl_add_u64 v[68:69], s[0:1], 0, v[148:149]
	s_add_i32 m0, s24, 0x2000
	s_nop 0
	global_load_lds_dwordx4 v[68:69], off
	v_add_u32_e32 v80, 0x10000, v163
	ds_read_b128 v[68:71], v80
	ds_read_b128 v[72:75], v80 offset:1024
	ds_read_b128 v[76:79], v80 offset:2048
	ds_read_b128 v[80:83], v80 offset:3072
	s_waitcnt vmcnt(10)
	s_setprio 1
	s_barrier
	v_mfma_f32_16x16x32_bf16 v[56:59], v[202:205], v[158:161], v[56:59]
	v_mfma_f32_16x16x32_bf16 v[52:55], v[210:213], v[158:161], v[52:55]
	v_mfma_f32_16x16x32_bf16 v[40:43], v[202:205], v[178:181], v[40:43]
	v_mfma_f32_16x16x32_bf16 v[36:39], v[210:213], v[178:181], v[36:39]
	v_mfma_f32_16x16x32_bf16 v[22:25], v[202:205], v[186:189], v[22:25]
	v_mfma_f32_16x16x32_bf16 v[18:21], v[210:213], v[186:189], v[18:21]
	v_mfma_f32_16x16x32_bf16 v[6:9], v[202:205], v[194:197], v[6:9]
	v_mfma_f32_16x16x32_bf16 v[2:5], v[210:213], v[194:197], v[2:5]
	v_mfma_f32_16x16x32_bf16 v[56:59], v[206:209], v[174:177], v[56:59]
	v_mfma_f32_16x16x32_bf16 v[52:55], v[214:217], v[174:177], v[52:55]
	v_mfma_f32_16x16x32_bf16 v[40:43], v[206:209], v[182:185], v[40:43]
	v_mfma_f32_16x16x32_bf16 v[36:39], v[214:217], v[182:185], v[36:39]
	v_mfma_f32_16x16x32_bf16 v[22:25], v[206:209], v[190:193], v[22:25]
	v_mfma_f32_16x16x32_bf16 v[18:21], v[214:217], v[190:193], v[18:21]
	v_mfma_f32_16x16x32_bf16 v[6:9], v[206:209], v[198:201], v[6:9]
	v_mfma_f32_16x16x32_bf16 v[2:5], v[214:217], v[198:201], v[2:5]
	s_barrier
	s_setprio 0
	s_add_i32 s69, s69, 2
	s_add_u32 s22, s22, 0x100
	s_addc_u32 s23, s23, 0
	s_add_u32 s59, s59, 0x100
	s_addc_u32 s68, s68, 0
	s_cmp_gt_u32 s69, 13
	s_cbranch_scc0 .LBB0_287
	s_waitcnt lgkmcnt(0)
	s_cmpk_gt_i32 s58, 0xff
	s_mov_b64 s[18:19], 0xb000
	s_cbranch_scc1 .LBB0_283
	s_ashr_i32 s0, s58, 5
	s_mul_hi_i32 s19, s0, 0x1600
	s_mul_i32 s18, s0, 0x1600
	s_branch .LBB0_283

.LBB0_360:
	s_add_u32 s18, s28, 0x100
	v_mov_b32_e32 v2, 0
	s_addc_u32 s19, s29, 0
	s_mov_b32 s46, -2
	v_mov_b32_e32 v3, v2
	v_mov_b32_e32 v4, v2
	v_mov_b32_e32 v5, v2
	v_mov_b32_e32 v6, v2
	v_mov_b32_e32 v7, v2
	v_mov_b32_e32 v8, v2
	v_mov_b32_e32 v9, v2
	v_mov_b32_e32 v10, v2
	v_mov_b32_e32 v11, v2
	v_mov_b32_e32 v12, v2
	v_mov_b32_e32 v13, v2
	v_mov_b32_e32 v14, v2
	v_mov_b32_e32 v15, v2
	v_mov_b32_e32 v16, v2
	v_mov_b32_e32 v17, v2
	v_mov_b32_e32 v18, v2
	v_mov_b32_e32 v19, v2
	v_mov_b32_e32 v20, v2
	v_mov_b32_e32 v21, v2
	v_mov_b32_e32 v22, v2
	v_mov_b32_e32 v23, v2
	v_mov_b32_e32 v24, v2
	v_mov_b32_e32 v25, v2
	v_mov_b32_e32 v28, v2
	v_mov_b32_e32 v29, v2
	v_mov_b32_e32 v30, v2
	v_mov_b32_e32 v31, v2
	v_mov_b32_e32 v32, v2
	v_mov_b32_e32 v33, v2
	v_mov_b32_e32 v34, v2
	v_mov_b32_e32 v35, v2
	v_mov_b32_e32 v68, v2
	v_mov_b32_e32 v69, v2
	v_mov_b32_e32 v70, v2
	v_mov_b32_e32 v71, v2
	v_mov_b32_e32 v72, v2
	v_mov_b32_e32 v73, v2
	v_mov_b32_e32 v74, v2
	v_mov_b32_e32 v75, v2
	v_mov_b32_e32 v76, v2
	v_mov_b32_e32 v77, v2
	v_mov_b32_e32 v78, v2
	v_mov_b32_e32 v79, v2
	v_mov_b32_e32 v80, v2
	v_mov_b32_e32 v81, v2
	v_mov_b32_e32 v82, v2
	v_mov_b32_e32 v83, v2
	v_mov_b32_e32 v84, v2
	v_mov_b32_e32 v85, v2
	v_mov_b32_e32 v86, v2
	v_mov_b32_e32 v87, v2
	v_mov_b32_e32 v88, v2
	v_mov_b32_e32 v89, v2
	v_mov_b32_e32 v90, v2
	v_mov_b32_e32 v91, v2
	v_mov_b32_e32 v92, v2
	v_mov_b32_e32 v93, v2
	v_mov_b32_e32 v94, v2
	v_mov_b32_e32 v95, v2
	v_mov_b32_e32 v96, v2
	v_mov_b32_e32 v97, v2
	v_mov_b32_e32 v98, v2
	v_mov_b32_e32 v99, v2
	s_waitcnt vmcnt(0)
	v_mov_b32_e32 v36, v2
	v_mov_b32_e32 v37, v2
	v_mov_b32_e32 v38, v2
	v_mov_b32_e32 v39, v2
	v_mov_b32_e32 v40, v2
	v_mov_b32_e32 v41, v2
	v_mov_b32_e32 v42, v2
	v_mov_b32_e32 v43, v2
	v_mov_b32_e32 v44, v2
	v_mov_b32_e32 v45, v2
	v_mov_b32_e32 v46, v2
	v_mov_b32_e32 v47, v2
	v_mov_b32_e32 v48, v2
	v_mov_b32_e32 v49, v2
	v_mov_b32_e32 v50, v2
	v_mov_b32_e32 v51, v2
	v_mov_b32_e32 v52, v2
	v_mov_b32_e32 v53, v2
	v_mov_b32_e32 v54, v2
	v_mov_b32_e32 v55, v2
	v_mov_b32_e32 v56, v2
	v_mov_b32_e32 v57, v2
	v_mov_b32_e32 v58, v2
	v_mov_b32_e32 v59, v2
	v_mov_b32_e32 v60, v2
	v_mov_b32_e32 v61, v2
	v_mov_b32_e32 v62, v2
	v_mov_b32_e32 v63, v2
	v_mov_b32_e32 v64, v2
	v_mov_b32_e32 v65, v2
	v_mov_b32_e32 v66, v2
	v_mov_b32_e32 v67, v2
	v_mov_b32_e32 v100, v2
	v_mov_b32_e32 v101, v2
	v_mov_b32_e32 v102, v2
	v_mov_b32_e32 v103, v2
	v_mov_b32_e32 v104, v2
	v_mov_b32_e32 v105, v2
	v_mov_b32_e32 v106, v2
	v_mov_b32_e32 v107, v2
	v_mov_b32_e32 v108, v2
	v_mov_b32_e32 v109, v2
	v_mov_b32_e32 v110, v2
	v_mov_b32_e32 v111, v2
	v_mov_b32_e32 v112, v2
	v_mov_b32_e32 v113, v2
	v_mov_b32_e32 v114, v2
	v_mov_b32_e32 v115, v2
	v_mov_b32_e32 v116, v2
	v_mov_b32_e32 v117, v2
	v_mov_b32_e32 v118, v2
	v_mov_b32_e32 v119, v2
	v_mov_b32_e32 v120, v2
	v_mov_b32_e32 v121, v2
	v_mov_b32_e32 v122, v2
	v_mov_b32_e32 v123, v2
	v_mov_b32_e32 v124, v2
	v_mov_b32_e32 v125, v2
	v_mov_b32_e32 v126, v2
	v_mov_b32_e32 v127, v2
	v_mov_b32_e32 v128, v2
	v_mov_b32_e32 v129, v2
	v_mov_b32_e32 v130, v2
	v_mov_b32_e32 v131, v2
	v_add_u32_e32 v160, 0x10000, v222
	ds_read_b128 v[132:135], v160
	ds_read_b128 v[136:139], v160 offset:1024
	ds_read_b128 v[156:159], v160 offset:2048
	ds_read_b128 v[160:163], v160 offset:3072
.LBB0_361:
	s_add_u32 s28, s26, 0x100
	s_addc_u32 s29, s27, 0
	s_add_i32 s0, 0, 0x10000
	s_cmp_eq_u32 s46, 40
	s_cselect_b32 s35, s45, s29
	s_cselect_b32 s34, s44, s28
	s_cselect_b32 s31, s23, s19
	s_cselect_b32 s30, s22, s18
	v_lshl_add_u64 v[164:165], s[26:27], 0, v[152:153]
	s_add_i32 m0, s20, 0xc000
	ds_read_b128 v[172:175], v224
	ds_read_b128 v[176:179], v224 offset:1024
	ds_read_b128 v[180:183], v224 offset:2048
	ds_read_b128 v[184:187], v224 offset:3072
	ds_read_b128 v[188:191], v224 offset:4096
	ds_read_b128 v[192:195], v224 offset:5120
	ds_read_b128 v[196:199], v224 offset:6144
	ds_read_b128 v[200:203], v224 offset:7168
	global_load_lds_dwordx4 v[164:165], off
	v_lshl_add_u64 v[164:165], s[26:27], 0, v[154:155]
	s_add_i32 m0, s20, 0xe000
	s_nop 0
	global_load_lds_dwordx4 v[164:165], off
	s_waitcnt vmcnt(10) lgkmcnt(8)
	s_setprio 1
	s_barrier
	s_waitcnt lgkmcnt(0)
	v_mfma_f32_16x16x32_bf16 v[128:131], v[132:135], v[172:175], v[128:131]
	v_mfma_f32_16x16x32_bf16 v[124:127], v[156:159], v[172:175], v[124:127]
	v_mfma_f32_16x16x32_bf16 v[120:123], v[132:135], v[180:183], v[120:123]
	v_mfma_f32_16x16x32_bf16 v[116:119], v[156:159], v[180:183], v[116:119]
	v_mfma_f32_16x16x32_bf16 v[112:115], v[132:135], v[188:191], v[112:115]
	v_mfma_f32_16x16x32_bf16 v[108:111], v[156:159], v[188:191], v[108:111]
	v_mfma_f32_16x16x32_bf16 v[104:107], v[132:135], v[196:199], v[104:107]
	v_mfma_f32_16x16x32_bf16 v[100:103], v[156:159], v[196:199], v[100:103]
	v_mfma_f32_16x16x32_bf16 v[128:131], v[136:139], v[176:179], v[128:131]
	v_mfma_f32_16x16x32_bf16 v[124:127], v[160:163], v[176:179], v[124:127]
	v_mfma_f32_16x16x32_bf16 v[120:123], v[136:139], v[184:187], v[120:123]
	v_mfma_f32_16x16x32_bf16 v[116:119], v[160:163], v[184:187], v[116:119]
	v_mfma_f32_16x16x32_bf16 v[112:115], v[136:139], v[192:195], v[112:115]
	v_mfma_f32_16x16x32_bf16 v[108:111], v[160:163], v[192:195], v[108:111]
	v_mfma_f32_16x16x32_bf16 v[104:107], v[136:139], v[200:203], v[104:107]
	v_mfma_f32_16x16x32_bf16 v[100:103], v[160:163], v[200:203], v[100:103]
	s_barrier
	s_setprio 0
	s_add_i32 s26, 0, 0x14000
	v_add_u32_e32 v164, s26, v222
	s_add_i32 s0, s0, s17
	ds_read_b128 v[204:207], v164
	ds_read_b128 v[208:211], v164 offset:1024
	ds_read_b128 v[212:215], v164 offset:2048
	ds_read_b128 v[216:219], v164 offset:3072
	v_lshl_add_u64 v[164:165], s[30:31], 0, v[26:27]
	s_mov_b32 m0, s0
	v_lshl_add_u64 v[166:167], s[30:31], 0, v[140:141]
	global_load_lds_dwordx4 v[164:165], off
	s_add_i32 m0, s0, 0x2000
	s_nop 0
	global_load_lds_dwordx4 v[166:167], off
	s_waitcnt vmcnt(10)
	s_setprio 1
	s_barrier
	s_waitcnt lgkmcnt(0)
	v_mfma_f32_16x16x32_bf16 v[64:67], v[204:207], v[172:175], v[64:67]
	v_mfma_f32_16x16x32_bf16 v[60:63], v[212:215], v[172:175], v[60:63]
	v_mfma_f32_16x16x32_bf16 v[56:59], v[204:207], v[180:183], v[56:59]
	v_mfma_f32_16x16x32_bf16 v[52:55], v[212:215], v[180:183], v[52:55]
	v_mfma_f32_16x16x32_bf16 v[48:51], v[204:207], v[188:191], v[48:51]
	v_mfma_f32_16x16x32_bf16 v[44:47], v[212:215], v[188:191], v[44:47]
	v_mfma_f32_16x16x32_bf16 v[40:43], v[204:207], v[196:199], v[40:43]
	v_mfma_f32_16x16x32_bf16 v[36:39], v[212:215], v[196:199], v[36:39]
	v_mfma_f32_16x16x32_bf16 v[64:67], v[208:211], v[176:179], v[64:67]
	v_mfma_f32_16x16x32_bf16 v[60:63], v[216:219], v[176:179], v[60:63]
	v_mfma_f32_16x16x32_bf16 v[56:59], v[208:211], v[184:187], v[56:59]
	v_mfma_f32_16x16x32_bf16 v[52:55], v[216:219], v[184:187], v[52:55]
	v_mfma_f32_16x16x32_bf16 v[48:51], v[208:211], v[192:195], v[48:51]
	v_mfma_f32_16x16x32_bf16 v[44:47], v[216:219], v[192:195], v[44:47]
	v_mfma_f32_16x16x32_bf16 v[40:43], v[208:211], v[200:203], v[40:43]
	v_mfma_f32_16x16x32_bf16 v[36:39], v[216:219], v[200:203], v[36:39]
	s_barrier
	s_setprio 0
	s_mov_b32 m0, s20
	v_lshl_add_u64 v[168:169], s[34:35], 0, v[144:145]
	ds_read_b128 v[172:175], v224 offset:16384
	ds_read_b128 v[176:179], v224 offset:17408
	ds_read_b128 v[180:183], v224 offset:18432
	ds_read_b128 v[184:187], v224 offset:19456
	ds_read_b128 v[188:191], v224 offset:20480
	ds_read_b128 v[192:195], v224 offset:21504
	ds_read_b128 v[196:199], v224 offset:22528
	ds_read_b128 v[200:203], v224 offset:23552
	global_load_lds_dwordx4 v[168:169], off
	v_lshl_add_u64 v[220:221], s[34:35], 0, v[142:143]
	s_mov_b32 m0, s21
	s_nop 0
	global_load_lds_dwordx4 v[220:221], off
	s_waitcnt vmcnt(10)
	s_setprio 1
	s_barrier
	s_waitcnt lgkmcnt(0)
	v_mfma_f32_16x16x32_bf16 v[96:99], v[132:135], v[172:175], v[96:99]
	v_mfma_f32_16x16x32_bf16 v[92:95], v[156:159], v[172:175], v[92:95]
	v_mfma_f32_16x16x32_bf16 v[88:91], v[132:135], v[180:183], v[88:91]
	v_mfma_f32_16x16x32_bf16 v[84:87], v[156:159], v[180:183], v[84:87]
	v_mfma_f32_16x16x32_bf16 v[80:83], v[132:135], v[188:191], v[80:83]
	v_mfma_f32_16x16x32_bf16 v[76:79], v[156:159], v[188:191], v[76:79]
	v_mfma_f32_16x16x32_bf16 v[72:75], v[132:135], v[196:199], v[72:75]
	v_mfma_f32_16x16x32_bf16 v[68:71], v[156:159], v[196:199], v[68:71]
	v_mfma_f32_16x16x32_bf16 v[96:99], v[136:139], v[176:179], v[96:99]
	v_mfma_f32_16x16x32_bf16 v[92:95], v[160:163], v[176:179], v[92:95]
	v_mfma_f32_16x16x32_bf16 v[88:91], v[136:139], v[184:187], v[88:91]
	v_mfma_f32_16x16x32_bf16 v[84:87], v[160:163], v[184:187], v[84:87]
	v_mfma_f32_16x16x32_bf16 v[80:83], v[136:139], v[192:195], v[80:83]
	v_mfma_f32_16x16x32_bf16 v[76:79], v[160:163], v[192:195], v[76:79]
	v_mfma_f32_16x16x32_bf16 v[72:75], v[136:139], v[200:203], v[72:75]
	v_mfma_f32_16x16x32_bf16 v[68:71], v[160:163], v[200:203], v[68:71]
	s_barrier
	s_setprio 0
	s_add_u32 s0, s30, 0xb0000
	s_addc_u32 s1, s31, 0
	s_add_i32 s26, s26, s17
	v_lshl_add_u64 v[132:133], s[0:1], 0, v[26:27]
	s_mov_b32 m0, s26
	s_nop 0
	global_load_lds_dwordx4 v[132:133], off
	v_lshl_add_u64 v[132:133], s[0:1], 0, v[140:141]
	s_add_i32 m0, s26, 0x2000
	s_nop 0
	global_load_lds_dwordx4 v[132:133], off
	v_add_u32_e32 v160, 0x18000, v222
	ds_read_b128 v[132:135], v160
	ds_read_b128 v[136:139], v160 offset:1024
	ds_read_b128 v[156:159], v160 offset:2048
	ds_read_b128 v[160:163], v160 offset:3072
	s_waitcnt vmcnt(10)
	s_setprio 1
	s_barrier
	v_mfma_f32_16x16x32_bf16 v[32:35], v[204:207], v[172:175], v[32:35]
	v_mfma_f32_16x16x32_bf16 v[28:31], v[212:215], v[172:175], v[28:31]
	v_mfma_f32_16x16x32_bf16 v[22:25], v[204:207], v[180:183], v[22:25]
	v_mfma_f32_16x16x32_bf16 v[18:21], v[212:215], v[180:183], v[18:21]
	v_mfma_f32_16x16x32_bf16 v[14:17], v[204:207], v[188:191], v[14:17]
	v_mfma_f32_16x16x32_bf16 v[10:13], v[212:215], v[188:191], v[10:13]
	v_mfma_f32_16x16x32_bf16 v[6:9], v[204:207], v[196:199], v[6:9]
	v_mfma_f32_16x16x32_bf16 v[2:5], v[212:215], v[196:199], v[2:5]
	v_mfma_f32_16x16x32_bf16 v[32:35], v[208:211], v[176:179], v[32:35]
	v_mfma_f32_16x16x32_bf16 v[28:31], v[216:219], v[176:179], v[28:31]
	v_mfma_f32_16x16x32_bf16 v[22:25], v[208:211], v[184:187], v[22:25]
	v_mfma_f32_16x16x32_bf16 v[18:21], v[216:219], v[184:187], v[18:21]
	v_mfma_f32_16x16x32_bf16 v[14:17], v[208:211], v[192:195], v[14:17]
	v_mfma_f32_16x16x32_bf16 v[10:13], v[216:219], v[192:195], v[10:13]
	v_mfma_f32_16x16x32_bf16 v[6:9], v[208:211], v[200:203], v[6:9]
	v_mfma_f32_16x16x32_bf16 v[2:5], v[216:219], v[200:203], v[2:5]
	s_barrier
	s_setprio 0
	s_add_i32 s26, 0, 0x18000
	s_add_u32 s0, s34, 0xb0000
	s_addc_u32 s1, s35, 0
	s_mov_b32 m0, s36
	v_lshl_add_u64 v[204:205], s[0:1], 0, v[144:145]
	ds_read_b128 v[172:175], v224 offset:32768
	ds_read_b128 v[176:179], v224 offset:33792
	ds_read_b128 v[180:183], v224 offset:34816
	ds_read_b128 v[184:187], v224 offset:35840
	ds_read_b128 v[188:191], v224 offset:36864
	ds_read_b128 v[192:195], v224 offset:37888
	ds_read_b128 v[196:199], v224 offset:38912
	ds_read_b128 v[200:203], v224 offset:39936
	global_load_lds_dwordx4 v[204:205], off
	v_lshl_add_u64 v[204:205], s[0:1], 0, v[142:143]
	s_mov_b32 m0, s37
	s_nop 0
	global_load_lds_dwordx4 v[204:205], off
	s_waitcnt vmcnt(10) lgkmcnt(8)
	s_setprio 1
	s_barrier
	s_waitcnt lgkmcnt(0)
	v_mfma_f32_16x16x32_bf16 v[128:131], v[132:135], v[172:175], v[128:131]
	v_mfma_f32_16x16x32_bf16 v[124:127], v[156:159], v[172:175], v[124:127]
	v_mfma_f32_16x16x32_bf16 v[120:123], v[132:135], v[180:183], v[120:123]
	v_mfma_f32_16x16x32_bf16 v[116:119], v[156:159], v[180:183], v[116:119]
	v_mfma_f32_16x16x32_bf16 v[112:115], v[132:135], v[188:191], v[112:115]
	v_mfma_f32_16x16x32_bf16 v[108:111], v[156:159], v[188:191], v[108:111]
	v_mfma_f32_16x16x32_bf16 v[104:107], v[132:135], v[196:199], v[104:107]
	v_mfma_f32_16x16x32_bf16 v[100:103], v[156:159], v[196:199], v[100:103]
	v_mfma_f32_16x16x32_bf16 v[128:131], v[136:139], v[176:179], v[128:131]
	v_mfma_f32_16x16x32_bf16 v[124:127], v[160:163], v[176:179], v[124:127]
	v_mfma_f32_16x16x32_bf16 v[120:123], v[136:139], v[184:187], v[120:123]
	v_mfma_f32_16x16x32_bf16 v[116:119], v[160:163], v[184:187], v[116:119]
	v_mfma_f32_16x16x32_bf16 v[112:115], v[136:139], v[192:195], v[112:115]
	v_mfma_f32_16x16x32_bf16 v[108:111], v[160:163], v[192:195], v[108:111]
	v_mfma_f32_16x16x32_bf16 v[104:107], v[136:139], v[200:203], v[104:107]
	v_mfma_f32_16x16x32_bf16 v[100:103], v[160:163], v[200:203], v[100:103]
	s_barrier
	s_setprio 0
	s_add_i32 s27, 0, 0x1c000
	s_add_i32 s0, s26, s17
	v_add_u32_e32 v216, s27, v222
	v_lshl_add_u64 v[164:165], v[164:165], 0, s[12:13]
	s_mov_b32 m0, s0
	ds_read_b128 v[204:207], v216
	ds_read_b128 v[208:211], v216 offset:1024
	ds_read_b128 v[212:215], v216 offset:2048
	ds_read_b128 v[216:219], v216 offset:3072
	global_load_lds_dwordx4 v[164:165], off
	v_lshl_add_u64 v[164:165], v[166:167], 0, s[12:13]
	s_add_i32 m0, s0, 0x2000
	s_nop 0
	global_load_lds_dwordx4 v[164:165], off
	s_waitcnt vmcnt(10)
	s_setprio 1
	s_barrier
	s_waitcnt lgkmcnt(0)
	v_mfma_f32_16x16x32_bf16 v[64:67], v[204:207], v[172:175], v[64:67]
	v_mfma_f32_16x16x32_bf16 v[60:63], v[212:215], v[172:175], v[60:63]
	v_mfma_f32_16x16x32_bf16 v[56:59], v[204:207], v[180:183], v[56:59]
	v_mfma_f32_16x16x32_bf16 v[52:55], v[212:215], v[180:183], v[52:55]
	v_mfma_f32_16x16x32_bf16 v[48:51], v[204:207], v[188:191], v[48:51]
	v_mfma_f32_16x16x32_bf16 v[44:47], v[212:215], v[188:191], v[44:47]
	v_mfma_f32_16x16x32_bf16 v[40:43], v[204:207], v[196:199], v[40:43]
	v_mfma_f32_16x16x32_bf16 v[36:39], v[212:215], v[196:199], v[36:39]
	v_mfma_f32_16x16x32_bf16 v[64:67], v[208:211], v[176:179], v[64:67]
	v_mfma_f32_16x16x32_bf16 v[60:63], v[216:219], v[176:179], v[60:63]
	v_mfma_f32_16x16x32_bf16 v[56:59], v[208:211], v[184:187], v[56:59]
	v_mfma_f32_16x16x32_bf16 v[52:55], v[216:219], v[184:187], v[52:55]
	v_mfma_f32_16x16x32_bf16 v[48:51], v[208:211], v[192:195], v[48:51]
	v_mfma_f32_16x16x32_bf16 v[44:47], v[216:219], v[192:195], v[44:47]
	v_mfma_f32_16x16x32_bf16 v[40:43], v[208:211], v[200:203], v[40:43]
	v_mfma_f32_16x16x32_bf16 v[36:39], v[216:219], v[200:203], v[36:39]
	s_barrier
	s_setprio 0
	s_mov_b32 m0, s59
	v_lshl_add_u64 v[164:165], v[168:169], 0, s[12:13]
	ds_read_b128 v[172:175], v224 offset:49152
	ds_read_b128 v[176:179], v224 offset:50176
	ds_read_b128 v[180:183], v224 offset:51200
	ds_read_b128 v[184:187], v224 offset:52224
	ds_read_b128 v[188:191], v224 offset:53248
	ds_read_b128 v[192:195], v224 offset:54272
	ds_read_b128 v[196:199], v224 offset:55296
	ds_read_b128 v[200:203], v224 offset:56320
	global_load_lds_dwordx4 v[164:165], off
	v_lshl_add_u64 v[164:165], v[220:221], 0, s[12:13]
	s_mov_b32 m0, s68
	s_nop 0
	global_load_lds_dwordx4 v[164:165], off
	s_waitcnt vmcnt(10)
	s_setprio 1
	s_barrier
	s_waitcnt lgkmcnt(0)
	v_mfma_f32_16x16x32_bf16 v[96:99], v[132:135], v[172:175], v[96:99]
	v_mfma_f32_16x16x32_bf16 v[92:95], v[156:159], v[172:175], v[92:95]
	v_mfma_f32_16x16x32_bf16 v[88:91], v[132:135], v[180:183], v[88:91]
	v_mfma_f32_16x16x32_bf16 v[84:87], v[156:159], v[180:183], v[84:87]
	v_mfma_f32_16x16x32_bf16 v[80:83], v[132:135], v[188:191], v[80:83]
	v_mfma_f32_16x16x32_bf16 v[76:79], v[156:159], v[188:191], v[76:79]
	v_mfma_f32_16x16x32_bf16 v[72:75], v[132:135], v[196:199], v[72:75]
	v_mfma_f32_16x16x32_bf16 v[68:71], v[156:159], v[196:199], v[68:71]
	v_mfma_f32_16x16x32_bf16 v[96:99], v[136:139], v[176:179], v[96:99]
	v_mfma_f32_16x16x32_bf16 v[92:95], v[160:163], v[176:179], v[92:95]
	v_mfma_f32_16x16x32_bf16 v[88:91], v[136:139], v[184:187], v[88:91]
	v_mfma_f32_16x16x32_bf16 v[84:87], v[160:163], v[184:187], v[84:87]
	v_mfma_f32_16x16x32_bf16 v[80:83], v[136:139], v[192:195], v[80:83]
	v_mfma_f32_16x16x32_bf16 v[76:79], v[160:163], v[192:195], v[76:79]
	v_mfma_f32_16x16x32_bf16 v[72:75], v[136:139], v[200:203], v[72:75]
	v_mfma_f32_16x16x32_bf16 v[68:71], v[160:163], v[200:203], v[68:71]
	s_barrier
	s_setprio 0
	s_add_u32 s0, s30, 0xb0080
	s_addc_u32 s1, s31, 0
	s_add_i32 s26, s27, s17
	v_lshl_add_u64 v[132:133], s[0:1], 0, v[26:27]
	s_mov_b32 m0, s26
	s_nop 0
	global_load_lds_dwordx4 v[132:133], off
	v_lshl_add_u64 v[132:133], s[0:1], 0, v[140:141]
	s_add_i32 m0, s26, 0x2000
	s_nop 0
	global_load_lds_dwordx4 v[132:133], off
	v_add_u32_e32 v160, 0x10000, v222
	ds_read_b128 v[132:135], v160
	ds_read_b128 v[136:139], v160 offset:1024
	ds_read_b128 v[156:159], v160 offset:2048
	ds_read_b128 v[160:163], v160 offset:3072
	s_waitcnt vmcnt(10)
	s_setprio 1
	s_barrier
	v_mfma_f32_16x16x32_bf16 v[32:35], v[204:207], v[172:175], v[32:35]
	v_mfma_f32_16x16x32_bf16 v[28:31], v[212:215], v[172:175], v[28:31]
	v_mfma_f32_16x16x32_bf16 v[22:25], v[204:207], v[180:183], v[22:25]
	v_mfma_f32_16x16x32_bf16 v[18:21], v[212:215], v[180:183], v[18:21]
	v_mfma_f32_16x16x32_bf16 v[14:17], v[204:207], v[188:191], v[14:17]
	v_mfma_f32_16x16x32_bf16 v[10:13], v[212:215], v[188:191], v[10:13]
	v_mfma_f32_16x16x32_bf16 v[6:9], v[204:207], v[196:199], v[6:9]
	v_mfma_f32_16x16x32_bf16 v[2:5], v[212:215], v[196:199], v[2:5]
	v_mfma_f32_16x16x32_bf16 v[32:35], v[208:211], v[176:179], v[32:35]
	v_mfma_f32_16x16x32_bf16 v[28:31], v[216:219], v[176:179], v[28:31]
	v_mfma_f32_16x16x32_bf16 v[22:25], v[208:211], v[184:187], v[22:25]
	v_mfma_f32_16x16x32_bf16 v[18:21], v[216:219], v[184:187], v[18:21]
	v_mfma_f32_16x16x32_bf16 v[14:17], v[208:211], v[192:195], v[14:17]
	v_mfma_f32_16x16x32_bf16 v[10:13], v[216:219], v[192:195], v[10:13]
	v_mfma_f32_16x16x32_bf16 v[6:9], v[208:211], v[200:203], v[6:9]
	v_mfma_f32_16x16x32_bf16 v[2:5], v[216:219], v[200:203], v[2:5]
	s_barrier
	s_setprio 0
	s_add_i32 s46, s46, 2
	s_add_u32 s18, s18, 0x100
	s_addc_u32 s19, s19, 0
	s_cmp_gt_u32 s46, 41
	s_mov_b64 s[26:27], s[28:29]
	s_cbranch_scc0 .LBB0_361
	s_waitcnt lgkmcnt(0)
	s_min_i32 s0, s24, 0x100
	s_ashr_i32 s0, s0, 5
	s_ashr_i32 s1, s0, 31
	s_add_i32 s18, s24, 0xffffff00
	s_cmpk_lt_i32 s24, 0x100
	s_cselect_b32 s18, s24, s18
	s_cselect_b32 s27, 0, s58
	s_cselect_b32 s26, 0, s57
	s_ashr_i32 s19, s18, 31
	s_lshl_b64 s[18:19], s[18:19], 19
	s_add_u32 s26, s50, s26
	v_lshl_or_b32 v178, s25, 8, v223
	s_addc_u32 s27, s51, s27
	s_ashr_i32 s25, s24, 31
	v_lshl_add_u64 v[132:133], s[18:19], 0, v[146:147]
	s_lshl_b64 s[18:19], s[24:25], 19
	v_lshl_add_u64 v[184:185], v[148:149], 0, s[18:19]
	s_lshl_b64 s[24:25], s[24:25], 10
	s_mul_i32 s18, s0, 0x9000
	v_ashrrev_i32_e32 v179, 31, v178
	s_mul_hi_i32 s19, s0, 0x9000
	s_add_u32 s18, s48, s18
	s_addc_u32 s19, s49, s19
	v_lshlrev_b64 v[186:187], 2, v[178:179]
	v_lshl_add_u64 v[156:157], s[18:19], 0, v[186:187]
	v_lshl_add_u64 v[180:181], v[132:133], 0, v[178:179]
	v_lshl_add_u64 v[182:183], v[132:133], 1, s[26:27]
	global_load_dwordx4 v[132:135], v[156:157], off offset:16
	global_load_dwordx4 v[136:139], v[156:157], off
	s_lshl_b64 s[0:1], s[0:1], 12
	s_add_u32 s28, s52, s0
	s_addc_u32 s29, s53, s1
	v_lshl_add_u64 v[196:197], v[180:181], 1, s[26:27]
	v_lshl_add_u64 v[180:181], s[28:29], 0, v[186:187]
	v_add_co_u32_e32 v210, vcc, s65, v196
	v_lshlrev_b64 v[188:189], 1, v[178:179]
	s_nop 0
	v_addc_co_u32_e32 v211, vcc, 0, v197, vcc
	s_mov_b32 s1, 0x20000
	v_lshl_add_u64 v[178:179], v[184:185], 0, v[188:189]
	v_add_co_u32_e32 v184, vcc, s1, v196
	s_mov_b32 s18, 0x30000
	s_nop 0
	v_addc_co_u32_e32 v185, vcc, 0, v197, vcc
	v_lshl_add_u64 v[182:183], v[182:183], 0, v[188:189]
	v_add_co_u32_e32 v188, vcc, s18, v196
	s_mov_b32 s0, 0x8000
	s_nop 0
	v_addc_co_u32_e32 v189, vcc, 0, v197, vcc
	s_mov_b32 s19, 0x80000
	s_mov_b32 s26, 0x90000
	s_waitcnt vmcnt(0)
	v_pk_mul_f32 v[172:173], v[134:135], 0.5 op_sel_hi:[1,0]
	v_pk_mul_f32 v[176:177], v[138:139], 0.5 op_sel_hi:[1,0]
	v_pk_mul_f32 v[174:175], v[136:137], 0.5 op_sel_hi:[1,0]
	v_pk_mul_f32 v[164:165], v[132:133], 0.5 op_sel_hi:[1,0]
	global_load_dwordx4 v[132:135], v[156:157], off offset:528
	global_load_dwordx4 v[136:139], v[156:157], off offset:512
	s_waitcnt vmcnt(0)
	v_pk_mul_f32 v[158:159], v[134:135], 0.5 op_sel_hi:[1,0]
	v_pk_mul_f32 v[162:163], v[138:139], 0.5 op_sel_hi:[1,0]
	v_pk_mul_f32 v[160:161], v[136:137], 0.5 op_sel_hi:[1,0]
	v_pk_mul_f32 v[156:157], v[132:133], 0.5 op_sel_hi:[1,0]
	global_load_dwordx4 v[132:135], v[180:181], off offset:16
	global_load_dwordx4 v[136:139], v[180:181], off
	global_load_dwordx4 v[190:193], v[196:197], off offset:2048
	global_load_dwordx4 v[198:201], v[210:211], off offset:2048
	global_load_dwordx4 v[202:205], v[184:185], off offset:2048
	global_load_dwordx4 v[206:209], v[188:189], off offset:2048
	s_waitcnt vmcnt(0)
	v_lshlrev_b32_e32 v186, 16, v190
	v_and_b32_e32 v187, 0xffff0000, v190
	v_lshlrev_b32_e32 v190, 16, v191
	v_and_b32_e32 v191, 0xffff0000, v191
	v_lshlrev_b32_e32 v194, 16, v192
	v_and_b32_e32 v195, 0xffff0000, v192
	v_lshlrev_b32_e32 v192, 16, v193
	v_and_b32_e32 v193, 0xffff0000, v193
	v_pk_fma_f32 v[130:131], v[130:131], v[176:177], v[190:191]
	v_pk_fma_f32 v[128:129], v[128:129], v[174:175], v[186:187]
	v_pk_fma_f32 v[126:127], v[126:127], v[172:173], v[192:193]
	v_pk_fma_f32 v[124:125], v[124:125], v[164:165], v[194:195]
	v_cvt_pk_bf16_f32 v190, v128, v129
	v_cvt_pk_bf16_f32 v191, v130, v131
	v_cvt_pk_bf16_f32 v192, v124, v125
	v_cvt_pk_bf16_f32 v193, v126, v127
	v_lshlrev_b32_e32 v130, 16, v190
	v_and_b32_e32 v131, 0xffff0000, v190
	v_lshlrev_b32_e32 v128, 16, v191
	v_and_b32_e32 v129, 0xffff0000, v191
	v_lshlrev_b32_e32 v126, 16, v192
	v_and_b32_e32 v127, 0xffff0000, v192
	v_lshlrev_b32_e32 v124, 16, v193
	v_and_b32_e32 v125, 0xffff0000, v193
	v_lshlrev_b32_e32 v212, 16, v198
	v_and_b32_e32 v213, 0xffff0000, v198
	v_lshlrev_b32_e32 v198, 16, v199
	v_and_b32_e32 v199, 0xffff0000, v199
	global_store_dwordx4 v[182:183], v[190:193], off offset:2048
	v_pk_mul_f32 v[186:187], v[138:139], v[128:129]
	v_pk_mul_f32 v[194:195], v[134:135], v[124:125]
	v_pk_mul_f32 v[190:191], v[136:137], v[130:131]
	v_pk_mul_f32 v[192:193], v[132:133], v[126:127]
	v_lshlrev_b32_e32 v214, 16, v200
	v_and_b32_e32 v215, 0xffff0000, v200
	v_lshlrev_b32_e32 v200, 16, v201
	v_and_b32_e32 v201, 0xffff0000, v201
	v_cvt_pk_bf16_f32 v190, v190, v191
	v_cvt_pk_bf16_f32 v191, v186, v187
	v_cvt_pk_bf16_f32 v192, v192, v193
	v_cvt_pk_bf16_f32 v193, v194, v195
	v_pk_fma_f32 v[122:123], v[122:123], v[176:177], v[198:199]
	v_pk_fma_f32 v[120:121], v[120:121], v[174:175], v[212:213]
	global_store_dwordx4 v[178:179], v[190:193], off
	v_pk_fma_f32 v[118:119], v[118:119], v[172:173], v[200:201]
	v_pk_fma_f32 v[116:117], v[116:117], v[164:165], v[214:215]
	v_cvt_pk_bf16_f32 v190, v120, v121
	v_cvt_pk_bf16_f32 v191, v122, v123
	v_add_co_u32_e32 v186, vcc, s65, v182
	v_cvt_pk_bf16_f32 v192, v116, v117
	v_cvt_pk_bf16_f32 v193, v118, v119
	v_addc_co_u32_e32 v187, vcc, 0, v183, vcc
	v_lshlrev_b32_e32 v122, 16, v190
	v_and_b32_e32 v123, 0xffff0000, v190
	v_lshlrev_b32_e32 v120, 16, v191
	v_and_b32_e32 v121, 0xffff0000, v191
	global_store_dwordx4 v[186:187], v[190:193], off offset:2048
	v_lshlrev_b32_e32 v118, 16, v192
	v_and_b32_e32 v119, 0xffff0000, v192
	v_lshlrev_b32_e32 v116, 16, v193
	v_and_b32_e32 v117, 0xffff0000, v193
	v_pk_mul_f32 v[190:191], v[138:139], v[120:121]
	v_pk_mul_f32 v[192:193], v[136:137], v[122:123]
	v_pk_mul_f32 v[198:199], v[134:135], v[116:117]
	v_pk_mul_f32 v[194:195], v[132:133], v[118:119]
	v_cvt_pk_bf16_f32 v192, v192, v193
	v_cvt_pk_bf16_f32 v193, v190, v191
	v_add_co_u32_e32 v190, vcc, s0, v178
	v_cvt_pk_bf16_f32 v194, v194, v195
	v_cvt_pk_bf16_f32 v195, v198, v199
	v_addc_co_u32_e32 v191, vcc, 0, v179, vcc
	global_store_dwordx4 v[190:191], v[192:195], off
	v_lshlrev_b32_e32 v198, 16, v202
	v_and_b32_e32 v199, 0xffff0000, v202
	v_add_co_u32_e32 v192, vcc, s19, v196
	v_lshlrev_b32_e32 v200, 16, v203
	s_nop 0
	v_addc_co_u32_e32 v193, vcc, 0, v197, vcc
	v_add_co_u32_e32 v194, vcc, s26, v196
	v_and_b32_e32 v201, 0xffff0000, v203
	global_load_dwordx4 v[212:215], v[192:193], off offset:2048
	v_addc_co_u32_e32 v195, vcc, 0, v197, vcc
	v_lshlrev_b32_e32 v202, 16, v204
	v_and_b32_e32 v203, 0xffff0000, v204
	v_lshlrev_b32_e32 v204, 16, v205
	v_and_b32_e32 v205, 0xffff0000, v205
	v_pk_fma_f32 v[114:115], v[114:115], v[176:177], v[200:201]
	v_pk_fma_f32 v[112:113], v[112:113], v[174:175], v[198:199]
	v_pk_fma_f32 v[110:111], v[110:111], v[172:173], v[204:205]
	v_pk_fma_f32 v[108:109], v[108:109], v[164:165], v[202:203]
	v_cvt_pk_bf16_f32 v200, v112, v113
	v_cvt_pk_bf16_f32 v201, v114, v115
	v_add_co_u32_e32 v198, vcc, s1, v182
	v_cvt_pk_bf16_f32 v202, v108, v109
	v_cvt_pk_bf16_f32 v203, v110, v111
	v_addc_co_u32_e32 v199, vcc, 0, v183, vcc
	v_lshlrev_b32_e32 v114, 16, v200
	v_and_b32_e32 v115, 0xffff0000, v200
	v_lshlrev_b32_e32 v112, 16, v201
	v_and_b32_e32 v113, 0xffff0000, v201
	global_load_dwordx4 v[216:219], v[194:195], off offset:2048
	v_lshlrev_b32_e32 v110, 16, v202
	global_store_dwordx4 v[198:199], v[200:203], off offset:2048
	v_and_b32_e32 v111, 0xffff0000, v202
	v_lshlrev_b32_e32 v108, 16, v203
	v_and_b32_e32 v109, 0xffff0000, v203
	v_pk_mul_f32 v[200:201], v[138:139], v[112:113]
	v_pk_mul_f32 v[202:203], v[136:137], v[114:115]
	v_lshlrev_b32_e32 v220, 16, v206
	v_and_b32_e32 v221, 0xffff0000, v206
	v_lshlrev_b32_e32 v206, 16, v207
	v_and_b32_e32 v207, 0xffff0000, v207
	v_pk_mul_f32 v[238:239], v[134:135], v[108:109]
	v_pk_mul_f32 v[204:205], v[132:133], v[110:111]
	v_cvt_pk_bf16_f32 v202, v202, v203
	v_cvt_pk_bf16_f32 v203, v200, v201
	v_add_co_u32_e32 v200, vcc, s65, v178
	v_lshlrev_b32_e32 v234, 16, v208
	v_and_b32_e32 v235, 0xffff0000, v208
	v_lshlrev_b32_e32 v208, 16, v209
	v_and_b32_e32 v209, 0xffff0000, v209
	v_cvt_pk_bf16_f32 v204, v204, v205
	v_cvt_pk_bf16_f32 v205, v238, v239
	v_addc_co_u32_e32 v201, vcc, 0, v179, vcc
	v_pk_fma_f32 v[106:107], v[106:107], v[176:177], v[206:207]
	v_pk_fma_f32 v[104:105], v[104:105], v[174:175], v[220:221]
	global_store_dwordx4 v[200:201], v[202:205], off
	v_pk_fma_f32 v[102:103], v[102:103], v[172:173], v[208:209]
	v_pk_fma_f32 v[100:101], v[100:101], v[164:165], v[234:235]
	v_cvt_pk_bf16_f32 v204, v104, v105
	v_cvt_pk_bf16_f32 v205, v106, v107
	v_add_co_u32_e32 v202, vcc, s18, v182
	v_cvt_pk_bf16_f32 v206, v100, v101
	v_cvt_pk_bf16_f32 v207, v102, v103
	v_addc_co_u32_e32 v203, vcc, 0, v183, vcc
	v_lshlrev_b32_e32 v106, 16, v204
	v_and_b32_e32 v107, 0xffff0000, v204
	v_lshlrev_b32_e32 v104, 16, v205
	v_and_b32_e32 v105, 0xffff0000, v205
	global_store_dwordx4 v[202:203], v[204:207], off offset:2048
	v_lshlrev_b32_e32 v102, 16, v206
	v_and_b32_e32 v103, 0xffff0000, v206
	v_lshlrev_b32_e32 v100, 16, v207
	v_and_b32_e32 v101, 0xffff0000, v207
	v_pk_mul_f32 v[204:205], v[138:139], v[104:105]
	v_pk_mul_f32 v[206:207], v[136:137], v[106:107]
	s_mov_b32 s0, 0x18000
	v_pk_mul_f32 v[220:221], v[134:135], v[100:101]
	v_pk_mul_f32 v[208:209], v[132:133], v[102:103]
	v_cvt_pk_bf16_f32 v206, v206, v207
	v_cvt_pk_bf16_f32 v207, v204, v205
	v_add_co_u32_e32 v204, vcc, s0, v178
	v_cvt_pk_bf16_f32 v208, v208, v209
	v_cvt_pk_bf16_f32 v209, v220, v221
	v_addc_co_u32_e32 v205, vcc, 0, v179, vcc
	global_store_dwordx4 v[204:205], v[206:209], off
	s_mov_b32 s0, 0xb0000
	s_waitcnt vmcnt(0)
	v_lshlrev_b32_e32 v220, 16, v212
	v_add_co_u32_e32 v206, vcc, s76, v196
	v_and_b32_e32 v221, 0xffff0000, v212
	s_nop 0
	v_addc_co_u32_e32 v207, vcc, 0, v197, vcc
	global_load_dwordx4 v[238:241], v[206:207], off offset:2048
	v_add_co_u32_e32 v208, vcc, s0, v196
	v_lshlrev_b32_e32 v212, 16, v213
	s_nop 0
	v_addc_co_u32_e32 v209, vcc, 0, v197, vcc
	global_load_dwordx4 v[242:245], v[208:209], off offset:2048
	v_and_b32_e32 v213, 0xffff0000, v213
	v_lshlrev_b32_e32 v234, 16, v214
	v_and_b32_e32 v235, 0xffff0000, v214
	v_lshlrev_b32_e32 v214, 16, v215
	v_and_b32_e32 v215, 0xffff0000, v215
	v_pk_fma_f32 v[98:99], v[98:99], v[176:177], v[212:213]
	v_pk_fma_f32 v[96:97], v[96:97], v[174:175], v[220:221]
	v_pk_fma_f32 v[94:95], v[94:95], v[172:173], v[214:215]
	v_pk_fma_f32 v[92:93], v[92:93], v[164:165], v[234:235]
	v_cvt_pk_bf16_f32 v214, v96, v97
	v_cvt_pk_bf16_f32 v215, v98, v99
	v_add_co_u32_e32 v212, vcc, s19, v182
	v_lshlrev_b32_e32 v246, 16, v216
	v_and_b32_e32 v247, 0xffff0000, v216
	v_lshlrev_b32_e32 v248, 16, v217
	v_and_b32_e32 v249, 0xffff0000, v217
	v_cvt_pk_bf16_f32 v216, v92, v93
	v_cvt_pk_bf16_f32 v217, v94, v95
	v_addc_co_u32_e32 v213, vcc, 0, v183, vcc
	v_lshlrev_b32_e32 v98, 16, v214
	v_and_b32_e32 v99, 0xffff0000, v214
	v_lshlrev_b32_e32 v96, 16, v215
	v_and_b32_e32 v97, 0xffff0000, v215
	global_store_dwordx4 v[212:213], v[214:217], off offset:2048
	v_lshlrev_b32_e32 v94, 16, v216
	v_and_b32_e32 v95, 0xffff0000, v216
	v_lshlrev_b32_e32 v92, 16, v217
	v_and_b32_e32 v93, 0xffff0000, v217
	v_pk_mul_f32 v[214:215], v[138:139], v[96:97]
	v_pk_mul_f32 v[216:217], v[136:137], v[98:99]
	s_mov_b32 s1, 0x40000
	v_lshlrev_b32_e32 v250, 16, v218
	v_and_b32_e32 v251, 0xffff0000, v218
	v_lshlrev_b32_e32 v252, 16, v219
	v_and_b32_e32 v253, 0xffff0000, v219
	v_pk_mul_f32 v[220:221], v[134:135], v[92:93]
	v_pk_mul_f32 v[218:219], v[132:133], v[94:95]
	v_cvt_pk_bf16_f32 v216, v216, v217
	v_cvt_pk_bf16_f32 v217, v214, v215
	v_add_co_u32_e32 v214, vcc, s1, v178
	v_cvt_pk_bf16_f32 v218, v218, v219
	v_cvt_pk_bf16_f32 v219, v220, v221
	v_addc_co_u32_e32 v215, vcc, 0, v179, vcc
	v_pk_fma_f32 v[90:91], v[90:91], v[176:177], v[248:249]
	global_store_dwordx4 v[214:215], v[216:219], off
	v_pk_fma_f32 v[88:89], v[88:89], v[174:175], v[246:247]
	v_pk_fma_f32 v[86:87], v[86:87], v[172:173], v[252:253]
	v_pk_fma_f32 v[84:85], v[84:85], v[164:165], v[250:251]
	v_cvt_pk_bf16_f32 v219, v90, v91
	v_add_co_u32_e32 v216, vcc, s26, v182
	v_cvt_pk_bf16_f32 v218, v88, v89
	v_cvt_pk_bf16_f32 v220, v84, v85
	v_cvt_pk_bf16_f32 v221, v86, v87
	v_addc_co_u32_e32 v217, vcc, 0, v183, vcc
	v_lshlrev_b32_e32 v88, 16, v219
	v_and_b32_e32 v89, 0xffff0000, v219
	global_store_dwordx4 v[216:217], v[218:221], off offset:2048
	v_lshlrev_b32_e32 v90, 16, v218
	v_and_b32_e32 v91, 0xffff0000, v218
	v_lshlrev_b32_e32 v86, 16, v220
	v_and_b32_e32 v87, 0xffff0000, v220
	v_lshlrev_b32_e32 v84, 16, v221
	v_and_b32_e32 v85, 0xffff0000, v221
	v_pk_mul_f32 v[218:219], v[138:139], v[88:89]
	s_mov_b32 s1, 0x48000
	v_pk_mul_f32 v[220:221], v[136:137], v[90:91]
	v_pk_mul_f32 v[234:235], v[134:135], v[84:85]
	v_pk_mul_f32 v[248:249], v[132:133], v[86:87]
	v_cvt_pk_bf16_f32 v247, v218, v219
	v_add_co_u32_e32 v218, vcc, s1, v178
	v_cvt_pk_bf16_f32 v246, v220, v221
	v_cvt_pk_bf16_f32 v248, v248, v249
	v_cvt_pk_bf16_f32 v249, v234, v235
	v_addc_co_u32_e32 v219, vcc, 0, v179, vcc
	global_store_dwordx4 v[218:219], v[246:249], off
	global_load_dwordx4 v[246:249], v[196:197], off offset:2304
	s_nop 0
	global_load_dwordx4 v[250:253], v[210:211], off offset:2304
	s_waitcnt vmcnt(0)
	v_lshlrev_b32_e32 v210, 16, v239
	v_and_b32_e32 v211, 0xffff0000, v239
	v_lshlrev_b32_e32 v196, 16, v238
	v_and_b32_e32 v197, 0xffff0000, v238
	v_pk_fma_f32 v[82:83], v[82:83], v[176:177], v[210:211]
	v_lshlrev_b32_e32 v220, 16, v240
	v_and_b32_e32 v221, 0xffff0000, v240
	v_lshlrev_b32_e32 v234, 16, v241
	v_and_b32_e32 v235, 0xffff0000, v241
	v_pk_fma_f32 v[80:81], v[80:81], v[174:175], v[196:197]
	v_cvt_pk_bf16_f32 v239, v82, v83
	v_pk_fma_f32 v[78:79], v[78:79], v[172:173], v[234:235]
	v_pk_fma_f32 v[76:77], v[76:77], v[164:165], v[220:221]
	v_cvt_pk_bf16_f32 v238, v80, v81
	v_add_co_u32_e32 v196, vcc, s76, v182
	v_lshlrev_b32_e32 v80, 16, v239
	v_and_b32_e32 v81, 0xffff0000, v239
	v_cvt_pk_bf16_f32 v240, v76, v77
	v_cvt_pk_bf16_f32 v241, v78, v79
	v_addc_co_u32_e32 v197, vcc, 0, v183, vcc
	v_pk_mul_f32 v[210:211], v[138:139], v[80:81]
	v_lshlrev_b32_e32 v166, 16, v242
	v_and_b32_e32 v167, 0xffff0000, v242
	v_lshlrev_b32_e32 v242, 16, v243
	v_and_b32_e32 v243, 0xffff0000, v243
	v_lshlrev_b32_e32 v168, 16, v244
	v_and_b32_e32 v169, 0xffff0000, v244
	v_lshlrev_b32_e32 v244, 16, v245
	v_and_b32_e32 v245, 0xffff0000, v245
	global_store_dwordx4 v[196:197], v[238:241], off offset:2048
	v_lshlrev_b32_e32 v82, 16, v238
	v_and_b32_e32 v83, 0xffff0000, v238
	v_cvt_pk_bf16_f32 v239, v210, v211
	v_add_co_u32_e32 v210, vcc, s77, v178
	v_lshlrev_b32_e32 v78, 16, v240
	v_and_b32_e32 v79, 0xffff0000, v240
	v_lshlrev_b32_e32 v76, 16, v241
	v_and_b32_e32 v77, 0xffff0000, v241
	v_pk_mul_f32 v[220:221], v[136:137], v[82:83]
	v_addc_co_u32_e32 v211, vcc, 0, v179, vcc
	v_pk_fma_f32 v[74:75], v[74:75], v[176:177], v[242:243]
	v_pk_fma_f32 v[72:73], v[72:73], v[174:175], v[166:167]
	v_pk_fma_f32 v[166:167], v[70:71], v[172:173], v[244:245]
	v_pk_fma_f32 v[70:71], v[68:69], v[164:165], v[168:169]
	v_pk_mul_f32 v[234:235], v[134:135], v[76:77]
	v_pk_mul_f32 v[240:241], v[132:133], v[78:79]
	v_cvt_pk_bf16_f32 v238, v220, v221
	v_cvt_pk_bf16_f32 v68, v72, v73
	v_cvt_pk_bf16_f32 v69, v74, v75
	v_cvt_pk_bf16_f32 v70, v70, v71
	v_cvt_pk_bf16_f32 v71, v166, v167
	v_add_co_u32_e32 v220, vcc, s0, v182
	v_cvt_pk_bf16_f32 v240, v240, v241
	v_cvt_pk_bf16_f32 v241, v234, v235
	v_addc_co_u32_e32 v221, vcc, 0, v183, vcc
	v_lshlrev_b32_e32 v176, 16, v68
	v_and_b32_e32 v177, 0xffff0000, v68
	v_lshlrev_b32_e32 v174, 16, v69
	v_and_b32_e32 v175, 0xffff0000, v69
	v_lshlrev_b32_e32 v172, 16, v70
	v_and_b32_e32 v173, 0xffff0000, v70
	v_lshlrev_b32_e32 v164, 16, v71
	v_and_b32_e32 v165, 0xffff0000, v71
	s_mov_b32 s0, 0x58000
	global_store_dwordx4 v[210:211], v[238:241], off
	global_store_dwordx4 v[220:221], v[68:71], off offset:2048
	v_pk_mul_f32 v[72:73], v[134:135], v[164:165]
	v_pk_mul_f32 v[74:75], v[132:133], v[172:173]
	v_pk_mul_f32 v[70:71], v[138:139], v[174:175]
	v_pk_mul_f32 v[68:69], v[136:137], v[176:177]
	v_add_co_u32_e32 v132, vcc, s0, v178
	v_cvt_pk_bf16_f32 v68, v68, v69
	v_cvt_pk_bf16_f32 v69, v70, v71
	v_cvt_pk_bf16_f32 v70, v74, v75
	v_cvt_pk_bf16_f32 v71, v72, v73
	v_addc_co_u32_e32 v133, vcc, 0, v179, vcc
	global_store_dwordx4 v[132:133], v[68:71], off
	global_load_dwordx4 v[134:137], v[184:185], off offset:2304
	global_load_dwordx4 v[238:241], v[188:189], off offset:2304
	s_nop 0
	global_load_dwordx4 v[68:71], v[180:181], off offset:528
	global_load_dwordx4 v[72:75], v[180:181], off offset:512
	v_lshlrev_b32_e32 v138, 16, v246
	v_and_b32_e32 v139, 0xffff0000, v246
	v_lshlrev_b32_e32 v166, 16, v247
	v_and_b32_e32 v167, 0xffff0000, v247
	v_lshlrev_b32_e32 v168, 16, v248
	v_and_b32_e32 v169, 0xffff0000, v248
	v_lshlrev_b32_e32 v180, 16, v249
	v_and_b32_e32 v181, 0xffff0000, v249
	v_pk_fma_f32 v[66:67], v[66:67], v[162:163], v[166:167]
	v_pk_fma_f32 v[64:65], v[64:65], v[160:161], v[138:139]
	v_pk_fma_f32 v[62:63], v[62:63], v[158:159], v[180:181]
	v_pk_fma_f32 v[60:61], v[60:61], v[156:157], v[168:169]
	v_cvt_pk_bf16_f32 v242, v64, v65
	v_cvt_pk_bf16_f32 v243, v66, v67
	v_cvt_pk_bf16_f32 v244, v60, v61
	v_cvt_pk_bf16_f32 v245, v62, v63
	v_lshlrev_b32_e32 v66, 16, v242
	v_and_b32_e32 v67, 0xffff0000, v242
	v_lshlrev_b32_e32 v64, 16, v243
	v_and_b32_e32 v65, 0xffff0000, v243
	v_lshlrev_b32_e32 v62, 16, v244
	v_and_b32_e32 v63, 0xffff0000, v244
	v_lshlrev_b32_e32 v60, 16, v245
	v_and_b32_e32 v61, 0xffff0000, v245
	v_lshlrev_b32_e32 v184, 16, v250
	v_and_b32_e32 v185, 0xffff0000, v250
	v_lshlrev_b32_e32 v188, 16, v251
	v_and_b32_e32 v189, 0xffff0000, v251
	v_lshlrev_b32_e32 v234, 16, v252
	v_and_b32_e32 v235, 0xffff0000, v252
	v_lshlrev_b32_e32 v246, 16, v253
	v_and_b32_e32 v247, 0xffff0000, v253
	global_store_dwordx4 v[182:183], v[242:245], off offset:2304
	v_pk_fma_f32 v[58:59], v[58:59], v[162:163], v[188:189]
	v_pk_fma_f32 v[56:57], v[56:57], v[160:161], v[184:185]
	v_pk_fma_f32 v[54:55], v[54:55], v[158:159], v[246:247]
	v_pk_fma_f32 v[52:53], v[52:53], v[156:157], v[234:235]
	s_waitcnt vmcnt(0)
	v_lshlrev_b32_e32 v188, 16, v240
	v_pk_mul_f32 v[168:169], v[70:71], v[60:61]
	v_pk_mul_f32 v[138:139], v[74:75], v[64:65]
	v_pk_mul_f32 v[166:167], v[72:73], v[66:67]
	v_pk_mul_f32 v[182:183], v[68:69], v[62:63]
	v_cvt_pk_bf16_f32 v180, v166, v167
	v_cvt_pk_bf16_f32 v181, v138, v139
	v_cvt_pk_bf16_f32 v182, v182, v183
	v_cvt_pk_bf16_f32 v183, v168, v169
	global_store_dwordx4 v[178:179], v[180:183], off offset:256
	v_cvt_pk_bf16_f32 v178, v56, v57
	v_cvt_pk_bf16_f32 v179, v58, v59
	v_cvt_pk_bf16_f32 v180, v52, v53
	v_cvt_pk_bf16_f32 v181, v54, v55
	v_lshlrev_b32_e32 v58, 16, v178
	v_and_b32_e32 v59, 0xffff0000, v178
	v_lshlrev_b32_e32 v56, 16, v179
	v_and_b32_e32 v57, 0xffff0000, v179
	v_lshlrev_b32_e32 v54, 16, v180
	v_and_b32_e32 v55, 0xffff0000, v180
	v_lshlrev_b32_e32 v52, 16, v181
	v_and_b32_e32 v53, 0xffff0000, v181
	global_store_dwordx4 v[186:187], v[178:181], off offset:2304
	v_pk_mul_f32 v[138:139], v[74:75], v[56:57]
	v_pk_mul_f32 v[166:167], v[72:73], v[58:59]
	v_pk_mul_f32 v[168:169], v[70:71], v[52:53]
	v_pk_mul_f32 v[180:181], v[68:69], v[54:55]
	v_cvt_pk_bf16_f32 v178, v166, v167
	v_cvt_pk_bf16_f32 v179, v138, v139
	v_cvt_pk_bf16_f32 v180, v180, v181
	v_cvt_pk_bf16_f32 v181, v168, v169
	v_lshlrev_b32_e32 v138, 16, v134
	v_and_b32_e32 v139, 0xffff0000, v134
	v_lshlrev_b32_e32 v134, 16, v135
	v_and_b32_e32 v135, 0xffff0000, v135
	v_lshlrev_b32_e32 v166, 16, v136
	v_and_b32_e32 v167, 0xffff0000, v136
	v_lshlrev_b32_e32 v136, 16, v137
	v_and_b32_e32 v137, 0xffff0000, v137
	global_store_dwordx4 v[190:191], v[178:181], off offset:256
	v_pk_fma_f32 v[50:51], v[50:51], v[162:163], v[134:135]
	v_pk_fma_f32 v[48:49], v[48:49], v[160:161], v[138:139]
	v_pk_fma_f32 v[46:47], v[46:47], v[158:159], v[136:137]
	v_pk_fma_f32 v[44:45], v[44:45], v[156:157], v[166:167]
	global_load_dwordx4 v[178:181], v[192:193], off offset:2304
	global_load_dwordx4 v[182:185], v[194:195], off offset:2304
	v_cvt_pk_bf16_f32 v134, v48, v49
	v_cvt_pk_bf16_f32 v135, v50, v51
	v_cvt_pk_bf16_f32 v136, v44, v45
	v_cvt_pk_bf16_f32 v137, v46, v47
	v_lshlrev_b32_e32 v50, 16, v134
	v_and_b32_e32 v51, 0xffff0000, v134
	v_lshlrev_b32_e32 v48, 16, v135
	v_and_b32_e32 v49, 0xffff0000, v135
	v_lshlrev_b32_e32 v46, 16, v136
	v_and_b32_e32 v47, 0xffff0000, v136
	v_lshlrev_b32_e32 v44, 16, v137
	v_and_b32_e32 v45, 0xffff0000, v137
	v_lshlrev_b32_e32 v168, 16, v238
	v_and_b32_e32 v169, 0xffff0000, v238
	v_lshlrev_b32_e32 v186, 16, v239
	v_and_b32_e32 v187, 0xffff0000, v239
	v_and_b32_e32 v189, 0xffff0000, v240
	v_lshlrev_b32_e32 v190, 16, v241
	v_and_b32_e32 v191, 0xffff0000, v241
	global_store_dwordx4 v[198:199], v[134:137], off offset:2304
	v_pk_mul_f32 v[138:139], v[70:71], v[44:45]
	v_pk_mul_f32 v[166:167], v[68:69], v[46:47]
	v_pk_mul_f32 v[136:137], v[74:75], v[48:49]
	v_pk_mul_f32 v[134:135], v[72:73], v[50:51]
	v_pk_fma_f32 v[42:43], v[42:43], v[162:163], v[186:187]
	v_cvt_pk_bf16_f32 v134, v134, v135
	v_cvt_pk_bf16_f32 v135, v136, v137
	v_cvt_pk_bf16_f32 v136, v166, v167
	v_cvt_pk_bf16_f32 v137, v138, v139
	v_pk_fma_f32 v[40:41], v[40:41], v[160:161], v[168:169]
	v_pk_fma_f32 v[38:39], v[38:39], v[158:159], v[190:191]
	v_pk_fma_f32 v[36:37], v[36:37], v[156:157], v[188:189]
	global_store_dwordx4 v[200:201], v[134:137], off offset:256
	v_mul_f32_e32 v67, v67, v67
	v_mul_f32_e32 v65, v65, v65
	v_cvt_pk_bf16_f32 v134, v40, v41
	v_cvt_pk_bf16_f32 v135, v42, v43
	v_cvt_pk_bf16_f32 v136, v36, v37
	v_cvt_pk_bf16_f32 v137, v38, v39
	v_lshlrev_b32_e32 v42, 16, v134
	v_and_b32_e32 v43, 0xffff0000, v134
	v_lshlrev_b32_e32 v40, 16, v135
	v_and_b32_e32 v41, 0xffff0000, v135
	v_lshlrev_b32_e32 v38, 16, v136
	v_and_b32_e32 v39, 0xffff0000, v136
	v_lshlrev_b32_e32 v36, 16, v137
	v_and_b32_e32 v37, 0xffff0000, v137
	global_store_dwordx4 v[202:203], v[134:137], off offset:2304
	v_pk_mul_f32 v[138:139], v[70:71], v[36:37]
	v_pk_mul_f32 v[166:167], v[68:69], v[38:39]
	v_pk_mul_f32 v[136:137], v[74:75], v[40:41]
	v_pk_mul_f32 v[134:135], v[72:73], v[42:43]
	v_fmac_f32_e32 v67, v66, v66
	v_cvt_pk_bf16_f32 v134, v134, v135
	v_cvt_pk_bf16_f32 v135, v136, v137
	v_cvt_pk_bf16_f32 v136, v166, v167
	v_cvt_pk_bf16_f32 v137, v138, v139
	global_store_dwordx4 v[204:205], v[134:137], off offset:256
	global_load_dwordx4 v[134:137], v[206:207], off offset:2304
	s_nop 0
	global_load_dwordx4 v[186:189], v[208:209], off offset:2304
	v_fmac_f32_e32 v65, v64, v64
	v_mul_f32_e32 v63, v63, v63
	v_mul_f32_e32 v61, v61, v61
	v_add_f32_e32 v64, v67, v65
	v_fmac_f32_e32 v63, v62, v62
	v_fmac_f32_e32 v61, v60, v60
	v_add_f32_e32 v60, v63, v61
	s_waitcnt vmcnt(0)
	v_lshlrev_b32_e32 v138, 16, v178
	v_and_b32_e32 v139, 0xffff0000, v178
	v_lshlrev_b32_e32 v166, 16, v179
	v_and_b32_e32 v167, 0xffff0000, v179
	v_lshlrev_b32_e32 v168, 16, v180
	v_and_b32_e32 v169, 0xffff0000, v180
	v_lshlrev_b32_e32 v178, 16, v181
	v_and_b32_e32 v179, 0xffff0000, v181
	v_pk_fma_f32 v[34:35], v[34:35], v[162:163], v[166:167]
	v_pk_fma_f32 v[32:33], v[32:33], v[160:161], v[138:139]
	v_pk_fma_f32 v[30:31], v[30:31], v[158:159], v[178:179]
	v_pk_fma_f32 v[28:29], v[28:29], v[156:157], v[168:169]
	v_cvt_pk_bf16_f32 v178, v32, v33
	v_cvt_pk_bf16_f32 v179, v34, v35
	v_cvt_pk_bf16_f32 v180, v28, v29
	v_cvt_pk_bf16_f32 v181, v30, v31
	v_lshlrev_b32_e32 v34, 16, v178
	v_and_b32_e32 v35, 0xffff0000, v178
	v_lshlrev_b32_e32 v32, 16, v179
	v_and_b32_e32 v33, 0xffff0000, v179
	v_lshlrev_b32_e32 v30, 16, v180
	v_and_b32_e32 v31, 0xffff0000, v180
	v_lshlrev_b32_e32 v28, 16, v181
	v_and_b32_e32 v29, 0xffff0000, v181
	v_lshlrev_b32_e32 v190, 16, v182
	v_and_b32_e32 v191, 0xffff0000, v182
	v_lshlrev_b32_e32 v182, 16, v183
	v_and_b32_e32 v183, 0xffff0000, v183
	global_store_dwordx4 v[212:213], v[178:181], off offset:2304
	v_pk_mul_f32 v[138:139], v[74:75], v[32:33]
	v_pk_mul_f32 v[166:167], v[72:73], v[34:35]
	v_pk_mul_f32 v[168:169], v[70:71], v[28:29]
	v_pk_mul_f32 v[180:181], v[68:69], v[30:31]
	v_cvt_pk_bf16_f32 v178, v166, v167
	v_cvt_pk_bf16_f32 v179, v138, v139
	v_cvt_pk_bf16_f32 v180, v180, v181
	v_cvt_pk_bf16_f32 v181, v168, v169
	v_pk_fma_f32 v[24:25], v[24:25], v[162:163], v[182:183]
	v_pk_fma_f32 v[22:23], v[22:23], v[160:161], v[190:191]
	v_lshlrev_b32_e32 v192, 16, v184
	v_and_b32_e32 v193, 0xffff0000, v184
	v_lshlrev_b32_e32 v184, 16, v185
	v_and_b32_e32 v185, 0xffff0000, v185
	global_store_dwordx4 v[214:215], v[178:181], off offset:256
	v_pk_fma_f32 v[20:21], v[20:21], v[158:159], v[184:185]
	v_pk_fma_f32 v[18:19], v[18:19], v[156:157], v[192:193]
	v_cvt_pk_bf16_f32 v178, v22, v23
	v_cvt_pk_bf16_f32 v179, v24, v25
	v_lshlrev_b32_e32 v24, 16, v178
	v_and_b32_e32 v25, 0xffff0000, v178
	v_lshlrev_b32_e32 v22, 16, v179
	v_and_b32_e32 v23, 0xffff0000, v179
	v_cvt_pk_bf16_f32 v180, v18, v19
	v_cvt_pk_bf16_f32 v181, v20, v21
	v_pk_mul_f32 v[138:139], v[74:75], v[22:23]
	v_pk_mul_f32 v[166:167], v[72:73], v[24:25]
	global_store_dwordx4 v[216:217], v[178:181], off offset:2304
	v_lshlrev_b32_e32 v20, 16, v180
	v_and_b32_e32 v21, 0xffff0000, v180
	v_cvt_pk_bf16_f32 v178, v166, v167
	v_cvt_pk_bf16_f32 v179, v138, v139
	v_lshlrev_b32_e32 v138, 16, v134
	v_and_b32_e32 v139, 0xffff0000, v134
	v_lshlrev_b32_e32 v134, 16, v135
	v_and_b32_e32 v135, 0xffff0000, v135
	v_lshlrev_b32_e32 v166, 16, v136
	v_and_b32_e32 v167, 0xffff0000, v136
	v_lshlrev_b32_e32 v136, 16, v137
	v_and_b32_e32 v137, 0xffff0000, v137
	v_lshlrev_b32_e32 v18, 16, v181
	v_and_b32_e32 v19, 0xffff0000, v181
	v_pk_fma_f32 v[16:17], v[16:17], v[162:163], v[134:135]
	v_pk_fma_f32 v[14:15], v[14:15], v[160:161], v[138:139]
	v_pk_fma_f32 v[12:13], v[12:13], v[158:159], v[136:137]
	v_pk_fma_f32 v[10:11], v[10:11], v[156:157], v[166:167]
	v_pk_mul_f32 v[168:169], v[70:71], v[18:19]
	v_pk_mul_f32 v[180:181], v[68:69], v[20:21]
	v_cvt_pk_bf16_f32 v134, v14, v15
	v_cvt_pk_bf16_f32 v135, v16, v17
	v_cvt_pk_bf16_f32 v136, v10, v11
	v_cvt_pk_bf16_f32 v137, v12, v13
	v_cvt_pk_bf16_f32 v180, v180, v181
	v_cvt_pk_bf16_f32 v181, v168, v169
	v_lshlrev_b32_e32 v16, 16, v134
	v_and_b32_e32 v17, 0xffff0000, v134
	v_lshlrev_b32_e32 v14, 16, v135
	v_and_b32_e32 v15, 0xffff0000, v135
	v_lshlrev_b32_e32 v12, 16, v136
	v_and_b32_e32 v13, 0xffff0000, v136
	v_lshlrev_b32_e32 v10, 16, v137
	v_and_b32_e32 v11, 0xffff0000, v137
	global_store_dwordx4 v[218:219], v[178:181], off offset:256
	v_lshlrev_b32_e32 v168, 16, v186
	v_and_b32_e32 v169, 0xffff0000, v186
	v_lshlrev_b32_e32 v178, 16, v187
	v_and_b32_e32 v179, 0xffff0000, v187
	v_lshlrev_b32_e32 v180, 16, v188
	v_and_b32_e32 v181, 0xffff0000, v188
	v_lshlrev_b32_e32 v182, 16, v189
	v_and_b32_e32 v183, 0xffff0000, v189
	global_store_dwordx4 v[196:197], v[134:137], off offset:2304
	v_pk_mul_f32 v[138:139], v[70:71], v[10:11]
	v_pk_mul_f32 v[166:167], v[68:69], v[12:13]
	v_pk_mul_f32 v[136:137], v[74:75], v[14:15]
	v_pk_mul_f32 v[134:135], v[72:73], v[16:17]
	v_pk_fma_f32 v[8:9], v[8:9], v[162:163], v[178:179]
	v_cvt_pk_bf16_f32 v134, v134, v135
	v_cvt_pk_bf16_f32 v135, v136, v137
	v_cvt_pk_bf16_f32 v136, v166, v167
	v_cvt_pk_bf16_f32 v137, v138, v139
	v_pk_fma_f32 v[6:7], v[6:7], v[160:161], v[168:169]
	v_pk_fma_f32 v[4:5], v[4:5], v[158:159], v[182:183]
	v_pk_fma_f32 v[2:3], v[2:3], v[156:157], v[180:181]
	global_store_dwordx4 v[210:211], v[134:137], off offset:256
	s_nop 1
	v_cvt_pk_bf16_f32 v134, v6, v7
	v_cvt_pk_bf16_f32 v135, v8, v9
	v_cvt_pk_bf16_f32 v136, v2, v3
	v_cvt_pk_bf16_f32 v137, v4, v5
	v_lshlrev_b32_e32 v8, 16, v134
	v_and_b32_e32 v9, 0xffff0000, v134
	v_lshlrev_b32_e32 v6, 16, v135
	v_and_b32_e32 v7, 0xffff0000, v135
	v_lshlrev_b32_e32 v4, 16, v136
	v_and_b32_e32 v5, 0xffff0000, v136
	v_lshlrev_b32_e32 v2, 16, v137
	v_and_b32_e32 v3, 0xffff0000, v137
	global_store_dwordx4 v[220:221], v[134:137], off offset:2304
	v_pk_mul_f32 v[74:75], v[74:75], v[6:7]
	v_pk_mul_f32 v[72:73], v[72:73], v[8:9]
	v_pk_mul_f32 v[134:135], v[70:71], v[2:3]
	v_pk_mul_f32 v[70:71], v[68:69], v[4:5]
	v_cvt_pk_bf16_f32 v68, v72, v73
	v_cvt_pk_bf16_f32 v69, v74, v75
	v_cvt_pk_bf16_f32 v70, v70, v71
	v_cvt_pk_bf16_f32 v71, v134, v135
	global_store_dwordx4 v[132:133], v[68:71], off offset:256
	v_xor_b32_e32 v72, 32, v227
	v_mul_f32_e32 v73, v129, v129
	v_and_b32_e32 v71, 64, v227
	v_xor_b32_e32 v70, 16, v227
	v_add_u32_e32 v71, 64, v71
	v_cmp_lt_i32_e32 vcc, v70, v71
	v_fmac_f32_e32 v73, v128, v128
	v_mul_f32_e32 v74, v125, v125
	v_cndmask_b32_e32 v70, v227, v70, vcc
	v_cmp_lt_i32_e32 vcc, v72, v71
	v_fmac_f32_e32 v74, v124, v124
	v_lshlrev_b32_e32 v70, 2, v70
	v_cndmask_b32_e32 v71, v227, v72, vcc
	v_mul_f32_e32 v72, v131, v131
	v_fmac_f32_e32 v72, v130, v130
	v_add_f32_e32 v72, v72, v73
	v_mul_f32_e32 v73, v127, v127
	v_fmac_f32_e32 v73, v126, v126
	v_add_f32_e32 v73, v73, v74
	v_add_f32_e32 v72, v72, v73
	v_add_f32_e32 v64, v72, v64
	v_add_f32_e32 v60, v60, v64
	ds_bpermute_b32 v61, v70, v60
	v_lshlrev_b32_e32 v71, 2, v71
	v_lshl_add_u64 v[68:69], v[150:151], 0, s[24:25]
	s_waitcnt lgkmcnt(0)
	v_add_f32_e32 v60, v60, v61
	ds_bpermute_b32 v61, v71, v60
	s_and_saveexec_b64 s[18:19], s[40:41]
	s_cbranch_execz .LBB0_364
	s_waitcnt lgkmcnt(0)
	v_add_f32_e32 v60, v60, v61
	global_atomic_add_f32 v[68:69], v60, off

.LBB0_394:
	s_add_u32 s18, s26, 0x100
	v_mov_b32_e32 v2, 0
	s_addc_u32 s19, s27, 0
	s_mov_b32 s52, -2
	v_mov_b32_e32 v3, v2
	v_mov_b32_e32 v4, v2
	s_waitcnt lgkmcnt(0)
	v_mov_b32_e32 v5, v2
	v_mov_b32_e32 v6, v2
	v_mov_b32_e32 v7, v2
	v_mov_b32_e32 v8, v2
	v_mov_b32_e32 v9, v2
	v_mov_b32_e32 v10, v2
	v_mov_b32_e32 v11, v2
	v_mov_b32_e32 v12, v2
	v_mov_b32_e32 v13, v2
	v_mov_b32_e32 v14, v2
	v_mov_b32_e32 v15, v2
	v_mov_b32_e32 v16, v2
	v_mov_b32_e32 v17, v2
	v_mov_b32_e32 v18, v2
	v_mov_b32_e32 v19, v2
	v_mov_b32_e32 v20, v2
	v_mov_b32_e32 v21, v2
	v_mov_b32_e32 v22, v2
	v_mov_b32_e32 v23, v2
	v_mov_b32_e32 v24, v2
	v_mov_b32_e32 v25, v2
	v_mov_b32_e32 v28, v2
	v_mov_b32_e32 v29, v2
	v_mov_b32_e32 v30, v2
	v_mov_b32_e32 v31, v2
	v_mov_b32_e32 v32, v2
	v_mov_b32_e32 v33, v2
	v_mov_b32_e32 v34, v2
	v_mov_b32_e32 v35, v2
	v_mov_b32_e32 v68, v2
	v_mov_b32_e32 v69, v2
	v_mov_b32_e32 v70, v2
	v_mov_b32_e32 v71, v2
	v_mov_b32_e32 v72, v2
	v_mov_b32_e32 v73, v2
	v_mov_b32_e32 v74, v2
	v_mov_b32_e32 v75, v2
	v_mov_b32_e32 v76, v2
	v_mov_b32_e32 v77, v2
	v_mov_b32_e32 v78, v2
	v_mov_b32_e32 v79, v2
	v_mov_b32_e32 v80, v2
	v_mov_b32_e32 v81, v2
	v_mov_b32_e32 v82, v2
	v_mov_b32_e32 v83, v2
	v_mov_b32_e32 v84, v2
	v_mov_b32_e32 v85, v2
	v_mov_b32_e32 v86, v2
	v_mov_b32_e32 v87, v2
	v_mov_b32_e32 v88, v2
	v_mov_b32_e32 v89, v2
	v_mov_b32_e32 v90, v2
	v_mov_b32_e32 v91, v2
	v_mov_b32_e32 v92, v2
	v_mov_b32_e32 v93, v2
	v_mov_b32_e32 v94, v2
	v_mov_b32_e32 v95, v2
	v_mov_b32_e32 v96, v2
	v_mov_b32_e32 v97, v2
	v_mov_b32_e32 v98, v2
	v_mov_b32_e32 v99, v2
	s_waitcnt vmcnt(0)
	v_mov_b32_e32 v36, v2
	v_mov_b32_e32 v37, v2
	v_mov_b32_e32 v38, v2
	v_mov_b32_e32 v39, v2
	v_mov_b32_e32 v40, v2
	v_mov_b32_e32 v41, v2
	v_mov_b32_e32 v42, v2
	v_mov_b32_e32 v43, v2
	v_mov_b32_e32 v44, v2
	v_mov_b32_e32 v45, v2
	v_mov_b32_e32 v46, v2
	v_mov_b32_e32 v47, v2
	v_mov_b32_e32 v48, v2
	v_mov_b32_e32 v49, v2
	v_mov_b32_e32 v50, v2
	v_mov_b32_e32 v51, v2
	v_mov_b32_e32 v52, v2
	v_mov_b32_e32 v53, v2
	v_mov_b32_e32 v54, v2
	v_mov_b32_e32 v55, v2
	v_mov_b32_e32 v56, v2
	v_mov_b32_e32 v57, v2
	v_mov_b32_e32 v58, v2
	v_mov_b32_e32 v59, v2
	v_mov_b32_e32 v60, v2
	v_mov_b32_e32 v61, v2
	v_mov_b32_e32 v62, v2
	v_mov_b32_e32 v63, v2
	v_mov_b32_e32 v64, v2
	v_mov_b32_e32 v65, v2
	v_mov_b32_e32 v66, v2
	v_mov_b32_e32 v67, v2
	v_mov_b32_e32 v108, v2
	v_mov_b32_e32 v109, v2
	v_mov_b32_e32 v110, v2
	v_mov_b32_e32 v111, v2
	v_mov_b32_e32 v112, v2
	v_mov_b32_e32 v113, v2
	v_mov_b32_e32 v114, v2
	v_mov_b32_e32 v115, v2
	v_mov_b32_e32 v116, v2
	v_mov_b32_e32 v117, v2
	v_mov_b32_e32 v118, v2
	v_mov_b32_e32 v119, v2
	v_mov_b32_e32 v120, v2
	v_mov_b32_e32 v121, v2
	v_mov_b32_e32 v122, v2
	v_mov_b32_e32 v123, v2
	v_mov_b32_e32 v124, v2
	v_mov_b32_e32 v125, v2
	v_mov_b32_e32 v126, v2
	v_mov_b32_e32 v127, v2
	v_mov_b32_e32 v128, v2
	v_mov_b32_e32 v129, v2
	v_mov_b32_e32 v130, v2
	v_mov_b32_e32 v131, v2
	v_mov_b32_e32 v132, v2
	v_mov_b32_e32 v133, v2
	v_mov_b32_e32 v134, v2
	v_mov_b32_e32 v135, v2
	v_mov_b32_e32 v136, v2
	v_mov_b32_e32 v137, v2
	v_mov_b32_e32 v138, v2
	v_mov_b32_e32 v139, v2
	v_add_u32_e32 v160, 0x10000, v233
	ds_read_b128 v[100:103], v160
	ds_read_b128 v[104:107], v160 offset:1024
	ds_read_b128 v[156:159], v160 offset:2048
	ds_read_b128 v[160:163], v160 offset:3072
.LBB0_395:
	s_add_u32 s26, s24, 0x100
	s_addc_u32 s27, s25, 0
	s_add_i32 s0, 0, 0x10000
	s_cmp_eq_u32 s52, 40
	s_cselect_b32 s31, s43, s27
	s_cselect_b32 s30, s42, s26
	s_cselect_b32 s29, s45, s19
	s_cselect_b32 s28, s44, s18
	v_lshl_add_u64 v[164:165], s[24:25], 0, v[152:153]
	s_add_i32 m0, s69, 0xc000
	ds_read_b128 v[172:175], v235
	ds_read_b128 v[176:179], v235 offset:1024
	ds_read_b128 v[180:183], v235 offset:2048
	ds_read_b128 v[184:187], v235 offset:3072
	ds_read_b128 v[188:191], v235 offset:4096
	ds_read_b128 v[192:195], v235 offset:5120
	ds_read_b128 v[196:199], v235 offset:6144
	ds_read_b128 v[200:203], v235 offset:7168
	global_load_lds_dwordx4 v[164:165], off
	v_lshl_add_u64 v[164:165], s[24:25], 0, v[154:155]
	s_add_i32 m0, s69, 0xe000
	s_nop 0
	global_load_lds_dwordx4 v[164:165], off
	s_waitcnt vmcnt(10) lgkmcnt(8)
	s_setprio 1
	s_barrier
	s_waitcnt lgkmcnt(0)
	v_mfma_f32_16x16x32_bf16 v[136:139], v[100:103], v[172:175], v[136:139]
	v_mfma_f32_16x16x32_bf16 v[132:135], v[156:159], v[172:175], v[132:135]
	v_mfma_f32_16x16x32_bf16 v[128:131], v[100:103], v[180:183], v[128:131]
	v_mfma_f32_16x16x32_bf16 v[124:127], v[156:159], v[180:183], v[124:127]
	v_mfma_f32_16x16x32_bf16 v[120:123], v[100:103], v[188:191], v[120:123]
	v_mfma_f32_16x16x32_bf16 v[116:119], v[156:159], v[188:191], v[116:119]
	v_mfma_f32_16x16x32_bf16 v[112:115], v[100:103], v[196:199], v[112:115]
	v_mfma_f32_16x16x32_bf16 v[108:111], v[156:159], v[196:199], v[108:111]
	v_mfma_f32_16x16x32_bf16 v[136:139], v[104:107], v[176:179], v[136:139]
	v_mfma_f32_16x16x32_bf16 v[132:135], v[160:163], v[176:179], v[132:135]
	v_mfma_f32_16x16x32_bf16 v[128:131], v[104:107], v[184:187], v[128:131]
	v_mfma_f32_16x16x32_bf16 v[124:127], v[160:163], v[184:187], v[124:127]
	v_mfma_f32_16x16x32_bf16 v[120:123], v[104:107], v[192:195], v[120:123]
	v_mfma_f32_16x16x32_bf16 v[116:119], v[160:163], v[192:195], v[116:119]
	v_mfma_f32_16x16x32_bf16 v[112:115], v[104:107], v[200:203], v[112:115]
	v_mfma_f32_16x16x32_bf16 v[108:111], v[160:163], v[200:203], v[108:111]
	s_barrier
	s_setprio 0
	s_add_i32 s24, 0, 0x14000
	v_add_u32_e32 v164, s24, v233
	s_add_i32 s0, s0, s68
	ds_read_b128 v[204:207], v164
	ds_read_b128 v[208:211], v164 offset:1024
	ds_read_b128 v[212:215], v164 offset:2048
	ds_read_b128 v[216:219], v164 offset:3072
	v_lshl_add_u64 v[164:165], s[28:29], 0, v[26:27]
	s_mov_b32 m0, s0
	v_lshl_add_u64 v[220:221], s[28:29], 0, v[140:141]
	global_load_lds_dwordx4 v[164:165], off
	s_add_i32 m0, s0, 0x2000
	s_nop 0
	global_load_lds_dwordx4 v[220:221], off
	s_waitcnt vmcnt(10)
	s_setprio 1
	s_barrier
	s_waitcnt lgkmcnt(0)
	v_mfma_f32_16x16x32_bf16 v[64:67], v[204:207], v[172:175], v[64:67]
	v_mfma_f32_16x16x32_bf16 v[60:63], v[212:215], v[172:175], v[60:63]
	v_mfma_f32_16x16x32_bf16 v[56:59], v[204:207], v[180:183], v[56:59]
	v_mfma_f32_16x16x32_bf16 v[52:55], v[212:215], v[180:183], v[52:55]
	v_mfma_f32_16x16x32_bf16 v[48:51], v[204:207], v[188:191], v[48:51]
	v_mfma_f32_16x16x32_bf16 v[44:47], v[212:215], v[188:191], v[44:47]
	v_mfma_f32_16x16x32_bf16 v[40:43], v[204:207], v[196:199], v[40:43]
	v_mfma_f32_16x16x32_bf16 v[36:39], v[212:215], v[196:199], v[36:39]
	v_mfma_f32_16x16x32_bf16 v[64:67], v[208:211], v[176:179], v[64:67]
	v_mfma_f32_16x16x32_bf16 v[60:63], v[216:219], v[176:179], v[60:63]
	v_mfma_f32_16x16x32_bf16 v[56:59], v[208:211], v[184:187], v[56:59]
	v_mfma_f32_16x16x32_bf16 v[52:55], v[216:219], v[184:187], v[52:55]
	v_mfma_f32_16x16x32_bf16 v[48:51], v[208:211], v[192:195], v[48:51]
	v_mfma_f32_16x16x32_bf16 v[44:47], v[216:219], v[192:195], v[44:47]
	v_mfma_f32_16x16x32_bf16 v[40:43], v[208:211], v[200:203], v[40:43]
	v_mfma_f32_16x16x32_bf16 v[36:39], v[216:219], v[200:203], v[36:39]
	s_barrier
	s_setprio 0
	s_mov_b32 m0, s69
	v_lshl_add_u64 v[222:223], s[30:31], 0, v[144:145]
	ds_read_b128 v[172:175], v235 offset:16384
	ds_read_b128 v[176:179], v235 offset:17408
	ds_read_b128 v[180:183], v235 offset:18432
	ds_read_b128 v[184:187], v235 offset:19456
	ds_read_b128 v[188:191], v235 offset:20480
	ds_read_b128 v[192:195], v235 offset:21504
	ds_read_b128 v[196:199], v235 offset:22528
	ds_read_b128 v[200:203], v235 offset:23552
	global_load_lds_dwordx4 v[222:223], off
	v_lshl_add_u64 v[224:225], s[30:31], 0, v[142:143]
	s_mov_b32 m0, s72
	s_nop 0
	global_load_lds_dwordx4 v[224:225], off
	s_waitcnt vmcnt(10)
	s_setprio 1
	s_barrier
	s_waitcnt lgkmcnt(0)
	v_mfma_f32_16x16x32_bf16 v[96:99], v[100:103], v[172:175], v[96:99]
	v_mfma_f32_16x16x32_bf16 v[92:95], v[156:159], v[172:175], v[92:95]
	v_mfma_f32_16x16x32_bf16 v[88:91], v[100:103], v[180:183], v[88:91]
	v_mfma_f32_16x16x32_bf16 v[84:87], v[156:159], v[180:183], v[84:87]
	v_mfma_f32_16x16x32_bf16 v[80:83], v[100:103], v[188:191], v[80:83]
	v_mfma_f32_16x16x32_bf16 v[76:79], v[156:159], v[188:191], v[76:79]
	v_mfma_f32_16x16x32_bf16 v[72:75], v[100:103], v[196:199], v[72:75]
	v_mfma_f32_16x16x32_bf16 v[68:71], v[156:159], v[196:199], v[68:71]
	v_mfma_f32_16x16x32_bf16 v[96:99], v[104:107], v[176:179], v[96:99]
	v_mfma_f32_16x16x32_bf16 v[92:95], v[160:163], v[176:179], v[92:95]
	v_mfma_f32_16x16x32_bf16 v[88:91], v[104:107], v[184:187], v[88:91]
	v_mfma_f32_16x16x32_bf16 v[84:87], v[160:163], v[184:187], v[84:87]
	v_mfma_f32_16x16x32_bf16 v[80:83], v[104:107], v[192:195], v[80:83]
	v_mfma_f32_16x16x32_bf16 v[76:79], v[160:163], v[192:195], v[76:79]
	v_mfma_f32_16x16x32_bf16 v[72:75], v[104:107], v[200:203], v[72:75]
	v_mfma_f32_16x16x32_bf16 v[68:71], v[160:163], v[200:203], v[68:71]
	s_barrier
	s_setprio 0
	s_add_u32 s0, s28, 0xb0000
	s_addc_u32 s1, s29, 0
	s_add_i32 s24, s24, s68
	v_lshl_add_u64 v[100:101], s[0:1], 0, v[26:27]
	s_mov_b32 m0, s24
	s_nop 0
	global_load_lds_dwordx4 v[100:101], off
	v_lshl_add_u64 v[100:101], s[0:1], 0, v[140:141]
	s_add_i32 m0, s24, 0x2000
	s_nop 0
	global_load_lds_dwordx4 v[100:101], off
	v_add_u32_e32 v160, 0x18000, v233
	ds_read_b128 v[100:103], v160
	ds_read_b128 v[104:107], v160 offset:1024
	ds_read_b128 v[156:159], v160 offset:2048
	ds_read_b128 v[160:163], v160 offset:3072
	s_waitcnt vmcnt(10)
	s_setprio 1
	s_barrier
	v_mfma_f32_16x16x32_bf16 v[32:35], v[204:207], v[172:175], v[32:35]
	v_mfma_f32_16x16x32_bf16 v[28:31], v[212:215], v[172:175], v[28:31]
	v_mfma_f32_16x16x32_bf16 v[22:25], v[204:207], v[180:183], v[22:25]
	v_mfma_f32_16x16x32_bf16 v[18:21], v[212:215], v[180:183], v[18:21]
	v_mfma_f32_16x16x32_bf16 v[14:17], v[204:207], v[188:191], v[14:17]
	v_mfma_f32_16x16x32_bf16 v[10:13], v[212:215], v[188:191], v[10:13]
	v_mfma_f32_16x16x32_bf16 v[6:9], v[204:207], v[196:199], v[6:9]
	v_mfma_f32_16x16x32_bf16 v[2:5], v[212:215], v[196:199], v[2:5]
	v_mfma_f32_16x16x32_bf16 v[32:35], v[208:211], v[176:179], v[32:35]
	v_mfma_f32_16x16x32_bf16 v[28:31], v[216:219], v[176:179], v[28:31]
	v_mfma_f32_16x16x32_bf16 v[22:25], v[208:211], v[184:187], v[22:25]
	v_mfma_f32_16x16x32_bf16 v[18:21], v[216:219], v[184:187], v[18:21]
	v_mfma_f32_16x16x32_bf16 v[14:17], v[208:211], v[192:195], v[14:17]
	v_mfma_f32_16x16x32_bf16 v[10:13], v[216:219], v[192:195], v[10:13]
	v_mfma_f32_16x16x32_bf16 v[6:9], v[208:211], v[200:203], v[6:9]
	v_mfma_f32_16x16x32_bf16 v[2:5], v[216:219], v[200:203], v[2:5]
	s_barrier
	s_setprio 0
	s_add_i32 s24, 0, 0x18000
	s_add_u32 s0, s30, 0xb0000
	s_addc_u32 s1, s31, 0
	s_mov_b32 m0, s73
	v_lshl_add_u64 v[204:205], s[0:1], 0, v[144:145]
	ds_read_b128 v[172:175], v235 offset:32768
	ds_read_b128 v[176:179], v235 offset:33792
	ds_read_b128 v[180:183], v235 offset:34816
	ds_read_b128 v[184:187], v235 offset:35840
	ds_read_b128 v[188:191], v235 offset:36864
	ds_read_b128 v[192:195], v235 offset:37888
	ds_read_b128 v[196:199], v235 offset:38912
	ds_read_b128 v[200:203], v235 offset:39936
	global_load_lds_dwordx4 v[204:205], off
	v_lshl_add_u64 v[204:205], s[0:1], 0, v[142:143]
	s_mov_b32 m0, s81
	s_nop 0
	global_load_lds_dwordx4 v[204:205], off
	s_waitcnt vmcnt(10) lgkmcnt(8)
	s_setprio 1
	s_barrier
	s_waitcnt lgkmcnt(0)
	v_mfma_f32_16x16x32_bf16 v[136:139], v[100:103], v[172:175], v[136:139]
	v_mfma_f32_16x16x32_bf16 v[132:135], v[156:159], v[172:175], v[132:135]
	v_mfma_f32_16x16x32_bf16 v[128:131], v[100:103], v[180:183], v[128:131]
	v_mfma_f32_16x16x32_bf16 v[124:127], v[156:159], v[180:183], v[124:127]
	v_mfma_f32_16x16x32_bf16 v[120:123], v[100:103], v[188:191], v[120:123]
	v_mfma_f32_16x16x32_bf16 v[116:119], v[156:159], v[188:191], v[116:119]
	v_mfma_f32_16x16x32_bf16 v[112:115], v[100:103], v[196:199], v[112:115]
	v_mfma_f32_16x16x32_bf16 v[108:111], v[156:159], v[196:199], v[108:111]
	v_mfma_f32_16x16x32_bf16 v[136:139], v[104:107], v[176:179], v[136:139]
	v_mfma_f32_16x16x32_bf16 v[132:135], v[160:163], v[176:179], v[132:135]
	v_mfma_f32_16x16x32_bf16 v[128:131], v[104:107], v[184:187], v[128:131]
	v_mfma_f32_16x16x32_bf16 v[124:127], v[160:163], v[184:187], v[124:127]
	v_mfma_f32_16x16x32_bf16 v[120:123], v[104:107], v[192:195], v[120:123]
	v_mfma_f32_16x16x32_bf16 v[116:119], v[160:163], v[192:195], v[116:119]
	v_mfma_f32_16x16x32_bf16 v[112:115], v[104:107], v[200:203], v[112:115]
	v_mfma_f32_16x16x32_bf16 v[108:111], v[160:163], v[200:203], v[108:111]
	s_barrier
	s_setprio 0
	s_add_i32 s25, 0, 0x1c000
	s_add_i32 s0, s24, s68
	v_add_u32_e32 v166, s25, v233
	v_lshl_add_u64 v[164:165], v[164:165], 0, s[12:13]
	s_mov_b32 m0, s0
	ds_read_b128 v[204:207], v166
	ds_read_b128 v[208:211], v166 offset:1024
	ds_read_b128 v[212:215], v166 offset:2048
	ds_read_b128 v[216:219], v166 offset:3072
	global_load_lds_dwordx4 v[164:165], off
	v_lshl_add_u64 v[164:165], v[220:221], 0, s[12:13]
	s_add_i32 m0, s0, 0x2000
	s_nop 0
	global_load_lds_dwordx4 v[164:165], off
	s_waitcnt vmcnt(10)
	s_setprio 1
	s_barrier
	s_waitcnt lgkmcnt(0)
	v_mfma_f32_16x16x32_bf16 v[64:67], v[204:207], v[172:175], v[64:67]
	v_mfma_f32_16x16x32_bf16 v[60:63], v[212:215], v[172:175], v[60:63]
	v_mfma_f32_16x16x32_bf16 v[56:59], v[204:207], v[180:183], v[56:59]
	v_mfma_f32_16x16x32_bf16 v[52:55], v[212:215], v[180:183], v[52:55]
	v_mfma_f32_16x16x32_bf16 v[48:51], v[204:207], v[188:191], v[48:51]
	v_mfma_f32_16x16x32_bf16 v[44:47], v[212:215], v[188:191], v[44:47]
	v_mfma_f32_16x16x32_bf16 v[40:43], v[204:207], v[196:199], v[40:43]
	v_mfma_f32_16x16x32_bf16 v[36:39], v[212:215], v[196:199], v[36:39]
	v_mfma_f32_16x16x32_bf16 v[64:67], v[208:211], v[176:179], v[64:67]
	v_mfma_f32_16x16x32_bf16 v[60:63], v[216:219], v[176:179], v[60:63]
	v_mfma_f32_16x16x32_bf16 v[56:59], v[208:211], v[184:187], v[56:59]
	v_mfma_f32_16x16x32_bf16 v[52:55], v[216:219], v[184:187], v[52:55]
	v_mfma_f32_16x16x32_bf16 v[48:51], v[208:211], v[192:195], v[48:51]
	v_mfma_f32_16x16x32_bf16 v[44:47], v[216:219], v[192:195], v[44:47]
	v_mfma_f32_16x16x32_bf16 v[40:43], v[208:211], v[200:203], v[40:43]
	v_mfma_f32_16x16x32_bf16 v[36:39], v[216:219], v[200:203], v[36:39]
	s_barrier
	s_setprio 0
	s_mov_b32 m0, s21
	v_lshl_add_u64 v[164:165], v[222:223], 0, s[12:13]
	ds_read_b128 v[172:175], v235 offset:49152
	ds_read_b128 v[176:179], v235 offset:50176
	ds_read_b128 v[180:183], v235 offset:51200
	ds_read_b128 v[184:187], v235 offset:52224
	ds_read_b128 v[188:191], v235 offset:53248
	ds_read_b128 v[192:195], v235 offset:54272
	ds_read_b128 v[196:199], v235 offset:55296
	ds_read_b128 v[200:203], v235 offset:56320
	global_load_lds_dwordx4 v[164:165], off
	v_lshl_add_u64 v[164:165], v[224:225], 0, s[12:13]
	s_mov_b32 m0, s48
	s_nop 0
	global_load_lds_dwordx4 v[164:165], off
	s_waitcnt vmcnt(10)
	s_setprio 1
	s_barrier
	s_waitcnt lgkmcnt(0)
	v_mfma_f32_16x16x32_bf16 v[96:99], v[100:103], v[172:175], v[96:99]
	v_mfma_f32_16x16x32_bf16 v[92:95], v[156:159], v[172:175], v[92:95]
	v_mfma_f32_16x16x32_bf16 v[88:91], v[100:103], v[180:183], v[88:91]
	v_mfma_f32_16x16x32_bf16 v[84:87], v[156:159], v[180:183], v[84:87]
	v_mfma_f32_16x16x32_bf16 v[80:83], v[100:103], v[188:191], v[80:83]
	v_mfma_f32_16x16x32_bf16 v[76:79], v[156:159], v[188:191], v[76:79]
	v_mfma_f32_16x16x32_bf16 v[72:75], v[100:103], v[196:199], v[72:75]
	v_mfma_f32_16x16x32_bf16 v[68:71], v[156:159], v[196:199], v[68:71]
	v_mfma_f32_16x16x32_bf16 v[96:99], v[104:107], v[176:179], v[96:99]
	v_mfma_f32_16x16x32_bf16 v[92:95], v[160:163], v[176:179], v[92:95]
	v_mfma_f32_16x16x32_bf16 v[88:91], v[104:107], v[184:187], v[88:91]
	v_mfma_f32_16x16x32_bf16 v[84:87], v[160:163], v[184:187], v[84:87]
	v_mfma_f32_16x16x32_bf16 v[80:83], v[104:107], v[192:195], v[80:83]
	v_mfma_f32_16x16x32_bf16 v[76:79], v[160:163], v[192:195], v[76:79]
	v_mfma_f32_16x16x32_bf16 v[72:75], v[104:107], v[200:203], v[72:75]
	v_mfma_f32_16x16x32_bf16 v[68:71], v[160:163], v[200:203], v[68:71]
	s_barrier
	s_setprio 0
	s_add_u32 s0, s28, 0xb0080
	s_addc_u32 s1, s29, 0
	s_add_i32 s24, s25, s68
	v_lshl_add_u64 v[100:101], s[0:1], 0, v[26:27]
	s_mov_b32 m0, s24
	s_nop 0
	global_load_lds_dwordx4 v[100:101], off
	v_lshl_add_u64 v[100:101], s[0:1], 0, v[140:141]
	s_add_i32 m0, s24, 0x2000
	s_nop 0
	global_load_lds_dwordx4 v[100:101], off
	v_add_u32_e32 v160, 0x10000, v233
	ds_read_b128 v[100:103], v160
	ds_read_b128 v[104:107], v160 offset:1024
	ds_read_b128 v[156:159], v160 offset:2048
	ds_read_b128 v[160:163], v160 offset:3072
	s_waitcnt vmcnt(10)
	s_setprio 1
	s_barrier
	v_mfma_f32_16x16x32_bf16 v[32:35], v[204:207], v[172:175], v[32:35]
	v_mfma_f32_16x16x32_bf16 v[28:31], v[212:215], v[172:175], v[28:31]
	v_mfma_f32_16x16x32_bf16 v[22:25], v[204:207], v[180:183], v[22:25]
	v_mfma_f32_16x16x32_bf16 v[18:21], v[212:215], v[180:183], v[18:21]
	v_mfma_f32_16x16x32_bf16 v[14:17], v[204:207], v[188:191], v[14:17]
	v_mfma_f32_16x16x32_bf16 v[10:13], v[212:215], v[188:191], v[10:13]
	v_mfma_f32_16x16x32_bf16 v[6:9], v[204:207], v[196:199], v[6:9]
	v_mfma_f32_16x16x32_bf16 v[2:5], v[212:215], v[196:199], v[2:5]
	v_mfma_f32_16x16x32_bf16 v[32:35], v[208:211], v[176:179], v[32:35]
	v_mfma_f32_16x16x32_bf16 v[28:31], v[216:219], v[176:179], v[28:31]
	v_mfma_f32_16x16x32_bf16 v[22:25], v[208:211], v[184:187], v[22:25]
	v_mfma_f32_16x16x32_bf16 v[18:21], v[216:219], v[184:187], v[18:21]
	v_mfma_f32_16x16x32_bf16 v[14:17], v[208:211], v[192:195], v[14:17]
	v_mfma_f32_16x16x32_bf16 v[10:13], v[216:219], v[192:195], v[10:13]
	v_mfma_f32_16x16x32_bf16 v[6:9], v[208:211], v[200:203], v[6:9]
	v_mfma_f32_16x16x32_bf16 v[2:5], v[216:219], v[200:203], v[2:5]
	s_barrier
	s_setprio 0
	s_add_i32 s52, s52, 2
	s_add_u32 s18, s18, 0x100
	s_addc_u32 s19, s19, 0
	s_cmp_gt_u32 s52, 41
	s_mov_b64 s[24:25], s[26:27]
	s_cbranch_scc0 .LBB0_395
	s_waitcnt lgkmcnt(0)
	s_min_i32 s0, s22, 0x100
	s_ashr_i32 s0, s0, 5
	s_ashr_i32 s1, s0, 31
	s_add_i32 s18, s22, 0xffffff00
	s_cmpk_lt_i32 s22, 0x100
	s_cselect_b32 s18, s22, s18
	s_cselect_b32 s25, 0, s35
	s_cselect_b32 s24, 0, s34
	s_cselect_b32 s26, 0, s57
	s_cselect_b32 s27, 0, s58
	s_ashr_i32 s19, s18, 31
	s_add_u32 s24, s46, s24
	s_addc_u32 s25, s47, s25
	s_lshl_b64 s[18:19], s[18:19], 20
	v_lshl_add_u64 v[100:101], s[18:19], 0, v[146:147]
	s_add_u32 s18, s50, s26
	v_lshl_or_b32 v172, s23, 8, v234
	s_addc_u32 s19, s51, s27
	s_ashr_i32 s23, s22, 31
	v_lshl_add_u64 v[180:181], s[18:19], 0, v[100:101]
	s_lshl_b64 s[18:19], s[22:23], 19
	v_lshl_add_u64 v[184:185], v[148:149], 0, s[18:19]
	s_lshl_b64 s[52:53], s[22:23], 10
	s_mul_i32 s18, s0, 0x9000
	v_ashrrev_i32_e32 v173, 31, v172
	s_mul_hi_i32 s19, s0, 0x9000
	s_add_u32 s18, s36, s18
	s_addc_u32 s19, s37, s19
	v_lshlrev_b64 v[186:187], 2, v[172:173]
	v_lshl_add_u64 v[156:157], s[18:19], 0, v[186:187]
	v_lshl_add_u64 v[164:165], s[24:25], 0, v[100:101]
	global_load_dwordx4 v[100:103], v[156:157], off offset:16
	global_load_dwordx4 v[104:107], v[156:157], off
	s_lshl_b64 s[0:1], s[0:1], 12
	s_add_u32 s0, s59, s0
	s_addc_u32 s1, s20, s1
	v_lshl_add_u64 v[164:165], v[164:165], 0, v[186:187]
	s_mov_b32 s18, 0x20000
	s_waitcnt vmcnt(0)
	v_pk_mul_f32 v[178:179], v[102:103], 0.5 op_sel_hi:[1,0]
	v_pk_mul_f32 v[174:175], v[106:107], 0.5 op_sel_hi:[1,0]
	v_pk_mul_f32 v[176:177], v[104:105], 0.5 op_sel_hi:[1,0]
	v_pk_mul_f32 v[210:211], v[100:101], 0.5 op_sel_hi:[1,0]
	global_load_dwordx4 v[100:103], v[156:157], off offset:528
	global_load_dwordx4 v[104:107], v[156:157], off offset:512
	s_waitcnt vmcnt(0)
	v_pk_mul_f32 v[162:163], v[100:101], 0.5 op_sel_hi:[1,0]
	v_lshlrev_b64 v[100:101], 1, v[172:173]
	v_lshl_add_u64 v[182:183], v[180:181], 0, v[100:101]
	v_lshl_add_u64 v[180:181], v[184:185], 0, v[100:101]
	v_lshl_add_u64 v[184:185], s[0:1], 0, v[186:187]
	v_pk_mul_f32 v[156:157], v[106:107], 0.5 op_sel_hi:[1,0]
	v_pk_mul_f32 v[158:159], v[104:105], 0.5 op_sel_hi:[1,0]
	v_pk_mul_f32 v[160:161], v[102:103], 0.5 op_sel_hi:[1,0]
	global_load_dwordx4 v[100:103], v[184:185], off offset:16
	global_load_dwordx4 v[104:107], v[184:185], off
	global_load_dwordx4 v[188:191], v[164:165], off offset:16
	global_load_dwordx4 v[192:195], v[164:165], off
	v_add_co_u32_e32 v186, vcc, s65, v164
	s_mov_b64 s[0:1], 0x10000
	s_nop 0
	v_addc_co_u32_e32 v187, vcc, 0, v165, vcc
	v_lshl_add_u64 v[172:173], v[164:165], 0, s[0:1]
	global_load_dwordx4 v[196:199], v[186:187], off
	global_load_dwordx4 v[200:203], v[172:173], off offset:16
	s_mov_b32 s0, 0x8000
	s_waitcnt vmcnt(0)
	v_pk_fma_f32 v[134:135], v[134:135], v[178:179], v[190:191]
	v_pk_fma_f32 v[138:139], v[138:139], v[174:175], v[194:195]
	v_pk_fma_f32 v[136:137], v[136:137], v[176:177], v[192:193]
	v_pk_fma_f32 v[132:133], v[132:133], v[210:211], v[188:189]
	v_cvt_pk_bf16_f32 v188, v136, v137
	v_cvt_pk_bf16_f32 v189, v138, v139
	v_cvt_pk_bf16_f32 v190, v132, v133
	v_cvt_pk_bf16_f32 v191, v134, v135
	v_lshlrev_b32_e32 v138, 16, v188
	v_and_b32_e32 v139, 0xffff0000, v188
	v_lshlrev_b32_e32 v136, 16, v189
	v_and_b32_e32 v137, 0xffff0000, v189
	global_store_dwordx4 v[182:183], v[188:191], off offset:2048
	v_lshlrev_b32_e32 v134, 16, v190
	v_and_b32_e32 v135, 0xffff0000, v190
	v_lshlrev_b32_e32 v132, 16, v191
	v_and_b32_e32 v133, 0xffff0000, v191
	v_pk_mul_f32 v[172:173], v[106:107], v[136:137]
	v_pk_mul_f32 v[188:189], v[104:105], v[138:139]
	v_pk_mul_f32 v[192:193], v[102:103], v[132:133]
	v_pk_mul_f32 v[190:191], v[100:101], v[134:135]
	v_cvt_pk_bf16_f32 v188, v188, v189
	v_cvt_pk_bf16_f32 v189, v172, v173
	v_pk_fma_f32 v[130:131], v[130:131], v[174:175], v[198:199]
	v_pk_fma_f32 v[128:129], v[128:129], v[176:177], v[196:197]
	v_pk_fma_f32 v[172:173], v[126:127], v[178:179], v[202:203]
	v_pk_fma_f32 v[126:127], v[124:125], v[210:211], v[200:201]
	v_add_co_u32_e32 v202, vcc, s65, v182
	v_cvt_pk_bf16_f32 v190, v190, v191
	v_cvt_pk_bf16_f32 v191, v192, v193
	v_cvt_pk_bf16_f32 v124, v128, v129
	v_cvt_pk_bf16_f32 v125, v130, v131
	v_cvt_pk_bf16_f32 v126, v126, v127
	v_cvt_pk_bf16_f32 v127, v172, v173
	v_addc_co_u32_e32 v203, vcc, 0, v183, vcc
	global_store_dwordx4 v[180:181], v[188:191], off
	global_store_dwordx4 v[202:203], v[124:127], off offset:2048
	v_lshlrev_b32_e32 v128, 16, v124
	v_and_b32_e32 v129, 0xffff0000, v124
	v_lshlrev_b32_e32 v124, 16, v125
	v_and_b32_e32 v125, 0xffff0000, v125
	v_lshlrev_b32_e32 v130, 16, v126
	v_and_b32_e32 v131, 0xffff0000, v126
	v_lshlrev_b32_e32 v126, 16, v127
	v_and_b32_e32 v127, 0xffff0000, v127
	v_pk_mul_f32 v[172:173], v[106:107], v[124:125]
	v_pk_mul_f32 v[188:189], v[104:105], v[128:129]
	v_pk_mul_f32 v[192:193], v[102:103], v[126:127]
	v_pk_mul_f32 v[190:191], v[100:101], v[130:131]
	v_add_co_u32_e32 v220, vcc, s0, v180
	v_cvt_pk_bf16_f32 v188, v188, v189
	v_cvt_pk_bf16_f32 v189, v172, v173
	v_cvt_pk_bf16_f32 v190, v190, v191
	v_cvt_pk_bf16_f32 v191, v192, v193
	v_addc_co_u32_e32 v221, vcc, 0, v181, vcc
	global_store_dwordx4 v[220:221], v[188:191], off
	s_mov_b64 s[0:1], 0x20000
	v_lshl_add_u64 v[172:173], v[164:165], 0, s[0:1]
	v_add_co_u32_e32 v188, vcc, s18, v164
	s_mov_b64 s[0:1], 0x30000
	s_nop 0
	v_addc_co_u32_e32 v189, vcc, 0, v165, vcc
	global_load_dwordx4 v[192:195], v[188:189], off
	global_load_dwordx4 v[196:199], v[172:173], off offset:16
	v_lshl_add_u64 v[172:173], v[164:165], 0, s[0:1]
	s_mov_b32 s0, 0x30000
	v_add_co_u32_e32 v190, vcc, s0, v164
	s_waitcnt vmcnt(0)
	v_pk_fma_f32 v[120:121], v[120:121], v[176:177], v[192:193]
	v_addc_co_u32_e32 v191, vcc, 0, v165, vcc
	global_load_dwordx4 v[204:207], v[190:191], off
	global_load_dwordx4 v[212:215], v[172:173], off offset:16
	v_pk_fma_f32 v[122:123], v[122:123], v[174:175], v[194:195]
	v_pk_fma_f32 v[118:119], v[118:119], v[178:179], v[198:199]
	v_pk_fma_f32 v[116:117], v[116:117], v[210:211], v[196:197]
	v_cvt_pk_bf16_f32 v194, v120, v121
	v_add_co_u32_e32 v192, vcc, s18, v182
	v_cvt_pk_bf16_f32 v195, v122, v123
	v_cvt_pk_bf16_f32 v196, v116, v117
	v_cvt_pk_bf16_f32 v197, v118, v119
	v_addc_co_u32_e32 v193, vcc, 0, v183, vcc
	v_lshlrev_b32_e32 v122, 16, v194
	v_and_b32_e32 v123, 0xffff0000, v194
	global_store_dwordx4 v[192:193], v[194:197], off offset:2048
	v_lshlrev_b32_e32 v120, 16, v195
	v_and_b32_e32 v121, 0xffff0000, v195
	v_pk_mul_f32 v[194:195], v[104:105], v[122:123]
	v_lshlrev_b32_e32 v118, 16, v196
	v_and_b32_e32 v119, 0xffff0000, v196
	v_cvt_pk_bf16_f32 v196, v194, v195
	v_add_co_u32_e32 v194, vcc, s65, v180
	v_lshlrev_b32_e32 v116, 16, v197
	v_and_b32_e32 v117, 0xffff0000, v197
	v_pk_mul_f32 v[172:173], v[106:107], v[120:121]
	v_addc_co_u32_e32 v195, vcc, 0, v181, vcc
	v_pk_mul_f32 v[200:201], v[102:103], v[116:117]
	v_pk_mul_f32 v[198:199], v[100:101], v[118:119]
	v_cvt_pk_bf16_f32 v197, v172, v173
	v_cvt_pk_bf16_f32 v198, v198, v199
	v_cvt_pk_bf16_f32 v199, v200, v201
	global_store_dwordx4 v[194:195], v[196:199], off
	s_mov_b32 s18, 0x80000
	s_waitcnt vmcnt(0)
	v_pk_fma_f32 v[114:115], v[114:115], v[174:175], v[206:207]
	v_pk_fma_f32 v[112:113], v[112:113], v[176:177], v[204:205]
	v_pk_fma_f32 v[172:173], v[110:111], v[178:179], v[214:215]
	v_pk_fma_f32 v[110:111], v[108:109], v[210:211], v[212:213]
	v_add_co_u32_e32 v212, vcc, s0, v182
	v_cvt_pk_bf16_f32 v108, v112, v113
	v_cvt_pk_bf16_f32 v109, v114, v115
	v_cvt_pk_bf16_f32 v110, v110, v111
	v_cvt_pk_bf16_f32 v111, v172, v173
	v_addc_co_u32_e32 v213, vcc, 0, v183, vcc
	global_store_dwordx4 v[212:213], v[108:111], off offset:2048
	v_lshlrev_b32_e32 v112, 16, v108
	v_and_b32_e32 v113, 0xffff0000, v108
	v_lshlrev_b32_e32 v172, 16, v109
	v_and_b32_e32 v173, 0xffff0000, v109
	v_lshlrev_b32_e32 v114, 16, v110
	v_and_b32_e32 v115, 0xffff0000, v110
	v_lshlrev_b32_e32 v108, 16, v111
	v_and_b32_e32 v109, 0xffff0000, v111
	s_mov_b32 s0, 0x18000
	v_pk_mul_f32 v[110:111], v[106:107], v[172:173]
	v_pk_mul_f32 v[196:197], v[104:105], v[112:113]
	v_pk_mul_f32 v[200:201], v[102:103], v[108:109]
	v_pk_mul_f32 v[198:199], v[100:101], v[114:115]
	v_add_co_u32_e32 v222, vcc, s0, v180
	v_cvt_pk_bf16_f32 v196, v196, v197
	v_cvt_pk_bf16_f32 v197, v110, v111
	v_cvt_pk_bf16_f32 v198, v198, v199
	v_cvt_pk_bf16_f32 v199, v200, v201
	v_addc_co_u32_e32 v223, vcc, 0, v181, vcc
	global_store_dwordx4 v[222:223], v[196:199], off
	s_mov_b64 s[0:1], 0x80000
	v_lshl_add_u64 v[110:111], v[164:165], 0, s[0:1]
	v_add_co_u32_e32 v196, vcc, s18, v164
	s_mov_b64 s[0:1], 0x90000
	s_nop 0
	v_addc_co_u32_e32 v197, vcc, 0, v165, vcc
	global_load_dwordx4 v[204:207], v[196:197], off
	global_load_dwordx4 v[214:217], v[110:111], off offset:16
	v_lshl_add_u64 v[110:111], v[164:165], 0, s[0:1]
	s_mov_b32 s0, 0x90000
	v_add_co_u32_e32 v198, vcc, s0, v164
	s_mov_b32 s1, 0x40000
	s_nop 0
	v_addc_co_u32_e32 v199, vcc, 0, v165, vcc
	global_load_dwordx4 v[238:241], v[198:199], off
	global_load_dwordx4 v[242:245], v[110:111], off offset:16
	v_add_co_u32_e32 v200, vcc, s18, v182
	s_waitcnt vmcnt(0)
	v_pk_fma_f32 v[96:97], v[96:97], v[176:177], v[204:205]
	v_pk_fma_f32 v[98:99], v[98:99], v[174:175], v[206:207]
	v_pk_fma_f32 v[94:95], v[94:95], v[178:179], v[216:217]
	v_pk_fma_f32 v[92:93], v[92:93], v[210:211], v[214:215]
	v_cvt_pk_bf16_f32 v204, v96, v97
	v_cvt_pk_bf16_f32 v205, v98, v99
	v_cvt_pk_bf16_f32 v206, v92, v93
	v_cvt_pk_bf16_f32 v207, v94, v95
	v_addc_co_u32_e32 v201, vcc, 0, v183, vcc
	v_lshlrev_b32_e32 v98, 16, v204
	v_and_b32_e32 v99, 0xffff0000, v204
	global_store_dwordx4 v[200:201], v[204:207], off offset:2048
	v_lshlrev_b32_e32 v96, 16, v205
	v_and_b32_e32 v97, 0xffff0000, v205
	v_pk_mul_f32 v[204:205], v[104:105], v[98:99]
	v_lshlrev_b32_e32 v94, 16, v206
	v_and_b32_e32 v95, 0xffff0000, v206
	v_cvt_pk_bf16_f32 v206, v204, v205
	v_add_co_u32_e32 v204, vcc, s1, v180
	v_lshlrev_b32_e32 v92, 16, v207
	v_and_b32_e32 v93, 0xffff0000, v207
	v_pk_mul_f32 v[110:111], v[106:107], v[96:97]
	v_addc_co_u32_e32 v205, vcc, 0, v181, vcc
	v_pk_mul_f32 v[214:215], v[102:103], v[92:93]
	v_pk_mul_f32 v[208:209], v[100:101], v[94:95]
	v_cvt_pk_bf16_f32 v207, v110, v111
	v_pk_fma_f32 v[90:91], v[90:91], v[174:175], v[240:241]
	v_pk_fma_f32 v[88:89], v[88:89], v[176:177], v[238:239]
	v_pk_fma_f32 v[110:111], v[86:87], v[178:179], v[244:245]
	v_pk_fma_f32 v[86:87], v[84:85], v[210:211], v[242:243]
	v_add_co_u32_e32 v218, vcc, s0, v182
	v_cvt_pk_bf16_f32 v208, v208, v209
	v_cvt_pk_bf16_f32 v209, v214, v215
	v_cvt_pk_bf16_f32 v84, v88, v89
	v_cvt_pk_bf16_f32 v85, v90, v91
	v_cvt_pk_bf16_f32 v86, v86, v87
	v_cvt_pk_bf16_f32 v87, v110, v111
	v_addc_co_u32_e32 v219, vcc, 0, v183, vcc
	global_store_dwordx4 v[204:205], v[206:209], off
	global_store_dwordx4 v[218:219], v[84:87], off offset:2048
	v_lshlrev_b32_e32 v88, 16, v84
	v_and_b32_e32 v89, 0xffff0000, v84
	v_lshlrev_b32_e32 v110, 16, v85
	v_and_b32_e32 v111, 0xffff0000, v85
	v_lshlrev_b32_e32 v90, 16, v86
	v_and_b32_e32 v91, 0xffff0000, v86
	v_lshlrev_b32_e32 v84, 16, v87
	v_and_b32_e32 v85, 0xffff0000, v87
	s_mov_b32 s0, 0x48000
	v_pk_mul_f32 v[86:87], v[106:107], v[110:111]
	v_pk_mul_f32 v[206:207], v[104:105], v[88:89]
	v_pk_mul_f32 v[214:215], v[102:103], v[84:85]
	v_pk_mul_f32 v[208:209], v[100:101], v[90:91]
	v_add_co_u32_e32 v224, vcc, s0, v180
	v_cvt_pk_bf16_f32 v206, v206, v207
	v_cvt_pk_bf16_f32 v207, v86, v87
	v_cvt_pk_bf16_f32 v208, v208, v209
	v_cvt_pk_bf16_f32 v209, v214, v215
	v_addc_co_u32_e32 v225, vcc, 0, v181, vcc
	global_store_dwordx4 v[224:225], v[206:209], off
	s_mov_b64 s[0:1], 0xa0000
	v_lshl_add_u64 v[86:87], v[164:165], 0, s[0:1]
	v_add_co_u32_e32 v206, vcc, s76, v164
	s_mov_b64 s[0:1], 0xb0000
	s_nop 0
	v_addc_co_u32_e32 v207, vcc, 0, v165, vcc
	global_load_dwordx4 v[214:217], v[206:207], off
	global_load_dwordx4 v[238:241], v[86:87], off offset:16
	v_lshl_add_u64 v[86:87], v[164:165], 0, s[0:1]
	s_mov_b32 s0, 0xb0000
	v_add_co_u32_e32 v208, vcc, s0, v164
	s_waitcnt vmcnt(0)
	v_pk_fma_f32 v[80:81], v[80:81], v[176:177], v[214:215]
	v_addc_co_u32_e32 v209, vcc, 0, v165, vcc
	global_load_dwordx4 v[242:245], v[208:209], off
	global_load_dwordx4 v[246:249], v[86:87], off offset:16
	v_pk_fma_f32 v[82:83], v[82:83], v[174:175], v[216:217]
	v_pk_fma_f32 v[76:77], v[76:77], v[210:211], v[238:239]
	v_cvt_pk_bf16_f32 v238, v80, v81
	v_pk_fma_f32 v[78:79], v[78:79], v[178:179], v[240:241]
	v_cvt_pk_bf16_f32 v239, v82, v83
	v_add_co_u32_e32 v214, vcc, s76, v182
	v_lshlrev_b32_e32 v82, 16, v238
	v_and_b32_e32 v83, 0xffff0000, v238
	v_cvt_pk_bf16_f32 v240, v76, v77
	v_cvt_pk_bf16_f32 v241, v78, v79
	v_addc_co_u32_e32 v215, vcc, 0, v183, vcc
	v_lshlrev_b32_e32 v80, 16, v239
	v_and_b32_e32 v81, 0xffff0000, v239
	v_pk_mul_f32 v[216:217], v[104:105], v[82:83]
	global_store_dwordx4 v[214:215], v[238:241], off offset:2048
	v_pk_mul_f32 v[86:87], v[106:107], v[80:81]
	v_lshlrev_b32_e32 v78, 16, v240
	v_cvt_pk_bf16_f32 v238, v216, v217
	v_add_co_u32_e32 v216, vcc, s77, v180
	v_and_b32_e32 v79, 0xffff0000, v240
	v_lshlrev_b32_e32 v76, 16, v241
	v_and_b32_e32 v77, 0xffff0000, v241
	v_cvt_pk_bf16_f32 v239, v86, v87
	v_addc_co_u32_e32 v217, vcc, 0, v181, vcc
	v_pk_mul_f32 v[250:251], v[102:103], v[76:77]
	v_pk_mul_f32 v[240:241], v[100:101], v[78:79]
	s_waitcnt vmcnt(0)
	v_pk_fma_f32 v[74:75], v[74:75], v[174:175], v[244:245]
	v_pk_fma_f32 v[72:73], v[72:73], v[176:177], v[242:243]
	v_pk_fma_f32 v[86:87], v[70:71], v[178:179], v[248:249]
	v_pk_fma_f32 v[70:71], v[68:69], v[210:211], v[246:247]
	v_cvt_pk_bf16_f32 v68, v72, v73
	v_cvt_pk_bf16_f32 v69, v74, v75
	v_cvt_pk_bf16_f32 v70, v70, v71
	v_cvt_pk_bf16_f32 v71, v86, v87
	v_add_co_u32_e32 v210, vcc, s0, v182
	v_cvt_pk_bf16_f32 v240, v240, v241
	v_cvt_pk_bf16_f32 v241, v250, v251
	v_addc_co_u32_e32 v211, vcc, 0, v183, vcc
	v_lshlrev_b32_e32 v86, 16, v68
	v_and_b32_e32 v87, 0xffff0000, v68
	v_lshlrev_b32_e32 v178, 16, v69
	v_and_b32_e32 v179, 0xffff0000, v69
	v_lshlrev_b32_e32 v176, 16, v70
	v_and_b32_e32 v177, 0xffff0000, v70
	v_lshlrev_b32_e32 v174, 16, v71
	v_and_b32_e32 v175, 0xffff0000, v71
	s_mov_b32 s0, 0x58000
	global_store_dwordx4 v[216:217], v[238:241], off
	global_store_dwordx4 v[210:211], v[68:71], off offset:2048
	v_pk_mul_f32 v[72:73], v[102:103], v[174:175]
	v_pk_mul_f32 v[74:75], v[100:101], v[176:177]
	v_pk_mul_f32 v[70:71], v[106:107], v[178:179]
	v_pk_mul_f32 v[68:69], v[104:105], v[86:87]
	v_add_co_u32_e32 v100, vcc, s0, v180
	v_cvt_pk_bf16_f32 v68, v68, v69
	v_cvt_pk_bf16_f32 v69, v70, v71
	v_cvt_pk_bf16_f32 v70, v74, v75
	v_cvt_pk_bf16_f32 v71, v72, v73
	v_addc_co_u32_e32 v101, vcc, 0, v181, vcc
	global_store_dwordx4 v[100:101], v[68:71], off
	global_load_dwordx4 v[68:71], v[184:185], off offset:528
	s_nop 0
	global_load_dwordx4 v[72:75], v[184:185], off offset:512
	global_load_dwordx4 v[102:105], v[164:165], off offset:528
	global_load_dwordx4 v[238:241], v[164:165], off offset:512
	s_mov_b64 s[0:1], 0x10200
	v_lshl_add_u64 v[106:107], v[164:165], 0, s[0:1]
	global_load_dwordx4 v[184:187], v[186:187], off offset:512
	s_nop 0
	global_load_dwordx4 v[242:245], v[106:107], off offset:16
	s_mov_b64 s[0:1], 0x20200
	s_waitcnt vmcnt(0)
	v_pk_fma_f32 v[62:63], v[62:63], v[160:161], v[104:105]
	v_pk_fma_f32 v[66:67], v[66:67], v[156:157], v[240:241]
	v_pk_fma_f32 v[64:65], v[64:65], v[158:159], v[238:239]
	v_pk_fma_f32 v[60:61], v[60:61], v[162:163], v[102:103]
	v_cvt_pk_bf16_f32 v102, v64, v65
	v_cvt_pk_bf16_f32 v103, v66, v67
	v_cvt_pk_bf16_f32 v104, v60, v61
	v_cvt_pk_bf16_f32 v105, v62, v63
	v_lshlrev_b32_e32 v66, 16, v102
	v_and_b32_e32 v67, 0xffff0000, v102
	v_lshlrev_b32_e32 v64, 16, v103
	v_and_b32_e32 v65, 0xffff0000, v103
	v_lshlrev_b32_e32 v62, 16, v104
	v_and_b32_e32 v63, 0xffff0000, v104
	v_lshlrev_b32_e32 v60, 16, v105
	v_and_b32_e32 v61, 0xffff0000, v105
	global_store_dwordx4 v[182:183], v[102:105], off offset:2304
	v_pk_mul_f32 v[106:107], v[70:71], v[60:61]
	v_pk_mul_f32 v[182:183], v[68:69], v[62:63]
	v_pk_mul_f32 v[104:105], v[74:75], v[64:65]
	v_pk_mul_f32 v[102:103], v[72:73], v[66:67]
	v_pk_fma_f32 v[58:59], v[58:59], v[156:157], v[186:187]
	v_cvt_pk_bf16_f32 v102, v102, v103
	v_cvt_pk_bf16_f32 v103, v104, v105
	v_cvt_pk_bf16_f32 v104, v182, v183
	v_cvt_pk_bf16_f32 v105, v106, v107
	v_pk_fma_f32 v[56:57], v[56:57], v[158:159], v[184:185]
	v_pk_fma_f32 v[54:55], v[54:55], v[160:161], v[244:245]
	v_pk_fma_f32 v[52:53], v[52:53], v[162:163], v[242:243]
	global_store_dwordx4 v[180:181], v[102:105], off offset:256
	v_mul_f32_e32 v67, v67, v67
	v_mul_f32_e32 v65, v65, v65
	v_cvt_pk_bf16_f32 v102, v56, v57
	v_cvt_pk_bf16_f32 v103, v58, v59
	v_cvt_pk_bf16_f32 v104, v52, v53
	v_cvt_pk_bf16_f32 v105, v54, v55
	v_lshlrev_b32_e32 v58, 16, v102
	v_and_b32_e32 v59, 0xffff0000, v102
	v_lshlrev_b32_e32 v56, 16, v103
	v_and_b32_e32 v57, 0xffff0000, v103
	v_lshlrev_b32_e32 v54, 16, v104
	v_and_b32_e32 v55, 0xffff0000, v104
	v_lshlrev_b32_e32 v52, 16, v105
	v_and_b32_e32 v53, 0xffff0000, v105
	global_store_dwordx4 v[202:203], v[102:105], off offset:2304
	v_pk_mul_f32 v[106:107], v[70:71], v[52:53]
	v_pk_mul_f32 v[180:181], v[68:69], v[54:55]
	v_pk_mul_f32 v[104:105], v[74:75], v[56:57]
	v_pk_mul_f32 v[102:103], v[72:73], v[58:59]
	v_fmac_f32_e32 v67, v66, v66
	v_cvt_pk_bf16_f32 v102, v102, v103
	v_cvt_pk_bf16_f32 v103, v104, v105
	v_cvt_pk_bf16_f32 v104, v180, v181
	v_cvt_pk_bf16_f32 v105, v106, v107
	global_store_dwordx4 v[220:221], v[102:105], off offset:256
	v_lshl_add_u64 v[106:107], v[164:165], 0, s[0:1]
	global_load_dwordx4 v[102:105], v[188:189], off offset:512
	global_load_dwordx4 v[180:183], v[106:107], off offset:16
	s_mov_b64 s[0:1], 0x30200
	v_lshl_add_u64 v[106:107], v[164:165], 0, s[0:1]
	global_load_dwordx4 v[184:187], v[190:191], off offset:512
	s_nop 0
	global_load_dwordx4 v[188:191], v[106:107], off offset:16
	s_mov_b64 s[0:1], 0x80200
	v_fmac_f32_e32 v65, v64, v64
	v_mul_f32_e32 v63, v63, v63
	v_mul_f32_e32 v61, v61, v61
	v_add_f32_e32 v64, v67, v65
	v_fmac_f32_e32 v63, v62, v62
	v_fmac_f32_e32 v61, v60, v60
	v_add_f32_e32 v60, v63, v61
	s_waitcnt vmcnt(0)
	v_pk_fma_f32 v[50:51], v[50:51], v[156:157], v[104:105]
	v_pk_fma_f32 v[48:49], v[48:49], v[158:159], v[102:103]
	v_pk_fma_f32 v[46:47], v[46:47], v[160:161], v[182:183]
	v_pk_fma_f32 v[44:45], v[44:45], v[162:163], v[180:181]
	v_cvt_pk_bf16_f32 v102, v48, v49
	v_cvt_pk_bf16_f32 v103, v50, v51
	v_cvt_pk_bf16_f32 v104, v44, v45
	v_cvt_pk_bf16_f32 v105, v46, v47
	v_lshlrev_b32_e32 v50, 16, v102
	v_and_b32_e32 v51, 0xffff0000, v102
	v_lshlrev_b32_e32 v48, 16, v103
	v_and_b32_e32 v49, 0xffff0000, v103
	v_lshlrev_b32_e32 v46, 16, v104
	v_and_b32_e32 v47, 0xffff0000, v104
	v_lshlrev_b32_e32 v44, 16, v105
	v_and_b32_e32 v45, 0xffff0000, v105
	global_store_dwordx4 v[192:193], v[102:105], off offset:2304
	v_pk_mul_f32 v[106:107], v[70:71], v[44:45]
	v_pk_mul_f32 v[180:181], v[68:69], v[46:47]
	v_pk_mul_f32 v[104:105], v[74:75], v[48:49]
	v_pk_mul_f32 v[102:103], v[72:73], v[50:51]
	v_pk_fma_f32 v[42:43], v[42:43], v[156:157], v[186:187]
	v_cvt_pk_bf16_f32 v102, v102, v103
	v_cvt_pk_bf16_f32 v103, v104, v105
	v_cvt_pk_bf16_f32 v104, v180, v181
	v_cvt_pk_bf16_f32 v105, v106, v107
	v_pk_fma_f32 v[40:41], v[40:41], v[158:159], v[184:185]
	v_pk_fma_f32 v[38:39], v[38:39], v[160:161], v[190:191]
	v_pk_fma_f32 v[36:37], v[36:37], v[162:163], v[188:189]
	global_store_dwordx4 v[194:195], v[102:105], off offset:256
	s_nop 1
	v_cvt_pk_bf16_f32 v102, v40, v41
	v_cvt_pk_bf16_f32 v103, v42, v43
	v_cvt_pk_bf16_f32 v104, v36, v37
	v_cvt_pk_bf16_f32 v105, v38, v39
	v_lshlrev_b32_e32 v42, 16, v102
	v_and_b32_e32 v43, 0xffff0000, v102
	v_lshlrev_b32_e32 v40, 16, v103
	v_and_b32_e32 v41, 0xffff0000, v103
	v_lshlrev_b32_e32 v38, 16, v104
	v_and_b32_e32 v39, 0xffff0000, v104
	v_lshlrev_b32_e32 v36, 16, v105
	v_and_b32_e32 v37, 0xffff0000, v105
	global_store_dwordx4 v[212:213], v[102:105], off offset:2304
	v_pk_mul_f32 v[106:107], v[70:71], v[36:37]
	v_pk_mul_f32 v[180:181], v[68:69], v[38:39]
	v_pk_mul_f32 v[104:105], v[74:75], v[40:41]
	v_pk_mul_f32 v[102:103], v[72:73], v[42:43]
	s_nop 0
	v_cvt_pk_bf16_f32 v102, v102, v103
	v_cvt_pk_bf16_f32 v103, v104, v105
	v_cvt_pk_bf16_f32 v104, v180, v181
	v_cvt_pk_bf16_f32 v105, v106, v107
	global_store_dwordx4 v[222:223], v[102:105], off offset:256
	v_lshl_add_u64 v[106:107], v[164:165], 0, s[0:1]
	global_load_dwordx4 v[102:105], v[196:197], off offset:512
	global_load_dwordx4 v[180:183], v[106:107], off offset:16
	s_mov_b64 s[0:1], 0x90200
	v_lshl_add_u64 v[106:107], v[164:165], 0, s[0:1]
	global_load_dwordx4 v[184:187], v[198:199], off offset:512
	global_load_dwordx4 v[188:191], v[106:107], off offset:16
	s_mov_b64 s[0:1], 0xa0200
	s_waitcnt vmcnt(0)
	v_pk_fma_f32 v[34:35], v[34:35], v[156:157], v[104:105]
	v_pk_fma_f32 v[32:33], v[32:33], v[158:159], v[102:103]
	v_pk_fma_f32 v[30:31], v[30:31], v[160:161], v[182:183]
	v_pk_fma_f32 v[28:29], v[28:29], v[162:163], v[180:181]
	v_cvt_pk_bf16_f32 v102, v32, v33
	v_cvt_pk_bf16_f32 v103, v34, v35
	v_cvt_pk_bf16_f32 v104, v28, v29
	v_cvt_pk_bf16_f32 v105, v30, v31
	v_lshlrev_b32_e32 v34, 16, v102
	v_and_b32_e32 v35, 0xffff0000, v102
	v_lshlrev_b32_e32 v32, 16, v103
	v_and_b32_e32 v33, 0xffff0000, v103
	v_lshlrev_b32_e32 v30, 16, v104
	v_and_b32_e32 v31, 0xffff0000, v104
	v_lshlrev_b32_e32 v28, 16, v105
	v_and_b32_e32 v29, 0xffff0000, v105
	global_store_dwordx4 v[200:201], v[102:105], off offset:2304
	v_pk_mul_f32 v[106:107], v[70:71], v[28:29]
	v_pk_mul_f32 v[180:181], v[68:69], v[30:31]
	v_pk_mul_f32 v[104:105], v[74:75], v[32:33]
	v_pk_mul_f32 v[102:103], v[72:73], v[34:35]
	v_pk_fma_f32 v[24:25], v[24:25], v[156:157], v[186:187]
	v_cvt_pk_bf16_f32 v102, v102, v103
	v_cvt_pk_bf16_f32 v103, v104, v105
	v_cvt_pk_bf16_f32 v104, v180, v181
	v_cvt_pk_bf16_f32 v105, v106, v107
	v_pk_fma_f32 v[22:23], v[22:23], v[158:159], v[184:185]
	v_pk_fma_f32 v[20:21], v[20:21], v[160:161], v[190:191]
	v_pk_fma_f32 v[18:19], v[18:19], v[162:163], v[188:189]
	global_store_dwordx4 v[204:205], v[102:105], off offset:256
	s_nop 1
	v_cvt_pk_bf16_f32 v102, v22, v23
	v_cvt_pk_bf16_f32 v103, v24, v25
	v_cvt_pk_bf16_f32 v104, v18, v19
	v_cvt_pk_bf16_f32 v105, v20, v21
	v_lshlrev_b32_e32 v24, 16, v102
	v_and_b32_e32 v25, 0xffff0000, v102
	v_lshlrev_b32_e32 v22, 16, v103
	v_and_b32_e32 v23, 0xffff0000, v103
	v_lshlrev_b32_e32 v20, 16, v104
	v_and_b32_e32 v21, 0xffff0000, v104
	v_lshlrev_b32_e32 v18, 16, v105
	v_and_b32_e32 v19, 0xffff0000, v105
	global_store_dwordx4 v[218:219], v[102:105], off offset:2304
	v_pk_mul_f32 v[106:107], v[70:71], v[18:19]
	v_pk_mul_f32 v[180:181], v[68:69], v[20:21]
	v_pk_mul_f32 v[104:105], v[74:75], v[22:23]
	v_pk_mul_f32 v[102:103], v[72:73], v[24:25]
	s_nop 0
	v_cvt_pk_bf16_f32 v102, v102, v103
	v_cvt_pk_bf16_f32 v103, v104, v105
	v_cvt_pk_bf16_f32 v104, v180, v181
	v_cvt_pk_bf16_f32 v105, v106, v107
	global_store_dwordx4 v[224:225], v[102:105], off offset:256
	v_lshl_add_u64 v[106:107], v[164:165], 0, s[0:1]
	global_load_dwordx4 v[102:105], v[206:207], off offset:512
	global_load_dwordx4 v[180:183], v[106:107], off offset:16
	s_mov_b64 s[0:1], 0xb0200
	v_lshl_add_u64 v[106:107], v[164:165], 0, s[0:1]
	global_load_dwordx4 v[184:187], v[208:209], off offset:512
	global_load_dwordx4 v[188:191], v[106:107], off offset:16
	s_waitcnt vmcnt(0)
	v_pk_fma_f32 v[16:17], v[16:17], v[156:157], v[104:105]
	v_pk_fma_f32 v[14:15], v[14:15], v[158:159], v[102:103]
	v_pk_fma_f32 v[102:103], v[12:13], v[160:161], v[182:183]
	v_pk_fma_f32 v[12:13], v[10:11], v[162:163], v[180:181]
	v_cvt_pk_bf16_f32 v10, v14, v15
	v_cvt_pk_bf16_f32 v11, v16, v17
	v_cvt_pk_bf16_f32 v12, v12, v13
	v_cvt_pk_bf16_f32 v13, v102, v103
	v_lshlrev_b32_e32 v102, 16, v10
	v_and_b32_e32 v103, 0xffff0000, v10
	v_lshlrev_b32_e32 v16, 16, v11
	v_and_b32_e32 v17, 0xffff0000, v11
	global_store_dwordx4 v[214:215], v[10:13], off offset:2304
	v_lshlrev_b32_e32 v14, 16, v12
	v_and_b32_e32 v15, 0xffff0000, v12
	v_lshlrev_b32_e32 v12, 16, v13
	v_and_b32_e32 v13, 0xffff0000, v13
	v_pk_mul_f32 v[10:11], v[74:75], v[16:17]
	v_pk_mul_f32 v[104:105], v[72:73], v[102:103]
	v_pk_mul_f32 v[164:165], v[70:71], v[12:13]
	v_pk_mul_f32 v[106:107], v[68:69], v[14:15]
	v_cvt_pk_bf16_f32 v104, v104, v105
	v_cvt_pk_bf16_f32 v105, v10, v11
	v_pk_fma_f32 v[8:9], v[8:9], v[156:157], v[186:187]
	v_pk_fma_f32 v[6:7], v[6:7], v[158:159], v[184:185]
	v_pk_fma_f32 v[10:11], v[4:5], v[160:161], v[190:191]
	v_pk_fma_f32 v[4:5], v[2:3], v[162:163], v[188:189]
	v_cvt_pk_bf16_f32 v106, v106, v107
	v_cvt_pk_bf16_f32 v107, v164, v165
	v_cvt_pk_bf16_f32 v2, v6, v7
	v_cvt_pk_bf16_f32 v3, v8, v9
	v_cvt_pk_bf16_f32 v4, v4, v5
	v_cvt_pk_bf16_f32 v5, v10, v11
	global_store_dwordx4 v[216:217], v[104:107], off offset:256
	global_store_dwordx4 v[210:211], v[2:5], off offset:2304
	v_lshlrev_b32_e32 v10, 16, v2
	v_and_b32_e32 v11, 0xffff0000, v2
	v_lshlrev_b32_e32 v8, 16, v3
	v_and_b32_e32 v9, 0xffff0000, v3
	v_lshlrev_b32_e32 v6, 16, v4
	v_and_b32_e32 v7, 0xffff0000, v4
	v_lshlrev_b32_e32 v4, 16, v5
	v_and_b32_e32 v5, 0xffff0000, v5
	v_pk_mul_f32 v[2:3], v[74:75], v[8:9]
	v_pk_mul_f32 v[72:73], v[72:73], v[10:11]
	v_pk_mul_f32 v[74:75], v[70:71], v[4:5]
	v_pk_mul_f32 v[70:71], v[68:69], v[6:7]
	v_cvt_pk_bf16_f32 v68, v72, v73
	v_cvt_pk_bf16_f32 v69, v2, v3
	v_cvt_pk_bf16_f32 v70, v70, v71
	v_cvt_pk_bf16_f32 v71, v74, v75
	global_store_dwordx4 v[100:101], v[68:71], off offset:256
	v_mul_f32_e32 v72, v133, v133
	v_fmac_f32_e32 v72, v132, v132
	v_and_b32_e32 v69, 64, v227
	v_xor_b32_e32 v68, 16, v227
	v_add_u32_e32 v69, 64, v69
	v_cmp_lt_i32_e32 vcc, v68, v69
	v_xor_b32_e32 v70, 32, v227
	v_mul_f32_e32 v71, v137, v137
	v_cndmask_b32_e32 v68, v227, v68, vcc
	v_cmp_lt_i32_e32 vcc, v70, v69
	v_fmac_f32_e32 v71, v136, v136
	v_lshlrev_b32_e32 v68, 2, v68
	v_cndmask_b32_e32 v69, v227, v70, vcc
	v_mul_f32_e32 v70, v139, v139
	v_fmac_f32_e32 v70, v138, v138
	v_add_f32_e32 v70, v70, v71
	v_mul_f32_e32 v71, v135, v135
	v_fmac_f32_e32 v71, v134, v134
	v_add_f32_e32 v71, v71, v72
	v_add_f32_e32 v70, v70, v71
	v_add_f32_e32 v64, v70, v64
	v_add_f32_e32 v60, v64, v60
	ds_bpermute_b32 v61, v68, v60
	v_lshlrev_b32_e32 v69, 2, v69
	v_lshl_add_u64 v[2:3], v[150:151], 0, s[52:53]
	s_waitcnt lgkmcnt(0)
	v_add_f32_e32 v60, v60, v61
	ds_bpermute_b32 v61, v69, v60
	s_and_saveexec_b64 s[18:19], s[38:39]
	s_cbranch_execz .LBB0_398
	s_waitcnt lgkmcnt(0)
	v_add_f32_e32 v60, v60, v61
	global_atomic_add_f32 v[2:3], v60, off

.LBB0_478:
	s_ashr_i32 s49, s48, 31
	s_lshl_b64 s[0:1], s[48:49], 19
	s_add_u32 s52, s16, s0
	v_cmp_lt_i64_e32 vcc, s[26:27], v[170:171]
	s_addc_u32 s53, s17, s1
	s_and_b64 s[0:1], vcc, exec
	s_cselect_b32 s35, s53, s23
	s_cselect_b32 s40, s52, s22
	s_ashr_i32 s51, s50, 31
	s_lshl_b64 s[0:1], s[50:51], 19
	s_add_u32 s54, s20, s0
	s_addc_u32 s55, s21, s1
	s_and_b64 s[0:1], vcc, exec
	s_cselect_b32 s41, s55, s25
	s_cselect_b32 s49, s54, s24
	s_add_u32 s22, s22, 0x40080
	s_addc_u32 s23, s23, 0
	s_add_u32 s51, s24, 0x100
	v_mov_b32_e32 v2, 0
	s_addc_u32 s59, s25, 0
	s_mov_b32 s68, -2
	v_mov_b32_e32 v3, v2
	v_mov_b32_e32 v4, v2
	v_mov_b32_e32 v5, v2
	v_mov_b32_e32 v6, v2
	v_mov_b32_e32 v7, v2
	v_mov_b32_e32 v8, v2
	v_mov_b32_e32 v9, v2
	v_mov_b32_e32 v10, v2
	v_mov_b32_e32 v11, v2
	v_mov_b32_e32 v12, v2
	v_mov_b32_e32 v13, v2
	v_mov_b32_e32 v14, v2
	v_mov_b32_e32 v15, v2
	v_mov_b32_e32 v16, v2
	v_mov_b32_e32 v17, v2
	v_mov_b32_e32 v18, v2
	v_mov_b32_e32 v19, v2
	v_mov_b32_e32 v20, v2
	v_mov_b32_e32 v21, v2
	v_mov_b32_e32 v22, v2
	v_mov_b32_e32 v23, v2
	v_mov_b32_e32 v24, v2
	v_mov_b32_e32 v25, v2
	v_mov_b32_e32 v28, v2
	v_mov_b32_e32 v29, v2
	v_mov_b32_e32 v30, v2
	v_mov_b32_e32 v31, v2
	v_mov_b32_e32 v32, v2
	v_mov_b32_e32 v33, v2
	v_mov_b32_e32 v34, v2
	v_mov_b32_e32 v35, v2
	v_mov_b32_e32 v68, v2
	v_mov_b32_e32 v69, v2
	v_mov_b32_e32 v70, v2
	v_mov_b32_e32 v71, v2
	v_mov_b32_e32 v72, v2
	v_mov_b32_e32 v73, v2
	v_mov_b32_e32 v74, v2
	v_mov_b32_e32 v75, v2
	v_mov_b32_e32 v76, v2
	v_mov_b32_e32 v77, v2
	v_mov_b32_e32 v78, v2
	v_mov_b32_e32 v79, v2
	v_mov_b32_e32 v80, v2
	v_mov_b32_e32 v81, v2
	v_mov_b32_e32 v82, v2
	v_mov_b32_e32 v83, v2
	v_mov_b32_e32 v84, v2
	v_mov_b32_e32 v85, v2
	v_mov_b32_e32 v86, v2
	v_mov_b32_e32 v87, v2
	v_mov_b32_e32 v88, v2
	v_mov_b32_e32 v89, v2
	v_mov_b32_e32 v90, v2
	v_mov_b32_e32 v91, v2
	v_mov_b32_e32 v92, v2
	v_mov_b32_e32 v93, v2
	v_mov_b32_e32 v94, v2
	v_mov_b32_e32 v95, v2
	v_mov_b32_e32 v96, v2
	v_mov_b32_e32 v97, v2
	v_mov_b32_e32 v98, v2
	v_mov_b32_e32 v99, v2
	s_waitcnt vmcnt(0)
	v_mov_b32_e32 v36, v2
	v_mov_b32_e32 v37, v2
	v_mov_b32_e32 v38, v2
	v_mov_b32_e32 v39, v2
	v_mov_b32_e32 v40, v2
	v_mov_b32_e32 v41, v2
	v_mov_b32_e32 v42, v2
	v_mov_b32_e32 v43, v2
	v_mov_b32_e32 v44, v2
	v_mov_b32_e32 v45, v2
	v_mov_b32_e32 v46, v2
	v_mov_b32_e32 v47, v2
	v_mov_b32_e32 v48, v2
	v_mov_b32_e32 v49, v2
	v_mov_b32_e32 v50, v2
	v_mov_b32_e32 v51, v2
	v_mov_b32_e32 v52, v2
	v_mov_b32_e32 v53, v2
	v_mov_b32_e32 v54, v2
	v_mov_b32_e32 v55, v2
	v_mov_b32_e32 v56, v2
	v_mov_b32_e32 v57, v2
	v_mov_b32_e32 v58, v2
	v_mov_b32_e32 v59, v2
	v_mov_b32_e32 v60, v2
	v_mov_b32_e32 v61, v2
	v_mov_b32_e32 v62, v2
	v_mov_b32_e32 v63, v2
	v_mov_b32_e32 v64, v2
	v_mov_b32_e32 v65, v2
	v_mov_b32_e32 v66, v2
	v_mov_b32_e32 v67, v2
	v_mov_b32_e32 v108, v2
	v_mov_b32_e32 v109, v2
	v_mov_b32_e32 v110, v2
	v_mov_b32_e32 v111, v2
	v_mov_b32_e32 v112, v2
	v_mov_b32_e32 v113, v2
	v_mov_b32_e32 v114, v2
	v_mov_b32_e32 v115, v2
	v_mov_b32_e32 v116, v2
	v_mov_b32_e32 v117, v2
	v_mov_b32_e32 v118, v2
	v_mov_b32_e32 v119, v2
	v_mov_b32_e32 v120, v2
	v_mov_b32_e32 v121, v2
	v_mov_b32_e32 v122, v2
	v_mov_b32_e32 v123, v2
	v_mov_b32_e32 v124, v2
	v_mov_b32_e32 v125, v2
	v_mov_b32_e32 v126, v2
	v_mov_b32_e32 v127, v2
	v_mov_b32_e32 v128, v2
	v_mov_b32_e32 v129, v2
	v_mov_b32_e32 v130, v2
	v_mov_b32_e32 v131, v2
	v_mov_b32_e32 v132, v2
	v_mov_b32_e32 v133, v2
	v_mov_b32_e32 v134, v2
	v_mov_b32_e32 v135, v2
	v_mov_b32_e32 v136, v2
	v_mov_b32_e32 v137, v2
	v_mov_b32_e32 v138, v2
	v_mov_b32_e32 v139, v2
	v_add_u32_e32 v154, 0x10000, v163
	ds_read_b128 v[100:103], v154
	ds_read_b128 v[104:107], v154 offset:1024
	ds_read_b128 v[150:153], v154 offset:2048
	ds_read_b128 v[154:157], v154 offset:3072
.LBB0_479:
	s_add_u32 s0, s22, 0xfffc0080
	s_addc_u32 s1, s23, -1
	s_add_i32 s69, 0, 0x10000
	s_cmp_eq_u32 s68, 12
	s_cselect_b32 s27, s35, s1
	s_cselect_b32 s26, s40, s0
	s_cselect_b32 s25, s41, s59
	s_cselect_b32 s24, s49, s51
	v_lshl_add_u64 v[166:167], s[22:23], 0, v[146:147]
	s_add_i32 m0, s37, 0xc000
	ds_read_b128 v[158:161], v165
	ds_read_b128 v[172:175], v165 offset:1024
	ds_read_b128 v[176:179], v165 offset:2048
	ds_read_b128 v[180:183], v165 offset:3072
	ds_read_b128 v[184:187], v165 offset:4096
	ds_read_b128 v[188:191], v165 offset:5120
	ds_read_b128 v[192:195], v165 offset:6144
	ds_read_b128 v[196:199], v165 offset:7168
	global_load_lds_dwordx4 v[166:167], off
	v_lshl_add_u64 v[166:167], s[22:23], 0, v[148:149]
	s_add_i32 m0, s37, 0xe000
	s_nop 0
	global_load_lds_dwordx4 v[166:167], off
	s_waitcnt vmcnt(10) lgkmcnt(8)
	s_setprio 1
	s_barrier
	s_waitcnt lgkmcnt(0)
	v_mfma_f32_16x16x32_bf16 v[136:139], v[100:103], v[158:161], v[136:139]
	v_mfma_f32_16x16x32_bf16 v[132:135], v[150:153], v[158:161], v[132:135]
	v_mfma_f32_16x16x32_bf16 v[128:131], v[100:103], v[176:179], v[128:131]
	v_mfma_f32_16x16x32_bf16 v[124:127], v[150:153], v[176:179], v[124:127]
	v_mfma_f32_16x16x32_bf16 v[120:123], v[100:103], v[184:187], v[120:123]
	v_mfma_f32_16x16x32_bf16 v[116:119], v[150:153], v[184:187], v[116:119]
	v_mfma_f32_16x16x32_bf16 v[112:115], v[100:103], v[192:195], v[112:115]
	v_mfma_f32_16x16x32_bf16 v[108:111], v[150:153], v[192:195], v[108:111]
	v_mfma_f32_16x16x32_bf16 v[136:139], v[104:107], v[172:175], v[136:139]
	v_mfma_f32_16x16x32_bf16 v[132:135], v[154:157], v[172:175], v[132:135]
	v_mfma_f32_16x16x32_bf16 v[128:131], v[104:107], v[180:183], v[128:131]
	v_mfma_f32_16x16x32_bf16 v[124:127], v[154:157], v[180:183], v[124:127]
	v_mfma_f32_16x16x32_bf16 v[120:123], v[104:107], v[188:191], v[120:123]
	v_mfma_f32_16x16x32_bf16 v[116:119], v[154:157], v[188:191], v[116:119]
	v_mfma_f32_16x16x32_bf16 v[112:115], v[104:107], v[196:199], v[112:115]
	v_mfma_f32_16x16x32_bf16 v[108:111], v[154:157], v[196:199], v[108:111]
	s_barrier
	s_setprio 0
	s_add_i32 s72, 0, 0x14000
	v_add_u32_e32 v166, s72, v163
	s_add_i32 s0, s69, s36
	ds_read_b128 v[200:203], v166
	ds_read_b128 v[204:207], v166 offset:1024
	ds_read_b128 v[208:211], v166 offset:2048
	ds_read_b128 v[212:215], v166 offset:3072
	v_lshl_add_u64 v[166:167], s[24:25], 0, v[26:27]
	s_mov_b32 m0, s0
	v_lshl_add_u64 v[168:169], s[24:25], 0, v[140:141]
	global_load_lds_dwordx4 v[166:167], off
	s_add_i32 m0, s0, 0x2000
	s_nop 0
	global_load_lds_dwordx4 v[168:169], off
	s_waitcnt vmcnt(10)
	s_setprio 1
	s_barrier
	s_waitcnt lgkmcnt(0)
	v_mfma_f32_16x16x32_bf16 v[64:67], v[200:203], v[158:161], v[64:67]
	v_mfma_f32_16x16x32_bf16 v[60:63], v[208:211], v[158:161], v[60:63]
	v_mfma_f32_16x16x32_bf16 v[56:59], v[200:203], v[176:179], v[56:59]
	v_mfma_f32_16x16x32_bf16 v[52:55], v[208:211], v[176:179], v[52:55]
	v_mfma_f32_16x16x32_bf16 v[48:51], v[200:203], v[184:187], v[48:51]
	v_mfma_f32_16x16x32_bf16 v[44:47], v[208:211], v[184:187], v[44:47]
	v_mfma_f32_16x16x32_bf16 v[40:43], v[200:203], v[192:195], v[40:43]
	v_mfma_f32_16x16x32_bf16 v[36:39], v[208:211], v[192:195], v[36:39]
	v_mfma_f32_16x16x32_bf16 v[64:67], v[204:207], v[172:175], v[64:67]
	v_mfma_f32_16x16x32_bf16 v[60:63], v[212:215], v[172:175], v[60:63]
	v_mfma_f32_16x16x32_bf16 v[56:59], v[204:207], v[180:183], v[56:59]
	v_mfma_f32_16x16x32_bf16 v[52:55], v[212:215], v[180:183], v[52:55]
	v_mfma_f32_16x16x32_bf16 v[48:51], v[204:207], v[188:191], v[48:51]
	v_mfma_f32_16x16x32_bf16 v[44:47], v[212:215], v[188:191], v[44:47]
	v_mfma_f32_16x16x32_bf16 v[40:43], v[204:207], v[196:199], v[40:43]
	v_mfma_f32_16x16x32_bf16 v[36:39], v[212:215], v[196:199], v[36:39]
	s_barrier
	s_setprio 0
	s_mov_b32 m0, s37
	v_lshl_add_u64 v[216:217], s[26:27], 0, v[144:145]
	ds_read_b128 v[158:161], v165 offset:16384
	ds_read_b128 v[172:175], v165 offset:17408
	ds_read_b128 v[176:179], v165 offset:18432
	ds_read_b128 v[180:183], v165 offset:19456
	ds_read_b128 v[184:187], v165 offset:20480
	ds_read_b128 v[188:191], v165 offset:21504
	ds_read_b128 v[192:195], v165 offset:22528
	ds_read_b128 v[196:199], v165 offset:23552
	global_load_lds_dwordx4 v[216:217], off
	v_lshl_add_u64 v[218:219], s[26:27], 0, v[142:143]
	s_mov_b32 m0, s56
	s_nop 0
	global_load_lds_dwordx4 v[218:219], off
	s_waitcnt vmcnt(10)
	s_setprio 1
	s_barrier
	s_waitcnt lgkmcnt(0)
	v_mfma_f32_16x16x32_bf16 v[96:99], v[100:103], v[158:161], v[96:99]
	v_mfma_f32_16x16x32_bf16 v[92:95], v[150:153], v[158:161], v[92:95]
	v_mfma_f32_16x16x32_bf16 v[88:91], v[100:103], v[176:179], v[88:91]
	v_mfma_f32_16x16x32_bf16 v[84:87], v[150:153], v[176:179], v[84:87]
	v_mfma_f32_16x16x32_bf16 v[80:83], v[100:103], v[184:187], v[80:83]
	v_mfma_f32_16x16x32_bf16 v[76:79], v[150:153], v[184:187], v[76:79]
	v_mfma_f32_16x16x32_bf16 v[72:75], v[100:103], v[192:195], v[72:75]
	v_mfma_f32_16x16x32_bf16 v[68:71], v[150:153], v[192:195], v[68:71]
	v_mfma_f32_16x16x32_bf16 v[96:99], v[104:107], v[172:175], v[96:99]
	v_mfma_f32_16x16x32_bf16 v[92:95], v[154:157], v[172:175], v[92:95]
	v_mfma_f32_16x16x32_bf16 v[88:91], v[104:107], v[180:183], v[88:91]
	v_mfma_f32_16x16x32_bf16 v[84:87], v[154:157], v[180:183], v[84:87]
	v_mfma_f32_16x16x32_bf16 v[80:83], v[104:107], v[188:191], v[80:83]
	v_mfma_f32_16x16x32_bf16 v[76:79], v[154:157], v[188:191], v[76:79]
	v_mfma_f32_16x16x32_bf16 v[72:75], v[104:107], v[196:199], v[72:75]
	v_mfma_f32_16x16x32_bf16 v[68:71], v[154:157], v[196:199], v[68:71]
	s_barrier
	s_setprio 0
	s_add_u32 s0, s24, 0x40000
	s_addc_u32 s1, s25, 0
	s_add_i32 s69, s72, s36
	v_lshl_add_u64 v[100:101], s[0:1], 0, v[26:27]
	s_mov_b32 m0, s69
	s_nop 0
	global_load_lds_dwordx4 v[100:101], off
	v_lshl_add_u64 v[100:101], s[0:1], 0, v[140:141]
	s_add_i32 m0, s69, 0x2000
	s_nop 0
	global_load_lds_dwordx4 v[100:101], off
	v_add_u32_e32 v154, 0x18000, v163
	ds_read_b128 v[100:103], v154
	ds_read_b128 v[104:107], v154 offset:1024
	ds_read_b128 v[150:153], v154 offset:2048
	ds_read_b128 v[154:157], v154 offset:3072
	s_waitcnt vmcnt(10)
	s_setprio 1
	s_barrier
	v_mfma_f32_16x16x32_bf16 v[32:35], v[200:203], v[158:161], v[32:35]
	v_mfma_f32_16x16x32_bf16 v[28:31], v[208:211], v[158:161], v[28:31]
	v_mfma_f32_16x16x32_bf16 v[22:25], v[200:203], v[176:179], v[22:25]
	v_mfma_f32_16x16x32_bf16 v[18:21], v[208:211], v[176:179], v[18:21]
	v_mfma_f32_16x16x32_bf16 v[14:17], v[200:203], v[184:187], v[14:17]
	v_mfma_f32_16x16x32_bf16 v[10:13], v[208:211], v[184:187], v[10:13]
	v_mfma_f32_16x16x32_bf16 v[6:9], v[200:203], v[192:195], v[6:9]
	v_mfma_f32_16x16x32_bf16 v[2:5], v[208:211], v[192:195], v[2:5]
	v_mfma_f32_16x16x32_bf16 v[32:35], v[204:207], v[172:175], v[32:35]
	v_mfma_f32_16x16x32_bf16 v[28:31], v[212:215], v[172:175], v[28:31]
	v_mfma_f32_16x16x32_bf16 v[22:25], v[204:207], v[180:183], v[22:25]
	v_mfma_f32_16x16x32_bf16 v[18:21], v[212:215], v[180:183], v[18:21]
	v_mfma_f32_16x16x32_bf16 v[14:17], v[204:207], v[188:191], v[14:17]
	v_mfma_f32_16x16x32_bf16 v[10:13], v[212:215], v[188:191], v[10:13]
	v_mfma_f32_16x16x32_bf16 v[6:9], v[204:207], v[196:199], v[6:9]
	v_mfma_f32_16x16x32_bf16 v[2:5], v[212:215], v[196:199], v[2:5]
	s_barrier
	s_setprio 0
	s_add_i32 s69, 0, 0x18000
	s_add_u32 s0, s26, 0x40000
	s_addc_u32 s1, s27, 0
	s_mov_b32 m0, s57
	v_lshl_add_u64 v[200:201], s[0:1], 0, v[144:145]
	ds_read_b128 v[158:161], v165 offset:32768
	ds_read_b128 v[172:175], v165 offset:33792
	ds_read_b128 v[176:179], v165 offset:34816
	ds_read_b128 v[180:183], v165 offset:35840
	ds_read_b128 v[184:187], v165 offset:36864
	ds_read_b128 v[188:191], v165 offset:37888
	ds_read_b128 v[192:195], v165 offset:38912
	ds_read_b128 v[196:199], v165 offset:39936
	global_load_lds_dwordx4 v[200:201], off
	v_lshl_add_u64 v[200:201], s[0:1], 0, v[142:143]
	s_mov_b32 m0, s58
	s_nop 0
	global_load_lds_dwordx4 v[200:201], off
	s_waitcnt vmcnt(10) lgkmcnt(8)
	s_setprio 1
	s_barrier
	s_waitcnt lgkmcnt(0)
	v_mfma_f32_16x16x32_bf16 v[136:139], v[100:103], v[158:161], v[136:139]
	v_mfma_f32_16x16x32_bf16 v[132:135], v[150:153], v[158:161], v[132:135]
	v_mfma_f32_16x16x32_bf16 v[128:131], v[100:103], v[176:179], v[128:131]
	v_mfma_f32_16x16x32_bf16 v[124:127], v[150:153], v[176:179], v[124:127]
	v_mfma_f32_16x16x32_bf16 v[120:123], v[100:103], v[184:187], v[120:123]
	v_mfma_f32_16x16x32_bf16 v[116:119], v[150:153], v[184:187], v[116:119]
	v_mfma_f32_16x16x32_bf16 v[112:115], v[100:103], v[192:195], v[112:115]
	v_mfma_f32_16x16x32_bf16 v[108:111], v[150:153], v[192:195], v[108:111]
	v_mfma_f32_16x16x32_bf16 v[136:139], v[104:107], v[172:175], v[136:139]
	v_mfma_f32_16x16x32_bf16 v[132:135], v[154:157], v[172:175], v[132:135]
	v_mfma_f32_16x16x32_bf16 v[128:131], v[104:107], v[180:183], v[128:131]
	v_mfma_f32_16x16x32_bf16 v[124:127], v[154:157], v[180:183], v[124:127]
	v_mfma_f32_16x16x32_bf16 v[120:123], v[104:107], v[188:191], v[120:123]
	v_mfma_f32_16x16x32_bf16 v[116:119], v[154:157], v[188:191], v[116:119]
	v_mfma_f32_16x16x32_bf16 v[112:115], v[104:107], v[196:199], v[112:115]
	v_mfma_f32_16x16x32_bf16 v[108:111], v[154:157], v[196:199], v[108:111]
	s_barrier
	s_setprio 0
	s_add_i32 s26, 0, 0x1c000
	s_add_i32 s0, s69, s36
	v_add_u32_e32 v212, s26, v163
	v_lshl_add_u64 v[166:167], v[166:167], 0, s[12:13]
	s_mov_b32 m0, s0
	ds_read_b128 v[200:203], v212
	ds_read_b128 v[204:207], v212 offset:1024
	ds_read_b128 v[208:211], v212 offset:2048
	ds_read_b128 v[212:215], v212 offset:3072
	global_load_lds_dwordx4 v[166:167], off
	v_lshl_add_u64 v[166:167], v[168:169], 0, s[12:13]
	s_add_i32 m0, s0, 0x2000
	s_nop 0
	global_load_lds_dwordx4 v[166:167], off
	s_waitcnt vmcnt(10)
	s_setprio 1
	s_barrier
	s_waitcnt lgkmcnt(0)
	v_mfma_f32_16x16x32_bf16 v[64:67], v[200:203], v[158:161], v[64:67]
	v_mfma_f32_16x16x32_bf16 v[60:63], v[208:211], v[158:161], v[60:63]
	v_mfma_f32_16x16x32_bf16 v[56:59], v[200:203], v[176:179], v[56:59]
	v_mfma_f32_16x16x32_bf16 v[52:55], v[208:211], v[176:179], v[52:55]
	v_mfma_f32_16x16x32_bf16 v[48:51], v[200:203], v[184:187], v[48:51]
	v_mfma_f32_16x16x32_bf16 v[44:47], v[208:211], v[184:187], v[44:47]
	v_mfma_f32_16x16x32_bf16 v[40:43], v[200:203], v[192:195], v[40:43]
	v_mfma_f32_16x16x32_bf16 v[36:39], v[208:211], v[192:195], v[36:39]
	v_mfma_f32_16x16x32_bf16 v[64:67], v[204:207], v[172:175], v[64:67]
	v_mfma_f32_16x16x32_bf16 v[60:63], v[212:215], v[172:175], v[60:63]
	v_mfma_f32_16x16x32_bf16 v[56:59], v[204:207], v[180:183], v[56:59]
	v_mfma_f32_16x16x32_bf16 v[52:55], v[212:215], v[180:183], v[52:55]
	v_mfma_f32_16x16x32_bf16 v[48:51], v[204:207], v[188:191], v[48:51]
	v_mfma_f32_16x16x32_bf16 v[44:47], v[212:215], v[188:191], v[44:47]
	v_mfma_f32_16x16x32_bf16 v[40:43], v[204:207], v[196:199], v[40:43]
	v_mfma_f32_16x16x32_bf16 v[36:39], v[212:215], v[196:199], v[36:39]
	s_barrier
	s_setprio 0
	s_mov_b32 m0, s28
	v_lshl_add_u64 v[166:167], v[216:217], 0, s[12:13]
	ds_read_b128 v[158:161], v165 offset:49152
	ds_read_b128 v[172:175], v165 offset:50176
	ds_read_b128 v[176:179], v165 offset:51200
	ds_read_b128 v[180:183], v165 offset:52224
	ds_read_b128 v[184:187], v165 offset:53248
	ds_read_b128 v[188:191], v165 offset:54272
	ds_read_b128 v[192:195], v165 offset:55296
	ds_read_b128 v[196:199], v165 offset:56320
	global_load_lds_dwordx4 v[166:167], off
	v_lshl_add_u64 v[166:167], v[218:219], 0, s[12:13]
	s_mov_b32 m0, s29
	s_nop 0
	global_load_lds_dwordx4 v[166:167], off
	s_waitcnt vmcnt(10)
	s_setprio 1
	s_barrier
	s_waitcnt lgkmcnt(0)
	v_mfma_f32_16x16x32_bf16 v[96:99], v[100:103], v[158:161], v[96:99]
	v_mfma_f32_16x16x32_bf16 v[92:95], v[150:153], v[158:161], v[92:95]
	v_mfma_f32_16x16x32_bf16 v[88:91], v[100:103], v[176:179], v[88:91]
	v_mfma_f32_16x16x32_bf16 v[84:87], v[150:153], v[176:179], v[84:87]
	v_mfma_f32_16x16x32_bf16 v[80:83], v[100:103], v[184:187], v[80:83]
	v_mfma_f32_16x16x32_bf16 v[76:79], v[150:153], v[184:187], v[76:79]
	v_mfma_f32_16x16x32_bf16 v[72:75], v[100:103], v[192:195], v[72:75]
	v_mfma_f32_16x16x32_bf16 v[68:71], v[150:153], v[192:195], v[68:71]
	v_mfma_f32_16x16x32_bf16 v[96:99], v[104:107], v[172:175], v[96:99]
	v_mfma_f32_16x16x32_bf16 v[92:95], v[154:157], v[172:175], v[92:95]
	v_mfma_f32_16x16x32_bf16 v[88:91], v[104:107], v[180:183], v[88:91]
	v_mfma_f32_16x16x32_bf16 v[84:87], v[154:157], v[180:183], v[84:87]
	v_mfma_f32_16x16x32_bf16 v[80:83], v[104:107], v[188:191], v[80:83]
	v_mfma_f32_16x16x32_bf16 v[76:79], v[154:157], v[188:191], v[76:79]
	v_mfma_f32_16x16x32_bf16 v[72:75], v[104:107], v[196:199], v[72:75]
	v_mfma_f32_16x16x32_bf16 v[68:71], v[154:157], v[196:199], v[68:71]
	s_barrier
	s_setprio 0
	s_add_u32 s0, s24, 0x40080
	s_addc_u32 s1, s25, 0
	s_add_i32 s24, s26, s36
	v_lshl_add_u64 v[100:101], s[0:1], 0, v[26:27]
	s_mov_b32 m0, s24
	s_nop 0
	global_load_lds_dwordx4 v[100:101], off
	v_lshl_add_u64 v[100:101], s[0:1], 0, v[140:141]
	s_add_i32 m0, s24, 0x2000
	s_nop 0
	global_load_lds_dwordx4 v[100:101], off
	v_add_u32_e32 v154, 0x10000, v163
	ds_read_b128 v[100:103], v154
	ds_read_b128 v[104:107], v154 offset:1024
	ds_read_b128 v[150:153], v154 offset:2048
	ds_read_b128 v[154:157], v154 offset:3072
	s_waitcnt vmcnt(10)
	s_setprio 1
	s_barrier
	v_mfma_f32_16x16x32_bf16 v[32:35], v[200:203], v[158:161], v[32:35]
	v_mfma_f32_16x16x32_bf16 v[28:31], v[208:211], v[158:161], v[28:31]
	v_mfma_f32_16x16x32_bf16 v[22:25], v[200:203], v[176:179], v[22:25]
	v_mfma_f32_16x16x32_bf16 v[18:21], v[208:211], v[176:179], v[18:21]
	v_mfma_f32_16x16x32_bf16 v[14:17], v[200:203], v[184:187], v[14:17]
	v_mfma_f32_16x16x32_bf16 v[10:13], v[208:211], v[184:187], v[10:13]
	v_mfma_f32_16x16x32_bf16 v[6:9], v[200:203], v[192:195], v[6:9]
	v_mfma_f32_16x16x32_bf16 v[2:5], v[208:211], v[192:195], v[2:5]
	v_mfma_f32_16x16x32_bf16 v[32:35], v[204:207], v[172:175], v[32:35]
	v_mfma_f32_16x16x32_bf16 v[28:31], v[212:215], v[172:175], v[28:31]
	v_mfma_f32_16x16x32_bf16 v[22:25], v[204:207], v[180:183], v[22:25]
	v_mfma_f32_16x16x32_bf16 v[18:21], v[212:215], v[180:183], v[18:21]
	v_mfma_f32_16x16x32_bf16 v[14:17], v[204:207], v[188:191], v[14:17]
	v_mfma_f32_16x16x32_bf16 v[10:13], v[212:215], v[188:191], v[10:13]
	v_mfma_f32_16x16x32_bf16 v[6:9], v[204:207], v[196:199], v[6:9]
	v_mfma_f32_16x16x32_bf16 v[2:5], v[212:215], v[196:199], v[2:5]
	s_barrier
	s_setprio 0
	s_add_i32 s68, s68, 2
	s_add_u32 s22, s22, 0x100
	s_addc_u32 s23, s23, 0
	s_add_u32 s51, s51, 0x100
	s_addc_u32 s59, s59, 0
	s_cmp_gt_u32 s68, 13
	s_cbranch_scc0 .LBB0_479
	s_waitcnt lgkmcnt(0)
	s_cmpk_gt_i32 s34, 0xff
	s_mov_b64 s[22:23], 0xb000
	s_cbranch_scc1 .LBB0_482
	s_ashr_i32 s0, s34, 5
	s_mul_hi_i32 s23, s0, 0x1600
	s_mul_i32 s22, s0, 0x1600

.LBB0_886:
	s_lshl_b32 s0, s73, 21
	s_add_u32 s18, s53, s0
	s_addc_u32 s19, s54, 0
	s_ashr_i32 s45, s44, 31
	s_lshl_b64 s[0:1], s[44:45], 18
	s_add_u32 s48, s18, s0
	s_addc_u32 s49, s19, s1
	s_and_b64 s[0:1], s[38:39], exec
	s_cselect_b32 s18, s49, s25
	s_cselect_b32 s19, s48, s24
	s_add_u32 s45, s24, 0x100
	s_addc_u32 s50, s25, 0
	s_mov_b32 s51, -2
	v_add_u32_e32 v26, 0x10000, v191
	ds_read_b128 v[134:137], v26
	ds_read_b128 v[138:141], v26 offset:1024
	ds_read_b128 v[142:145], v26 offset:2048
	ds_read_b128 v[146:149], v26 offset:3072
.LBB0_887:
	s_add_u32 s24, s22, 0x100
	s_addc_u32 s25, s23, 0
	s_add_i32 s0, 0, 0x10000
	s_cmp_eq_u32 s51, 4
	s_cselect_b32 s29, s47, s25
	s_cselect_b32 s28, s46, s24
	s_cselect_b32 s27, s18, s50
	s_cselect_b32 s26, s19, s45
	v_lshl_add_u64 v[28:29], s[22:23], 0, v[180:181]
	s_add_i32 m0, s58, 0xc000
	ds_read_b128 v[150:153], v193
	ds_read_b128 v[154:157], v193 offset:1024
	ds_read_b128 v[158:161], v193 offset:2048
	ds_read_b128 v[162:165], v193 offset:3072
	ds_read_b128 v[184:187], v193 offset:4096
	ds_read_b128 v[194:197], v193 offset:5120
	ds_read_b128 v[198:201], v193 offset:6144
	ds_read_b128 v[202:205], v193 offset:7168
	global_load_lds_dwordx4 v[28:29], off
	v_lshl_add_u64 v[28:29], s[22:23], 0, v[182:183]
	s_add_i32 m0, s58, 0xe000
	s_nop 0
	global_load_lds_dwordx4 v[28:29], off
	s_waitcnt vmcnt(10) lgkmcnt(8)
	s_setprio 1
	s_barrier
	s_waitcnt lgkmcnt(0)
	v_mfma_f32_16x16x32_bf16 v[130:133], v[134:137], v[150:153], v[130:133]
	v_mfma_f32_16x16x32_bf16 v[126:129], v[142:145], v[150:153], v[126:129]
	v_mfma_f32_16x16x32_bf16 v[122:125], v[134:137], v[158:161], v[122:125]
	v_mfma_f32_16x16x32_bf16 v[118:121], v[142:145], v[158:161], v[118:121]
	v_mfma_f32_16x16x32_bf16 v[114:117], v[134:137], v[184:187], v[114:117]
	v_mfma_f32_16x16x32_bf16 v[110:113], v[142:145], v[184:187], v[110:113]
	v_mfma_f32_16x16x32_bf16 v[106:109], v[134:137], v[198:201], v[106:109]
	v_mfma_f32_16x16x32_bf16 v[102:105], v[142:145], v[198:201], v[102:105]
	v_mfma_f32_16x16x32_bf16 v[130:133], v[138:141], v[154:157], v[130:133]
	v_mfma_f32_16x16x32_bf16 v[126:129], v[146:149], v[154:157], v[126:129]
	v_mfma_f32_16x16x32_bf16 v[122:125], v[138:141], v[162:165], v[122:125]
	v_mfma_f32_16x16x32_bf16 v[118:121], v[146:149], v[162:165], v[118:121]
	v_mfma_f32_16x16x32_bf16 v[114:117], v[138:141], v[194:197], v[114:117]
	v_mfma_f32_16x16x32_bf16 v[110:113], v[146:149], v[194:197], v[110:113]
	v_mfma_f32_16x16x32_bf16 v[106:109], v[138:141], v[202:205], v[106:109]
	v_mfma_f32_16x16x32_bf16 v[102:105], v[146:149], v[202:205], v[102:105]
	s_barrier
	s_setprio 0
	s_add_i32 s22, 0, 0x14000
	s_add_i32 s0, s0, s55
	v_add_u32_e32 v26, s22, v191
	v_lshl_add_u64 v[166:167], s[26:27], 0, v[176:177]
	s_mov_b32 m0, s0
	ds_read_b128 v[206:209], v26
	ds_read_b128 v[210:213], v26 offset:1024
	ds_read_b128 v[214:217], v26 offset:2048
	ds_read_b128 v[218:221], v26 offset:3072
	global_load_lds_dwordx4 v[166:167], off
	v_lshl_add_u64 v[168:169], s[26:27], 0, v[172:173]
	s_add_i32 m0, s0, 0x2000
	s_nop 0
	global_load_lds_dwordx4 v[168:169], off
	s_waitcnt vmcnt(10)
	s_setprio 1
	s_barrier
	s_waitcnt lgkmcnt(0)
	v_mfma_f32_16x16x32_bf16 v[98:101], v[206:209], v[150:153], v[98:101]
	v_mfma_f32_16x16x32_bf16 v[94:97], v[214:217], v[150:153], v[94:97]
	v_mfma_f32_16x16x32_bf16 v[90:93], v[206:209], v[158:161], v[90:93]
	v_mfma_f32_16x16x32_bf16 v[86:89], v[214:217], v[158:161], v[86:89]
	v_mfma_f32_16x16x32_bf16 v[82:85], v[206:209], v[184:187], v[82:85]
	v_mfma_f32_16x16x32_bf16 v[78:81], v[214:217], v[184:187], v[78:81]
	v_mfma_f32_16x16x32_bf16 v[74:77], v[206:209], v[198:201], v[74:77]
	v_mfma_f32_16x16x32_bf16 v[70:73], v[214:217], v[198:201], v[70:73]
	v_mfma_f32_16x16x32_bf16 v[98:101], v[210:213], v[154:157], v[98:101]
	v_mfma_f32_16x16x32_bf16 v[94:97], v[218:221], v[154:157], v[94:97]
	v_mfma_f32_16x16x32_bf16 v[90:93], v[210:213], v[162:165], v[90:93]
	v_mfma_f32_16x16x32_bf16 v[86:89], v[218:221], v[162:165], v[86:89]
	v_mfma_f32_16x16x32_bf16 v[82:85], v[210:213], v[194:197], v[82:85]
	v_mfma_f32_16x16x32_bf16 v[78:81], v[218:221], v[194:197], v[78:81]
	v_mfma_f32_16x16x32_bf16 v[74:77], v[210:213], v[202:205], v[74:77]
	v_mfma_f32_16x16x32_bf16 v[70:73], v[218:221], v[202:205], v[70:73]
	s_barrier
	s_setprio 0
	s_mov_b32 m0, s58
	v_lshl_add_u64 v[188:189], s[28:29], 0, v[178:179]
	ds_read_b128 v[150:153], v193 offset:16384
	ds_read_b128 v[154:157], v193 offset:17408
	ds_read_b128 v[158:161], v193 offset:18432
	ds_read_b128 v[162:165], v193 offset:19456
	ds_read_b128 v[184:187], v193 offset:20480
	ds_read_b128 v[194:197], v193 offset:21504
	ds_read_b128 v[198:201], v193 offset:22528
	ds_read_b128 v[202:205], v193 offset:23552
	global_load_lds_dwordx4 v[188:189], off
	v_lshl_add_u64 v[222:223], s[28:29], 0, v[174:175]
	s_mov_b32 m0, s59
	s_nop 0
	global_load_lds_dwordx4 v[222:223], off
	s_waitcnt vmcnt(10)
	s_setprio 1
	s_barrier
	s_waitcnt lgkmcnt(0)
	v_mfma_f32_16x16x32_bf16 v[66:69], v[134:137], v[150:153], v[66:69]
	v_mfma_f32_16x16x32_bf16 v[62:65], v[142:145], v[150:153], v[62:65]
	v_mfma_f32_16x16x32_bf16 v[58:61], v[134:137], v[158:161], v[58:61]
	v_mfma_f32_16x16x32_bf16 v[54:57], v[142:145], v[158:161], v[54:57]
	v_mfma_f32_16x16x32_bf16 v[50:53], v[134:137], v[184:187], v[50:53]
	v_mfma_f32_16x16x32_bf16 v[46:49], v[142:145], v[184:187], v[46:49]
	v_mfma_f32_16x16x32_bf16 v[42:45], v[134:137], v[198:201], v[42:45]
	v_mfma_f32_16x16x32_bf16 v[38:41], v[142:145], v[198:201], v[38:41]
	v_mfma_f32_16x16x32_bf16 v[66:69], v[138:141], v[154:157], v[66:69]
	v_mfma_f32_16x16x32_bf16 v[62:65], v[146:149], v[154:157], v[62:65]
	v_mfma_f32_16x16x32_bf16 v[58:61], v[138:141], v[162:165], v[58:61]
	v_mfma_f32_16x16x32_bf16 v[54:57], v[146:149], v[162:165], v[54:57]
	v_mfma_f32_16x16x32_bf16 v[50:53], v[138:141], v[194:197], v[50:53]
	v_mfma_f32_16x16x32_bf16 v[46:49], v[146:149], v[194:197], v[46:49]
	v_mfma_f32_16x16x32_bf16 v[42:45], v[138:141], v[202:205], v[42:45]
	v_mfma_f32_16x16x32_bf16 v[38:41], v[146:149], v[202:205], v[38:41]
	s_barrier
	s_setprio 0
	s_add_u32 s0, s26, 0x20000
	s_addc_u32 s1, s27, 0
	s_add_i32 s22, s22, s55
	v_lshl_add_u64 v[28:29], s[0:1], 0, v[176:177]
	s_mov_b32 m0, s22
	s_nop 0
	global_load_lds_dwordx4 v[28:29], off
	v_lshl_add_u64 v[28:29], s[0:1], 0, v[172:173]
	s_add_i32 m0, s22, 0x2000
	s_nop 0
	global_load_lds_dwordx4 v[28:29], off
	v_add_u32_e32 v26, 0x18000, v191
	ds_read_b128 v[134:137], v26
	ds_read_b128 v[138:141], v26 offset:1024
	ds_read_b128 v[142:145], v26 offset:2048
	ds_read_b128 v[146:149], v26 offset:3072
	s_waitcnt vmcnt(10)
	s_setprio 1
	s_barrier
	v_mfma_f32_16x16x32_bf16 v[34:37], v[206:209], v[150:153], v[34:37]
	v_mfma_f32_16x16x32_bf16 v[28:31], v[214:217], v[150:153], v[30:33]
	v_mfma_f32_16x16x32_bf16 v[22:25], v[206:209], v[158:161], v[22:25]
	v_mfma_f32_16x16x32_bf16 v[18:21], v[214:217], v[158:161], v[18:21]
	v_mfma_f32_16x16x32_bf16 v[14:17], v[206:209], v[184:187], v[14:17]
	v_mfma_f32_16x16x32_bf16 v[10:13], v[214:217], v[184:187], v[10:13]
	v_mfma_f32_16x16x32_bf16 v[6:9], v[206:209], v[198:201], v[6:9]
	v_mfma_f32_16x16x32_bf16 v[2:5], v[214:217], v[198:201], v[2:5]
	v_mfma_f32_16x16x32_bf16 v[34:37], v[210:213], v[154:157], v[34:37]
	v_mfma_f32_16x16x32_bf16 v[28:31], v[218:221], v[154:157], v[28:31]
	v_mfma_f32_16x16x32_bf16 v[22:25], v[210:213], v[162:165], v[22:25]
	v_mfma_f32_16x16x32_bf16 v[18:21], v[218:221], v[162:165], v[18:21]
	v_mfma_f32_16x16x32_bf16 v[14:17], v[210:213], v[194:197], v[14:17]
	v_mfma_f32_16x16x32_bf16 v[10:13], v[218:221], v[194:197], v[10:13]
	v_mfma_f32_16x16x32_bf16 v[6:9], v[210:213], v[202:205], v[6:9]
	v_mfma_f32_16x16x32_bf16 v[2:5], v[218:221], v[202:205], v[2:5]
	s_barrier
	s_setprio 0
	s_add_i32 s22, 0, 0x18000
	s_add_u32 s0, s28, 0x140000
	s_addc_u32 s1, s29, 0
	s_mov_b32 m0, s68
	v_lshl_add_u64 v[32:33], s[0:1], 0, v[178:179]
	ds_read_b128 v[150:153], v193 offset:32768
	ds_read_b128 v[154:157], v193 offset:33792
	ds_read_b128 v[158:161], v193 offset:34816
	ds_read_b128 v[162:165], v193 offset:35840
	ds_read_b128 v[184:187], v193 offset:36864
	ds_read_b128 v[194:197], v193 offset:37888
	ds_read_b128 v[198:201], v193 offset:38912
	ds_read_b128 v[202:205], v193 offset:39936
	global_load_lds_dwordx4 v[32:33], off
	v_lshl_add_u64 v[32:33], s[0:1], 0, v[174:175]
	s_mov_b32 m0, s69
	s_nop 0
	global_load_lds_dwordx4 v[32:33], off
	s_waitcnt vmcnt(10) lgkmcnt(8)
	s_setprio 1
	s_barrier
	s_waitcnt lgkmcnt(0)
	v_mfma_f32_16x16x32_bf16 v[130:133], v[134:137], v[150:153], v[130:133]
	v_mfma_f32_16x16x32_bf16 v[126:129], v[142:145], v[150:153], v[126:129]
	v_mfma_f32_16x16x32_bf16 v[122:125], v[134:137], v[158:161], v[122:125]
	v_mfma_f32_16x16x32_bf16 v[118:121], v[142:145], v[158:161], v[118:121]
	v_mfma_f32_16x16x32_bf16 v[114:117], v[134:137], v[184:187], v[114:117]
	v_mfma_f32_16x16x32_bf16 v[110:113], v[142:145], v[184:187], v[110:113]
	v_mfma_f32_16x16x32_bf16 v[106:109], v[134:137], v[198:201], v[106:109]
	v_mfma_f32_16x16x32_bf16 v[102:105], v[142:145], v[198:201], v[102:105]
	v_mfma_f32_16x16x32_bf16 v[130:133], v[138:141], v[154:157], v[130:133]
	v_mfma_f32_16x16x32_bf16 v[126:129], v[146:149], v[154:157], v[126:129]
	v_mfma_f32_16x16x32_bf16 v[122:125], v[138:141], v[162:165], v[122:125]
	v_mfma_f32_16x16x32_bf16 v[118:121], v[146:149], v[162:165], v[118:121]
	v_mfma_f32_16x16x32_bf16 v[114:117], v[138:141], v[194:197], v[114:117]
	v_mfma_f32_16x16x32_bf16 v[110:113], v[146:149], v[194:197], v[110:113]
	v_mfma_f32_16x16x32_bf16 v[106:109], v[138:141], v[202:205], v[106:109]
	v_mfma_f32_16x16x32_bf16 v[102:105], v[146:149], v[202:205], v[102:105]
	s_barrier
	s_setprio 0
	s_add_i32 s23, 0, 0x1c000
	s_add_i32 s0, s22, s55
	v_add_u32_e32 v26, s23, v191
	v_lshl_add_u64 v[32:33], v[166:167], 0, s[12:13]
	s_mov_b32 m0, s0
	ds_read_b128 v[206:209], v26
	ds_read_b128 v[210:213], v26 offset:1024
	ds_read_b128 v[214:217], v26 offset:2048
	ds_read_b128 v[218:221], v26 offset:3072
	global_load_lds_dwordx4 v[32:33], off
	v_lshl_add_u64 v[32:33], v[168:169], 0, s[12:13]
	s_add_i32 m0, s0, 0x2000
	s_nop 0
	global_load_lds_dwordx4 v[32:33], off
	s_waitcnt vmcnt(10)
	s_setprio 1
	s_barrier
	s_waitcnt lgkmcnt(0)
	v_mfma_f32_16x16x32_bf16 v[98:101], v[206:209], v[150:153], v[98:101]
	v_mfma_f32_16x16x32_bf16 v[94:97], v[214:217], v[150:153], v[94:97]
	v_mfma_f32_16x16x32_bf16 v[90:93], v[206:209], v[158:161], v[90:93]
	v_mfma_f32_16x16x32_bf16 v[86:89], v[214:217], v[158:161], v[86:89]
	v_mfma_f32_16x16x32_bf16 v[82:85], v[206:209], v[184:187], v[82:85]
	v_mfma_f32_16x16x32_bf16 v[78:81], v[214:217], v[184:187], v[78:81]
	v_mfma_f32_16x16x32_bf16 v[74:77], v[206:209], v[198:201], v[74:77]
	v_mfma_f32_16x16x32_bf16 v[70:73], v[214:217], v[198:201], v[70:73]
	v_mfma_f32_16x16x32_bf16 v[98:101], v[210:213], v[154:157], v[98:101]
	v_mfma_f32_16x16x32_bf16 v[94:97], v[218:221], v[154:157], v[94:97]
	v_mfma_f32_16x16x32_bf16 v[90:93], v[210:213], v[162:165], v[90:93]
	v_mfma_f32_16x16x32_bf16 v[86:89], v[218:221], v[162:165], v[86:89]
	v_mfma_f32_16x16x32_bf16 v[82:85], v[210:213], v[194:197], v[82:85]
	v_mfma_f32_16x16x32_bf16 v[78:81], v[218:221], v[194:197], v[78:81]
	v_mfma_f32_16x16x32_bf16 v[74:77], v[210:213], v[202:205], v[74:77]
	v_mfma_f32_16x16x32_bf16 v[70:73], v[218:221], v[202:205], v[70:73]
	s_barrier
	s_setprio 0
	s_mov_b32 m0, s30
	v_lshl_add_u64 v[32:33], v[188:189], 0, s[12:13]
	ds_read_b128 v[150:153], v193 offset:49152
	ds_read_b128 v[154:157], v193 offset:50176
	ds_read_b128 v[158:161], v193 offset:51200
	ds_read_b128 v[162:165], v193 offset:52224
	ds_read_b128 v[184:187], v193 offset:53248
	ds_read_b128 v[194:197], v193 offset:54272
	ds_read_b128 v[198:201], v193 offset:55296
	ds_read_b128 v[202:205], v193 offset:56320
	global_load_lds_dwordx4 v[32:33], off
	v_lshl_add_u64 v[32:33], v[222:223], 0, s[12:13]
	s_mov_b32 m0, s34
	s_nop 0
	global_load_lds_dwordx4 v[32:33], off
	s_waitcnt vmcnt(10)
	s_setprio 1
	s_barrier
	s_waitcnt lgkmcnt(0)
	v_mfma_f32_16x16x32_bf16 v[66:69], v[134:137], v[150:153], v[66:69]
	v_mfma_f32_16x16x32_bf16 v[62:65], v[142:145], v[150:153], v[62:65]
	v_mfma_f32_16x16x32_bf16 v[58:61], v[134:137], v[158:161], v[58:61]
	v_mfma_f32_16x16x32_bf16 v[54:57], v[142:145], v[158:161], v[54:57]
	v_mfma_f32_16x16x32_bf16 v[50:53], v[134:137], v[184:187], v[50:53]
	v_mfma_f32_16x16x32_bf16 v[46:49], v[142:145], v[184:187], v[46:49]
	v_mfma_f32_16x16x32_bf16 v[42:45], v[134:137], v[198:201], v[42:45]
	v_mfma_f32_16x16x32_bf16 v[38:41], v[142:145], v[198:201], v[38:41]
	v_mfma_f32_16x16x32_bf16 v[66:69], v[138:141], v[154:157], v[66:69]
	v_mfma_f32_16x16x32_bf16 v[62:65], v[146:149], v[154:157], v[62:65]
	v_mfma_f32_16x16x32_bf16 v[58:61], v[138:141], v[162:165], v[58:61]
	v_mfma_f32_16x16x32_bf16 v[54:57], v[146:149], v[162:165], v[54:57]
	v_mfma_f32_16x16x32_bf16 v[50:53], v[138:141], v[194:197], v[50:53]
	v_mfma_f32_16x16x32_bf16 v[46:49], v[146:149], v[194:197], v[46:49]
	v_mfma_f32_16x16x32_bf16 v[42:45], v[138:141], v[202:205], v[42:45]
	v_mfma_f32_16x16x32_bf16 v[38:41], v[146:149], v[202:205], v[38:41]
	s_barrier
	s_setprio 0
	s_add_u32 s0, s26, 0x20080
	s_addc_u32 s1, s27, 0
	s_add_i32 s22, s23, s55
	v_lshl_add_u64 v[32:33], s[0:1], 0, v[176:177]
	s_mov_b32 m0, s22
	s_nop 0
	global_load_lds_dwordx4 v[32:33], off
	v_lshl_add_u64 v[32:33], s[0:1], 0, v[172:173]
	s_add_i32 m0, s22, 0x2000
	s_nop 0
	global_load_lds_dwordx4 v[32:33], off
	v_add_u32_e32 v26, 0x10000, v191
	ds_read_b128 v[134:137], v26
	ds_read_b128 v[138:141], v26 offset:1024
	ds_read_b128 v[142:145], v26 offset:2048
	ds_read_b128 v[146:149], v26 offset:3072
	s_waitcnt vmcnt(10)
	s_setprio 1
	s_barrier
	v_mfma_f32_16x16x32_bf16 v[32:35], v[206:209], v[150:153], v[34:37]
	v_mfma_f32_16x16x32_bf16 v[28:31], v[214:217], v[150:153], v[28:31]
	v_mfma_f32_16x16x32_bf16 v[22:25], v[206:209], v[158:161], v[22:25]
	v_mfma_f32_16x16x32_bf16 v[18:21], v[214:217], v[158:161], v[18:21]
	v_mfma_f32_16x16x32_bf16 v[14:17], v[206:209], v[184:187], v[14:17]
	v_mfma_f32_16x16x32_bf16 v[10:13], v[214:217], v[184:187], v[10:13]
	v_mfma_f32_16x16x32_bf16 v[6:9], v[206:209], v[198:201], v[6:9]
	v_mfma_f32_16x16x32_bf16 v[2:5], v[214:217], v[198:201], v[2:5]
	v_mfma_f32_16x16x32_bf16 v[34:37], v[210:213], v[154:157], v[32:35]
	v_mfma_f32_16x16x32_bf16 v[30:33], v[218:221], v[154:157], v[28:31]
	v_mfma_f32_16x16x32_bf16 v[22:25], v[210:213], v[162:165], v[22:25]
	v_mfma_f32_16x16x32_bf16 v[18:21], v[218:221], v[162:165], v[18:21]
	v_mfma_f32_16x16x32_bf16 v[14:17], v[210:213], v[194:197], v[14:17]
	v_mfma_f32_16x16x32_bf16 v[10:13], v[218:221], v[194:197], v[10:13]
	v_mfma_f32_16x16x32_bf16 v[6:9], v[210:213], v[202:205], v[6:9]
	v_mfma_f32_16x16x32_bf16 v[2:5], v[218:221], v[202:205], v[2:5]
	s_barrier
	s_setprio 0
	s_add_i32 s51, s51, 2
	s_add_u32 s45, s45, 0x100
	s_addc_u32 s50, s50, 0
	s_cmp_gt_u32 s51, 5
	s_mov_b64 s[22:23], s[24:25]
	s_cbranch_scc0 .LBB0_887
	s_waitcnt lgkmcnt(0)
	v_lshl_or_b32 v186, s17, 8, v192
	v_ashrrev_i32_e32 v187, 31, v186
	v_lshl_add_u32 v26, s16, 8, v190
	s_cmp_lg_u32 s81, 0
	v_lshl_add_u64 v[28:29], v[186:187], 1, s[40:41]
	s_cselect_b64 s[50:51], -1, 0
	s_cmp_eq_u32 s81, 0
	v_mad_i64_i32 v[184:185], s[0:1], v26, s78, v[28:29]
	v_or_b32_e32 v198, 16, v26
	v_or_b32_e32 v197, 32, v26
	v_or_b32_e32 v196, 48, v26
	v_add_u32_e32 v195, 0x80, v26
	v_add_u32_e32 v194, 0x90, v26
	s_cbranch_scc1 .LBB0_894
	v_add_co_u32_e32 v134, vcc, 0x2000, v184
	v_mad_i64_i32 v[166:167], s[0:1], v26, s78, 0
	s_nop 0
	v_addc_co_u32_e32 v135, vcc, 0, v185, vcc
	global_load_dwordx4 v[162:165], v[134:135], off
	global_load_dwordx4 v[158:161], v[134:135], off offset:256
	v_mad_i64_i32 v[134:135], s[0:1], v198, s78, v[28:29]
	v_add_co_u32_e32 v134, vcc, 0x2000, v134
	v_lshlrev_b64 v[186:187], 1, v[186:187]
	s_nop 0
	v_addc_co_u32_e32 v135, vcc, 0, v135, vcc
	global_load_dwordx4 v[154:157], v[134:135], off
	global_load_dwordx4 v[150:153], v[134:135], off offset:256
	v_mad_i64_i32 v[134:135], s[0:1], v197, s78, v[28:29]
	v_add_co_u32_e32 v134, vcc, 0x2000, v134
	s_movk_i32 s16, 0x2000
	s_nop 0
	v_addc_co_u32_e32 v135, vcc, 0, v135, vcc
	global_load_dwordx4 v[146:149], v[134:135], off
	global_load_dwordx4 v[142:145], v[134:135], off offset:256
	v_mad_i64_i32 v[134:135], s[0:1], v196, s78, v[28:29]
	v_add_co_u32_e32 v134, vcc, 0x2000, v134
	s_nop 1
	v_addc_co_u32_e32 v135, vcc, 0, v135, vcc
	global_load_dwordx4 v[138:141], v[134:135], off
	s_nop 0
	global_load_dwordx4 v[134:137], v[134:135], off offset:256
	s_waitcnt vmcnt(0)
	v_lshlrev_b32_e32 v168, 16, v162
	v_and_b32_e32 v162, 0xffff0000, v162
	v_mul_f32_e32 v162, 0xbfb8aa3b, v162
	v_exp_f32_e32 v162, v162
	v_mul_f32_e32 v168, 0xbfb8aa3b, v168
	v_exp_f32_e32 v168, v168
	v_add_f32_e32 v162, 1.0, v162
	v_rcp_f32_e32 v169, v162
	v_lshlrev_b32_e32 v162, 16, v163
	v_and_b32_e32 v163, 0xffff0000, v163
	v_mul_f32_e32 v162, 0xbfb8aa3b, v162
	v_mul_f32_e32 v163, 0xbfb8aa3b, v163
	v_exp_f32_e32 v162, v162
	v_exp_f32_e32 v163, v163
	v_add_f32_e32 v168, 1.0, v168
	v_rcp_f32_e32 v168, v168
	v_add_f32_e32 v162, 1.0, v162
	v_add_f32_e32 v163, 1.0, v163
	v_rcp_f32_e32 v162, v162
	v_rcp_f32_e32 v163, v163
	v_pk_mul_f32 v[168:169], v[130:131], v[168:169]
	v_pk_mul_f32 v[188:189], v[132:133], v[162:163]
	v_lshlrev_b32_e32 v162, 16, v164
	v_and_b32_e32 v163, 0xffff0000, v164
	v_mul_f32_e32 v162, 0xbfb8aa3b, v162
	v_mul_f32_e32 v163, 0xbfb8aa3b, v163
	v_exp_f32_e32 v162, v162
	v_exp_f32_e32 v163, v163
	v_add_f32_e32 v162, 1.0, v162
	v_add_f32_e32 v163, 1.0, v163
	v_rcp_f32_e32 v162, v162
	v_rcp_f32_e32 v163, v163
	s_nop 0
	v_pk_mul_f32 v[200:201], v[126:127], v[162:163]
	v_lshlrev_b32_e32 v162, 16, v165
	v_and_b32_e32 v163, 0xffff0000, v165
	v_mul_f32_e32 v162, 0xbfb8aa3b, v162
	v_mul_f32_e32 v163, 0xbfb8aa3b, v163
	v_exp_f32_e32 v162, v162
	v_exp_f32_e32 v163, v163
	v_cvt_pk_bf16_f32 v164, v200, v201
	v_add_f32_e32 v162, 1.0, v162
	v_add_f32_e32 v163, 1.0, v163
	v_rcp_f32_e32 v162, v162
	v_rcp_f32_e32 v163, v163
	s_nop 0
	v_pk_mul_f32 v[202:203], v[128:129], v[162:163]
	v_cvt_pk_bf16_f32 v163, v188, v189
	v_lshl_add_u64 v[188:189], s[42:43], 0, v[166:167]
	v_cvt_pk_bf16_f32 v162, v168, v169
	v_cvt_pk_bf16_f32 v165, v202, v203
	v_lshl_add_u64 v[188:189], v[188:189], 0, v[186:187]
	global_store_dwordx4 v[188:189], v[162:165], off
	s_nop 1
	v_lshlrev_b32_e32 v162, 16, v158
	v_and_b32_e32 v158, 0xffff0000, v158
	v_mul_f32_e32 v158, 0xbfb8aa3b, v158
	v_exp_f32_e32 v158, v158
	v_mul_f32_e32 v162, 0xbfb8aa3b, v162
	v_exp_f32_e32 v162, v162
	v_add_f32_e32 v158, 1.0, v158
	v_rcp_f32_e32 v163, v158
	v_lshlrev_b32_e32 v158, 16, v159
	v_and_b32_e32 v159, 0xffff0000, v159
	v_mul_f32_e32 v158, 0xbfb8aa3b, v158
	v_mul_f32_e32 v159, 0xbfb8aa3b, v159
	v_exp_f32_e32 v158, v158
	v_exp_f32_e32 v159, v159
	v_add_f32_e32 v162, 1.0, v162
	v_rcp_f32_e32 v162, v162
	v_add_f32_e32 v158, 1.0, v158
	v_add_f32_e32 v159, 1.0, v159
	v_rcp_f32_e32 v158, v158
	v_rcp_f32_e32 v159, v159
	v_pk_mul_f32 v[162:163], v[98:99], v[162:163]
	v_pk_mul_f32 v[164:165], v[100:101], v[158:159]
	v_lshlrev_b32_e32 v158, 16, v160
	v_and_b32_e32 v159, 0xffff0000, v160
	v_mul_f32_e32 v158, 0xbfb8aa3b, v158
	v_mul_f32_e32 v159, 0xbfb8aa3b, v159
	v_exp_f32_e32 v158, v158
	v_exp_f32_e32 v159, v159
	v_add_f32_e32 v158, 1.0, v158
	v_add_f32_e32 v159, 1.0, v159
	v_rcp_f32_e32 v158, v158
	v_rcp_f32_e32 v159, v159
	s_nop 0
	v_pk_mul_f32 v[166:167], v[94:95], v[158:159]
	v_lshlrev_b32_e32 v158, 16, v161
	v_and_b32_e32 v159, 0xffff0000, v161
	v_mul_f32_e32 v158, 0xbfb8aa3b, v158
	v_mul_f32_e32 v159, 0xbfb8aa3b, v159
	v_exp_f32_e32 v158, v158
	v_exp_f32_e32 v159, v159
	v_cvt_pk_bf16_f32 v160, v166, v167
	v_add_f32_e32 v158, 1.0, v158
	v_add_f32_e32 v159, 1.0, v159
	v_rcp_f32_e32 v158, v158
	v_rcp_f32_e32 v159, v159
	s_nop 0
	v_pk_mul_f32 v[168:169], v[96:97], v[158:159]
	v_cvt_pk_bf16_f32 v158, v162, v163
	v_cvt_pk_bf16_f32 v159, v164, v165
	v_cvt_pk_bf16_f32 v161, v168, v169
	global_store_dwordx4 v[188:189], v[158:161], off offset:256
	s_nop 1
	v_lshlrev_b32_e32 v158, 16, v154
	v_and_b32_e32 v154, 0xffff0000, v154
	v_mul_f32_e32 v154, 0xbfb8aa3b, v154
	v_exp_f32_e32 v154, v154
	v_mul_f32_e32 v158, 0xbfb8aa3b, v158
	v_exp_f32_e32 v158, v158
	v_add_f32_e32 v154, 1.0, v154
	v_rcp_f32_e32 v159, v154
	v_lshlrev_b32_e32 v154, 16, v155
	v_and_b32_e32 v155, 0xffff0000, v155
	v_mul_f32_e32 v154, 0xbfb8aa3b, v154
	v_mul_f32_e32 v155, 0xbfb8aa3b, v155
	v_exp_f32_e32 v154, v154
	v_exp_f32_e32 v155, v155
	v_add_f32_e32 v158, 1.0, v158
	v_rcp_f32_e32 v158, v158
	v_add_f32_e32 v154, 1.0, v154
	v_add_f32_e32 v155, 1.0, v155
	v_rcp_f32_e32 v154, v154
	v_rcp_f32_e32 v155, v155
	v_pk_mul_f32 v[158:159], v[122:123], v[158:159]
	v_pk_mul_f32 v[160:161], v[124:125], v[154:155]
	v_lshlrev_b32_e32 v154, 16, v156
	v_and_b32_e32 v155, 0xffff0000, v156
	v_mul_f32_e32 v154, 0xbfb8aa3b, v154
	v_mul_f32_e32 v155, 0xbfb8aa3b, v155
	v_exp_f32_e32 v154, v154
	v_exp_f32_e32 v155, v155
	v_add_f32_e32 v154, 1.0, v154
	v_add_f32_e32 v155, 1.0, v155
	v_rcp_f32_e32 v154, v154
	v_rcp_f32_e32 v155, v155
	s_nop 0
	v_pk_mul_f32 v[162:163], v[118:119], v[154:155]
	v_lshlrev_b32_e32 v154, 16, v157
	v_and_b32_e32 v155, 0xffff0000, v157
	v_mul_f32_e32 v154, 0xbfb8aa3b, v154
	v_mul_f32_e32 v155, 0xbfb8aa3b, v155
	v_exp_f32_e32 v154, v154
	v_exp_f32_e32 v155, v155
	v_cvt_pk_bf16_f32 v156, v162, v163
	v_mov_b64_e32 v[162:163], s[42:43]
	v_add_f32_e32 v154, 1.0, v154
	v_add_f32_e32 v155, 1.0, v155
	v_rcp_f32_e32 v154, v154
	v_rcp_f32_e32 v155, v155
	s_nop 0
	v_pk_mul_f32 v[164:165], v[120:121], v[154:155]
	v_cvt_pk_bf16_f32 v154, v158, v159
	v_mad_i64_i32 v[158:159], s[0:1], v198, s78, v[162:163]
	v_cvt_pk_bf16_f32 v155, v160, v161
	v_cvt_pk_bf16_f32 v157, v164, v165
	v_lshl_add_u64 v[158:159], v[158:159], 0, v[186:187]
	global_store_dwordx4 v[158:159], v[154:157], off
	s_nop 1
	v_lshlrev_b32_e32 v154, 16, v150
	v_and_b32_e32 v150, 0xffff0000, v150
	v_mul_f32_e32 v150, 0xbfb8aa3b, v150
	v_exp_f32_e32 v150, v150
	v_mul_f32_e32 v154, 0xbfb8aa3b, v154
	v_exp_f32_e32 v154, v154
	v_add_f32_e32 v150, 1.0, v150
	v_rcp_f32_e32 v155, v150
	v_lshlrev_b32_e32 v150, 16, v151
	v_and_b32_e32 v151, 0xffff0000, v151
	v_mul_f32_e32 v150, 0xbfb8aa3b, v150
	v_mul_f32_e32 v151, 0xbfb8aa3b, v151
	v_exp_f32_e32 v150, v150
	v_exp_f32_e32 v151, v151
	v_add_f32_e32 v154, 1.0, v154
	v_rcp_f32_e32 v154, v154
	v_add_f32_e32 v150, 1.0, v150
	v_add_f32_e32 v151, 1.0, v151
	v_rcp_f32_e32 v150, v150
	v_rcp_f32_e32 v151, v151
	v_pk_mul_f32 v[154:155], v[90:91], v[154:155]
	v_pk_mul_f32 v[156:157], v[92:93], v[150:151]
	v_lshlrev_b32_e32 v150, 16, v152
	v_and_b32_e32 v151, 0xffff0000, v152
	v_mul_f32_e32 v150, 0xbfb8aa3b, v150
	v_mul_f32_e32 v151, 0xbfb8aa3b, v151
	v_exp_f32_e32 v150, v150
	v_exp_f32_e32 v151, v151
	v_add_f32_e32 v150, 1.0, v150
	v_add_f32_e32 v151, 1.0, v151
	v_rcp_f32_e32 v150, v150
	v_rcp_f32_e32 v151, v151
	s_nop 0
	v_pk_mul_f32 v[160:161], v[86:87], v[150:151]
	v_lshlrev_b32_e32 v150, 16, v153
	v_and_b32_e32 v151, 0xffff0000, v153
	v_mul_f32_e32 v150, 0xbfb8aa3b, v150
	v_mul_f32_e32 v151, 0xbfb8aa3b, v151
	v_exp_f32_e32 v150, v150
	v_exp_f32_e32 v151, v151
	v_cvt_pk_bf16_f32 v152, v160, v161
	v_add_f32_e32 v150, 1.0, v150
	v_add_f32_e32 v151, 1.0, v151
	v_rcp_f32_e32 v150, v150
	v_rcp_f32_e32 v151, v151
	s_nop 0
	v_pk_mul_f32 v[164:165], v[88:89], v[150:151]
	v_cvt_pk_bf16_f32 v150, v154, v155
	v_cvt_pk_bf16_f32 v151, v156, v157
	v_cvt_pk_bf16_f32 v153, v164, v165
	global_store_dwordx4 v[158:159], v[150:153], off offset:256
	v_add_u32_e32 v165, 0xa0, v26
	v_add_u32_e32 v164, 0xb0, v26
	v_lshlrev_b32_e32 v150, 16, v146
	v_and_b32_e32 v146, 0xffff0000, v146
	v_mul_f32_e32 v146, 0xbfb8aa3b, v146
	v_exp_f32_e32 v146, v146
	v_mul_f32_e32 v150, 0xbfb8aa3b, v150
	v_exp_f32_e32 v150, v150
	v_add_f32_e32 v146, 1.0, v146
	v_rcp_f32_e32 v151, v146
	v_lshlrev_b32_e32 v146, 16, v147
	v_and_b32_e32 v147, 0xffff0000, v147
	v_mul_f32_e32 v146, 0xbfb8aa3b, v146
	v_mul_f32_e32 v147, 0xbfb8aa3b, v147
	v_exp_f32_e32 v146, v146
	v_exp_f32_e32 v147, v147
	v_add_f32_e32 v150, 1.0, v150
	v_rcp_f32_e32 v150, v150
	v_add_f32_e32 v146, 1.0, v146
	v_add_f32_e32 v147, 1.0, v147
	v_rcp_f32_e32 v146, v146
	v_rcp_f32_e32 v147, v147
	v_pk_mul_f32 v[150:151], v[114:115], v[150:151]
	v_pk_mul_f32 v[152:153], v[116:117], v[146:147]
	v_lshlrev_b32_e32 v146, 16, v148
	v_and_b32_e32 v147, 0xffff0000, v148
	v_mul_f32_e32 v146, 0xbfb8aa3b, v146
	v_mul_f32_e32 v147, 0xbfb8aa3b, v147
	v_exp_f32_e32 v146, v146
	v_exp_f32_e32 v147, v147
	v_add_f32_e32 v146, 1.0, v146
	v_add_f32_e32 v147, 1.0, v147
	v_rcp_f32_e32 v146, v146
	v_rcp_f32_e32 v147, v147
	s_nop 0
	v_pk_mul_f32 v[154:155], v[110:111], v[146:147]
	v_lshlrev_b32_e32 v146, 16, v149
	v_and_b32_e32 v147, 0xffff0000, v149
	v_mul_f32_e32 v146, 0xbfb8aa3b, v146
	v_mul_f32_e32 v147, 0xbfb8aa3b, v147
	v_exp_f32_e32 v146, v146
	v_exp_f32_e32 v147, v147
	v_cvt_pk_bf16_f32 v148, v154, v155
	v_add_f32_e32 v146, 1.0, v146
	v_add_f32_e32 v147, 1.0, v147
	v_rcp_f32_e32 v146, v146
	v_rcp_f32_e32 v147, v147
	s_nop 0
	v_pk_mul_f32 v[156:157], v[112:113], v[146:147]
	v_cvt_pk_bf16_f32 v146, v150, v151
	v_mad_i64_i32 v[150:151], s[0:1], v197, s78, v[162:163]
	v_cvt_pk_bf16_f32 v147, v152, v153
	v_cvt_pk_bf16_f32 v149, v156, v157
	v_lshl_add_u64 v[150:151], v[150:151], 0, v[186:187]
	global_store_dwordx4 v[150:151], v[146:149], off
	s_nop 1
	v_lshlrev_b32_e32 v146, 16, v142
	v_and_b32_e32 v142, 0xffff0000, v142
	v_mul_f32_e32 v142, 0xbfb8aa3b, v142
	v_exp_f32_e32 v142, v142
	v_mul_f32_e32 v146, 0xbfb8aa3b, v146
	v_exp_f32_e32 v146, v146
	v_add_f32_e32 v142, 1.0, v142
	v_rcp_f32_e32 v147, v142
	v_lshlrev_b32_e32 v142, 16, v143
	v_and_b32_e32 v143, 0xffff0000, v143
	v_mul_f32_e32 v142, 0xbfb8aa3b, v142
	v_mul_f32_e32 v143, 0xbfb8aa3b, v143
	v_exp_f32_e32 v142, v142
	v_exp_f32_e32 v143, v143
	v_add_f32_e32 v146, 1.0, v146
	v_rcp_f32_e32 v146, v146
	v_add_f32_e32 v142, 1.0, v142
	v_add_f32_e32 v143, 1.0, v143
	v_rcp_f32_e32 v142, v142
	v_rcp_f32_e32 v143, v143
	v_pk_mul_f32 v[146:147], v[82:83], v[146:147]
	v_pk_mul_f32 v[148:149], v[84:85], v[142:143]
	v_lshlrev_b32_e32 v142, 16, v144
	v_and_b32_e32 v143, 0xffff0000, v144
	v_mul_f32_e32 v142, 0xbfb8aa3b, v142
	v_mul_f32_e32 v143, 0xbfb8aa3b, v143
	v_exp_f32_e32 v142, v142
	v_exp_f32_e32 v143, v143
	v_add_f32_e32 v142, 1.0, v142
	v_add_f32_e32 v143, 1.0, v143
	v_rcp_f32_e32 v142, v142
	v_rcp_f32_e32 v143, v143
	s_nop 0
	v_pk_mul_f32 v[152:153], v[78:79], v[142:143]
	v_lshlrev_b32_e32 v142, 16, v145
	v_and_b32_e32 v143, 0xffff0000, v145
	v_mul_f32_e32 v142, 0xbfb8aa3b, v142
	v_mul_f32_e32 v143, 0xbfb8aa3b, v143
	v_exp_f32_e32 v142, v142
	v_exp_f32_e32 v143, v143
	v_cvt_pk_bf16_f32 v144, v152, v153
	v_add_f32_e32 v142, 1.0, v142
	v_add_f32_e32 v143, 1.0, v143
	v_rcp_f32_e32 v142, v142
	v_rcp_f32_e32 v143, v143
	s_nop 0
	v_pk_mul_f32 v[154:155], v[80:81], v[142:143]
	v_cvt_pk_bf16_f32 v142, v146, v147
	v_cvt_pk_bf16_f32 v143, v148, v149
	v_cvt_pk_bf16_f32 v145, v154, v155
	global_store_dwordx4 v[150:151], v[142:145], off offset:256
	s_nop 1
	v_lshlrev_b32_e32 v142, 16, v138
	v_and_b32_e32 v138, 0xffff0000, v138
	v_mul_f32_e32 v138, 0xbfb8aa3b, v138
	v_exp_f32_e32 v138, v138
	v_mul_f32_e32 v142, 0xbfb8aa3b, v142
	v_exp_f32_e32 v142, v142
	v_add_f32_e32 v138, 1.0, v138
	v_rcp_f32_e32 v143, v138
	v_lshlrev_b32_e32 v138, 16, v139
	v_and_b32_e32 v139, 0xffff0000, v139
	v_mul_f32_e32 v138, 0xbfb8aa3b, v138
	v_mul_f32_e32 v139, 0xbfb8aa3b, v139
	v_exp_f32_e32 v138, v138
	v_exp_f32_e32 v139, v139
	v_add_f32_e32 v142, 1.0, v142
	v_rcp_f32_e32 v142, v142
	v_add_f32_e32 v138, 1.0, v138
	v_add_f32_e32 v139, 1.0, v139
	v_rcp_f32_e32 v138, v138
	v_rcp_f32_e32 v139, v139
	v_pk_mul_f32 v[142:143], v[106:107], v[142:143]
	v_pk_mul_f32 v[144:145], v[108:109], v[138:139]
	v_lshlrev_b32_e32 v138, 16, v140
	v_and_b32_e32 v139, 0xffff0000, v140
	v_mul_f32_e32 v138, 0xbfb8aa3b, v138
	v_mul_f32_e32 v139, 0xbfb8aa3b, v139
	v_exp_f32_e32 v138, v138
	v_exp_f32_e32 v139, v139
	v_add_f32_e32 v138, 1.0, v138
	v_add_f32_e32 v139, 1.0, v139
	v_rcp_f32_e32 v138, v138
	v_rcp_f32_e32 v139, v139
	s_nop 0
	v_pk_mul_f32 v[146:147], v[102:103], v[138:139]
	v_lshlrev_b32_e32 v138, 16, v141
	v_and_b32_e32 v139, 0xffff0000, v141
	v_mul_f32_e32 v138, 0xbfb8aa3b, v138
	v_mul_f32_e32 v139, 0xbfb8aa3b, v139
	v_exp_f32_e32 v138, v138
	v_exp_f32_e32 v139, v139
	v_cvt_pk_bf16_f32 v140, v146, v147
	v_add_f32_e32 v138, 1.0, v138
	v_add_f32_e32 v139, 1.0, v139
	v_rcp_f32_e32 v138, v138
	v_rcp_f32_e32 v139, v139
	s_nop 0
	v_pk_mul_f32 v[148:149], v[104:105], v[138:139]
	v_cvt_pk_bf16_f32 v138, v142, v143
	v_mad_i64_i32 v[142:143], s[0:1], v196, s78, v[162:163]
	v_cvt_pk_bf16_f32 v139, v144, v145
	v_cvt_pk_bf16_f32 v141, v148, v149
	v_lshl_add_u64 v[142:143], v[142:143], 0, v[186:187]
	global_store_dwordx4 v[142:143], v[138:141], off
	s_nop 1
	v_lshlrev_b32_e32 v138, 16, v134
	v_and_b32_e32 v134, 0xffff0000, v134
	v_mul_f32_e32 v134, 0xbfb8aa3b, v134
	v_exp_f32_e32 v134, v134
	v_mul_f32_e32 v138, 0xbfb8aa3b, v138
	v_exp_f32_e32 v138, v138
	v_add_f32_e32 v134, 1.0, v134
	v_rcp_f32_e32 v139, v134
	v_lshlrev_b32_e32 v134, 16, v135
	v_and_b32_e32 v135, 0xffff0000, v135
	v_mul_f32_e32 v134, 0xbfb8aa3b, v134
	v_mul_f32_e32 v135, 0xbfb8aa3b, v135
	v_exp_f32_e32 v134, v134
	v_exp_f32_e32 v135, v135
	v_add_f32_e32 v138, 1.0, v138
	v_rcp_f32_e32 v138, v138
	v_add_f32_e32 v134, 1.0, v134
	v_add_f32_e32 v135, 1.0, v135
	v_rcp_f32_e32 v134, v134
	v_rcp_f32_e32 v135, v135
	v_pk_mul_f32 v[138:139], v[74:75], v[138:139]
	v_pk_mul_f32 v[140:141], v[76:77], v[134:135]
	v_lshlrev_b32_e32 v134, 16, v136
	v_and_b32_e32 v135, 0xffff0000, v136
	v_mul_f32_e32 v134, 0xbfb8aa3b, v134
	v_mul_f32_e32 v135, 0xbfb8aa3b, v135
	v_exp_f32_e32 v134, v134
	v_exp_f32_e32 v135, v135
	v_add_f32_e32 v134, 1.0, v134
	v_add_f32_e32 v135, 1.0, v135
	v_rcp_f32_e32 v134, v134
	v_rcp_f32_e32 v135, v135
	s_nop 0
	v_pk_mul_f32 v[144:145], v[70:71], v[134:135]
	v_lshlrev_b32_e32 v134, 16, v137
	v_and_b32_e32 v135, 0xffff0000, v137
	v_mul_f32_e32 v134, 0xbfb8aa3b, v134
	v_mul_f32_e32 v135, 0xbfb8aa3b, v135
	v_exp_f32_e32 v134, v134
	v_exp_f32_e32 v135, v135
	v_cvt_pk_bf16_f32 v136, v144, v145
	v_add_f32_e32 v134, 1.0, v134
	v_add_f32_e32 v135, 1.0, v135
	v_rcp_f32_e32 v134, v134
	v_rcp_f32_e32 v135, v135
	s_nop 0
	v_pk_mul_f32 v[146:147], v[72:73], v[134:135]
	v_cvt_pk_bf16_f32 v134, v138, v139
	v_cvt_pk_bf16_f32 v135, v140, v141
	v_cvt_pk_bf16_f32 v137, v146, v147
	global_store_dwordx4 v[142:143], v[134:137], off offset:256
	s_nop 1
	v_mad_i64_i32 v[134:135], s[0:1], v195, s78, v[28:29]
	v_add_co_u32_e32 v134, vcc, s16, v134
	s_nop 1
	v_addc_co_u32_e32 v135, vcc, 0, v135, vcc
	global_load_dwordx4 v[200:203], v[134:135], off
	global_load_dwordx4 v[158:161], v[134:135], off offset:256
	v_mad_i64_i32 v[134:135], s[0:1], v194, s78, v[28:29]
	v_add_co_u32_e32 v134, vcc, s16, v134
	s_waitcnt vmcnt(0)
	v_lshlrev_b32_e32 v199, 16, v203
	v_addc_co_u32_e32 v135, vcc, 0, v135, vcc
	global_load_dwordx4 v[154:157], v[134:135], off
	global_load_dwordx4 v[150:153], v[134:135], off offset:256
	v_mul_f32_e32 v199, 0xbfb8aa3b, v199
	v_exp_f32_e32 v199, v199
	v_lshlrev_b32_e32 v168, 16, v201
	v_and_b32_e32 v169, 0xffff0000, v201
	v_lshlrev_b32_e32 v166, 16, v200
	v_add_f32_e32 v199, 1.0, v199
	v_and_b32_e32 v167, 0xffff0000, v200
	v_mul_f32_e32 v168, 0xbfb8aa3b, v168
	v_mul_f32_e32 v169, 0xbfb8aa3b, v169
	v_rcp_f32_e32 v200, v199
	v_and_b32_e32 v199, 0xffff0000, v203
	v_exp_f32_e32 v168, v168
	v_exp_f32_e32 v169, v169
	v_mul_f32_e32 v199, 0xbfb8aa3b, v199
	v_exp_f32_e32 v199, v199
	v_add_f32_e32 v168, 1.0, v168
	v_add_f32_e32 v169, 1.0, v169
	v_rcp_f32_e32 v168, v168
	v_rcp_f32_e32 v169, v169
	v_add_f32_e32 v199, 1.0, v199
	v_rcp_f32_e32 v201, v199
	v_lshlrev_b32_e32 v188, 16, v202
	v_pk_mul_f32 v[168:169], v[68:69], v[168:169]
	v_and_b32_e32 v189, 0xffff0000, v202
	v_pk_mul_f32 v[204:205], v[64:65], v[200:201]
	v_cvt_pk_bf16_f32 v201, v168, v169
	v_lshlrev_b32_e32 v168, 16, v158
	v_and_b32_e32 v158, 0xffff0000, v158
	v_mul_f32_e32 v158, 0xbfb8aa3b, v158
	v_exp_f32_e32 v158, v158
	v_mul_f32_e32 v188, 0xbfb8aa3b, v188
	v_mul_f32_e32 v189, 0xbfb8aa3b, v189
	v_exp_f32_e32 v188, v188
	v_add_f32_e32 v158, 1.0, v158
	v_rcp_f32_e32 v169, v158
	v_lshlrev_b32_e32 v158, 16, v159
	v_and_b32_e32 v159, 0xffff0000, v159
	v_exp_f32_e32 v189, v189
	v_mul_f32_e32 v158, 0xbfb8aa3b, v158
	v_mul_f32_e32 v159, 0xbfb8aa3b, v159
	v_exp_f32_e32 v158, v158
	v_exp_f32_e32 v159, v159
	v_add_f32_e32 v188, 1.0, v188
	v_add_f32_e32 v189, 1.0, v189
	v_rcp_f32_e32 v188, v188
	v_rcp_f32_e32 v189, v189
	v_add_f32_e32 v158, 1.0, v158
	v_add_f32_e32 v159, 1.0, v159
	v_rcp_f32_e32 v158, v158
	v_rcp_f32_e32 v159, v159
	v_mul_f32_e32 v166, 0xbfb8aa3b, v166
	v_mul_f32_e32 v167, 0xbfb8aa3b, v167
	v_exp_f32_e32 v166, v166
	v_exp_f32_e32 v167, v167
	v_pk_mul_f32 v[188:189], v[62:63], v[188:189]
	v_mad_i64_i32 v[134:135], s[0:1], v165, s78, v[28:29]
	v_cvt_pk_bf16_f32 v202, v188, v189
	v_pk_mul_f32 v[188:189], v[36:37], v[158:159]
	v_lshlrev_b32_e32 v158, 16, v160
	v_and_b32_e32 v159, 0xffff0000, v160
	v_mul_f32_e32 v158, 0xbfb8aa3b, v158
	v_mul_f32_e32 v159, 0xbfb8aa3b, v159
	v_exp_f32_e32 v158, v158
	v_exp_f32_e32 v159, v159
	v_add_f32_e32 v166, 1.0, v166
	v_add_f32_e32 v167, 1.0, v167
	v_rcp_f32_e32 v166, v166
	v_rcp_f32_e32 v167, v167
	v_add_co_u32_e32 v134, vcc, s16, v134
	v_add_f32_e32 v158, 1.0, v158
	v_add_f32_e32 v159, 1.0, v159
	v_addc_co_u32_e32 v135, vcc, 0, v135, vcc
	v_rcp_f32_e32 v158, v158
	v_rcp_f32_e32 v159, v159
	global_load_dwordx4 v[146:149], v[134:135], off
	global_load_dwordx4 v[142:145], v[134:135], off offset:256
	v_mad_i64_i32 v[134:135], s[0:1], v164, s78, v[28:29]
	v_pk_mul_f32 v[166:167], v[66:67], v[166:167]
	v_add_co_u32_e32 v134, vcc, s16, v134
	v_cvt_pk_bf16_f32 v200, v166, v167
	v_mad_i64_i32 v[166:167], s[0:1], v195, s78, v[162:163]
	v_addc_co_u32_e32 v135, vcc, 0, v135, vcc
	v_cvt_pk_bf16_f32 v203, v204, v205
	v_lshl_add_u64 v[166:167], v[166:167], 0, v[186:187]
	global_load_dwordx4 v[138:141], v[134:135], off
	s_nop 0
	global_load_dwordx4 v[134:137], v[134:135], off offset:256
	v_mul_f32_e32 v168, 0xbfb8aa3b, v168
	global_store_dwordx4 v[166:167], v[200:203], off
	v_exp_f32_e32 v168, v168
	s_nop 0
	v_pk_mul_f32 v[200:201], v[30:31], v[158:159]
	v_lshlrev_b32_e32 v158, 16, v161
	v_and_b32_e32 v159, 0xffff0000, v161
	v_mul_f32_e32 v158, 0xbfb8aa3b, v158
	v_mul_f32_e32 v159, 0xbfb8aa3b, v159
	v_exp_f32_e32 v158, v158
	v_exp_f32_e32 v159, v159
	v_add_f32_e32 v168, 1.0, v168
	v_rcp_f32_e32 v168, v168
	v_add_f32_e32 v158, 1.0, v158
	v_add_f32_e32 v159, 1.0, v159
	v_rcp_f32_e32 v158, v158
	v_rcp_f32_e32 v159, v159
	v_pk_mul_f32 v[168:169], v[34:35], v[168:169]
	v_cvt_pk_bf16_f32 v160, v200, v201
	v_pk_mul_f32 v[202:203], v[32:33], v[158:159]
	v_cvt_pk_bf16_f32 v158, v168, v169
	v_cvt_pk_bf16_f32 v159, v188, v189
	v_cvt_pk_bf16_f32 v161, v202, v203
	global_store_dwordx4 v[166:167], v[158:161], off offset:256
	s_waitcnt vmcnt(0)
	s_nop 0
	v_lshlrev_b32_e32 v158, 16, v154
	v_and_b32_e32 v154, 0xffff0000, v154
	v_mul_f32_e32 v154, 0xbfb8aa3b, v154
	v_exp_f32_e32 v154, v154
	v_mul_f32_e32 v158, 0xbfb8aa3b, v158
	v_exp_f32_e32 v158, v158
	v_add_f32_e32 v154, 1.0, v154
	v_rcp_f32_e32 v159, v154
	v_lshlrev_b32_e32 v154, 16, v155
	v_and_b32_e32 v155, 0xffff0000, v155
	v_mul_f32_e32 v154, 0xbfb8aa3b, v154
	v_mul_f32_e32 v155, 0xbfb8aa3b, v155
	v_exp_f32_e32 v154, v154
	v_exp_f32_e32 v155, v155
	v_add_f32_e32 v158, 1.0, v158
	v_rcp_f32_e32 v158, v158
	v_add_f32_e32 v154, 1.0, v154
	v_add_f32_e32 v155, 1.0, v155
	v_rcp_f32_e32 v154, v154
	v_rcp_f32_e32 v155, v155
	v_pk_mul_f32 v[158:159], v[58:59], v[158:159]
	v_pk_mul_f32 v[160:161], v[60:61], v[154:155]
	v_lshlrev_b32_e32 v154, 16, v156
	v_and_b32_e32 v155, 0xffff0000, v156
	v_mul_f32_e32 v154, 0xbfb8aa3b, v154
	v_mul_f32_e32 v155, 0xbfb8aa3b, v155
	v_exp_f32_e32 v154, v154
	v_exp_f32_e32 v155, v155
	v_add_f32_e32 v154, 1.0, v154
	v_add_f32_e32 v155, 1.0, v155
	v_rcp_f32_e32 v154, v154
	v_rcp_f32_e32 v155, v155
	s_nop 0
	v_pk_mul_f32 v[166:167], v[54:55], v[154:155]
	v_lshlrev_b32_e32 v154, 16, v157
	v_and_b32_e32 v155, 0xffff0000, v157
	v_mul_f32_e32 v154, 0xbfb8aa3b, v154
	v_mul_f32_e32 v155, 0xbfb8aa3b, v155
	v_exp_f32_e32 v154, v154
	v_exp_f32_e32 v155, v155
	v_cvt_pk_bf16_f32 v156, v166, v167
	v_add_f32_e32 v154, 1.0, v154
	v_add_f32_e32 v155, 1.0, v155
	v_rcp_f32_e32 v154, v154
	v_rcp_f32_e32 v155, v155
	s_nop 0
	v_pk_mul_f32 v[168:169], v[56:57], v[154:155]
	v_cvt_pk_bf16_f32 v154, v158, v159
	v_mad_i64_i32 v[158:159], s[0:1], v194, s78, v[162:163]
	v_cvt_pk_bf16_f32 v155, v160, v161
	v_cvt_pk_bf16_f32 v157, v168, v169
	v_lshl_add_u64 v[158:159], v[158:159], 0, v[186:187]
	global_store_dwordx4 v[158:159], v[154:157], off
	s_nop 1
	v_lshlrev_b32_e32 v154, 16, v150
	v_and_b32_e32 v150, 0xffff0000, v150
	v_mul_f32_e32 v150, 0xbfb8aa3b, v150
	v_exp_f32_e32 v150, v150
	v_mul_f32_e32 v154, 0xbfb8aa3b, v154
	v_exp_f32_e32 v154, v154
	v_add_f32_e32 v150, 1.0, v150
	v_rcp_f32_e32 v155, v150
	v_lshlrev_b32_e32 v150, 16, v151
	v_and_b32_e32 v151, 0xffff0000, v151
	v_mul_f32_e32 v150, 0xbfb8aa3b, v150
	v_mul_f32_e32 v151, 0xbfb8aa3b, v151
	v_exp_f32_e32 v150, v150
	v_exp_f32_e32 v151, v151
	v_add_f32_e32 v154, 1.0, v154
	v_rcp_f32_e32 v154, v154
	v_add_f32_e32 v150, 1.0, v150
	v_add_f32_e32 v151, 1.0, v151
	v_rcp_f32_e32 v150, v150
	v_rcp_f32_e32 v151, v151
	v_pk_mul_f32 v[154:155], v[22:23], v[154:155]
	v_pk_mul_f32 v[156:157], v[24:25], v[150:151]
	v_lshlrev_b32_e32 v150, 16, v152
	v_and_b32_e32 v151, 0xffff0000, v152
	v_mul_f32_e32 v150, 0xbfb8aa3b, v150
	v_mul_f32_e32 v151, 0xbfb8aa3b, v151
	v_exp_f32_e32 v150, v150
	v_exp_f32_e32 v151, v151
	v_add_f32_e32 v150, 1.0, v150
	v_add_f32_e32 v151, 1.0, v151
	v_rcp_f32_e32 v150, v150
	v_rcp_f32_e32 v151, v151
	s_nop 0
	v_pk_mul_f32 v[160:161], v[18:19], v[150:151]
	v_lshlrev_b32_e32 v150, 16, v153
	v_and_b32_e32 v151, 0xffff0000, v153
	v_mul_f32_e32 v150, 0xbfb8aa3b, v150
	v_mul_f32_e32 v151, 0xbfb8aa3b, v151
	v_exp_f32_e32 v150, v150
	v_exp_f32_e32 v151, v151
	v_cvt_pk_bf16_f32 v152, v160, v161
	v_add_f32_e32 v150, 1.0, v150
	v_add_f32_e32 v151, 1.0, v151
	v_rcp_f32_e32 v150, v150
	v_rcp_f32_e32 v151, v151
	s_nop 0
	v_pk_mul_f32 v[166:167], v[20:21], v[150:151]
	v_cvt_pk_bf16_f32 v150, v154, v155
	v_cvt_pk_bf16_f32 v151, v156, v157
	v_cvt_pk_bf16_f32 v153, v166, v167
	global_store_dwordx4 v[158:159], v[150:153], off offset:256
	s_nop 1
	v_lshlrev_b32_e32 v150, 16, v146
	v_and_b32_e32 v146, 0xffff0000, v146
	v_mul_f32_e32 v146, 0xbfb8aa3b, v146
	v_exp_f32_e32 v146, v146
	v_mul_f32_e32 v150, 0xbfb8aa3b, v150
	v_exp_f32_e32 v150, v150
	v_add_f32_e32 v146, 1.0, v146
	v_rcp_f32_e32 v151, v146
	v_lshlrev_b32_e32 v146, 16, v147
	v_and_b32_e32 v147, 0xffff0000, v147
	v_mul_f32_e32 v146, 0xbfb8aa3b, v146
	v_mul_f32_e32 v147, 0xbfb8aa3b, v147
	v_exp_f32_e32 v146, v146
	v_exp_f32_e32 v147, v147
	v_add_f32_e32 v150, 1.0, v150
	v_rcp_f32_e32 v150, v150
	v_add_f32_e32 v146, 1.0, v146
	v_add_f32_e32 v147, 1.0, v147
	v_rcp_f32_e32 v146, v146
	v_rcp_f32_e32 v147, v147
	v_pk_mul_f32 v[150:151], v[50:51], v[150:151]
	v_pk_mul_f32 v[152:153], v[52:53], v[146:147]
	v_lshlrev_b32_e32 v146, 16, v148
	v_and_b32_e32 v147, 0xffff0000, v148
	v_mul_f32_e32 v146, 0xbfb8aa3b, v146
	v_mul_f32_e32 v147, 0xbfb8aa3b, v147
	v_exp_f32_e32 v146, v146
	v_exp_f32_e32 v147, v147
	v_add_f32_e32 v146, 1.0, v146
	v_add_f32_e32 v147, 1.0, v147
	v_rcp_f32_e32 v146, v146
	v_rcp_f32_e32 v147, v147
	s_nop 0
	v_pk_mul_f32 v[154:155], v[46:47], v[146:147]
	v_lshlrev_b32_e32 v146, 16, v149
	v_and_b32_e32 v147, 0xffff0000, v149
	v_mul_f32_e32 v146, 0xbfb8aa3b, v146
	v_mul_f32_e32 v147, 0xbfb8aa3b, v147
	v_exp_f32_e32 v146, v146
	v_exp_f32_e32 v147, v147
	v_cvt_pk_bf16_f32 v148, v154, v155
	v_add_f32_e32 v146, 1.0, v146
	v_add_f32_e32 v147, 1.0, v147
	v_rcp_f32_e32 v146, v146
	v_rcp_f32_e32 v147, v147
	s_nop 0
	v_pk_mul_f32 v[156:157], v[48:49], v[146:147]
	v_cvt_pk_bf16_f32 v146, v150, v151
	v_mad_i64_i32 v[150:151], s[0:1], v165, s78, v[162:163]
	v_cvt_pk_bf16_f32 v147, v152, v153
	v_cvt_pk_bf16_f32 v149, v156, v157
	v_lshl_add_u64 v[150:151], v[150:151], 0, v[186:187]
	global_store_dwordx4 v[150:151], v[146:149], off
	s_nop 1
	v_lshlrev_b32_e32 v146, 16, v142
	v_and_b32_e32 v142, 0xffff0000, v142
	v_mul_f32_e32 v142, 0xbfb8aa3b, v142
	v_exp_f32_e32 v142, v142
	v_mul_f32_e32 v146, 0xbfb8aa3b, v146
	v_exp_f32_e32 v146, v146
	v_add_f32_e32 v142, 1.0, v142
	v_rcp_f32_e32 v147, v142
	v_lshlrev_b32_e32 v142, 16, v143
	v_and_b32_e32 v143, 0xffff0000, v143
	v_mul_f32_e32 v142, 0xbfb8aa3b, v142
	v_mul_f32_e32 v143, 0xbfb8aa3b, v143
	v_exp_f32_e32 v142, v142
	v_exp_f32_e32 v143, v143
	v_add_f32_e32 v146, 1.0, v146
	v_rcp_f32_e32 v146, v146
	v_add_f32_e32 v142, 1.0, v142
	v_add_f32_e32 v143, 1.0, v143
	v_rcp_f32_e32 v142, v142
	v_rcp_f32_e32 v143, v143
	v_pk_mul_f32 v[146:147], v[14:15], v[146:147]
	v_pk_mul_f32 v[148:149], v[16:17], v[142:143]
	v_lshlrev_b32_e32 v142, 16, v144
	v_and_b32_e32 v143, 0xffff0000, v144
	v_mul_f32_e32 v142, 0xbfb8aa3b, v142
	v_mul_f32_e32 v143, 0xbfb8aa3b, v143
	v_exp_f32_e32 v142, v142
	v_exp_f32_e32 v143, v143
	v_add_f32_e32 v142, 1.0, v142
	v_add_f32_e32 v143, 1.0, v143
	v_rcp_f32_e32 v142, v142
	v_rcp_f32_e32 v143, v143
	s_nop 0
	v_pk_mul_f32 v[152:153], v[10:11], v[142:143]
	v_lshlrev_b32_e32 v142, 16, v145
	v_and_b32_e32 v143, 0xffff0000, v145
	v_mul_f32_e32 v142, 0xbfb8aa3b, v142
	v_mul_f32_e32 v143, 0xbfb8aa3b, v143
	v_exp_f32_e32 v142, v142
	v_exp_f32_e32 v143, v143
	v_cvt_pk_bf16_f32 v144, v152, v153
	v_add_f32_e32 v142, 1.0, v142
	v_add_f32_e32 v143, 1.0, v143
	v_rcp_f32_e32 v142, v142
	v_rcp_f32_e32 v143, v143
	s_nop 0
	v_pk_mul_f32 v[154:155], v[12:13], v[142:143]
	v_cvt_pk_bf16_f32 v142, v146, v147
	v_cvt_pk_bf16_f32 v143, v148, v149
	v_cvt_pk_bf16_f32 v145, v154, v155
	global_store_dwordx4 v[150:151], v[142:145], off offset:256
	s_nop 1
	v_lshlrev_b32_e32 v142, 16, v138
	v_and_b32_e32 v138, 0xffff0000, v138
	v_mul_f32_e32 v138, 0xbfb8aa3b, v138
	v_exp_f32_e32 v138, v138
	v_mul_f32_e32 v142, 0xbfb8aa3b, v142
	v_exp_f32_e32 v142, v142
	v_add_f32_e32 v138, 1.0, v138
	v_rcp_f32_e32 v143, v138
	v_lshlrev_b32_e32 v138, 16, v139
	v_and_b32_e32 v139, 0xffff0000, v139
	v_mul_f32_e32 v138, 0xbfb8aa3b, v138
	v_mul_f32_e32 v139, 0xbfb8aa3b, v139
	v_exp_f32_e32 v138, v138
	v_exp_f32_e32 v139, v139
	v_add_f32_e32 v142, 1.0, v142
	v_rcp_f32_e32 v142, v142
	v_add_f32_e32 v138, 1.0, v138
	v_add_f32_e32 v139, 1.0, v139
	v_rcp_f32_e32 v138, v138
	v_rcp_f32_e32 v139, v139
	v_pk_mul_f32 v[142:143], v[42:43], v[142:143]
	v_pk_mul_f32 v[144:145], v[44:45], v[138:139]
	v_lshlrev_b32_e32 v138, 16, v140
	v_and_b32_e32 v139, 0xffff0000, v140
	v_mul_f32_e32 v138, 0xbfb8aa3b, v138
	v_mul_f32_e32 v139, 0xbfb8aa3b, v139
	v_exp_f32_e32 v138, v138
	v_exp_f32_e32 v139, v139
	v_add_f32_e32 v138, 1.0, v138
	v_add_f32_e32 v139, 1.0, v139
	v_rcp_f32_e32 v138, v138
	v_rcp_f32_e32 v139, v139
	s_nop 0
	v_pk_mul_f32 v[146:147], v[38:39], v[138:139]
	v_lshlrev_b32_e32 v138, 16, v141
	v_and_b32_e32 v139, 0xffff0000, v141
	v_mul_f32_e32 v138, 0xbfb8aa3b, v138
	v_mul_f32_e32 v139, 0xbfb8aa3b, v139
	v_exp_f32_e32 v138, v138
	v_exp_f32_e32 v139, v139
	v_cvt_pk_bf16_f32 v140, v146, v147
	v_add_f32_e32 v138, 1.0, v138
	v_add_f32_e32 v139, 1.0, v139
	v_rcp_f32_e32 v138, v138
	v_rcp_f32_e32 v139, v139
	s_nop 0
	v_pk_mul_f32 v[148:149], v[40:41], v[138:139]
	v_cvt_pk_bf16_f32 v138, v142, v143
	v_mad_i64_i32 v[142:143], s[0:1], v164, s78, v[162:163]
	v_cvt_pk_bf16_f32 v139, v144, v145
	v_cvt_pk_bf16_f32 v141, v148, v149
	v_lshl_add_u64 v[142:143], v[142:143], 0, v[186:187]
	global_store_dwordx4 v[142:143], v[138:141], off
	s_nop 1
	v_lshlrev_b32_e32 v138, 16, v134
	v_and_b32_e32 v134, 0xffff0000, v134
	v_mul_f32_e32 v134, 0xbfb8aa3b, v134
	v_exp_f32_e32 v134, v134
	v_mul_f32_e32 v138, 0xbfb8aa3b, v138
	v_exp_f32_e32 v138, v138
	v_add_f32_e32 v134, 1.0, v134
	v_rcp_f32_e32 v139, v134
	v_lshlrev_b32_e32 v134, 16, v135
	v_and_b32_e32 v135, 0xffff0000, v135
	v_mul_f32_e32 v134, 0xbfb8aa3b, v134
	v_mul_f32_e32 v135, 0xbfb8aa3b, v135
	v_exp_f32_e32 v134, v134
	v_exp_f32_e32 v135, v135
	v_add_f32_e32 v138, 1.0, v138
	v_rcp_f32_e32 v138, v138
	v_add_f32_e32 v134, 1.0, v134
	v_add_f32_e32 v135, 1.0, v135
	v_rcp_f32_e32 v134, v134
	v_rcp_f32_e32 v135, v135
	v_pk_mul_f32 v[138:139], v[6:7], v[138:139]
	v_pk_mul_f32 v[140:141], v[8:9], v[134:135]
	v_lshlrev_b32_e32 v134, 16, v136
	v_and_b32_e32 v135, 0xffff0000, v136
	v_mul_f32_e32 v134, 0xbfb8aa3b, v134
	v_mul_f32_e32 v135, 0xbfb8aa3b, v135
	v_exp_f32_e32 v134, v134
	v_exp_f32_e32 v135, v135
	v_add_f32_e32 v134, 1.0, v134
	v_add_f32_e32 v135, 1.0, v135
	v_rcp_f32_e32 v134, v134
	v_rcp_f32_e32 v135, v135
	s_nop 0
	v_pk_mul_f32 v[144:145], v[2:3], v[134:135]
	v_lshlrev_b32_e32 v134, 16, v137
	v_and_b32_e32 v135, 0xffff0000, v137
	v_mul_f32_e32 v134, 0xbfb8aa3b, v134
	v_mul_f32_e32 v135, 0xbfb8aa3b, v135
	v_exp_f32_e32 v134, v134
	v_exp_f32_e32 v135, v135
	v_cvt_pk_bf16_f32 v136, v144, v145
	v_add_f32_e32 v134, 1.0, v134
	v_add_f32_e32 v135, 1.0, v135
	v_rcp_f32_e32 v134, v134
	v_rcp_f32_e32 v135, v135
	s_nop 0
	v_pk_mul_f32 v[146:147], v[4:5], v[134:135]
	v_cvt_pk_bf16_f32 v134, v138, v139
	v_cvt_pk_bf16_f32 v135, v140, v141
	v_cvt_pk_bf16_f32 v137, v146, v147
	global_store_dwordx4 v[142:143], v[134:137], off offset:256
	s_cbranch_execnz .LBB0_891

.LBB0_964:
	s_ashr_i32 s23, s22, 31
	s_lshl_b64 s[0:1], s[22:23], 19
	s_add_u32 s26, s50, s0
	s_addc_u32 s27, s51, s1
	s_and_b64 s[0:1], s[42:43], exec
	s_cselect_b32 s18, s27, s37
	s_cselect_b32 s19, s26, s36
	s_add_u32 s23, s36, 0x100
	v_mov_b32_e32 v2, 0
	s_addc_u32 s29, s37, 0
	s_mov_b32 s31, -2
	v_mov_b32_e32 v3, v2
	v_mov_b32_e32 v4, v2
	v_mov_b32_e32 v5, v2
	v_mov_b32_e32 v6, v2
	v_mov_b32_e32 v7, v2
	v_mov_b32_e32 v8, v2
	v_mov_b32_e32 v9, v2
	v_mov_b32_e32 v10, v2
	v_mov_b32_e32 v11, v2
	v_mov_b32_e32 v12, v2
	v_mov_b32_e32 v13, v2
	v_mov_b32_e32 v14, v2
	v_mov_b32_e32 v15, v2
	v_mov_b32_e32 v16, v2
	v_mov_b32_e32 v17, v2
	v_mov_b32_e32 v18, v2
	v_mov_b32_e32 v19, v2
	v_mov_b32_e32 v20, v2
	v_mov_b32_e32 v21, v2
	v_mov_b32_e32 v22, v2
	v_mov_b32_e32 v23, v2
	v_mov_b32_e32 v24, v2
	v_mov_b32_e32 v25, v2
	v_mov_b32_e32 v28, v2
	v_mov_b32_e32 v29, v2
	v_mov_b32_e32 v30, v2
	v_mov_b32_e32 v31, v2
	v_mov_b32_e32 v32, v2
	v_mov_b32_e32 v33, v2
	v_mov_b32_e32 v34, v2
	v_mov_b32_e32 v35, v2
	v_mov_b32_e32 v68, v2
	v_mov_b32_e32 v69, v2
	v_mov_b32_e32 v70, v2
	v_mov_b32_e32 v71, v2
	v_mov_b32_e32 v72, v2
	v_mov_b32_e32 v73, v2
	v_mov_b32_e32 v74, v2
	v_mov_b32_e32 v75, v2
	v_mov_b32_e32 v76, v2
	v_mov_b32_e32 v77, v2
	v_mov_b32_e32 v78, v2
	v_mov_b32_e32 v79, v2
	v_mov_b32_e32 v80, v2
	v_mov_b32_e32 v81, v2
	v_mov_b32_e32 v82, v2
	v_mov_b32_e32 v83, v2
	v_mov_b32_e32 v84, v2
	v_mov_b32_e32 v85, v2
	v_mov_b32_e32 v86, v2
	v_mov_b32_e32 v87, v2
	v_mov_b32_e32 v88, v2
	v_mov_b32_e32 v89, v2
	v_mov_b32_e32 v90, v2
	v_mov_b32_e32 v91, v2
	v_mov_b32_e32 v92, v2
	v_mov_b32_e32 v93, v2
	v_mov_b32_e32 v94, v2
	v_mov_b32_e32 v95, v2
	v_mov_b32_e32 v96, v2
	v_mov_b32_e32 v97, v2
	v_mov_b32_e32 v98, v2
	v_mov_b32_e32 v99, v2
	s_waitcnt vmcnt(0)
	v_mov_b32_e32 v36, v2
	v_mov_b32_e32 v37, v2
	v_mov_b32_e32 v38, v2
	v_mov_b32_e32 v39, v2
	v_mov_b32_e32 v40, v2
	v_mov_b32_e32 v41, v2
	v_mov_b32_e32 v42, v2
	v_mov_b32_e32 v43, v2
	v_mov_b32_e32 v44, v2
	v_mov_b32_e32 v45, v2
	v_mov_b32_e32 v46, v2
	v_mov_b32_e32 v47, v2
	v_mov_b32_e32 v48, v2
	v_mov_b32_e32 v49, v2
	v_mov_b32_e32 v50, v2
	v_mov_b32_e32 v51, v2
	v_mov_b32_e32 v52, v2
	v_mov_b32_e32 v53, v2
	v_mov_b32_e32 v54, v2
	v_mov_b32_e32 v55, v2
	v_mov_b32_e32 v56, v2
	v_mov_b32_e32 v57, v2
	v_mov_b32_e32 v58, v2
	v_mov_b32_e32 v59, v2
	v_mov_b32_e32 v60, v2
	v_mov_b32_e32 v61, v2
	v_mov_b32_e32 v62, v2
	v_mov_b32_e32 v63, v2
	v_mov_b32_e32 v64, v2
	v_mov_b32_e32 v65, v2
	v_mov_b32_e32 v66, v2
	v_mov_b32_e32 v67, v2
	v_mov_b32_e32 v108, v2
	v_mov_b32_e32 v109, v2
	v_mov_b32_e32 v110, v2
	v_mov_b32_e32 v111, v2
	v_mov_b32_e32 v112, v2
	v_mov_b32_e32 v113, v2
	v_mov_b32_e32 v114, v2
	v_mov_b32_e32 v115, v2
	v_mov_b32_e32 v116, v2
	v_mov_b32_e32 v117, v2
	v_mov_b32_e32 v118, v2
	v_mov_b32_e32 v119, v2
	v_mov_b32_e32 v120, v2
	v_mov_b32_e32 v121, v2
	v_mov_b32_e32 v122, v2
	v_mov_b32_e32 v123, v2
	v_mov_b32_e32 v124, v2
	v_mov_b32_e32 v125, v2
	v_mov_b32_e32 v126, v2
	v_mov_b32_e32 v127, v2
	v_mov_b32_e32 v128, v2
	v_mov_b32_e32 v129, v2
	v_mov_b32_e32 v130, v2
	v_mov_b32_e32 v131, v2
	v_mov_b32_e32 v132, v2
	v_mov_b32_e32 v133, v2
	v_mov_b32_e32 v134, v2
	v_mov_b32_e32 v135, v2
	v_mov_b32_e32 v136, v2
	v_mov_b32_e32 v137, v2
	v_mov_b32_e32 v138, v2
	v_mov_b32_e32 v139, v2
	v_add_u32_e32 v144, 0x10000, v222
	ds_read_b128 v[100:103], v144
	ds_read_b128 v[104:107], v144 offset:1024
	ds_read_b128 v[140:143], v144 offset:2048
	ds_read_b128 v[144:147], v144 offset:3072
.LBB0_965:
	s_add_u32 s36, s34, 0x100
	s_addc_u32 s37, s35, 0
	s_add_i32 s0, 0, 0x10000
	s_cmp_eq_u32 s31, 12
	s_cselect_b32 s47, s25, s37
	s_cselect_b32 s46, s24, s36
	s_cselect_b32 s43, s18, s29
	s_cselect_b32 s42, s19, s23
	v_lshl_add_u64 v[166:167], s[34:35], 0, v[174:175]
	s_add_i32 m0, s54, 0xc000
	ds_read_b128 v[148:151], v224
	ds_read_b128 v[152:155], v224 offset:1024
	ds_read_b128 v[178:181], v224 offset:2048
	ds_read_b128 v[182:185], v224 offset:3072
	ds_read_b128 v[186:189], v224 offset:4096
	ds_read_b128 v[190:193], v224 offset:5120
	ds_read_b128 v[194:197], v224 offset:6144
	ds_read_b128 v[198:201], v224 offset:7168
	global_load_lds_dwordx4 v[166:167], off
	v_lshl_add_u64 v[166:167], s[34:35], 0, v[176:177]
	s_add_i32 m0, s54, 0xe000
	s_nop 0
	global_load_lds_dwordx4 v[166:167], off
	s_waitcnt vmcnt(10) lgkmcnt(8)
	s_setprio 1
	s_barrier
	s_waitcnt lgkmcnt(0)
	v_mfma_f32_16x16x32_bf16 v[136:139], v[100:103], v[148:151], v[136:139]
	v_mfma_f32_16x16x32_bf16 v[132:135], v[140:143], v[148:151], v[132:135]
	v_mfma_f32_16x16x32_bf16 v[128:131], v[100:103], v[178:181], v[128:131]
	v_mfma_f32_16x16x32_bf16 v[124:127], v[140:143], v[178:181], v[124:127]
	v_mfma_f32_16x16x32_bf16 v[120:123], v[100:103], v[186:189], v[120:123]
	v_mfma_f32_16x16x32_bf16 v[116:119], v[140:143], v[186:189], v[116:119]
	v_mfma_f32_16x16x32_bf16 v[112:115], v[100:103], v[194:197], v[112:115]
	v_mfma_f32_16x16x32_bf16 v[108:111], v[140:143], v[194:197], v[108:111]
	v_mfma_f32_16x16x32_bf16 v[136:139], v[104:107], v[152:155], v[136:139]
	v_mfma_f32_16x16x32_bf16 v[132:135], v[144:147], v[152:155], v[132:135]
	v_mfma_f32_16x16x32_bf16 v[128:131], v[104:107], v[182:185], v[128:131]
	v_mfma_f32_16x16x32_bf16 v[124:127], v[144:147], v[182:185], v[124:127]
	v_mfma_f32_16x16x32_bf16 v[120:123], v[104:107], v[190:193], v[120:123]
	v_mfma_f32_16x16x32_bf16 v[116:119], v[144:147], v[190:193], v[116:119]
	v_mfma_f32_16x16x32_bf16 v[112:115], v[104:107], v[198:201], v[112:115]
	v_mfma_f32_16x16x32_bf16 v[108:111], v[144:147], v[198:201], v[108:111]
	s_barrier
	s_setprio 0
	s_add_i32 s34, 0, 0x14000
	v_add_u32_e32 v166, s34, v222
	s_add_i32 s0, s0, s53
	ds_read_b128 v[202:205], v166
	ds_read_b128 v[206:209], v166 offset:1024
	ds_read_b128 v[210:213], v166 offset:2048
	ds_read_b128 v[214:217], v166 offset:3072
	v_lshl_add_u64 v[166:167], s[42:43], 0, v[26:27]
	s_mov_b32 m0, s0
	v_lshl_add_u64 v[168:169], s[42:43], 0, v[160:161]
	global_load_lds_dwordx4 v[166:167], off
	s_add_i32 m0, s0, 0x2000
	s_nop 0
	global_load_lds_dwordx4 v[168:169], off
	s_waitcnt vmcnt(10)
	s_setprio 1
	s_barrier
	s_waitcnt lgkmcnt(0)
	v_mfma_f32_16x16x32_bf16 v[64:67], v[202:205], v[148:151], v[64:67]
	v_mfma_f32_16x16x32_bf16 v[60:63], v[210:213], v[148:151], v[60:63]
	v_mfma_f32_16x16x32_bf16 v[56:59], v[202:205], v[178:181], v[56:59]
	v_mfma_f32_16x16x32_bf16 v[52:55], v[210:213], v[178:181], v[52:55]
	v_mfma_f32_16x16x32_bf16 v[48:51], v[202:205], v[186:189], v[48:51]
	v_mfma_f32_16x16x32_bf16 v[44:47], v[210:213], v[186:189], v[44:47]
	v_mfma_f32_16x16x32_bf16 v[40:43], v[202:205], v[194:197], v[40:43]
	v_mfma_f32_16x16x32_bf16 v[36:39], v[210:213], v[194:197], v[36:39]
	v_mfma_f32_16x16x32_bf16 v[64:67], v[206:209], v[152:155], v[64:67]
	v_mfma_f32_16x16x32_bf16 v[60:63], v[214:217], v[152:155], v[60:63]
	v_mfma_f32_16x16x32_bf16 v[56:59], v[206:209], v[182:185], v[56:59]
	v_mfma_f32_16x16x32_bf16 v[52:55], v[214:217], v[182:185], v[52:55]
	v_mfma_f32_16x16x32_bf16 v[48:51], v[206:209], v[190:193], v[48:51]
	v_mfma_f32_16x16x32_bf16 v[44:47], v[214:217], v[190:193], v[44:47]
	v_mfma_f32_16x16x32_bf16 v[40:43], v[206:209], v[198:201], v[40:43]
	v_mfma_f32_16x16x32_bf16 v[36:39], v[214:217], v[198:201], v[36:39]
	s_barrier
	s_setprio 0
	s_mov_b32 m0, s54
	v_lshl_add_u64 v[218:219], s[46:47], 0, v[156:157]
	ds_read_b128 v[148:151], v224 offset:16384
	ds_read_b128 v[152:155], v224 offset:17408
	ds_read_b128 v[178:181], v224 offset:18432
	ds_read_b128 v[182:185], v224 offset:19456
	ds_read_b128 v[186:189], v224 offset:20480
	ds_read_b128 v[190:193], v224 offset:21504
	ds_read_b128 v[194:197], v224 offset:22528
	ds_read_b128 v[198:201], v224 offset:23552
	global_load_lds_dwordx4 v[218:219], off
	v_lshl_add_u64 v[220:221], s[46:47], 0, v[158:159]
	s_mov_b32 m0, s55
	s_nop 0
	global_load_lds_dwordx4 v[220:221], off
	s_waitcnt vmcnt(10)
	s_setprio 1
	s_barrier
	s_waitcnt lgkmcnt(0)
	v_mfma_f32_16x16x32_bf16 v[96:99], v[100:103], v[148:151], v[96:99]
	v_mfma_f32_16x16x32_bf16 v[92:95], v[140:143], v[148:151], v[92:95]
	v_mfma_f32_16x16x32_bf16 v[88:91], v[100:103], v[178:181], v[88:91]
	v_mfma_f32_16x16x32_bf16 v[84:87], v[140:143], v[178:181], v[84:87]
	v_mfma_f32_16x16x32_bf16 v[80:83], v[100:103], v[186:189], v[80:83]
	v_mfma_f32_16x16x32_bf16 v[76:79], v[140:143], v[186:189], v[76:79]
	v_mfma_f32_16x16x32_bf16 v[72:75], v[100:103], v[194:197], v[72:75]
	v_mfma_f32_16x16x32_bf16 v[68:71], v[140:143], v[194:197], v[68:71]
	v_mfma_f32_16x16x32_bf16 v[96:99], v[104:107], v[152:155], v[96:99]
	v_mfma_f32_16x16x32_bf16 v[92:95], v[144:147], v[152:155], v[92:95]
	v_mfma_f32_16x16x32_bf16 v[88:91], v[104:107], v[182:185], v[88:91]
	v_mfma_f32_16x16x32_bf16 v[84:87], v[144:147], v[182:185], v[84:87]
	v_mfma_f32_16x16x32_bf16 v[80:83], v[104:107], v[190:193], v[80:83]
	v_mfma_f32_16x16x32_bf16 v[76:79], v[144:147], v[190:193], v[76:79]
	v_mfma_f32_16x16x32_bf16 v[72:75], v[104:107], v[198:201], v[72:75]
	v_mfma_f32_16x16x32_bf16 v[68:71], v[144:147], v[198:201], v[68:71]
	s_barrier
	s_setprio 0
	s_add_u32 s0, s42, 0x40000
	s_addc_u32 s1, s43, 0
	s_add_i32 s34, s34, s53
	v_lshl_add_u64 v[100:101], s[0:1], 0, v[26:27]
	s_mov_b32 m0, s34
	s_nop 0
	global_load_lds_dwordx4 v[100:101], off
	v_lshl_add_u64 v[100:101], s[0:1], 0, v[160:161]
	s_add_i32 m0, s34, 0x2000
	s_nop 0
	global_load_lds_dwordx4 v[100:101], off
	v_add_u32_e32 v144, 0x18000, v222
	ds_read_b128 v[100:103], v144
	ds_read_b128 v[104:107], v144 offset:1024
	ds_read_b128 v[140:143], v144 offset:2048
	ds_read_b128 v[144:147], v144 offset:3072
	s_waitcnt vmcnt(10)
	s_setprio 1
	s_barrier
	v_mfma_f32_16x16x32_bf16 v[32:35], v[202:205], v[148:151], v[32:35]
	v_mfma_f32_16x16x32_bf16 v[28:31], v[210:213], v[148:151], v[28:31]
	v_mfma_f32_16x16x32_bf16 v[22:25], v[202:205], v[178:181], v[22:25]
	v_mfma_f32_16x16x32_bf16 v[18:21], v[210:213], v[178:181], v[18:21]
	v_mfma_f32_16x16x32_bf16 v[14:17], v[202:205], v[186:189], v[14:17]
	v_mfma_f32_16x16x32_bf16 v[10:13], v[210:213], v[186:189], v[10:13]
	v_mfma_f32_16x16x32_bf16 v[6:9], v[202:205], v[194:197], v[6:9]
	v_mfma_f32_16x16x32_bf16 v[2:5], v[210:213], v[194:197], v[2:5]
	v_mfma_f32_16x16x32_bf16 v[32:35], v[206:209], v[152:155], v[32:35]
	v_mfma_f32_16x16x32_bf16 v[28:31], v[214:217], v[152:155], v[28:31]
	v_mfma_f32_16x16x32_bf16 v[22:25], v[206:209], v[182:185], v[22:25]
	v_mfma_f32_16x16x32_bf16 v[18:21], v[214:217], v[182:185], v[18:21]
	v_mfma_f32_16x16x32_bf16 v[14:17], v[206:209], v[190:193], v[14:17]
	v_mfma_f32_16x16x32_bf16 v[10:13], v[214:217], v[190:193], v[10:13]
	v_mfma_f32_16x16x32_bf16 v[6:9], v[206:209], v[198:201], v[6:9]
	v_mfma_f32_16x16x32_bf16 v[2:5], v[214:217], v[198:201], v[2:5]
	s_barrier
	s_setprio 0
	s_add_i32 s34, 0, 0x18000
	s_add_u32 s0, s46, 0x140000
	s_addc_u32 s1, s47, 0
	s_mov_b32 m0, s56
	v_lshl_add_u64 v[202:203], s[0:1], 0, v[156:157]
	ds_read_b128 v[148:151], v224 offset:32768
	ds_read_b128 v[152:155], v224 offset:33792
	ds_read_b128 v[178:181], v224 offset:34816
	ds_read_b128 v[182:185], v224 offset:35840
	ds_read_b128 v[186:189], v224 offset:36864
	ds_read_b128 v[190:193], v224 offset:37888
	ds_read_b128 v[194:197], v224 offset:38912
	ds_read_b128 v[198:201], v224 offset:39936
	global_load_lds_dwordx4 v[202:203], off
	v_lshl_add_u64 v[202:203], s[0:1], 0, v[158:159]
	s_mov_b32 m0, s57
	s_nop 0
	global_load_lds_dwordx4 v[202:203], off
	s_waitcnt vmcnt(10) lgkmcnt(8)
	s_setprio 1
	s_barrier
	s_waitcnt lgkmcnt(0)
	v_mfma_f32_16x16x32_bf16 v[136:139], v[100:103], v[148:151], v[136:139]
	v_mfma_f32_16x16x32_bf16 v[132:135], v[140:143], v[148:151], v[132:135]
	v_mfma_f32_16x16x32_bf16 v[128:131], v[100:103], v[178:181], v[128:131]
	v_mfma_f32_16x16x32_bf16 v[124:127], v[140:143], v[178:181], v[124:127]
	v_mfma_f32_16x16x32_bf16 v[120:123], v[100:103], v[186:189], v[120:123]
	v_mfma_f32_16x16x32_bf16 v[116:119], v[140:143], v[186:189], v[116:119]
	v_mfma_f32_16x16x32_bf16 v[112:115], v[100:103], v[194:197], v[112:115]
	v_mfma_f32_16x16x32_bf16 v[108:111], v[140:143], v[194:197], v[108:111]
	v_mfma_f32_16x16x32_bf16 v[136:139], v[104:107], v[152:155], v[136:139]
	v_mfma_f32_16x16x32_bf16 v[132:135], v[144:147], v[152:155], v[132:135]
	v_mfma_f32_16x16x32_bf16 v[128:131], v[104:107], v[182:185], v[128:131]
	v_mfma_f32_16x16x32_bf16 v[124:127], v[144:147], v[182:185], v[124:127]
	v_mfma_f32_16x16x32_bf16 v[120:123], v[104:107], v[190:193], v[120:123]
	v_mfma_f32_16x16x32_bf16 v[116:119], v[144:147], v[190:193], v[116:119]
	v_mfma_f32_16x16x32_bf16 v[112:115], v[104:107], v[198:201], v[112:115]
	v_mfma_f32_16x16x32_bf16 v[108:111], v[144:147], v[198:201], v[108:111]
	s_barrier
	s_setprio 0
	s_add_i32 s35, 0, 0x1c000
	s_add_i32 s0, s34, s53
	v_add_u32_e32 v214, s35, v222
	v_lshl_add_u64 v[166:167], v[166:167], 0, s[12:13]
	s_mov_b32 m0, s0
	ds_read_b128 v[202:205], v214
	ds_read_b128 v[206:209], v214 offset:1024
	ds_read_b128 v[210:213], v214 offset:2048
	ds_read_b128 v[214:217], v214 offset:3072
	global_load_lds_dwordx4 v[166:167], off
	v_lshl_add_u64 v[166:167], v[168:169], 0, s[12:13]
	s_add_i32 m0, s0, 0x2000
	s_nop 0
	global_load_lds_dwordx4 v[166:167], off
	s_waitcnt vmcnt(10)
	s_setprio 1
	s_barrier
	s_waitcnt lgkmcnt(0)
	v_mfma_f32_16x16x32_bf16 v[64:67], v[202:205], v[148:151], v[64:67]
	v_mfma_f32_16x16x32_bf16 v[60:63], v[210:213], v[148:151], v[60:63]
	v_mfma_f32_16x16x32_bf16 v[56:59], v[202:205], v[178:181], v[56:59]
	v_mfma_f32_16x16x32_bf16 v[52:55], v[210:213], v[178:181], v[52:55]
	v_mfma_f32_16x16x32_bf16 v[48:51], v[202:205], v[186:189], v[48:51]
	v_mfma_f32_16x16x32_bf16 v[44:47], v[210:213], v[186:189], v[44:47]
	v_mfma_f32_16x16x32_bf16 v[40:43], v[202:205], v[194:197], v[40:43]
	v_mfma_f32_16x16x32_bf16 v[36:39], v[210:213], v[194:197], v[36:39]
	v_mfma_f32_16x16x32_bf16 v[64:67], v[206:209], v[152:155], v[64:67]
	v_mfma_f32_16x16x32_bf16 v[60:63], v[214:217], v[152:155], v[60:63]
	v_mfma_f32_16x16x32_bf16 v[56:59], v[206:209], v[182:185], v[56:59]
	v_mfma_f32_16x16x32_bf16 v[52:55], v[214:217], v[182:185], v[52:55]
	v_mfma_f32_16x16x32_bf16 v[48:51], v[206:209], v[190:193], v[48:51]
	v_mfma_f32_16x16x32_bf16 v[44:47], v[214:217], v[190:193], v[44:47]
	v_mfma_f32_16x16x32_bf16 v[40:43], v[206:209], v[198:201], v[40:43]
	v_mfma_f32_16x16x32_bf16 v[36:39], v[214:217], v[198:201], v[36:39]
	s_barrier
	s_setprio 0
	s_mov_b32 m0, s81
	v_lshl_add_u64 v[166:167], v[218:219], 0, s[12:13]
	ds_read_b128 v[148:151], v224 offset:49152
	ds_read_b128 v[152:155], v224 offset:50176
	ds_read_b128 v[178:181], v224 offset:51200
	ds_read_b128 v[182:185], v224 offset:52224
	ds_read_b128 v[186:189], v224 offset:53248
	ds_read_b128 v[190:193], v224 offset:54272
	ds_read_b128 v[194:197], v224 offset:55296
	ds_read_b128 v[198:201], v224 offset:56320
	global_load_lds_dwordx4 v[166:167], off
	v_lshl_add_u64 v[166:167], v[220:221], 0, s[12:13]
	s_mov_b32 m0, s17
	s_nop 0
	global_load_lds_dwordx4 v[166:167], off
	s_waitcnt vmcnt(10)
	s_setprio 1
	s_barrier
	s_waitcnt lgkmcnt(0)
	v_mfma_f32_16x16x32_bf16 v[96:99], v[100:103], v[148:151], v[96:99]
	v_mfma_f32_16x16x32_bf16 v[92:95], v[140:143], v[148:151], v[92:95]
	v_mfma_f32_16x16x32_bf16 v[88:91], v[100:103], v[178:181], v[88:91]
	v_mfma_f32_16x16x32_bf16 v[84:87], v[140:143], v[178:181], v[84:87]
	v_mfma_f32_16x16x32_bf16 v[80:83], v[100:103], v[186:189], v[80:83]
	v_mfma_f32_16x16x32_bf16 v[76:79], v[140:143], v[186:189], v[76:79]
	v_mfma_f32_16x16x32_bf16 v[72:75], v[100:103], v[194:197], v[72:75]
	v_mfma_f32_16x16x32_bf16 v[68:71], v[140:143], v[194:197], v[68:71]
	v_mfma_f32_16x16x32_bf16 v[96:99], v[104:107], v[152:155], v[96:99]
	v_mfma_f32_16x16x32_bf16 v[92:95], v[144:147], v[152:155], v[92:95]
	v_mfma_f32_16x16x32_bf16 v[88:91], v[104:107], v[182:185], v[88:91]
	v_mfma_f32_16x16x32_bf16 v[84:87], v[144:147], v[182:185], v[84:87]
	v_mfma_f32_16x16x32_bf16 v[80:83], v[104:107], v[190:193], v[80:83]
	v_mfma_f32_16x16x32_bf16 v[76:79], v[144:147], v[190:193], v[76:79]
	v_mfma_f32_16x16x32_bf16 v[72:75], v[104:107], v[198:201], v[72:75]
	v_mfma_f32_16x16x32_bf16 v[68:71], v[144:147], v[198:201], v[68:71]
	s_barrier
	s_setprio 0
	s_add_u32 s0, s42, 0x40080
	s_addc_u32 s1, s43, 0
	s_add_i32 s34, s35, s53
	v_lshl_add_u64 v[100:101], s[0:1], 0, v[26:27]
	s_mov_b32 m0, s34
	s_nop 0
	global_load_lds_dwordx4 v[100:101], off
	v_lshl_add_u64 v[100:101], s[0:1], 0, v[160:161]
	s_add_i32 m0, s34, 0x2000
	s_nop 0
	global_load_lds_dwordx4 v[100:101], off
	v_add_u32_e32 v144, 0x10000, v222
	ds_read_b128 v[100:103], v144
	ds_read_b128 v[104:107], v144 offset:1024
	ds_read_b128 v[140:143], v144 offset:2048
	ds_read_b128 v[144:147], v144 offset:3072
	s_waitcnt vmcnt(10)
	s_setprio 1
	s_barrier
	v_mfma_f32_16x16x32_bf16 v[32:35], v[202:205], v[148:151], v[32:35]
	v_mfma_f32_16x16x32_bf16 v[28:31], v[210:213], v[148:151], v[28:31]
	v_mfma_f32_16x16x32_bf16 v[22:25], v[202:205], v[178:181], v[22:25]
	v_mfma_f32_16x16x32_bf16 v[18:21], v[210:213], v[178:181], v[18:21]
	v_mfma_f32_16x16x32_bf16 v[14:17], v[202:205], v[186:189], v[14:17]
	v_mfma_f32_16x16x32_bf16 v[10:13], v[210:213], v[186:189], v[10:13]
	v_mfma_f32_16x16x32_bf16 v[6:9], v[202:205], v[194:197], v[6:9]
	v_mfma_f32_16x16x32_bf16 v[2:5], v[210:213], v[194:197], v[2:5]
	v_mfma_f32_16x16x32_bf16 v[32:35], v[206:209], v[152:155], v[32:35]
	v_mfma_f32_16x16x32_bf16 v[28:31], v[214:217], v[152:155], v[28:31]
	v_mfma_f32_16x16x32_bf16 v[22:25], v[206:209], v[182:185], v[22:25]
	v_mfma_f32_16x16x32_bf16 v[18:21], v[214:217], v[182:185], v[18:21]
	v_mfma_f32_16x16x32_bf16 v[14:17], v[206:209], v[190:193], v[14:17]
	v_mfma_f32_16x16x32_bf16 v[10:13], v[214:217], v[190:193], v[10:13]
	v_mfma_f32_16x16x32_bf16 v[6:9], v[206:209], v[198:201], v[6:9]
	v_mfma_f32_16x16x32_bf16 v[2:5], v[214:217], v[198:201], v[2:5]
	s_barrier
	s_setprio 0
	s_add_i32 s31, s31, 2
	s_add_u32 s23, s23, 0x100
	s_addc_u32 s29, s29, 0
	s_cmp_gt_u32 s31, 13
	s_mov_b64 s[34:35], s[36:37]
	s_cbranch_scc0 .LBB0_965
	s_waitcnt lgkmcnt(0)
	s_min_i32 s0, s28, 0x100
	s_ashr_i32 s0, s0, 5
	s_ashr_i32 s1, s0, 31
	s_add_i32 s18, s28, 0xffffff00
	s_cmpk_lt_i32 s28, 0x100
	s_cselect_b32 s18, s28, s18
	s_cselect_b32 s23, 0, s59
	s_cselect_b32 s29, 0, s58
	s_ashr_i32 s19, s18, 31
	s_lshl_b64 s[18:19], s[18:19], 19
	v_lshl_or_b32 v148, s30, 8, v223
	s_add_u32 s30, s44, s29
	s_addc_u32 s31, s45, s23
	s_ashr_i32 s29, s28, 31
	v_lshl_add_u64 v[100:101], s[18:19], 0, v[162:163]
	s_lshl_b64 s[18:19], s[28:29], 19
	v_lshl_add_u64 v[152:153], v[164:165], 0, s[18:19]
	s_lshl_b64 s[28:29], s[28:29], 10
	s_mul_i32 s18, s0, 0x9000
	s_mul_hi_i32 s19, s0, 0x9000
	s_add_u32 s18, s68, s18
	s_addc_u32 s19, s69, s19
	s_lshl_b64 s[0:1], s[0:1], 12
	v_ashrrev_i32_e32 v149, 31, v148
	s_add_u32 s0, s72, s0
	v_lshlrev_b64 v[154:155], 2, v[148:149]
	s_addc_u32 s1, s73, s1
	v_lshl_add_u64 v[150:151], v[100:101], 0, v[148:149]
	v_lshl_add_u64 v[104:105], s[18:19], 0, v[154:155]
	v_lshlrev_b64 v[168:169], 1, v[148:149]
	v_lshl_add_u64 v[180:181], s[0:1], 0, v[154:155]
	v_lshl_add_u64 v[166:167], v[100:101], 1, s[30:31]
	global_load_dwordx4 v[140:143], v[104:105], off offset:16
	global_load_dwordx4 v[144:147], v[104:105], off
	global_load_dwordx4 v[100:103], v[104:105], off offset:528
	s_nop 0
	global_load_dwordx4 v[104:107], v[104:105], off offset:512
	v_lshl_add_u64 v[196:197], v[150:151], 1, s[30:31]
	v_lshl_add_u64 v[178:179], v[152:153], 0, v[168:169]
	global_load_dwordx4 v[148:151], v[180:181], off offset:16
	global_load_dwordx4 v[152:155], v[180:181], off
	global_load_dwordx4 v[190:193], v[196:197], off offset:2048
	v_add_co_u32_e32 v210, vcc, s65, v196
	s_mov_b32 s1, 0x20000
	s_nop 0
	v_addc_co_u32_e32 v211, vcc, 0, v197, vcc
	global_load_dwordx4 v[198:201], v[210:211], off offset:2048
	v_add_co_u32_e32 v184, vcc, s1, v196
	s_mov_b32 s18, 0x30000
	s_nop 0
	v_addc_co_u32_e32 v185, vcc, 0, v197, vcc
	global_load_dwordx4 v[202:205], v[184:185], off offset:2048
	v_add_co_u32_e32 v188, vcc, s18, v196
	v_lshl_add_u64 v[182:183], v[166:167], 0, v[168:169]
	s_nop 0
	v_addc_co_u32_e32 v189, vcc, 0, v197, vcc
	global_load_dwordx4 v[206:209], v[188:189], off offset:2048
	s_mov_b32 s0, 0x8000
	s_mov_b32 s19, 0x80000
	s_mov_b32 s23, 0x90000
	s_waitcnt vmcnt(0)
	v_lshlrev_b32_e32 v166, 16, v190
	v_and_b32_e32 v167, 0xffff0000, v190
	v_lshlrev_b32_e32 v168, 16, v191
	v_and_b32_e32 v169, 0xffff0000, v191
	v_lshlrev_b32_e32 v186, 16, v192
	v_and_b32_e32 v187, 0xffff0000, v192
	v_lshlrev_b32_e32 v190, 16, v193
	v_and_b32_e32 v191, 0xffff0000, v193
	v_pk_fma_f32 v[138:139], v[138:139], v[146:147], v[168:169]
	v_pk_fma_f32 v[136:137], v[136:137], v[144:145], v[166:167]
	v_pk_fma_f32 v[134:135], v[134:135], v[142:143], v[190:191]
	v_pk_fma_f32 v[132:133], v[132:133], v[140:141], v[186:187]
	v_cvt_pk_bf16_f32 v190, v136, v137
	v_cvt_pk_bf16_f32 v191, v138, v139
	v_cvt_pk_bf16_f32 v192, v132, v133
	v_cvt_pk_bf16_f32 v193, v134, v135
	v_lshlrev_b32_e32 v138, 16, v190
	v_and_b32_e32 v139, 0xffff0000, v190
	v_lshlrev_b32_e32 v136, 16, v191
	v_and_b32_e32 v137, 0xffff0000, v191
	v_lshlrev_b32_e32 v134, 16, v192
	v_and_b32_e32 v135, 0xffff0000, v192
	v_lshlrev_b32_e32 v132, 16, v193
	v_and_b32_e32 v133, 0xffff0000, v193
	v_lshlrev_b32_e32 v212, 16, v200
	v_and_b32_e32 v213, 0xffff0000, v200
	v_lshlrev_b32_e32 v200, 16, v201
	v_and_b32_e32 v201, 0xffff0000, v201
	global_store_dwordx4 v[182:183], v[190:193], off offset:2048
	v_pk_mul_f32 v[166:167], v[154:155], v[136:137]
	v_pk_mul_f32 v[168:169], v[152:153], v[138:139]
	v_pk_mul_f32 v[186:187], v[150:151], v[132:133]
	v_pk_mul_f32 v[192:193], v[148:149], v[134:135]
	v_lshlrev_b32_e32 v194, 16, v198
	v_and_b32_e32 v195, 0xffff0000, v198
	v_lshlrev_b32_e32 v198, 16, v199
	v_and_b32_e32 v199, 0xffff0000, v199
	v_cvt_pk_bf16_f32 v190, v168, v169
	v_cvt_pk_bf16_f32 v191, v166, v167
	v_cvt_pk_bf16_f32 v192, v192, v193
	v_cvt_pk_bf16_f32 v193, v186, v187
	v_pk_fma_f32 v[126:127], v[126:127], v[142:143], v[200:201]
	v_pk_fma_f32 v[124:125], v[124:125], v[140:141], v[212:213]
	global_store_dwordx4 v[178:179], v[190:193], off
	v_pk_fma_f32 v[130:131], v[130:131], v[146:147], v[198:199]
	v_pk_fma_f32 v[128:129], v[128:129], v[144:145], v[194:195]
	v_cvt_pk_bf16_f32 v192, v124, v125
	v_cvt_pk_bf16_f32 v193, v126, v127
	v_add_co_u32_e32 v186, vcc, s65, v182
	v_cvt_pk_bf16_f32 v190, v128, v129
	v_cvt_pk_bf16_f32 v191, v130, v131
	v_addc_co_u32_e32 v187, vcc, 0, v183, vcc
	v_lshlrev_b32_e32 v126, 16, v192
	v_and_b32_e32 v127, 0xffff0000, v192
	v_lshlrev_b32_e32 v124, 16, v193
	v_and_b32_e32 v125, 0xffff0000, v193
	global_store_dwordx4 v[186:187], v[190:193], off offset:2048
	v_lshlrev_b32_e32 v130, 16, v190
	v_and_b32_e32 v131, 0xffff0000, v190
	v_lshlrev_b32_e32 v128, 16, v191
	v_and_b32_e32 v129, 0xffff0000, v191
	v_pk_mul_f32 v[190:191], v[150:151], v[124:125]
	v_pk_mul_f32 v[194:195], v[148:149], v[126:127]
	v_pk_mul_f32 v[166:167], v[154:155], v[128:129]
	v_pk_mul_f32 v[168:169], v[152:153], v[130:131]
	v_cvt_pk_bf16_f32 v194, v194, v195
	v_cvt_pk_bf16_f32 v195, v190, v191
	v_add_co_u32_e32 v190, vcc, s0, v178
	v_cvt_pk_bf16_f32 v192, v168, v169
	v_cvt_pk_bf16_f32 v193, v166, v167
	v_addc_co_u32_e32 v191, vcc, 0, v179, vcc
	global_store_dwordx4 v[190:191], v[192:195], off
	v_lshlrev_b32_e32 v198, 16, v204
	v_and_b32_e32 v199, 0xffff0000, v204
	v_add_co_u32_e32 v192, vcc, s19, v196
	v_lshlrev_b32_e32 v200, 16, v205
	s_nop 0
	v_addc_co_u32_e32 v193, vcc, 0, v197, vcc
	v_add_co_u32_e32 v194, vcc, s23, v196
	v_and_b32_e32 v201, 0xffff0000, v205
	global_load_dwordx4 v[212:215], v[192:193], off offset:2048
	v_addc_co_u32_e32 v195, vcc, 0, v197, vcc
	v_lshlrev_b32_e32 v166, 16, v202
	v_and_b32_e32 v167, 0xffff0000, v202
	v_lshlrev_b32_e32 v168, 16, v203
	v_and_b32_e32 v169, 0xffff0000, v203
	v_pk_fma_f32 v[118:119], v[118:119], v[142:143], v[200:201]
	v_pk_fma_f32 v[116:117], v[116:117], v[140:141], v[198:199]
	v_pk_fma_f32 v[122:123], v[122:123], v[146:147], v[168:169]
	v_pk_fma_f32 v[120:121], v[120:121], v[144:145], v[166:167]
	v_cvt_pk_bf16_f32 v202, v116, v117
	v_cvt_pk_bf16_f32 v203, v118, v119
	v_add_co_u32_e32 v198, vcc, s1, v182
	global_load_dwordx4 v[216:219], v[194:195], off offset:2048
	v_cvt_pk_bf16_f32 v200, v120, v121
	v_cvt_pk_bf16_f32 v201, v122, v123
	v_addc_co_u32_e32 v199, vcc, 0, v183, vcc
	v_lshlrev_b32_e32 v118, 16, v202
	v_and_b32_e32 v119, 0xffff0000, v202
	v_lshlrev_b32_e32 v116, 16, v203
	v_and_b32_e32 v117, 0xffff0000, v203
	global_store_dwordx4 v[198:199], v[200:203], off offset:2048
	v_lshlrev_b32_e32 v122, 16, v200
	v_and_b32_e32 v123, 0xffff0000, v200
	v_lshlrev_b32_e32 v120, 16, v201
	v_and_b32_e32 v121, 0xffff0000, v201
	v_pk_mul_f32 v[200:201], v[150:151], v[116:117]
	v_pk_mul_f32 v[204:205], v[148:149], v[118:119]
	v_lshlrev_b32_e32 v234, 16, v208
	v_and_b32_e32 v235, 0xffff0000, v208
	v_lshlrev_b32_e32 v208, 16, v209
	v_and_b32_e32 v209, 0xffff0000, v209
	v_pk_mul_f32 v[166:167], v[154:155], v[120:121]
	v_pk_mul_f32 v[168:169], v[152:153], v[122:123]
	v_cvt_pk_bf16_f32 v204, v204, v205
	v_cvt_pk_bf16_f32 v205, v200, v201
	v_add_co_u32_e32 v200, vcc, s65, v178
	v_lshlrev_b32_e32 v220, 16, v206
	v_and_b32_e32 v221, 0xffff0000, v206
	v_lshlrev_b32_e32 v206, 16, v207
	v_and_b32_e32 v207, 0xffff0000, v207
	v_cvt_pk_bf16_f32 v202, v168, v169
	v_cvt_pk_bf16_f32 v203, v166, v167
	v_addc_co_u32_e32 v201, vcc, 0, v179, vcc
	v_pk_fma_f32 v[110:111], v[110:111], v[142:143], v[208:209]
	v_pk_fma_f32 v[108:109], v[108:109], v[140:141], v[234:235]
	global_store_dwordx4 v[200:201], v[202:205], off
	v_pk_fma_f32 v[114:115], v[114:115], v[146:147], v[206:207]
	v_pk_fma_f32 v[112:113], v[112:113], v[144:145], v[220:221]
	v_cvt_pk_bf16_f32 v206, v108, v109
	v_cvt_pk_bf16_f32 v207, v110, v111
	v_add_co_u32_e32 v202, vcc, s18, v182
	v_cvt_pk_bf16_f32 v204, v112, v113
	v_cvt_pk_bf16_f32 v205, v114, v115
	v_addc_co_u32_e32 v203, vcc, 0, v183, vcc
	v_lshlrev_b32_e32 v110, 16, v206
	v_and_b32_e32 v111, 0xffff0000, v206
	v_lshlrev_b32_e32 v108, 16, v207
	v_and_b32_e32 v109, 0xffff0000, v207
	global_store_dwordx4 v[202:203], v[204:207], off offset:2048
	v_lshlrev_b32_e32 v114, 16, v204
	v_and_b32_e32 v115, 0xffff0000, v204
	v_lshlrev_b32_e32 v112, 16, v205
	v_and_b32_e32 v113, 0xffff0000, v205
	v_pk_mul_f32 v[204:205], v[150:151], v[108:109]
	v_pk_mul_f32 v[208:209], v[148:149], v[110:111]
	s_mov_b32 s0, 0x18000
	v_pk_mul_f32 v[166:167], v[154:155], v[112:113]
	v_pk_mul_f32 v[168:169], v[152:153], v[114:115]
	v_cvt_pk_bf16_f32 v208, v208, v209
	v_cvt_pk_bf16_f32 v209, v204, v205
	v_add_co_u32_e32 v204, vcc, s0, v178
	v_cvt_pk_bf16_f32 v206, v168, v169
	v_cvt_pk_bf16_f32 v207, v166, v167
	v_addc_co_u32_e32 v205, vcc, 0, v179, vcc
	global_store_dwordx4 v[204:205], v[206:209], off
	s_mov_b32 s0, 0xb0000
	s_waitcnt vmcnt(0)
	v_lshlrev_b32_e32 v166, 16, v212
	v_add_co_u32_e32 v206, vcc, s76, v196
	v_and_b32_e32 v167, 0xffff0000, v212
	s_nop 0
	v_addc_co_u32_e32 v207, vcc, 0, v197, vcc
	global_load_dwordx4 v[238:241], v[206:207], off offset:2048
	v_add_co_u32_e32 v208, vcc, s0, v196
	v_lshlrev_b32_e32 v168, 16, v213
	s_nop 0
	v_addc_co_u32_e32 v209, vcc, 0, v197, vcc
	global_load_dwordx4 v[242:245], v[208:209], off offset:2048
	v_and_b32_e32 v169, 0xffff0000, v213
	v_lshlrev_b32_e32 v212, 16, v214
	v_and_b32_e32 v213, 0xffff0000, v214
	v_lshlrev_b32_e32 v214, 16, v215
	v_and_b32_e32 v215, 0xffff0000, v215
	v_pk_fma_f32 v[94:95], v[94:95], v[142:143], v[214:215]
	v_pk_fma_f32 v[92:93], v[92:93], v[140:141], v[212:213]
	v_lshlrev_b32_e32 v220, 16, v216
	v_and_b32_e32 v221, 0xffff0000, v216
	v_lshlrev_b32_e32 v234, 16, v217
	v_and_b32_e32 v235, 0xffff0000, v217
	v_pk_fma_f32 v[98:99], v[98:99], v[146:147], v[168:169]
	v_pk_fma_f32 v[96:97], v[96:97], v[144:145], v[166:167]
	v_cvt_pk_bf16_f32 v216, v92, v93
	v_cvt_pk_bf16_f32 v217, v94, v95
	v_add_co_u32_e32 v212, vcc, s19, v182
	v_cvt_pk_bf16_f32 v214, v96, v97
	v_cvt_pk_bf16_f32 v215, v98, v99
	v_addc_co_u32_e32 v213, vcc, 0, v183, vcc
	v_lshlrev_b32_e32 v94, 16, v216
	v_and_b32_e32 v95, 0xffff0000, v216
	v_lshlrev_b32_e32 v92, 16, v217
	v_and_b32_e32 v93, 0xffff0000, v217
	v_lshlrev_b32_e32 v246, 16, v218
	v_and_b32_e32 v247, 0xffff0000, v218
	v_lshlrev_b32_e32 v248, 16, v219
	v_and_b32_e32 v249, 0xffff0000, v219
	global_store_dwordx4 v[212:213], v[214:217], off offset:2048
	v_lshlrev_b32_e32 v98, 16, v214
	v_and_b32_e32 v99, 0xffff0000, v214
	v_lshlrev_b32_e32 v96, 16, v215
	v_and_b32_e32 v97, 0xffff0000, v215
	v_pk_mul_f32 v[214:215], v[150:151], v[92:93]
	v_pk_mul_f32 v[218:219], v[148:149], v[94:95]
	s_mov_b32 s1, 0x40000
	v_pk_mul_f32 v[166:167], v[154:155], v[96:97]
	v_pk_mul_f32 v[168:169], v[152:153], v[98:99]
	v_cvt_pk_bf16_f32 v218, v218, v219
	v_cvt_pk_bf16_f32 v219, v214, v215
	v_add_co_u32_e32 v214, vcc, s1, v178
	v_cvt_pk_bf16_f32 v216, v168, v169
	v_cvt_pk_bf16_f32 v217, v166, v167
	v_addc_co_u32_e32 v215, vcc, 0, v179, vcc
	v_pk_fma_f32 v[86:87], v[86:87], v[142:143], v[248:249]
	global_store_dwordx4 v[214:215], v[216:219], off
	v_pk_fma_f32 v[90:91], v[90:91], v[146:147], v[234:235]
	v_pk_fma_f32 v[88:89], v[88:89], v[144:145], v[220:221]
	v_pk_fma_f32 v[84:85], v[84:85], v[140:141], v[246:247]
	v_cvt_pk_bf16_f32 v221, v86, v87
	v_add_co_u32_e32 v216, vcc, s23, v182
	v_cvt_pk_bf16_f32 v218, v88, v89
	v_cvt_pk_bf16_f32 v219, v90, v91
	v_cvt_pk_bf16_f32 v220, v84, v85
	v_addc_co_u32_e32 v217, vcc, 0, v183, vcc
	v_lshlrev_b32_e32 v84, 16, v221
	v_and_b32_e32 v85, 0xffff0000, v221
	global_store_dwordx4 v[216:217], v[218:221], off offset:2048
	v_lshlrev_b32_e32 v90, 16, v218
	v_and_b32_e32 v91, 0xffff0000, v218
	v_lshlrev_b32_e32 v88, 16, v219
	v_and_b32_e32 v89, 0xffff0000, v219
	v_lshlrev_b32_e32 v86, 16, v220
	v_and_b32_e32 v87, 0xffff0000, v220
	v_pk_mul_f32 v[218:219], v[150:151], v[84:85]
	s_mov_b32 s1, 0x48000
	v_pk_mul_f32 v[166:167], v[154:155], v[88:89]
	v_pk_mul_f32 v[168:169], v[152:153], v[90:91]
	v_pk_mul_f32 v[220:221], v[148:149], v[86:87]
	v_cvt_pk_bf16_f32 v249, v218, v219
	v_add_co_u32_e32 v218, vcc, s1, v178
	v_cvt_pk_bf16_f32 v246, v168, v169
	v_cvt_pk_bf16_f32 v247, v166, v167
	v_cvt_pk_bf16_f32 v248, v220, v221
	v_addc_co_u32_e32 v219, vcc, 0, v179, vcc
	global_store_dwordx4 v[218:219], v[246:249], off
	global_load_dwordx4 v[246:249], v[196:197], off offset:2304
	s_nop 0
	global_load_dwordx4 v[250:253], v[210:211], off offset:2304
	s_waitcnt vmcnt(0)
	v_lshlrev_b32_e32 v196, 16, v240
	v_and_b32_e32 v197, 0xffff0000, v240
	v_lshlrev_b32_e32 v210, 16, v241
	v_and_b32_e32 v211, 0xffff0000, v241
	v_lshlrev_b32_e32 v166, 16, v238
	v_and_b32_e32 v167, 0xffff0000, v238
	v_lshlrev_b32_e32 v168, 16, v239
	v_and_b32_e32 v169, 0xffff0000, v239
	v_pk_fma_f32 v[78:79], v[78:79], v[142:143], v[210:211]
	v_pk_fma_f32 v[76:77], v[76:77], v[140:141], v[196:197]
	v_pk_fma_f32 v[82:83], v[82:83], v[146:147], v[168:169]
	v_pk_fma_f32 v[80:81], v[80:81], v[144:145], v[166:167]
	v_cvt_pk_bf16_f32 v240, v76, v77
	v_cvt_pk_bf16_f32 v241, v78, v79
	v_add_co_u32_e32 v196, vcc, s76, v182
	v_cvt_pk_bf16_f32 v238, v80, v81
	v_cvt_pk_bf16_f32 v239, v82, v83
	v_addc_co_u32_e32 v197, vcc, 0, v183, vcc
	v_lshlrev_b32_e32 v78, 16, v240
	v_and_b32_e32 v79, 0xffff0000, v240
	v_lshlrev_b32_e32 v76, 16, v241
	v_and_b32_e32 v77, 0xffff0000, v241
	global_store_dwordx4 v[196:197], v[238:241], off offset:2048
	v_pk_mul_f32 v[210:211], v[150:151], v[76:77]
	v_lshlrev_b32_e32 v220, 16, v242
	v_pk_mul_f32 v[240:241], v[148:149], v[78:79]
	v_and_b32_e32 v221, 0xffff0000, v242
	v_lshlrev_b32_e32 v234, 16, v243
	v_and_b32_e32 v235, 0xffff0000, v243
	v_lshlrev_b32_e32 v242, 16, v244
	v_and_b32_e32 v243, 0xffff0000, v244
	v_lshlrev_b32_e32 v244, 16, v245
	v_and_b32_e32 v245, 0xffff0000, v245
	v_cvt_pk_bf16_f32 v240, v240, v241
	v_cvt_pk_bf16_f32 v241, v210, v211
	v_add_co_u32_e32 v210, vcc, s77, v178
	v_lshlrev_b32_e32 v82, 16, v238
	v_and_b32_e32 v83, 0xffff0000, v238
	v_lshlrev_b32_e32 v80, 16, v239
	v_and_b32_e32 v81, 0xffff0000, v239
	v_addc_co_u32_e32 v211, vcc, 0, v179, vcc
	v_pk_fma_f32 v[74:75], v[74:75], v[146:147], v[234:235]
	v_pk_fma_f32 v[72:73], v[72:73], v[144:145], v[220:221]
	v_pk_fma_f32 v[142:143], v[70:71], v[142:143], v[244:245]
	v_pk_fma_f32 v[70:71], v[68:69], v[140:141], v[242:243]
	v_pk_mul_f32 v[166:167], v[154:155], v[80:81]
	v_pk_mul_f32 v[168:169], v[152:153], v[82:83]
	v_cvt_pk_bf16_f32 v68, v72, v73
	v_cvt_pk_bf16_f32 v69, v74, v75
	v_cvt_pk_bf16_f32 v70, v70, v71
	v_cvt_pk_bf16_f32 v71, v142, v143
	v_add_co_u32_e32 v220, vcc, s0, v182
	v_cvt_pk_bf16_f32 v238, v168, v169
	v_cvt_pk_bf16_f32 v239, v166, v167
	v_addc_co_u32_e32 v221, vcc, 0, v183, vcc
	v_lshlrev_b32_e32 v146, 16, v68
	v_and_b32_e32 v147, 0xffff0000, v68
	v_lshlrev_b32_e32 v144, 16, v69
	v_and_b32_e32 v145, 0xffff0000, v69
	v_lshlrev_b32_e32 v142, 16, v70
	v_and_b32_e32 v143, 0xffff0000, v70
	v_lshlrev_b32_e32 v140, 16, v71
	v_and_b32_e32 v141, 0xffff0000, v71
	s_mov_b32 s0, 0x58000
	global_store_dwordx4 v[210:211], v[238:241], off
	global_store_dwordx4 v[220:221], v[68:71], off offset:2048
	v_pk_mul_f32 v[72:73], v[150:151], v[140:141]
	v_pk_mul_f32 v[74:75], v[148:149], v[142:143]
	v_pk_mul_f32 v[70:71], v[154:155], v[144:145]
	v_pk_mul_f32 v[68:69], v[152:153], v[146:147]
	v_add_co_u32_e32 v148, vcc, s0, v178
	v_cvt_pk_bf16_f32 v68, v68, v69
	v_cvt_pk_bf16_f32 v69, v70, v71
	v_cvt_pk_bf16_f32 v70, v74, v75
	v_cvt_pk_bf16_f32 v71, v72, v73
	v_addc_co_u32_e32 v149, vcc, 0, v179, vcc
	global_store_dwordx4 v[148:149], v[68:71], off
	global_load_dwordx4 v[150:153], v[184:185], off offset:2304
	global_load_dwordx4 v[238:241], v[188:189], off offset:2304
	s_nop 0
	global_load_dwordx4 v[68:71], v[180:181], off offset:528
	global_load_dwordx4 v[72:75], v[180:181], off offset:512
	v_lshlrev_b32_e32 v154, 16, v246
	v_and_b32_e32 v155, 0xffff0000, v246
	v_lshlrev_b32_e32 v166, 16, v247
	v_and_b32_e32 v167, 0xffff0000, v247
	v_lshlrev_b32_e32 v168, 16, v248
	v_and_b32_e32 v169, 0xffff0000, v248
	v_lshlrev_b32_e32 v180, 16, v249
	v_and_b32_e32 v181, 0xffff0000, v249
	v_pk_fma_f32 v[66:67], v[66:67], v[106:107], v[166:167]
	v_pk_fma_f32 v[64:65], v[64:65], v[104:105], v[154:155]
	v_pk_fma_f32 v[62:63], v[62:63], v[102:103], v[180:181]
	v_pk_fma_f32 v[60:61], v[60:61], v[100:101], v[168:169]
	v_cvt_pk_bf16_f32 v242, v64, v65
	v_cvt_pk_bf16_f32 v243, v66, v67
	v_cvt_pk_bf16_f32 v244, v60, v61
	v_cvt_pk_bf16_f32 v245, v62, v63
	v_lshlrev_b32_e32 v66, 16, v242
	v_and_b32_e32 v67, 0xffff0000, v242
	v_lshlrev_b32_e32 v64, 16, v243
	v_and_b32_e32 v65, 0xffff0000, v243
	v_lshlrev_b32_e32 v62, 16, v244
	v_and_b32_e32 v63, 0xffff0000, v244
	v_lshlrev_b32_e32 v60, 16, v245
	v_and_b32_e32 v61, 0xffff0000, v245
	v_lshlrev_b32_e32 v184, 16, v250
	v_and_b32_e32 v185, 0xffff0000, v250
	v_lshlrev_b32_e32 v188, 16, v251
	v_and_b32_e32 v189, 0xffff0000, v251
	v_lshlrev_b32_e32 v234, 16, v252
	v_and_b32_e32 v235, 0xffff0000, v252
	v_lshlrev_b32_e32 v246, 16, v253
	v_and_b32_e32 v247, 0xffff0000, v253
	global_store_dwordx4 v[182:183], v[242:245], off offset:2304
	v_pk_fma_f32 v[58:59], v[58:59], v[106:107], v[188:189]
	v_pk_fma_f32 v[56:57], v[56:57], v[104:105], v[184:185]
	v_pk_fma_f32 v[54:55], v[54:55], v[102:103], v[246:247]
	v_pk_fma_f32 v[52:53], v[52:53], v[100:101], v[234:235]
	s_waitcnt vmcnt(0)
	v_lshlrev_b32_e32 v188, 16, v240
	v_pk_mul_f32 v[168:169], v[70:71], v[60:61]
	v_pk_mul_f32 v[154:155], v[74:75], v[64:65]
	v_pk_mul_f32 v[166:167], v[72:73], v[66:67]
	v_pk_mul_f32 v[182:183], v[68:69], v[62:63]
	v_cvt_pk_bf16_f32 v180, v166, v167
	v_cvt_pk_bf16_f32 v181, v154, v155
	v_cvt_pk_bf16_f32 v182, v182, v183
	v_cvt_pk_bf16_f32 v183, v168, v169
	global_store_dwordx4 v[178:179], v[180:183], off offset:256
	v_cvt_pk_bf16_f32 v178, v56, v57
	v_cvt_pk_bf16_f32 v179, v58, v59
	v_cvt_pk_bf16_f32 v180, v52, v53
	v_cvt_pk_bf16_f32 v181, v54, v55
	v_lshlrev_b32_e32 v58, 16, v178
	v_and_b32_e32 v59, 0xffff0000, v178
	v_lshlrev_b32_e32 v56, 16, v179
	v_and_b32_e32 v57, 0xffff0000, v179
	v_lshlrev_b32_e32 v54, 16, v180
	v_and_b32_e32 v55, 0xffff0000, v180
	v_lshlrev_b32_e32 v52, 16, v181
	v_and_b32_e32 v53, 0xffff0000, v181
	global_store_dwordx4 v[186:187], v[178:181], off offset:2304
	v_pk_mul_f32 v[154:155], v[74:75], v[56:57]
	v_pk_mul_f32 v[166:167], v[72:73], v[58:59]
	v_pk_mul_f32 v[168:169], v[70:71], v[52:53]
	v_pk_mul_f32 v[180:181], v[68:69], v[54:55]
	v_cvt_pk_bf16_f32 v178, v166, v167
	v_cvt_pk_bf16_f32 v179, v154, v155
	v_cvt_pk_bf16_f32 v180, v180, v181
	v_cvt_pk_bf16_f32 v181, v168, v169
	v_lshlrev_b32_e32 v154, 16, v150
	v_and_b32_e32 v155, 0xffff0000, v150
	v_lshlrev_b32_e32 v150, 16, v151
	v_and_b32_e32 v151, 0xffff0000, v151
	v_lshlrev_b32_e32 v166, 16, v152
	v_and_b32_e32 v167, 0xffff0000, v152
	v_lshlrev_b32_e32 v152, 16, v153
	v_and_b32_e32 v153, 0xffff0000, v153
	global_store_dwordx4 v[190:191], v[178:181], off offset:256
	v_pk_fma_f32 v[50:51], v[50:51], v[106:107], v[150:151]
	v_pk_fma_f32 v[48:49], v[48:49], v[104:105], v[154:155]
	v_pk_fma_f32 v[46:47], v[46:47], v[102:103], v[152:153]
	v_pk_fma_f32 v[44:45], v[44:45], v[100:101], v[166:167]
	global_load_dwordx4 v[178:181], v[192:193], off offset:2304
	global_load_dwordx4 v[182:185], v[194:195], off offset:2304
	v_cvt_pk_bf16_f32 v150, v48, v49
	v_cvt_pk_bf16_f32 v151, v50, v51
	v_cvt_pk_bf16_f32 v152, v44, v45
	v_cvt_pk_bf16_f32 v153, v46, v47
	v_lshlrev_b32_e32 v50, 16, v150
	v_and_b32_e32 v51, 0xffff0000, v150
	v_lshlrev_b32_e32 v48, 16, v151
	v_and_b32_e32 v49, 0xffff0000, v151
	v_lshlrev_b32_e32 v46, 16, v152
	v_and_b32_e32 v47, 0xffff0000, v152
	v_lshlrev_b32_e32 v44, 16, v153
	v_and_b32_e32 v45, 0xffff0000, v153
	v_lshlrev_b32_e32 v168, 16, v238
	v_and_b32_e32 v169, 0xffff0000, v238
	v_lshlrev_b32_e32 v186, 16, v239
	v_and_b32_e32 v187, 0xffff0000, v239
	v_and_b32_e32 v189, 0xffff0000, v240
	v_lshlrev_b32_e32 v190, 16, v241
	v_and_b32_e32 v191, 0xffff0000, v241
	global_store_dwordx4 v[198:199], v[150:153], off offset:2304
	v_pk_mul_f32 v[154:155], v[70:71], v[44:45]
	v_pk_mul_f32 v[166:167], v[68:69], v[46:47]
	v_pk_mul_f32 v[152:153], v[74:75], v[48:49]
	v_pk_mul_f32 v[150:151], v[72:73], v[50:51]
	v_pk_fma_f32 v[42:43], v[42:43], v[106:107], v[186:187]
	v_cvt_pk_bf16_f32 v150, v150, v151
	v_cvt_pk_bf16_f32 v151, v152, v153
	v_cvt_pk_bf16_f32 v152, v166, v167
	v_cvt_pk_bf16_f32 v153, v154, v155
	v_pk_fma_f32 v[40:41], v[40:41], v[104:105], v[168:169]
	v_pk_fma_f32 v[38:39], v[38:39], v[102:103], v[190:191]
	v_pk_fma_f32 v[36:37], v[36:37], v[100:101], v[188:189]
	global_store_dwordx4 v[200:201], v[150:153], off offset:256
	v_mul_f32_e32 v67, v67, v67
	v_mul_f32_e32 v65, v65, v65
	v_cvt_pk_bf16_f32 v150, v40, v41
	v_cvt_pk_bf16_f32 v151, v42, v43
	v_cvt_pk_bf16_f32 v152, v36, v37
	v_cvt_pk_bf16_f32 v153, v38, v39
	v_lshlrev_b32_e32 v42, 16, v150
	v_and_b32_e32 v43, 0xffff0000, v150
	v_lshlrev_b32_e32 v40, 16, v151
	v_and_b32_e32 v41, 0xffff0000, v151
	v_lshlrev_b32_e32 v38, 16, v152
	v_and_b32_e32 v39, 0xffff0000, v152
	v_lshlrev_b32_e32 v36, 16, v153
	v_and_b32_e32 v37, 0xffff0000, v153
	global_store_dwordx4 v[202:203], v[150:153], off offset:2304
	v_pk_mul_f32 v[154:155], v[70:71], v[36:37]
	v_pk_mul_f32 v[166:167], v[68:69], v[38:39]
	v_pk_mul_f32 v[152:153], v[74:75], v[40:41]
	v_pk_mul_f32 v[150:151], v[72:73], v[42:43]
	v_fmac_f32_e32 v67, v66, v66
	v_cvt_pk_bf16_f32 v150, v150, v151
	v_cvt_pk_bf16_f32 v151, v152, v153
	v_cvt_pk_bf16_f32 v152, v166, v167
	v_cvt_pk_bf16_f32 v153, v154, v155
	global_store_dwordx4 v[204:205], v[150:153], off offset:256
	global_load_dwordx4 v[150:153], v[206:207], off offset:2304
	s_nop 0
	global_load_dwordx4 v[186:189], v[208:209], off offset:2304
	v_fmac_f32_e32 v65, v64, v64
	v_mul_f32_e32 v63, v63, v63
	v_mul_f32_e32 v61, v61, v61
	v_add_f32_e32 v64, v67, v65
	v_fmac_f32_e32 v63, v62, v62
	v_fmac_f32_e32 v61, v60, v60
	v_add_f32_e32 v60, v63, v61
	s_waitcnt vmcnt(0)
	v_lshlrev_b32_e32 v154, 16, v178
	v_and_b32_e32 v155, 0xffff0000, v178
	v_lshlrev_b32_e32 v166, 16, v179
	v_and_b32_e32 v167, 0xffff0000, v179
	v_lshlrev_b32_e32 v168, 16, v180
	v_and_b32_e32 v169, 0xffff0000, v180
	v_lshlrev_b32_e32 v178, 16, v181
	v_and_b32_e32 v179, 0xffff0000, v181
	v_pk_fma_f32 v[34:35], v[34:35], v[106:107], v[166:167]
	v_pk_fma_f32 v[32:33], v[32:33], v[104:105], v[154:155]
	v_pk_fma_f32 v[30:31], v[30:31], v[102:103], v[178:179]
	v_pk_fma_f32 v[28:29], v[28:29], v[100:101], v[168:169]
	v_cvt_pk_bf16_f32 v178, v32, v33
	v_cvt_pk_bf16_f32 v179, v34, v35
	v_cvt_pk_bf16_f32 v180, v28, v29
	v_cvt_pk_bf16_f32 v181, v30, v31
	v_lshlrev_b32_e32 v34, 16, v178
	v_and_b32_e32 v35, 0xffff0000, v178
	v_lshlrev_b32_e32 v32, 16, v179
	v_and_b32_e32 v33, 0xffff0000, v179
	v_lshlrev_b32_e32 v30, 16, v180
	v_and_b32_e32 v31, 0xffff0000, v180
	v_lshlrev_b32_e32 v28, 16, v181
	v_and_b32_e32 v29, 0xffff0000, v181
	v_lshlrev_b32_e32 v190, 16, v182
	v_and_b32_e32 v191, 0xffff0000, v182
	v_lshlrev_b32_e32 v182, 16, v183
	v_and_b32_e32 v183, 0xffff0000, v183
	global_store_dwordx4 v[212:213], v[178:181], off offset:2304
	v_pk_mul_f32 v[154:155], v[74:75], v[32:33]
	v_pk_mul_f32 v[166:167], v[72:73], v[34:35]
	v_pk_mul_f32 v[168:169], v[70:71], v[28:29]
	v_pk_mul_f32 v[180:181], v[68:69], v[30:31]
	v_lshlrev_b32_e32 v192, 16, v184
	v_and_b32_e32 v193, 0xffff0000, v184
	v_lshlrev_b32_e32 v184, 16, v185
	v_and_b32_e32 v185, 0xffff0000, v185
	v_cvt_pk_bf16_f32 v178, v166, v167
	v_cvt_pk_bf16_f32 v179, v154, v155
	v_cvt_pk_bf16_f32 v180, v180, v181
	v_cvt_pk_bf16_f32 v181, v168, v169
	v_pk_fma_f32 v[24:25], v[24:25], v[106:107], v[182:183]
	v_pk_fma_f32 v[22:23], v[22:23], v[104:105], v[190:191]
	global_store_dwordx4 v[214:215], v[178:181], off offset:256
	v_pk_fma_f32 v[20:21], v[20:21], v[102:103], v[184:185]
	v_pk_fma_f32 v[18:19], v[18:19], v[100:101], v[192:193]
	v_cvt_pk_bf16_f32 v178, v22, v23
	v_cvt_pk_bf16_f32 v179, v24, v25
	v_cvt_pk_bf16_f32 v180, v18, v19
	v_cvt_pk_bf16_f32 v181, v20, v21
	v_lshlrev_b32_e32 v24, 16, v178
	v_and_b32_e32 v25, 0xffff0000, v178
	v_lshlrev_b32_e32 v22, 16, v179
	v_and_b32_e32 v23, 0xffff0000, v179
	v_lshlrev_b32_e32 v20, 16, v180
	v_and_b32_e32 v21, 0xffff0000, v180
	v_lshlrev_b32_e32 v18, 16, v181
	v_and_b32_e32 v19, 0xffff0000, v181
	v_pk_mul_f32 v[154:155], v[74:75], v[22:23]
	v_pk_mul_f32 v[166:167], v[72:73], v[24:25]
	global_store_dwordx4 v[216:217], v[178:181], off offset:2304
	v_pk_mul_f32 v[168:169], v[70:71], v[18:19]
	v_lshlrev_b32_e32 v182, 16, v189
	v_pk_mul_f32 v[180:181], v[68:69], v[20:21]
	v_cvt_pk_bf16_f32 v178, v166, v167
	v_cvt_pk_bf16_f32 v179, v154, v155
	v_lshlrev_b32_e32 v154, 16, v150
	v_and_b32_e32 v155, 0xffff0000, v150
	v_lshlrev_b32_e32 v150, 16, v151
	v_and_b32_e32 v151, 0xffff0000, v151
	v_lshlrev_b32_e32 v166, 16, v152
	v_and_b32_e32 v167, 0xffff0000, v152
	v_lshlrev_b32_e32 v152, 16, v153
	v_and_b32_e32 v153, 0xffff0000, v153
	v_cvt_pk_bf16_f32 v180, v180, v181
	v_cvt_pk_bf16_f32 v181, v168, v169
	v_pk_fma_f32 v[16:17], v[16:17], v[106:107], v[150:151]
	v_pk_fma_f32 v[14:15], v[14:15], v[104:105], v[154:155]
	v_pk_fma_f32 v[12:13], v[12:13], v[102:103], v[152:153]
	v_pk_fma_f32 v[10:11], v[10:11], v[100:101], v[166:167]
	global_store_dwordx4 v[218:219], v[178:181], off offset:256
	v_lshlrev_b32_e32 v168, 16, v186
	v_and_b32_e32 v169, 0xffff0000, v186
	v_lshlrev_b32_e32 v178, 16, v187
	v_and_b32_e32 v179, 0xffff0000, v187
	v_lshlrev_b32_e32 v180, 16, v188
	v_and_b32_e32 v181, 0xffff0000, v188
	v_and_b32_e32 v183, 0xffff0000, v189
	v_cvt_pk_bf16_f32 v150, v14, v15
	v_cvt_pk_bf16_f32 v151, v16, v17
	v_cvt_pk_bf16_f32 v152, v10, v11
	v_cvt_pk_bf16_f32 v153, v12, v13
	v_lshlrev_b32_e32 v16, 16, v150
	v_and_b32_e32 v17, 0xffff0000, v150
	v_lshlrev_b32_e32 v14, 16, v151
	v_and_b32_e32 v15, 0xffff0000, v151
	v_lshlrev_b32_e32 v12, 16, v152
	v_and_b32_e32 v13, 0xffff0000, v152
	v_lshlrev_b32_e32 v10, 16, v153
	v_and_b32_e32 v11, 0xffff0000, v153
	v_pk_fma_f32 v[8:9], v[8:9], v[106:107], v[178:179]
	v_pk_fma_f32 v[6:7], v[6:7], v[104:105], v[168:169]
	v_pk_fma_f32 v[4:5], v[4:5], v[102:103], v[182:183]
	v_pk_fma_f32 v[2:3], v[2:3], v[100:101], v[180:181]
	global_store_dwordx4 v[196:197], v[150:153], off offset:2304
	v_pk_mul_f32 v[154:155], v[70:71], v[10:11]
	v_pk_mul_f32 v[166:167], v[68:69], v[12:13]
	v_pk_mul_f32 v[152:153], v[74:75], v[14:15]
	v_pk_mul_f32 v[150:151], v[72:73], v[16:17]
	v_cvt_pk_bf16_f32 v100, v6, v7
	v_cvt_pk_bf16_f32 v101, v8, v9
	v_cvt_pk_bf16_f32 v102, v2, v3
	v_cvt_pk_bf16_f32 v103, v4, v5
	v_cvt_pk_bf16_f32 v150, v150, v151
	v_cvt_pk_bf16_f32 v151, v152, v153
	v_cvt_pk_bf16_f32 v152, v166, v167
	v_cvt_pk_bf16_f32 v153, v154, v155
	v_lshlrev_b32_e32 v8, 16, v100
	v_and_b32_e32 v9, 0xffff0000, v100
	v_lshlrev_b32_e32 v6, 16, v101
	v_and_b32_e32 v7, 0xffff0000, v101
	v_lshlrev_b32_e32 v4, 16, v102
	v_and_b32_e32 v5, 0xffff0000, v102
	v_lshlrev_b32_e32 v2, 16, v103
	v_and_b32_e32 v3, 0xffff0000, v103
	global_store_dwordx4 v[210:211], v[150:153], off offset:256
	global_store_dwordx4 v[220:221], v[100:103], off offset:2304
	v_pk_mul_f32 v[74:75], v[74:75], v[6:7]
	v_pk_mul_f32 v[72:73], v[72:73], v[8:9]
	v_pk_mul_f32 v[100:101], v[70:71], v[2:3]
	v_pk_mul_f32 v[70:71], v[68:69], v[4:5]
	v_cvt_pk_bf16_f32 v68, v72, v73
	v_cvt_pk_bf16_f32 v69, v74, v75
	v_cvt_pk_bf16_f32 v70, v70, v71
	v_cvt_pk_bf16_f32 v71, v100, v101
	global_store_dwordx4 v[148:149], v[68:71], off offset:256
	v_xor_b32_e32 v72, 32, v227
	v_mul_f32_e32 v73, v137, v137
	v_and_b32_e32 v71, 64, v227
	v_xor_b32_e32 v70, 16, v227
	v_add_u32_e32 v71, 64, v71
	v_cmp_lt_i32_e32 vcc, v70, v71
	v_fmac_f32_e32 v73, v136, v136
	v_mul_f32_e32 v74, v133, v133
	v_cndmask_b32_e32 v70, v227, v70, vcc
	v_cmp_lt_i32_e32 vcc, v72, v71
	v_fmac_f32_e32 v74, v132, v132
	v_lshlrev_b32_e32 v70, 2, v70
	v_cndmask_b32_e32 v71, v227, v72, vcc
	v_mul_f32_e32 v72, v139, v139
	v_fmac_f32_e32 v72, v138, v138
	v_add_f32_e32 v72, v72, v73
	v_mul_f32_e32 v73, v135, v135
	v_fmac_f32_e32 v73, v134, v134
	v_add_f32_e32 v73, v73, v74
	v_add_f32_e32 v72, v72, v73
	v_add_f32_e32 v64, v72, v64
	v_add_f32_e32 v60, v60, v64
	ds_bpermute_b32 v61, v70, v60
	v_lshlrev_b32_e32 v71, 2, v71
	v_lshl_add_u64 v[68:69], v[172:173], 0, s[28:29]
	s_waitcnt lgkmcnt(0)
	v_add_f32_e32 v60, v60, v61
	ds_bpermute_b32 v61, v71, v60
	s_and_saveexec_b64 s[18:19], s[38:39]
	s_cbranch_execz .LBB0_968
	s_waitcnt lgkmcnt(0)
	v_add_f32_e32 v60, v60, v61
	global_atomic_add_f32 v[68:69], v60, off

.LBB0_1047:
	s_ashr_i32 s43, s42, 31
	s_lshl_b64 s[0:1], s[42:43], 19
	v_mov_b64_e32 v[2:3], s[10:11]
	s_add_u32 s46, s17, s0
	v_cmp_lt_i64_e32 vcc, s[28:29], v[2:3]
	s_addc_u32 s47, s50, s1
	s_and_b64 s[0:1], vcc, exec
	s_cselect_b32 s43, s47, s25
	s_cselect_b32 s69, s46, s24
	s_ashr_i32 s45, s44, 31
	s_lshl_b64 s[0:1], s[44:45], 19
	s_add_u32 s48, s51, s0
	s_addc_u32 s49, s53, s1
	s_and_b64 s[0:1], vcc, exec
	s_cselect_b32 s45, s49, s27
	s_cselect_b32 s72, s48, s26
	s_add_u32 s24, s24, 0x40080
	s_addc_u32 s25, s25, 0
	s_add_u32 s73, s26, 0x100
	v_mov_b32_e32 v2, 0
	s_addc_u32 s81, s27, 0
	s_mov_b32 s82, -2
	v_mov_b32_e32 v3, v2
	v_mov_b32_e32 v4, v2
	v_mov_b32_e32 v5, v2
	v_mov_b32_e32 v6, v2
	v_mov_b32_e32 v7, v2
	v_mov_b32_e32 v8, v2
	v_mov_b32_e32 v9, v2
	v_mov_b32_e32 v18, v2
	v_mov_b32_e32 v19, v2
	v_mov_b32_e32 v20, v2
	v_mov_b32_e32 v21, v2
	v_mov_b32_e32 v22, v2
	v_mov_b32_e32 v23, v2
	v_mov_b32_e32 v24, v2
	v_mov_b32_e32 v25, v2
	s_waitcnt vmcnt(0)
	v_mov_b32_e32 v36, v2
	v_mov_b32_e32 v37, v2
	v_mov_b32_e32 v38, v2
	v_mov_b32_e32 v39, v2
	v_mov_b32_e32 v40, v2
	v_mov_b32_e32 v41, v2
	v_mov_b32_e32 v42, v2
	v_mov_b32_e32 v43, v2
	v_mov_b32_e32 v52, v2
	v_mov_b32_e32 v53, v2
	v_mov_b32_e32 v54, v2
	v_mov_b32_e32 v55, v2
	v_mov_b32_e32 v56, v2
	v_mov_b32_e32 v57, v2
	v_mov_b32_e32 v58, v2
	v_mov_b32_e32 v59, v2
	v_mov_b32_e32 v10, v2
	v_mov_b32_e32 v11, v2
	v_mov_b32_e32 v12, v2
	v_mov_b32_e32 v13, v2
	v_mov_b32_e32 v14, v2
	v_mov_b32_e32 v15, v2
	v_mov_b32_e32 v16, v2
	v_mov_b32_e32 v17, v2
	v_mov_b32_e32 v28, v2
	v_mov_b32_e32 v29, v2
	v_mov_b32_e32 v30, v2
	v_mov_b32_e32 v31, v2
	v_mov_b32_e32 v32, v2
	v_mov_b32_e32 v33, v2
	v_mov_b32_e32 v34, v2
	v_mov_b32_e32 v35, v2
	v_mov_b32_e32 v44, v2
	v_mov_b32_e32 v45, v2
	v_mov_b32_e32 v46, v2
	v_mov_b32_e32 v47, v2
	v_mov_b32_e32 v48, v2
	v_mov_b32_e32 v49, v2
	v_mov_b32_e32 v50, v2
	v_mov_b32_e32 v51, v2
	v_mov_b32_e32 v60, v2
	v_mov_b32_e32 v61, v2
	v_mov_b32_e32 v62, v2
	v_mov_b32_e32 v63, v2
	v_mov_b32_e32 v64, v2
	v_mov_b32_e32 v65, v2
	v_mov_b32_e32 v66, v2
	v_mov_b32_e32 v67, v2
	v_mov_b32_e32 v84, v2
	v_mov_b32_e32 v85, v2
	v_mov_b32_e32 v86, v2
	v_mov_b32_e32 v87, v2
	v_mov_b32_e32 v88, v2
	v_mov_b32_e32 v89, v2
	v_mov_b32_e32 v90, v2
	v_mov_b32_e32 v91, v2
	v_mov_b32_e32 v100, v2
	v_mov_b32_e32 v101, v2
	v_mov_b32_e32 v102, v2
	v_mov_b32_e32 v103, v2
	v_mov_b32_e32 v104, v2
	v_mov_b32_e32 v105, v2
	v_mov_b32_e32 v106, v2
	v_mov_b32_e32 v107, v2
	v_mov_b32_e32 v116, v2
	v_mov_b32_e32 v117, v2
	v_mov_b32_e32 v118, v2
	v_mov_b32_e32 v119, v2
	v_mov_b32_e32 v120, v2
	v_mov_b32_e32 v121, v2
	v_mov_b32_e32 v122, v2
	v_mov_b32_e32 v123, v2
	v_mov_b32_e32 v132, v2
	v_mov_b32_e32 v133, v2
	v_mov_b32_e32 v134, v2
	v_mov_b32_e32 v135, v2
	v_mov_b32_e32 v136, v2
	v_mov_b32_e32 v137, v2
	v_mov_b32_e32 v138, v2
	v_mov_b32_e32 v139, v2
	v_mov_b32_e32 v92, v2
	v_mov_b32_e32 v93, v2
	v_mov_b32_e32 v94, v2
	v_mov_b32_e32 v95, v2
	v_mov_b32_e32 v96, v2
	v_mov_b32_e32 v97, v2
	v_mov_b32_e32 v98, v2
	v_mov_b32_e32 v99, v2
	v_mov_b32_e32 v108, v2
	v_mov_b32_e32 v109, v2
	v_mov_b32_e32 v110, v2
	v_mov_b32_e32 v111, v2
	v_mov_b32_e32 v112, v2
	v_mov_b32_e32 v113, v2
	v_mov_b32_e32 v114, v2
	v_mov_b32_e32 v115, v2
	v_mov_b32_e32 v124, v2
	v_mov_b32_e32 v125, v2
	v_mov_b32_e32 v126, v2
	v_mov_b32_e32 v127, v2
	v_mov_b32_e32 v128, v2
	v_mov_b32_e32 v129, v2
	v_mov_b32_e32 v130, v2
	v_mov_b32_e32 v131, v2
	v_mov_b32_e32 v140, v2
	v_mov_b32_e32 v141, v2
	v_mov_b32_e32 v142, v2
	v_mov_b32_e32 v143, v2
	v_mov_b32_e32 v144, v2
	v_mov_b32_e32 v145, v2
	v_mov_b32_e32 v146, v2
	v_mov_b32_e32 v147, v2
	v_add_u32_e32 v80, 0x10000, v163
	ds_read_b128 v[68:71], v80
	ds_read_b128 v[72:75], v80 offset:1024
	ds_read_b128 v[76:79], v80 offset:2048
	ds_read_b128 v[80:83], v80 offset:3072
.LBB0_1048:
	s_add_u32 s0, s24, 0xfffc0080
	s_addc_u32 s1, s25, -1
	s_add_i32 s83, 0, 0x10000
	s_cmp_eq_u32 s82, 12
	s_cselect_b32 s29, s43, s1
	s_cselect_b32 s28, s69, s0
	s_cselect_b32 s27, s45, s81
	s_cselect_b32 s26, s72, s73
	v_lshl_add_u64 v[166:167], s[24:25], 0, v[154:155]
	s_add_i32 m0, s23, 0xc000
	ds_read_b128 v[158:161], v165
	ds_read_b128 v[174:177], v165 offset:1024
	ds_read_b128 v[178:181], v165 offset:2048
	ds_read_b128 v[182:185], v165 offset:3072
	ds_read_b128 v[186:189], v165 offset:4096
	ds_read_b128 v[190:193], v165 offset:5120
	ds_read_b128 v[194:197], v165 offset:6144
	ds_read_b128 v[198:201], v165 offset:7168
	global_load_lds_dwordx4 v[166:167], off
	v_lshl_add_u64 v[166:167], s[24:25], 0, v[156:157]
	s_add_i32 m0, s23, 0xe000
	s_nop 0
	global_load_lds_dwordx4 v[166:167], off
	s_waitcnt vmcnt(10) lgkmcnt(8)
	s_setprio 1
	s_barrier
	s_waitcnt lgkmcnt(0)
	v_mfma_f32_16x16x32_bf16 v[144:147], v[68:71], v[158:161], v[144:147]
	v_mfma_f32_16x16x32_bf16 v[140:143], v[76:79], v[158:161], v[140:143]
	v_mfma_f32_16x16x32_bf16 v[128:131], v[68:71], v[178:181], v[128:131]
	v_mfma_f32_16x16x32_bf16 v[124:127], v[76:79], v[178:181], v[124:127]
	v_mfma_f32_16x16x32_bf16 v[112:115], v[68:71], v[186:189], v[112:115]
	v_mfma_f32_16x16x32_bf16 v[108:111], v[76:79], v[186:189], v[108:111]
	v_mfma_f32_16x16x32_bf16 v[96:99], v[68:71], v[194:197], v[96:99]
	v_mfma_f32_16x16x32_bf16 v[92:95], v[76:79], v[194:197], v[92:95]
	v_mfma_f32_16x16x32_bf16 v[144:147], v[72:75], v[174:177], v[144:147]
	v_mfma_f32_16x16x32_bf16 v[140:143], v[80:83], v[174:177], v[140:143]
	v_mfma_f32_16x16x32_bf16 v[128:131], v[72:75], v[182:185], v[128:131]
	v_mfma_f32_16x16x32_bf16 v[124:127], v[80:83], v[182:185], v[124:127]
	v_mfma_f32_16x16x32_bf16 v[112:115], v[72:75], v[190:193], v[112:115]
	v_mfma_f32_16x16x32_bf16 v[108:111], v[80:83], v[190:193], v[108:111]
	v_mfma_f32_16x16x32_bf16 v[96:99], v[72:75], v[198:201], v[96:99]
	v_mfma_f32_16x16x32_bf16 v[92:95], v[80:83], v[198:201], v[92:95]
	s_barrier
	s_setprio 0
	s_add_i32 s84, 0, 0x14000
	v_add_u32_e32 v166, s84, v163
	s_add_i32 s0, s83, s54
	ds_read_b128 v[202:205], v166
	ds_read_b128 v[206:209], v166 offset:1024
	ds_read_b128 v[210:213], v166 offset:2048
	ds_read_b128 v[214:217], v166 offset:3072
	v_lshl_add_u64 v[166:167], s[26:27], 0, v[26:27]
	s_mov_b32 m0, s0
	v_lshl_add_u64 v[168:169], s[26:27], 0, v[148:149]
	global_load_lds_dwordx4 v[166:167], off
	s_add_i32 m0, s0, 0x2000
	s_nop 0
	global_load_lds_dwordx4 v[168:169], off
	s_waitcnt vmcnt(10)
	s_setprio 1
	s_barrier
	s_waitcnt lgkmcnt(0)
	v_mfma_f32_16x16x32_bf16 v[136:139], v[202:205], v[158:161], v[136:139]
	v_mfma_f32_16x16x32_bf16 v[132:135], v[210:213], v[158:161], v[132:135]
	v_mfma_f32_16x16x32_bf16 v[120:123], v[202:205], v[178:181], v[120:123]
	v_mfma_f32_16x16x32_bf16 v[116:119], v[210:213], v[178:181], v[116:119]
	v_mfma_f32_16x16x32_bf16 v[104:107], v[202:205], v[186:189], v[104:107]
	v_mfma_f32_16x16x32_bf16 v[100:103], v[210:213], v[186:189], v[100:103]
	v_mfma_f32_16x16x32_bf16 v[88:91], v[202:205], v[194:197], v[88:91]
	v_mfma_f32_16x16x32_bf16 v[84:87], v[210:213], v[194:197], v[84:87]
	v_mfma_f32_16x16x32_bf16 v[136:139], v[206:209], v[174:177], v[136:139]
	v_mfma_f32_16x16x32_bf16 v[132:135], v[214:217], v[174:177], v[132:135]
	v_mfma_f32_16x16x32_bf16 v[120:123], v[206:209], v[182:185], v[120:123]
	v_mfma_f32_16x16x32_bf16 v[116:119], v[214:217], v[182:185], v[116:119]
	v_mfma_f32_16x16x32_bf16 v[104:107], v[206:209], v[190:193], v[104:107]
	v_mfma_f32_16x16x32_bf16 v[100:103], v[214:217], v[190:193], v[100:103]
	v_mfma_f32_16x16x32_bf16 v[88:91], v[206:209], v[198:201], v[88:91]
	v_mfma_f32_16x16x32_bf16 v[84:87], v[214:217], v[198:201], v[84:87]
	s_barrier
	s_setprio 0
	s_mov_b32 m0, s23
	v_lshl_add_u64 v[218:219], s[28:29], 0, v[152:153]
	ds_read_b128 v[158:161], v165 offset:16384
	ds_read_b128 v[174:177], v165 offset:17408
	ds_read_b128 v[178:181], v165 offset:18432
	ds_read_b128 v[182:185], v165 offset:19456
	ds_read_b128 v[186:189], v165 offset:20480
	ds_read_b128 v[190:193], v165 offset:21504
	ds_read_b128 v[194:197], v165 offset:22528
	ds_read_b128 v[198:201], v165 offset:23552
	global_load_lds_dwordx4 v[218:219], off
	v_lshl_add_u64 v[220:221], s[28:29], 0, v[150:151]
	s_mov_b32 m0, s57
	s_nop 0
	global_load_lds_dwordx4 v[220:221], off
	s_waitcnt vmcnt(10)
	s_setprio 1
	s_barrier
	s_waitcnt lgkmcnt(0)
	v_mfma_f32_16x16x32_bf16 v[64:67], v[68:71], v[158:161], v[64:67]
	v_mfma_f32_16x16x32_bf16 v[60:63], v[76:79], v[158:161], v[60:63]
	v_mfma_f32_16x16x32_bf16 v[48:51], v[68:71], v[178:181], v[48:51]
	v_mfma_f32_16x16x32_bf16 v[44:47], v[76:79], v[178:181], v[44:47]
	v_mfma_f32_16x16x32_bf16 v[32:35], v[68:71], v[186:189], v[32:35]
	v_mfma_f32_16x16x32_bf16 v[28:31], v[76:79], v[186:189], v[28:31]
	v_mfma_f32_16x16x32_bf16 v[14:17], v[68:71], v[194:197], v[14:17]
	v_mfma_f32_16x16x32_bf16 v[10:13], v[76:79], v[194:197], v[10:13]
	v_mfma_f32_16x16x32_bf16 v[64:67], v[72:75], v[174:177], v[64:67]
	v_mfma_f32_16x16x32_bf16 v[60:63], v[80:83], v[174:177], v[60:63]
	v_mfma_f32_16x16x32_bf16 v[48:51], v[72:75], v[182:185], v[48:51]
	v_mfma_f32_16x16x32_bf16 v[44:47], v[80:83], v[182:185], v[44:47]
	v_mfma_f32_16x16x32_bf16 v[32:35], v[72:75], v[190:193], v[32:35]
	v_mfma_f32_16x16x32_bf16 v[28:31], v[80:83], v[190:193], v[28:31]
	v_mfma_f32_16x16x32_bf16 v[14:17], v[72:75], v[198:201], v[14:17]
	v_mfma_f32_16x16x32_bf16 v[10:13], v[80:83], v[198:201], v[10:13]
	s_barrier
	s_setprio 0
	s_add_u32 s0, s26, 0x40000
	s_addc_u32 s1, s27, 0
	s_add_i32 s83, s84, s54
	v_lshl_add_u64 v[68:69], s[0:1], 0, v[26:27]
	s_mov_b32 m0, s83
	s_nop 0
	global_load_lds_dwordx4 v[68:69], off
	v_lshl_add_u64 v[68:69], s[0:1], 0, v[148:149]
	s_add_i32 m0, s83, 0x2000
	s_nop 0
	global_load_lds_dwordx4 v[68:69], off
	v_add_u32_e32 v80, 0x18000, v163
	ds_read_b128 v[68:71], v80
	ds_read_b128 v[72:75], v80 offset:1024
	ds_read_b128 v[76:79], v80 offset:2048
	ds_read_b128 v[80:83], v80 offset:3072
	s_waitcnt vmcnt(10)
	s_setprio 1
	s_barrier
	v_mfma_f32_16x16x32_bf16 v[56:59], v[202:205], v[158:161], v[56:59]
	v_mfma_f32_16x16x32_bf16 v[52:55], v[210:213], v[158:161], v[52:55]
	v_mfma_f32_16x16x32_bf16 v[40:43], v[202:205], v[178:181], v[40:43]
	v_mfma_f32_16x16x32_bf16 v[36:39], v[210:213], v[178:181], v[36:39]
	v_mfma_f32_16x16x32_bf16 v[22:25], v[202:205], v[186:189], v[22:25]
	v_mfma_f32_16x16x32_bf16 v[18:21], v[210:213], v[186:189], v[18:21]
	v_mfma_f32_16x16x32_bf16 v[6:9], v[202:205], v[194:197], v[6:9]
	v_mfma_f32_16x16x32_bf16 v[2:5], v[210:213], v[194:197], v[2:5]
	v_mfma_f32_16x16x32_bf16 v[56:59], v[206:209], v[174:177], v[56:59]
	v_mfma_f32_16x16x32_bf16 v[52:55], v[214:217], v[174:177], v[52:55]
	v_mfma_f32_16x16x32_bf16 v[40:43], v[206:209], v[182:185], v[40:43]
	v_mfma_f32_16x16x32_bf16 v[36:39], v[214:217], v[182:185], v[36:39]
	v_mfma_f32_16x16x32_bf16 v[22:25], v[206:209], v[190:193], v[22:25]
	v_mfma_f32_16x16x32_bf16 v[18:21], v[214:217], v[190:193], v[18:21]
	v_mfma_f32_16x16x32_bf16 v[6:9], v[206:209], v[198:201], v[6:9]
	v_mfma_f32_16x16x32_bf16 v[2:5], v[214:217], v[198:201], v[2:5]
	s_barrier
	s_setprio 0
	s_add_i32 s83, 0, 0x18000
	s_add_u32 s0, s28, 0x40000
	s_addc_u32 s1, s29, 0
	s_mov_b32 m0, s58
	v_lshl_add_u64 v[202:203], s[0:1], 0, v[152:153]
	ds_read_b128 v[158:161], v165 offset:32768
	ds_read_b128 v[174:177], v165 offset:33792
	ds_read_b128 v[178:181], v165 offset:34816
	ds_read_b128 v[182:185], v165 offset:35840
	ds_read_b128 v[186:189], v165 offset:36864
	ds_read_b128 v[190:193], v165 offset:37888
	ds_read_b128 v[194:197], v165 offset:38912
	ds_read_b128 v[198:201], v165 offset:39936
	global_load_lds_dwordx4 v[202:203], off
	v_lshl_add_u64 v[202:203], s[0:1], 0, v[150:151]
	s_mov_b32 m0, s59
	s_nop 0
	global_load_lds_dwordx4 v[202:203], off
	s_waitcnt vmcnt(10) lgkmcnt(8)
	s_setprio 1
	s_barrier
	s_waitcnt lgkmcnt(0)
	v_mfma_f32_16x16x32_bf16 v[144:147], v[68:71], v[158:161], v[144:147]
	v_mfma_f32_16x16x32_bf16 v[140:143], v[76:79], v[158:161], v[140:143]
	v_mfma_f32_16x16x32_bf16 v[128:131], v[68:71], v[178:181], v[128:131]
	v_mfma_f32_16x16x32_bf16 v[124:127], v[76:79], v[178:181], v[124:127]
	v_mfma_f32_16x16x32_bf16 v[112:115], v[68:71], v[186:189], v[112:115]
	v_mfma_f32_16x16x32_bf16 v[108:111], v[76:79], v[186:189], v[108:111]
	v_mfma_f32_16x16x32_bf16 v[96:99], v[68:71], v[194:197], v[96:99]
	v_mfma_f32_16x16x32_bf16 v[92:95], v[76:79], v[194:197], v[92:95]
	v_mfma_f32_16x16x32_bf16 v[144:147], v[72:75], v[174:177], v[144:147]
	v_mfma_f32_16x16x32_bf16 v[140:143], v[80:83], v[174:177], v[140:143]
	v_mfma_f32_16x16x32_bf16 v[128:131], v[72:75], v[182:185], v[128:131]
	v_mfma_f32_16x16x32_bf16 v[124:127], v[80:83], v[182:185], v[124:127]
	v_mfma_f32_16x16x32_bf16 v[112:115], v[72:75], v[190:193], v[112:115]
	v_mfma_f32_16x16x32_bf16 v[108:111], v[80:83], v[190:193], v[108:111]
	v_mfma_f32_16x16x32_bf16 v[96:99], v[72:75], v[198:201], v[96:99]
	v_mfma_f32_16x16x32_bf16 v[92:95], v[80:83], v[198:201], v[92:95]
	s_barrier
	s_setprio 0
	s_add_i32 s28, 0, 0x1c000
	s_add_i32 s0, s83, s54
	v_add_u32_e32 v173, s28, v163
	v_lshl_add_u64 v[166:167], v[166:167], 0, s[12:13]
	s_mov_b32 m0, s0
	ds_read_b128 v[202:205], v173
	ds_read_b128 v[206:209], v173 offset:1024
	ds_read_b128 v[210:213], v173 offset:2048
	ds_read_b128 v[214:217], v173 offset:3072
	global_load_lds_dwordx4 v[166:167], off
	v_lshl_add_u64 v[166:167], v[168:169], 0, s[12:13]
	s_add_i32 m0, s0, 0x2000
	s_nop 0
	global_load_lds_dwordx4 v[166:167], off
	s_waitcnt vmcnt(10)
	s_setprio 1
	s_barrier
	s_waitcnt lgkmcnt(0)
	v_mfma_f32_16x16x32_bf16 v[136:139], v[202:205], v[158:161], v[136:139]
	v_mfma_f32_16x16x32_bf16 v[132:135], v[210:213], v[158:161], v[132:135]
	v_mfma_f32_16x16x32_bf16 v[120:123], v[202:205], v[178:181], v[120:123]
	v_mfma_f32_16x16x32_bf16 v[116:119], v[210:213], v[178:181], v[116:119]
	v_mfma_f32_16x16x32_bf16 v[104:107], v[202:205], v[186:189], v[104:107]
	v_mfma_f32_16x16x32_bf16 v[100:103], v[210:213], v[186:189], v[100:103]
	v_mfma_f32_16x16x32_bf16 v[88:91], v[202:205], v[194:197], v[88:91]
	v_mfma_f32_16x16x32_bf16 v[84:87], v[210:213], v[194:197], v[84:87]
	v_mfma_f32_16x16x32_bf16 v[136:139], v[206:209], v[174:177], v[136:139]
	v_mfma_f32_16x16x32_bf16 v[132:135], v[214:217], v[174:177], v[132:135]
	v_mfma_f32_16x16x32_bf16 v[120:123], v[206:209], v[182:185], v[120:123]
	v_mfma_f32_16x16x32_bf16 v[116:119], v[214:217], v[182:185], v[116:119]
	v_mfma_f32_16x16x32_bf16 v[104:107], v[206:209], v[190:193], v[104:107]
	v_mfma_f32_16x16x32_bf16 v[100:103], v[214:217], v[190:193], v[100:103]
	v_mfma_f32_16x16x32_bf16 v[88:91], v[206:209], v[198:201], v[88:91]
	v_mfma_f32_16x16x32_bf16 v[84:87], v[214:217], v[198:201], v[84:87]
	s_barrier
	s_setprio 0
	s_mov_b32 m0, s34
	v_lshl_add_u64 v[166:167], v[218:219], 0, s[12:13]
	ds_read_b128 v[158:161], v165 offset:49152
	ds_read_b128 v[174:177], v165 offset:50176
	ds_read_b128 v[178:181], v165 offset:51200
	ds_read_b128 v[182:185], v165 offset:52224
	ds_read_b128 v[186:189], v165 offset:53248
	ds_read_b128 v[190:193], v165 offset:54272
	ds_read_b128 v[194:197], v165 offset:55296
	ds_read_b128 v[198:201], v165 offset:56320
	global_load_lds_dwordx4 v[166:167], off
	v_lshl_add_u64 v[166:167], v[220:221], 0, s[12:13]
	s_mov_b32 m0, s35
	s_nop 0
	global_load_lds_dwordx4 v[166:167], off
	s_waitcnt vmcnt(10)
	s_setprio 1
	s_barrier
	s_waitcnt lgkmcnt(0)
	v_mfma_f32_16x16x32_bf16 v[64:67], v[68:71], v[158:161], v[64:67]
	v_mfma_f32_16x16x32_bf16 v[60:63], v[76:79], v[158:161], v[60:63]
	v_mfma_f32_16x16x32_bf16 v[48:51], v[68:71], v[178:181], v[48:51]
	v_mfma_f32_16x16x32_bf16 v[44:47], v[76:79], v[178:181], v[44:47]
	v_mfma_f32_16x16x32_bf16 v[32:35], v[68:71], v[186:189], v[32:35]
	v_mfma_f32_16x16x32_bf16 v[28:31], v[76:79], v[186:189], v[28:31]
	v_mfma_f32_16x16x32_bf16 v[14:17], v[68:71], v[194:197], v[14:17]
	v_mfma_f32_16x16x32_bf16 v[10:13], v[76:79], v[194:197], v[10:13]
	v_mfma_f32_16x16x32_bf16 v[64:67], v[72:75], v[174:177], v[64:67]
	v_mfma_f32_16x16x32_bf16 v[60:63], v[80:83], v[174:177], v[60:63]
	v_mfma_f32_16x16x32_bf16 v[48:51], v[72:75], v[182:185], v[48:51]
	v_mfma_f32_16x16x32_bf16 v[44:47], v[80:83], v[182:185], v[44:47]
	v_mfma_f32_16x16x32_bf16 v[32:35], v[72:75], v[190:193], v[32:35]
	v_mfma_f32_16x16x32_bf16 v[28:31], v[80:83], v[190:193], v[28:31]
	v_mfma_f32_16x16x32_bf16 v[14:17], v[72:75], v[198:201], v[14:17]
	v_mfma_f32_16x16x32_bf16 v[10:13], v[80:83], v[198:201], v[10:13]
	s_barrier
	s_setprio 0
	s_add_u32 s0, s26, 0x40080
	s_addc_u32 s1, s27, 0
	s_add_i32 s26, s28, s54
	v_lshl_add_u64 v[68:69], s[0:1], 0, v[26:27]
	s_mov_b32 m0, s26
	s_nop 0
	global_load_lds_dwordx4 v[68:69], off
	v_lshl_add_u64 v[68:69], s[0:1], 0, v[148:149]
	s_add_i32 m0, s26, 0x2000
	s_nop 0
	global_load_lds_dwordx4 v[68:69], off
	v_add_u32_e32 v80, 0x10000, v163
	ds_read_b128 v[68:71], v80
	ds_read_b128 v[72:75], v80 offset:1024
	ds_read_b128 v[76:79], v80 offset:2048
	ds_read_b128 v[80:83], v80 offset:3072
	s_waitcnt vmcnt(10)
	s_setprio 1
	s_barrier
	v_mfma_f32_16x16x32_bf16 v[56:59], v[202:205], v[158:161], v[56:59]
	v_mfma_f32_16x16x32_bf16 v[52:55], v[210:213], v[158:161], v[52:55]
	v_mfma_f32_16x16x32_bf16 v[40:43], v[202:205], v[178:181], v[40:43]
	v_mfma_f32_16x16x32_bf16 v[36:39], v[210:213], v[178:181], v[36:39]
	v_mfma_f32_16x16x32_bf16 v[22:25], v[202:205], v[186:189], v[22:25]
	v_mfma_f32_16x16x32_bf16 v[18:21], v[210:213], v[186:189], v[18:21]
	v_mfma_f32_16x16x32_bf16 v[6:9], v[202:205], v[194:197], v[6:9]
	v_mfma_f32_16x16x32_bf16 v[2:5], v[210:213], v[194:197], v[2:5]
	v_mfma_f32_16x16x32_bf16 v[56:59], v[206:209], v[174:177], v[56:59]
	v_mfma_f32_16x16x32_bf16 v[52:55], v[214:217], v[174:177], v[52:55]
	v_mfma_f32_16x16x32_bf16 v[40:43], v[206:209], v[182:185], v[40:43]
	v_mfma_f32_16x16x32_bf16 v[36:39], v[214:217], v[182:185], v[36:39]
	v_mfma_f32_16x16x32_bf16 v[22:25], v[206:209], v[190:193], v[22:25]
	v_mfma_f32_16x16x32_bf16 v[18:21], v[214:217], v[190:193], v[18:21]
	v_mfma_f32_16x16x32_bf16 v[6:9], v[206:209], v[198:201], v[6:9]
	v_mfma_f32_16x16x32_bf16 v[2:5], v[214:217], v[198:201], v[2:5]
	s_barrier
	s_setprio 0
	s_add_i32 s82, s82, 2
	s_add_u32 s24, s24, 0x100
	s_addc_u32 s25, s25, 0
	s_add_u32 s73, s73, 0x100
	s_addc_u32 s81, s81, 0
	s_cmp_gt_u32 s82, 13
	s_cbranch_scc0 .LBB0_1048
	s_waitcnt lgkmcnt(0)
	v_readlane_b32 s82, v255, 51
	s_cmpk_gt_i32 s22, 0xff
	s_mov_b64 s[24:25], 0xb000
	v_readlane_b32 s83, v255, 52
	s_cbranch_scc1 .LBB0_1044
	s_ashr_i32 s0, s22, 5
	s_mul_hi_i32 s25, s0, 0x1600
	s_mul_i32 s24, s0, 0x1600
	s_branch .LBB0_1044

.LBB0_1121:
	s_add_u32 s68, s26, 0x100
	v_mov_b32_e32 v2, 0
	s_addc_u32 s69, s27, 0
	s_mov_b32 s72, -2
	v_mov_b32_e32 v3, v2
	v_mov_b32_e32 v4, v2
	v_mov_b32_e32 v5, v2
	v_mov_b32_e32 v6, v2
	v_mov_b32_e32 v7, v2
	v_mov_b32_e32 v8, v2
	v_mov_b32_e32 v9, v2
	v_mov_b32_e32 v10, v2
	v_mov_b32_e32 v11, v2
	v_mov_b32_e32 v12, v2
	v_mov_b32_e32 v13, v2
	v_mov_b32_e32 v14, v2
	v_mov_b32_e32 v15, v2
	v_mov_b32_e32 v16, v2
	v_mov_b32_e32 v17, v2
	v_mov_b32_e32 v18, v2
	v_mov_b32_e32 v19, v2
	v_mov_b32_e32 v20, v2
	v_mov_b32_e32 v21, v2
	v_mov_b32_e32 v22, v2
	v_mov_b32_e32 v23, v2
	v_mov_b32_e32 v24, v2
	v_mov_b32_e32 v25, v2
	v_mov_b32_e32 v28, v2
	v_mov_b32_e32 v29, v2
	v_mov_b32_e32 v30, v2
	v_mov_b32_e32 v31, v2
	v_mov_b32_e32 v32, v2
	v_mov_b32_e32 v33, v2
	v_mov_b32_e32 v34, v2
	v_mov_b32_e32 v35, v2
	v_mov_b32_e32 v64, v2
	v_mov_b32_e32 v65, v2
	v_mov_b32_e32 v66, v2
	v_mov_b32_e32 v67, v2
	v_mov_b32_e32 v72, v2
	v_mov_b32_e32 v73, v2
	v_mov_b32_e32 v74, v2
	v_mov_b32_e32 v75, v2
	v_mov_b32_e32 v76, v2
	v_mov_b32_e32 v77, v2
	v_mov_b32_e32 v78, v2
	v_mov_b32_e32 v79, v2
	v_mov_b32_e32 v80, v2
	v_mov_b32_e32 v81, v2
	v_mov_b32_e32 v82, v2
	v_mov_b32_e32 v83, v2
	v_mov_b32_e32 v84, v2
	v_mov_b32_e32 v85, v2
	v_mov_b32_e32 v86, v2
	v_mov_b32_e32 v87, v2
	v_mov_b32_e32 v88, v2
	v_mov_b32_e32 v89, v2
	v_mov_b32_e32 v90, v2
	v_mov_b32_e32 v91, v2
	v_mov_b32_e32 v92, v2
	v_mov_b32_e32 v93, v2
	v_mov_b32_e32 v94, v2
	v_mov_b32_e32 v95, v2
	v_mov_b32_e32 v96, v2
	v_mov_b32_e32 v97, v2
	v_mov_b32_e32 v98, v2
	v_mov_b32_e32 v99, v2
	s_waitcnt vmcnt(0)
	v_mov_b32_e32 v36, v2
	v_mov_b32_e32 v37, v2
	v_mov_b32_e32 v38, v2
	v_mov_b32_e32 v39, v2
	v_mov_b32_e32 v40, v2
	v_mov_b32_e32 v41, v2
	v_mov_b32_e32 v42, v2
	v_mov_b32_e32 v43, v2
	v_mov_b32_e32 v44, v2
	v_mov_b32_e32 v45, v2
	v_mov_b32_e32 v46, v2
	v_mov_b32_e32 v47, v2
	v_mov_b32_e32 v48, v2
	v_mov_b32_e32 v49, v2
	v_mov_b32_e32 v50, v2
	v_mov_b32_e32 v51, v2
	v_mov_b32_e32 v52, v2
	v_mov_b32_e32 v53, v2
	v_mov_b32_e32 v54, v2
	v_mov_b32_e32 v55, v2
	v_mov_b32_e32 v56, v2
	v_mov_b32_e32 v57, v2
	v_mov_b32_e32 v58, v2
	v_mov_b32_e32 v59, v2
	v_mov_b32_e32 v60, v2
	v_mov_b32_e32 v61, v2
	v_mov_b32_e32 v62, v2
	v_mov_b32_e32 v63, v2
	v_mov_b32_e32 v68, v2
	v_mov_b32_e32 v69, v2
	v_mov_b32_e32 v70, v2
	v_mov_b32_e32 v71, v2
	v_mov_b32_e32 v100, v2
	v_mov_b32_e32 v101, v2
	v_mov_b32_e32 v102, v2
	v_mov_b32_e32 v103, v2
	v_mov_b32_e32 v104, v2
	v_mov_b32_e32 v105, v2
	v_mov_b32_e32 v106, v2
	v_mov_b32_e32 v107, v2
	v_mov_b32_e32 v108, v2
	v_mov_b32_e32 v109, v2
	v_mov_b32_e32 v110, v2
	v_mov_b32_e32 v111, v2
	v_mov_b32_e32 v112, v2
	v_mov_b32_e32 v113, v2
	v_mov_b32_e32 v114, v2
	v_mov_b32_e32 v115, v2
	v_mov_b32_e32 v116, v2
	v_mov_b32_e32 v117, v2
	v_mov_b32_e32 v118, v2
	v_mov_b32_e32 v119, v2
	v_mov_b32_e32 v120, v2
	v_mov_b32_e32 v121, v2
	v_mov_b32_e32 v122, v2
	v_mov_b32_e32 v123, v2
	v_mov_b32_e32 v124, v2
	v_mov_b32_e32 v125, v2
	v_mov_b32_e32 v126, v2
	v_mov_b32_e32 v127, v2
	v_mov_b32_e32 v128, v2
	v_mov_b32_e32 v129, v2
	v_mov_b32_e32 v130, v2
	v_mov_b32_e32 v131, v2
	v_add_u32_e32 v158, 0x10000, v186
	ds_read_b128 v[132:135], v158
	ds_read_b128 v[136:139], v158 offset:1024
	ds_read_b128 v[154:157], v158 offset:2048
	ds_read_b128 v[158:161], v158 offset:3072
.LBB0_1122:
	s_add_u32 s26, s24, 0x100
	s_addc_u32 s27, s25, 0
	s_add_i32 s0, 0, 0x10000
	s_cmp_eq_u32 s72, 40
	s_cselect_b32 s31, s43, s27
	s_cselect_b32 s30, s42, s26
	s_cselect_b32 s29, s45, s69
	s_cselect_b32 s28, s44, s68
	v_lshl_add_u64 v[166:167], s[24:25], 0, v[150:151]
	s_add_i32 m0, s36, 0xc000
	ds_read_b128 v[162:165], v188
	ds_read_b128 v[172:175], v188 offset:1024
	ds_read_b128 v[176:179], v188 offset:2048
	ds_read_b128 v[180:183], v188 offset:3072
	ds_read_b128 v[190:193], v188 offset:4096
	ds_read_b128 v[194:197], v188 offset:5120
	ds_read_b128 v[198:201], v188 offset:6144
	ds_read_b128 v[202:205], v188 offset:7168
	global_load_lds_dwordx4 v[166:167], off
	v_lshl_add_u64 v[166:167], s[24:25], 0, v[152:153]
	s_add_i32 m0, s36, 0xe000
	s_nop 0
	global_load_lds_dwordx4 v[166:167], off
	s_waitcnt vmcnt(10) lgkmcnt(8)
	s_setprio 1
	s_barrier
	s_waitcnt lgkmcnt(0)
	v_mfma_f32_16x16x32_bf16 v[128:131], v[132:135], v[162:165], v[128:131]
	v_mfma_f32_16x16x32_bf16 v[124:127], v[154:157], v[162:165], v[124:127]
	v_mfma_f32_16x16x32_bf16 v[120:123], v[132:135], v[176:179], v[120:123]
	v_mfma_f32_16x16x32_bf16 v[116:119], v[154:157], v[176:179], v[116:119]
	v_mfma_f32_16x16x32_bf16 v[112:115], v[132:135], v[190:193], v[112:115]
	v_mfma_f32_16x16x32_bf16 v[108:111], v[154:157], v[190:193], v[108:111]
	v_mfma_f32_16x16x32_bf16 v[104:107], v[132:135], v[198:201], v[104:107]
	v_mfma_f32_16x16x32_bf16 v[100:103], v[154:157], v[198:201], v[100:103]
	v_mfma_f32_16x16x32_bf16 v[128:131], v[136:139], v[172:175], v[128:131]
	v_mfma_f32_16x16x32_bf16 v[124:127], v[158:161], v[172:175], v[124:127]
	v_mfma_f32_16x16x32_bf16 v[120:123], v[136:139], v[180:183], v[120:123]
	v_mfma_f32_16x16x32_bf16 v[116:119], v[158:161], v[180:183], v[116:119]
	v_mfma_f32_16x16x32_bf16 v[112:115], v[136:139], v[194:197], v[112:115]
	v_mfma_f32_16x16x32_bf16 v[108:111], v[158:161], v[194:197], v[108:111]
	v_mfma_f32_16x16x32_bf16 v[104:107], v[136:139], v[202:205], v[104:107]
	v_mfma_f32_16x16x32_bf16 v[100:103], v[158:161], v[202:205], v[100:103]
	s_barrier
	s_setprio 0
	s_add_i32 s24, 0, 0x14000
	v_add_u32_e32 v166, s24, v186
	s_add_i32 s0, s0, s17
	ds_read_b128 v[206:209], v166
	ds_read_b128 v[210:213], v166 offset:1024
	ds_read_b128 v[214:217], v166 offset:2048
	ds_read_b128 v[218:221], v166 offset:3072
	v_lshl_add_u64 v[166:167], s[28:29], 0, v[26:27]
	s_mov_b32 m0, s0
	v_lshl_add_u64 v[168:169], s[28:29], 0, v[144:145]
	global_load_lds_dwordx4 v[166:167], off
	s_add_i32 m0, s0, 0x2000
	s_nop 0
	global_load_lds_dwordx4 v[168:169], off
	s_waitcnt vmcnt(10)
	s_setprio 1
	s_barrier
	s_waitcnt lgkmcnt(0)
	v_mfma_f32_16x16x32_bf16 v[68:71], v[206:209], v[162:165], v[68:71]
	v_mfma_f32_16x16x32_bf16 v[60:63], v[214:217], v[162:165], v[60:63]
	v_mfma_f32_16x16x32_bf16 v[56:59], v[206:209], v[176:179], v[56:59]
	v_mfma_f32_16x16x32_bf16 v[52:55], v[214:217], v[176:179], v[52:55]
	v_mfma_f32_16x16x32_bf16 v[48:51], v[206:209], v[190:193], v[48:51]
	v_mfma_f32_16x16x32_bf16 v[44:47], v[214:217], v[190:193], v[44:47]
	v_mfma_f32_16x16x32_bf16 v[40:43], v[206:209], v[198:201], v[40:43]
	v_mfma_f32_16x16x32_bf16 v[36:39], v[214:217], v[198:201], v[36:39]
	v_mfma_f32_16x16x32_bf16 v[68:71], v[210:213], v[172:175], v[68:71]
	v_mfma_f32_16x16x32_bf16 v[60:63], v[218:221], v[172:175], v[60:63]
	v_mfma_f32_16x16x32_bf16 v[56:59], v[210:213], v[180:183], v[56:59]
	v_mfma_f32_16x16x32_bf16 v[52:55], v[218:221], v[180:183], v[52:55]
	v_mfma_f32_16x16x32_bf16 v[48:51], v[210:213], v[194:197], v[48:51]
	v_mfma_f32_16x16x32_bf16 v[44:47], v[218:221], v[194:197], v[44:47]
	v_mfma_f32_16x16x32_bf16 v[40:43], v[210:213], v[202:205], v[40:43]
	v_mfma_f32_16x16x32_bf16 v[36:39], v[218:221], v[202:205], v[36:39]
	s_barrier
	s_setprio 0
	s_mov_b32 m0, s36
	v_lshl_add_u64 v[184:185], s[30:31], 0, v[140:141]
	ds_read_b128 v[162:165], v188 offset:16384
	ds_read_b128 v[172:175], v188 offset:17408
	ds_read_b128 v[176:179], v188 offset:18432
	ds_read_b128 v[180:183], v188 offset:19456
	ds_read_b128 v[190:193], v188 offset:20480
	ds_read_b128 v[194:197], v188 offset:21504
	ds_read_b128 v[198:201], v188 offset:22528
	ds_read_b128 v[202:205], v188 offset:23552
	global_load_lds_dwordx4 v[184:185], off
	v_lshl_add_u64 v[222:223], s[30:31], 0, v[142:143]
	s_mov_b32 m0, s37
	s_nop 0
	global_load_lds_dwordx4 v[222:223], off
	s_waitcnt vmcnt(10)
	s_setprio 1
	s_barrier
	s_waitcnt lgkmcnt(0)
	v_mfma_f32_16x16x32_bf16 v[96:99], v[132:135], v[162:165], v[96:99]
	v_mfma_f32_16x16x32_bf16 v[92:95], v[154:157], v[162:165], v[92:95]
	v_mfma_f32_16x16x32_bf16 v[88:91], v[132:135], v[176:179], v[88:91]
	v_mfma_f32_16x16x32_bf16 v[84:87], v[154:157], v[176:179], v[84:87]
	v_mfma_f32_16x16x32_bf16 v[80:83], v[132:135], v[190:193], v[80:83]
	v_mfma_f32_16x16x32_bf16 v[76:79], v[154:157], v[190:193], v[76:79]
	v_mfma_f32_16x16x32_bf16 v[72:75], v[132:135], v[198:201], v[72:75]
	v_mfma_f32_16x16x32_bf16 v[64:67], v[154:157], v[198:201], v[64:67]
	v_mfma_f32_16x16x32_bf16 v[96:99], v[136:139], v[172:175], v[96:99]
	v_mfma_f32_16x16x32_bf16 v[92:95], v[158:161], v[172:175], v[92:95]
	v_mfma_f32_16x16x32_bf16 v[88:91], v[136:139], v[180:183], v[88:91]
	v_mfma_f32_16x16x32_bf16 v[84:87], v[158:161], v[180:183], v[84:87]
	v_mfma_f32_16x16x32_bf16 v[80:83], v[136:139], v[194:197], v[80:83]
	v_mfma_f32_16x16x32_bf16 v[76:79], v[158:161], v[194:197], v[76:79]
	v_mfma_f32_16x16x32_bf16 v[72:75], v[136:139], v[202:205], v[72:75]
	v_mfma_f32_16x16x32_bf16 v[64:67], v[158:161], v[202:205], v[64:67]
	s_barrier
	s_setprio 0
	s_add_u32 s0, s28, 0xb0000
	s_addc_u32 s1, s29, 0
	s_add_i32 s24, s24, s17
	v_lshl_add_u64 v[132:133], s[0:1], 0, v[26:27]
	s_mov_b32 m0, s24
	s_nop 0
	global_load_lds_dwordx4 v[132:133], off
	v_lshl_add_u64 v[132:133], s[0:1], 0, v[144:145]
	s_add_i32 m0, s24, 0x2000
	s_nop 0
	global_load_lds_dwordx4 v[132:133], off
	v_add_u32_e32 v158, 0x18000, v186
	ds_read_b128 v[132:135], v158
	ds_read_b128 v[136:139], v158 offset:1024
	ds_read_b128 v[154:157], v158 offset:2048
	ds_read_b128 v[158:161], v158 offset:3072
	s_waitcnt vmcnt(10)
	s_setprio 1
	s_barrier
	v_mfma_f32_16x16x32_bf16 v[32:35], v[206:209], v[162:165], v[32:35]
	v_mfma_f32_16x16x32_bf16 v[28:31], v[214:217], v[162:165], v[28:31]
	v_mfma_f32_16x16x32_bf16 v[22:25], v[206:209], v[176:179], v[22:25]
	v_mfma_f32_16x16x32_bf16 v[18:21], v[214:217], v[176:179], v[18:21]
	v_mfma_f32_16x16x32_bf16 v[14:17], v[206:209], v[190:193], v[14:17]
	v_mfma_f32_16x16x32_bf16 v[10:13], v[214:217], v[190:193], v[10:13]
	v_mfma_f32_16x16x32_bf16 v[6:9], v[206:209], v[198:201], v[6:9]
	v_mfma_f32_16x16x32_bf16 v[2:5], v[214:217], v[198:201], v[2:5]
	v_mfma_f32_16x16x32_bf16 v[32:35], v[210:213], v[172:175], v[32:35]
	v_mfma_f32_16x16x32_bf16 v[28:31], v[218:221], v[172:175], v[28:31]
	v_mfma_f32_16x16x32_bf16 v[22:25], v[210:213], v[180:183], v[22:25]
	v_mfma_f32_16x16x32_bf16 v[18:21], v[218:221], v[180:183], v[18:21]
	v_mfma_f32_16x16x32_bf16 v[14:17], v[210:213], v[194:197], v[14:17]
	v_mfma_f32_16x16x32_bf16 v[10:13], v[218:221], v[194:197], v[10:13]
	v_mfma_f32_16x16x32_bf16 v[6:9], v[210:213], v[202:205], v[6:9]
	v_mfma_f32_16x16x32_bf16 v[2:5], v[218:221], v[202:205], v[2:5]
	s_barrier
	s_setprio 0
	s_add_i32 s24, 0, 0x18000
	s_add_u32 s0, s30, 0xb0000
	s_addc_u32 s1, s31, 0
	s_mov_b32 m0, s52
	v_lshl_add_u64 v[206:207], s[0:1], 0, v[140:141]
	ds_read_b128 v[162:165], v188 offset:32768
	ds_read_b128 v[172:175], v188 offset:33792
	ds_read_b128 v[176:179], v188 offset:34816
	ds_read_b128 v[180:183], v188 offset:35840
	ds_read_b128 v[190:193], v188 offset:36864
	ds_read_b128 v[194:197], v188 offset:37888
	ds_read_b128 v[198:201], v188 offset:38912
	ds_read_b128 v[202:205], v188 offset:39936
	global_load_lds_dwordx4 v[206:207], off
	v_lshl_add_u64 v[206:207], s[0:1], 0, v[142:143]
	s_mov_b32 m0, s54
	s_nop 0
	global_load_lds_dwordx4 v[206:207], off
	s_waitcnt vmcnt(10) lgkmcnt(8)
	s_setprio 1
	s_barrier
	s_waitcnt lgkmcnt(0)
	v_mfma_f32_16x16x32_bf16 v[128:131], v[132:135], v[162:165], v[128:131]
	v_mfma_f32_16x16x32_bf16 v[124:127], v[154:157], v[162:165], v[124:127]
	v_mfma_f32_16x16x32_bf16 v[120:123], v[132:135], v[176:179], v[120:123]
	v_mfma_f32_16x16x32_bf16 v[116:119], v[154:157], v[176:179], v[116:119]
	v_mfma_f32_16x16x32_bf16 v[112:115], v[132:135], v[190:193], v[112:115]
	v_mfma_f32_16x16x32_bf16 v[108:111], v[154:157], v[190:193], v[108:111]
	v_mfma_f32_16x16x32_bf16 v[104:107], v[132:135], v[198:201], v[104:107]
	v_mfma_f32_16x16x32_bf16 v[100:103], v[154:157], v[198:201], v[100:103]
	v_mfma_f32_16x16x32_bf16 v[128:131], v[136:139], v[172:175], v[128:131]
	v_mfma_f32_16x16x32_bf16 v[124:127], v[158:161], v[172:175], v[124:127]
	v_mfma_f32_16x16x32_bf16 v[120:123], v[136:139], v[180:183], v[120:123]
	v_mfma_f32_16x16x32_bf16 v[116:119], v[158:161], v[180:183], v[116:119]
	v_mfma_f32_16x16x32_bf16 v[112:115], v[136:139], v[194:197], v[112:115]
	v_mfma_f32_16x16x32_bf16 v[108:111], v[158:161], v[194:197], v[108:111]
	v_mfma_f32_16x16x32_bf16 v[104:107], v[136:139], v[202:205], v[104:107]
	v_mfma_f32_16x16x32_bf16 v[100:103], v[158:161], v[202:205], v[100:103]
	s_barrier
	s_setprio 0
	s_add_i32 s25, 0, 0x1c000
	s_add_i32 s0, s24, s17
	v_add_u32_e32 v189, s25, v186
	v_lshl_add_u64 v[166:167], v[166:167], 0, s[12:13]
	s_mov_b32 m0, s0
	ds_read_b128 v[206:209], v189
	ds_read_b128 v[210:213], v189 offset:1024
	ds_read_b128 v[214:217], v189 offset:2048
	ds_read_b128 v[218:221], v189 offset:3072
	global_load_lds_dwordx4 v[166:167], off
	v_lshl_add_u64 v[166:167], v[168:169], 0, s[12:13]
	s_add_i32 m0, s0, 0x2000
	s_nop 0
	global_load_lds_dwordx4 v[166:167], off
	s_waitcnt vmcnt(10)
	s_setprio 1
	s_barrier
	s_waitcnt lgkmcnt(0)
	v_mfma_f32_16x16x32_bf16 v[68:71], v[206:209], v[162:165], v[68:71]
	v_mfma_f32_16x16x32_bf16 v[60:63], v[214:217], v[162:165], v[60:63]
	v_mfma_f32_16x16x32_bf16 v[56:59], v[206:209], v[176:179], v[56:59]
	v_mfma_f32_16x16x32_bf16 v[52:55], v[214:217], v[176:179], v[52:55]
	v_mfma_f32_16x16x32_bf16 v[48:51], v[206:209], v[190:193], v[48:51]
	v_mfma_f32_16x16x32_bf16 v[44:47], v[214:217], v[190:193], v[44:47]
	v_mfma_f32_16x16x32_bf16 v[40:43], v[206:209], v[198:201], v[40:43]
	v_mfma_f32_16x16x32_bf16 v[36:39], v[214:217], v[198:201], v[36:39]
	v_mfma_f32_16x16x32_bf16 v[68:71], v[210:213], v[172:175], v[68:71]
	v_mfma_f32_16x16x32_bf16 v[60:63], v[218:221], v[172:175], v[60:63]
	v_mfma_f32_16x16x32_bf16 v[56:59], v[210:213], v[180:183], v[56:59]
	v_mfma_f32_16x16x32_bf16 v[52:55], v[218:221], v[180:183], v[52:55]
	v_mfma_f32_16x16x32_bf16 v[48:51], v[210:213], v[194:197], v[48:51]
	v_mfma_f32_16x16x32_bf16 v[44:47], v[218:221], v[194:197], v[44:47]
	v_mfma_f32_16x16x32_bf16 v[40:43], v[210:213], v[202:205], v[40:43]
	v_mfma_f32_16x16x32_bf16 v[36:39], v[218:221], v[202:205], v[36:39]
	s_barrier
	s_setprio 0
	s_mov_b32 m0, s55
	v_lshl_add_u64 v[166:167], v[184:185], 0, s[12:13]
	ds_read_b128 v[162:165], v188 offset:49152
	ds_read_b128 v[172:175], v188 offset:50176
	ds_read_b128 v[176:179], v188 offset:51200
	ds_read_b128 v[180:183], v188 offset:52224
	ds_read_b128 v[190:193], v188 offset:53248
	ds_read_b128 v[194:197], v188 offset:54272
	ds_read_b128 v[198:201], v188 offset:55296
	ds_read_b128 v[202:205], v188 offset:56320
	global_load_lds_dwordx4 v[166:167], off
	v_lshl_add_u64 v[166:167], v[222:223], 0, s[12:13]
	s_mov_b32 m0, s56
	s_nop 0
	global_load_lds_dwordx4 v[166:167], off
	s_waitcnt vmcnt(10)
	s_setprio 1
	s_barrier
	s_waitcnt lgkmcnt(0)
	v_mfma_f32_16x16x32_bf16 v[96:99], v[132:135], v[162:165], v[96:99]
	v_mfma_f32_16x16x32_bf16 v[92:95], v[154:157], v[162:165], v[92:95]
	v_mfma_f32_16x16x32_bf16 v[88:91], v[132:135], v[176:179], v[88:91]
	v_mfma_f32_16x16x32_bf16 v[84:87], v[154:157], v[176:179], v[84:87]
	v_mfma_f32_16x16x32_bf16 v[80:83], v[132:135], v[190:193], v[80:83]
	v_mfma_f32_16x16x32_bf16 v[76:79], v[154:157], v[190:193], v[76:79]
	v_mfma_f32_16x16x32_bf16 v[72:75], v[132:135], v[198:201], v[72:75]
	v_mfma_f32_16x16x32_bf16 v[64:67], v[154:157], v[198:201], v[64:67]
	v_mfma_f32_16x16x32_bf16 v[96:99], v[136:139], v[172:175], v[96:99]
	v_mfma_f32_16x16x32_bf16 v[92:95], v[158:161], v[172:175], v[92:95]
	v_mfma_f32_16x16x32_bf16 v[88:91], v[136:139], v[180:183], v[88:91]
	v_mfma_f32_16x16x32_bf16 v[84:87], v[158:161], v[180:183], v[84:87]
	v_mfma_f32_16x16x32_bf16 v[80:83], v[136:139], v[194:197], v[80:83]
	v_mfma_f32_16x16x32_bf16 v[76:79], v[158:161], v[194:197], v[76:79]
	v_mfma_f32_16x16x32_bf16 v[72:75], v[136:139], v[202:205], v[72:75]
	v_mfma_f32_16x16x32_bf16 v[64:67], v[158:161], v[202:205], v[64:67]
	s_barrier
	s_setprio 0
	s_add_u32 s0, s28, 0xb0080
	s_addc_u32 s1, s29, 0
	s_add_i32 s24, s25, s17
	v_lshl_add_u64 v[132:133], s[0:1], 0, v[26:27]
	s_mov_b32 m0, s24
	s_nop 0
	global_load_lds_dwordx4 v[132:133], off
	v_lshl_add_u64 v[132:133], s[0:1], 0, v[144:145]
	s_add_i32 m0, s24, 0x2000
	s_nop 0
	global_load_lds_dwordx4 v[132:133], off
	v_add_u32_e32 v158, 0x10000, v186
	ds_read_b128 v[132:135], v158
	ds_read_b128 v[136:139], v158 offset:1024
	ds_read_b128 v[154:157], v158 offset:2048
	ds_read_b128 v[158:161], v158 offset:3072
	s_waitcnt vmcnt(10)
	s_setprio 1
	s_barrier
	v_mfma_f32_16x16x32_bf16 v[32:35], v[206:209], v[162:165], v[32:35]
	v_mfma_f32_16x16x32_bf16 v[28:31], v[214:217], v[162:165], v[28:31]
	v_mfma_f32_16x16x32_bf16 v[22:25], v[206:209], v[176:179], v[22:25]
	v_mfma_f32_16x16x32_bf16 v[18:21], v[214:217], v[176:179], v[18:21]
	v_mfma_f32_16x16x32_bf16 v[14:17], v[206:209], v[190:193], v[14:17]
	v_mfma_f32_16x16x32_bf16 v[10:13], v[214:217], v[190:193], v[10:13]
	v_mfma_f32_16x16x32_bf16 v[6:9], v[206:209], v[198:201], v[6:9]
	v_mfma_f32_16x16x32_bf16 v[2:5], v[214:217], v[198:201], v[2:5]
	v_mfma_f32_16x16x32_bf16 v[32:35], v[210:213], v[172:175], v[32:35]
	v_mfma_f32_16x16x32_bf16 v[28:31], v[218:221], v[172:175], v[28:31]
	v_mfma_f32_16x16x32_bf16 v[22:25], v[210:213], v[180:183], v[22:25]
	v_mfma_f32_16x16x32_bf16 v[18:21], v[218:221], v[180:183], v[18:21]
	v_mfma_f32_16x16x32_bf16 v[14:17], v[210:213], v[194:197], v[14:17]
	v_mfma_f32_16x16x32_bf16 v[10:13], v[218:221], v[194:197], v[10:13]
	v_mfma_f32_16x16x32_bf16 v[6:9], v[210:213], v[202:205], v[6:9]
	v_mfma_f32_16x16x32_bf16 v[2:5], v[218:221], v[202:205], v[2:5]
	s_barrier
	s_setprio 0
	s_add_i32 s72, s72, 2
	s_add_u32 s68, s68, 0x100
	s_addc_u32 s69, s69, 0
	s_cmp_gt_u32 s72, 41
	s_mov_b64 s[24:25], s[26:27]
	s_cbranch_scc0 .LBB0_1122
	s_waitcnt lgkmcnt(0)
	s_min_i32 s0, s22, 0x100
	s_ashr_i32 s26, s0, 5
	s_add_i32 s0, s22, 0xffffff00
	s_cmpk_lt_i32 s22, 0x100
	s_cselect_b32 s0, s22, s0
	s_cselect_b32 s25, 0, s51
	s_cselect_b32 s24, 0, s50
	s_ashr_i32 s1, s0, 31
	s_lshl_b64 s[0:1], s[0:1], 19
	s_add_u32 s24, s20, s24
	v_lshl_or_b32 v166, s23, 8, v187
	s_addc_u32 s25, s21, s25
	s_ashr_i32 s23, s22, 31
	v_lshl_add_u64 v[132:133], s[0:1], 0, v[146:147]
	s_lshl_b64 s[22:23], s[22:23], 10
	s_mul_hi_i32 s1, s26, 0x9000
	s_mul_i32 s26, s26, 0x9000
	s_add_u32 s0, s34, s26
	v_ashrrev_i32_e32 v167, 31, v166
	s_addc_u32 s1, s35, s1
	v_lshl_add_u64 v[154:155], v[166:167], 2, s[0:1]
	v_lshl_add_u64 v[168:169], v[132:133], 0, v[166:167]
	v_lshl_add_u64 v[176:177], v[132:133], 1, s[24:25]
	global_load_dwordx4 v[132:135], v[154:155], off offset:16
	global_load_dwordx4 v[136:139], v[154:155], off
	v_lshl_add_u64 v[182:183], v[168:169], 1, s[24:25]
	v_add_co_u32_e32 v184, vcc, s65, v182
	s_mov_b32 s0, 0x20000
	s_nop 0
	v_addc_co_u32_e32 v185, vcc, 0, v183, vcc
	v_add_co_u32_e32 v178, vcc, s0, v182
	s_mov_b32 s1, 0x30000
	s_nop 0
	v_addc_co_u32_e32 v179, vcc, 0, v183, vcc
	v_add_co_u32_e32 v180, vcc, s1, v182
	v_lshl_add_u64 v[176:177], v[166:167], 1, v[176:177]
	s_nop 0
	v_addc_co_u32_e32 v181, vcc, 0, v183, vcc
	s_mov_b32 s24, 0x80000
	s_mov_b32 s25, 0x90000
	s_waitcnt vmcnt(0)
	v_pk_mul_f32 v[164:165], v[134:135], 0.5 op_sel_hi:[1,0]
	v_pk_mul_f32 v[174:175], v[138:139], 0.5 op_sel_hi:[1,0]
	v_pk_mul_f32 v[172:173], v[136:137], 0.5 op_sel_hi:[1,0]
	v_pk_mul_f32 v[162:163], v[132:133], 0.5 op_sel_hi:[1,0]
	global_load_dwordx4 v[132:135], v[154:155], off offset:528
	global_load_dwordx4 v[136:139], v[154:155], off offset:512
	global_load_dwordx4 v[190:193], v[182:183], off offset:2048
	global_load_dwordx4 v[194:197], v[184:185], off offset:2048
	s_waitcnt vmcnt(0)
	v_pk_mul_f32 v[156:157], v[134:135], 0.5 op_sel_hi:[1,0]
	v_pk_mul_f32 v[160:161], v[138:139], 0.5 op_sel_hi:[1,0]
	v_pk_mul_f32 v[158:159], v[136:137], 0.5 op_sel_hi:[1,0]
	global_load_dwordx4 v[136:139], v[178:179], off offset:2048
	v_pk_mul_f32 v[154:155], v[132:133], 0.5 op_sel_hi:[1,0]
	global_load_dwordx4 v[132:135], v[180:181], off offset:2048
	v_lshlrev_b32_e32 v166, 16, v190
	v_and_b32_e32 v167, 0xffff0000, v190
	v_lshlrev_b32_e32 v168, 16, v191
	v_and_b32_e32 v169, 0xffff0000, v191
	v_lshlrev_b32_e32 v190, 16, v192
	v_and_b32_e32 v191, 0xffff0000, v192
	v_lshlrev_b32_e32 v192, 16, v193
	v_and_b32_e32 v193, 0xffff0000, v193
	v_pk_fma_f32 v[130:131], v[130:131], v[174:175], v[168:169]
	v_pk_fma_f32 v[128:129], v[128:129], v[172:173], v[166:167]
	v_pk_fma_f32 v[166:167], v[126:127], v[164:165], v[192:193]
	v_pk_fma_f32 v[126:127], v[124:125], v[162:163], v[190:191]
	v_lshlrev_b32_e32 v202, 16, v196
	v_and_b32_e32 v203, 0xffff0000, v196
	v_lshlrev_b32_e32 v204, 16, v197
	v_and_b32_e32 v205, 0xffff0000, v197
	v_cvt_pk_bf16_f32 v124, v128, v129
	v_cvt_pk_bf16_f32 v125, v130, v131
	v_cvt_pk_bf16_f32 v126, v126, v127
	v_cvt_pk_bf16_f32 v127, v166, v167
	v_lshlrev_b32_e32 v200, 16, v195
	v_and_b32_e32 v201, 0xffff0000, v195
	global_store_dwordx4 v[176:177], v[124:127], off offset:2048
	v_lshlrev_b32_e32 v193, 16, v124
	v_and_b32_e32 v196, 0xffff0000, v124
	v_lshlrev_b32_e32 v191, 16, v125
	v_and_b32_e32 v195, 0xffff0000, v125
	v_pk_fma_f32 v[124:125], v[118:119], v[164:165], v[204:205]
	v_pk_fma_f32 v[118:119], v[116:117], v[162:163], v[202:203]
	v_lshlrev_b32_e32 v198, 16, v194
	v_cvt_pk_bf16_f32 v118, v118, v119
	v_cvt_pk_bf16_f32 v119, v124, v125
	v_add_co_u32_e32 v124, vcc, s65, v176
	v_and_b32_e32 v199, 0xffff0000, v194
	s_nop 0
	v_addc_co_u32_e32 v125, vcc, 0, v177, vcc
	v_lshlrev_b32_e32 v190, 16, v126
	v_and_b32_e32 v194, 0xffff0000, v126
	v_add_co_u32_e32 v126, vcc, s24, v182
	v_lshlrev_b32_e32 v189, 16, v127
	v_and_b32_e32 v192, 0xffff0000, v127
	v_addc_co_u32_e32 v127, vcc, 0, v183, vcc
	v_add_co_u32_e32 v128, vcc, s25, v182
	v_pk_fma_f32 v[122:123], v[122:123], v[174:175], v[200:201]
	v_pk_fma_f32 v[120:121], v[120:121], v[172:173], v[198:199]
	v_addc_co_u32_e32 v129, vcc, 0, v183, vcc
	v_cvt_pk_bf16_f32 v116, v120, v121
	v_cvt_pk_bf16_f32 v117, v122, v123
	global_store_dwordx4 v[124:125], v[116:119], off offset:2048
	global_load_dwordx4 v[120:123], v[126:127], off offset:2048
	global_load_dwordx4 v[198:201], v[128:129], off offset:2048
	s_waitcnt vmcnt(0)
	v_lshlrev_b32_e32 v130, 16, v136
	v_and_b32_e32 v131, 0xffff0000, v136
	v_lshlrev_b32_e32 v166, 16, v138
	v_and_b32_e32 v167, 0xffff0000, v138
	v_lshlrev_b32_e32 v138, 16, v139
	v_and_b32_e32 v139, 0xffff0000, v139
	v_pk_fma_f32 v[112:113], v[112:113], v[172:173], v[130:131]
	v_pk_fma_f32 v[130:131], v[110:111], v[164:165], v[138:139]
	v_pk_fma_f32 v[110:111], v[108:109], v[162:163], v[166:167]
	v_lshlrev_b32_e32 v168, 16, v132
	v_cvt_pk_bf16_f32 v110, v110, v111
	v_cvt_pk_bf16_f32 v111, v130, v131
	v_add_co_u32_e32 v130, vcc, s0, v176
	v_and_b32_e32 v169, 0xffff0000, v132
	v_lshlrev_b32_e32 v132, 16, v133
	v_and_b32_e32 v133, 0xffff0000, v133
	v_addc_co_u32_e32 v131, vcc, 0, v177, vcc
	v_lshlrev_b32_e32 v136, 16, v137
	v_and_b32_e32 v137, 0xffff0000, v137
	v_lshlrev_b32_e32 v202, 16, v134
	v_and_b32_e32 v203, 0xffff0000, v134
	v_lshlrev_b32_e32 v134, 16, v135
	v_and_b32_e32 v135, 0xffff0000, v135
	v_pk_fma_f32 v[106:107], v[106:107], v[174:175], v[132:133]
	v_add_co_u32_e32 v132, vcc, s1, v176
	v_pk_fma_f32 v[114:115], v[114:115], v[174:175], v[136:137]
	v_cvt_pk_bf16_f32 v108, v112, v113
	v_pk_fma_f32 v[104:105], v[104:105], v[172:173], v[168:169]
	v_pk_fma_f32 v[112:113], v[102:103], v[164:165], v[134:135]
	v_pk_fma_f32 v[102:103], v[100:101], v[162:163], v[202:203]
	v_addc_co_u32_e32 v133, vcc, 0, v177, vcc
	v_cvt_pk_bf16_f32 v109, v114, v115
	v_cvt_pk_bf16_f32 v100, v104, v105
	v_cvt_pk_bf16_f32 v101, v106, v107
	v_cvt_pk_bf16_f32 v102, v102, v103
	v_cvt_pk_bf16_f32 v103, v112, v113
	v_add_co_u32_e32 v134, vcc, s76, v182
	global_store_dwordx4 v[130:131], v[108:111], off offset:2048
	global_store_dwordx4 v[132:133], v[100:103], off offset:2048
	v_addc_co_u32_e32 v135, vcc, 0, v183, vcc
	s_mov_b32 s0, 0xb0000
	global_load_dwordx4 v[112:115], v[134:135], off offset:2048
	v_add_co_u32_e32 v136, vcc, s0, v182
	v_lshlrev_b32_e32 v138, 16, v120
	s_nop 0
	v_addc_co_u32_e32 v137, vcc, 0, v183, vcc
	global_load_dwordx4 v[104:107], v[136:137], off offset:2048
	v_and_b32_e32 v139, 0xffff0000, v120
	v_lshlrev_b32_e32 v120, 16, v121
	v_and_b32_e32 v121, 0xffff0000, v121
	v_lshlrev_b32_e32 v166, 16, v122
	v_and_b32_e32 v167, 0xffff0000, v122
	v_lshlrev_b32_e32 v122, 16, v123
	v_and_b32_e32 v123, 0xffff0000, v123
	v_pk_fma_f32 v[96:97], v[96:97], v[172:173], v[138:139]
	v_lshlrev_b32_e32 v168, 16, v198
	v_and_b32_e32 v169, 0xffff0000, v198
	v_lshlrev_b32_e32 v198, 16, v199
	v_and_b32_e32 v199, 0xffff0000, v199
	v_pk_fma_f32 v[98:99], v[98:99], v[174:175], v[120:121]
	v_pk_fma_f32 v[120:121], v[94:95], v[164:165], v[122:123]
	v_pk_fma_f32 v[94:95], v[92:93], v[162:163], v[166:167]
	v_cvt_pk_bf16_f32 v92, v96, v97
	v_add_co_u32_e32 v96, vcc, s24, v176
	v_lshlrev_b32_e32 v202, 16, v200
	v_and_b32_e32 v203, 0xffff0000, v200
	v_lshlrev_b32_e32 v200, 16, v201
	v_and_b32_e32 v201, 0xffff0000, v201
	v_addc_co_u32_e32 v97, vcc, 0, v177, vcc
	v_pk_fma_f32 v[90:91], v[90:91], v[174:175], v[198:199]
	v_pk_fma_f32 v[88:89], v[88:89], v[172:173], v[168:169]
	v_cvt_pk_bf16_f32 v93, v98, v99
	v_pk_fma_f32 v[98:99], v[86:87], v[164:165], v[200:201]
	v_pk_fma_f32 v[86:87], v[84:85], v[162:163], v[202:203]
	v_cvt_pk_bf16_f32 v84, v88, v89
	v_cvt_pk_bf16_f32 v85, v90, v91
	v_add_co_u32_e32 v88, vcc, s25, v176
	v_cvt_pk_bf16_f32 v86, v86, v87
	v_cvt_pk_bf16_f32 v87, v98, v99
	v_addc_co_u32_e32 v89, vcc, 0, v177, vcc
	v_cvt_pk_bf16_f32 v94, v94, v95
	v_cvt_pk_bf16_f32 v95, v120, v121
	global_store_dwordx4 v[96:97], v[92:95], off offset:2048
	global_store_dwordx4 v[88:89], v[84:87], off offset:2048
	global_load_dwordx4 v[120:123], v[182:183], off offset:2304
	s_nop 0
	global_load_dwordx4 v[182:185], v[184:185], off offset:2304
	s_waitcnt vmcnt(0)
	v_lshlrev_b32_e32 v90, 16, v112
	v_and_b32_e32 v91, 0xffff0000, v112
	v_lshlrev_b32_e32 v98, 16, v113
	v_and_b32_e32 v99, 0xffff0000, v113
	v_lshlrev_b32_e32 v112, 16, v114
	v_and_b32_e32 v113, 0xffff0000, v114
	v_lshlrev_b32_e32 v114, 16, v115
	v_and_b32_e32 v115, 0xffff0000, v115
	v_pk_fma_f32 v[80:81], v[80:81], v[172:173], v[90:91]
	v_pk_fma_f32 v[90:91], v[78:79], v[164:165], v[114:115]
	v_pk_fma_f32 v[78:79], v[76:77], v[162:163], v[112:113]
	v_cvt_pk_bf16_f32 v76, v80, v81
	v_add_co_u32_e32 v80, vcc, s76, v176
	v_lshlrev_b32_e32 v138, 16, v104
	v_and_b32_e32 v139, 0xffff0000, v104
	v_lshlrev_b32_e32 v104, 16, v105
	v_and_b32_e32 v105, 0xffff0000, v105
	v_lshlrev_b32_e32 v166, 16, v106
	v_and_b32_e32 v167, 0xffff0000, v106
	v_lshlrev_b32_e32 v106, 16, v107
	v_and_b32_e32 v107, 0xffff0000, v107
	v_pk_fma_f32 v[82:83], v[82:83], v[174:175], v[98:99]
	v_addc_co_u32_e32 v81, vcc, 0, v177, vcc
	v_pk_fma_f32 v[72:73], v[72:73], v[172:173], v[138:139]
	v_cvt_pk_bf16_f32 v77, v82, v83
	v_pk_fma_f32 v[74:75], v[74:75], v[174:175], v[104:105]
	v_pk_fma_f32 v[82:83], v[66:67], v[164:165], v[106:107]
	v_pk_fma_f32 v[66:67], v[64:65], v[162:163], v[166:167]
	v_cvt_pk_bf16_f32 v64, v72, v73
	v_add_co_u32_e32 v72, vcc, s0, v176
	v_cvt_pk_bf16_f32 v78, v78, v79
	v_cvt_pk_bf16_f32 v79, v90, v91
	v_cvt_pk_bf16_f32 v65, v74, v75
	v_cvt_pk_bf16_f32 v66, v66, v67
	v_cvt_pk_bf16_f32 v67, v82, v83
	v_addc_co_u32_e32 v73, vcc, 0, v177, vcc
	global_store_dwordx4 v[80:81], v[76:79], off offset:2048
	global_store_dwordx4 v[72:73], v[64:67], off offset:2048
	global_load_dwordx4 v[104:107], v[178:179], off offset:2304
	global_load_dwordx4 v[112:115], v[180:181], off offset:2304
	v_lshlrev_b32_e32 v74, 16, v120
	v_and_b32_e32 v75, 0xffff0000, v120
	v_lshlrev_b32_e32 v82, 16, v121
	v_and_b32_e32 v83, 0xffff0000, v121
	v_lshlrev_b32_e32 v90, 16, v122
	v_and_b32_e32 v91, 0xffff0000, v122
	v_lshlrev_b32_e32 v98, 16, v123
	v_and_b32_e32 v99, 0xffff0000, v123
	v_pk_fma_f32 v[70:71], v[70:71], v[160:161], v[82:83]
	v_pk_fma_f32 v[68:69], v[68:69], v[158:159], v[74:75]
	v_pk_fma_f32 v[74:75], v[62:63], v[156:157], v[98:99]
	v_pk_fma_f32 v[62:63], v[60:61], v[154:155], v[90:91]
	v_lshlrev_b32_e32 v120, 16, v182
	v_and_b32_e32 v121, 0xffff0000, v182
	v_lshlrev_b32_e32 v122, 16, v183
	v_and_b32_e32 v123, 0xffff0000, v183
	v_lshlrev_b32_e32 v138, 16, v184
	v_and_b32_e32 v139, 0xffff0000, v184
	v_lshlrev_b32_e32 v162, 16, v185
	v_and_b32_e32 v163, 0xffff0000, v185
	v_cvt_pk_bf16_f32 v60, v68, v69
	v_cvt_pk_bf16_f32 v61, v70, v71
	v_cvt_pk_bf16_f32 v62, v62, v63
	v_cvt_pk_bf16_f32 v63, v74, v75
	global_store_dwordx4 v[176:177], v[60:63], off offset:2304
	v_lshlrev_b32_e32 v164, 16, v60
	v_and_b32_e32 v165, 0xffff0000, v60
	v_lshlrev_b32_e32 v166, 16, v61
	v_and_b32_e32 v167, 0xffff0000, v61
	v_pk_fma_f32 v[58:59], v[58:59], v[160:161], v[122:123]
	v_pk_fma_f32 v[56:57], v[56:57], v[158:159], v[120:121]
	v_pk_fma_f32 v[60:61], v[54:55], v[156:157], v[162:163]
	v_pk_fma_f32 v[54:55], v[52:53], v[154:155], v[138:139]
	v_cvt_pk_bf16_f32 v52, v56, v57
	v_cvt_pk_bf16_f32 v53, v58, v59
	v_cvt_pk_bf16_f32 v54, v54, v55
	v_cvt_pk_bf16_f32 v55, v60, v61
	global_store_dwordx4 v[124:125], v[52:55], off offset:2304
	v_lshlrev_b32_e32 v168, 16, v62
	v_and_b32_e32 v169, 0xffff0000, v62
	v_lshlrev_b32_e32 v172, 16, v63
	v_and_b32_e32 v173, 0xffff0000, v63
	global_load_dwordx4 v[56:59], v[126:127], off offset:2304
	global_load_dwordx4 v[60:63], v[128:129], off offset:2304
	s_waitcnt vmcnt(0)
	v_lshlrev_b32_e32 v68, 16, v104
	v_and_b32_e32 v69, 0xffff0000, v104
	v_lshlrev_b32_e32 v70, 16, v105
	v_and_b32_e32 v71, 0xffff0000, v105
	v_lshlrev_b32_e32 v74, 16, v106
	v_and_b32_e32 v75, 0xffff0000, v106
	v_lshlrev_b32_e32 v82, 16, v107
	v_and_b32_e32 v83, 0xffff0000, v107
	v_lshlrev_b32_e32 v90, 16, v112
	v_and_b32_e32 v91, 0xffff0000, v112
	v_lshlrev_b32_e32 v98, 16, v113
	v_and_b32_e32 v99, 0xffff0000, v113
	v_lshlrev_b32_e32 v104, 16, v114
	v_and_b32_e32 v105, 0xffff0000, v114
	v_lshlrev_b32_e32 v106, 16, v115
	v_and_b32_e32 v107, 0xffff0000, v115
	v_pk_fma_f32 v[48:49], v[48:49], v[158:159], v[68:69]
	v_pk_fma_f32 v[50:51], v[50:51], v[160:161], v[70:71]
	v_pk_fma_f32 v[68:69], v[46:47], v[156:157], v[82:83]
	v_pk_fma_f32 v[46:47], v[44:45], v[154:155], v[74:75]
	v_cvt_pk_bf16_f32 v44, v48, v49
	v_pk_fma_f32 v[42:43], v[42:43], v[160:161], v[98:99]
	v_pk_fma_f32 v[40:41], v[40:41], v[158:159], v[90:91]
	v_pk_fma_f32 v[48:49], v[38:39], v[156:157], v[106:107]
	v_pk_fma_f32 v[38:39], v[36:37], v[154:155], v[104:105]
	v_cvt_pk_bf16_f32 v45, v50, v51
	v_cvt_pk_bf16_f32 v46, v46, v47
	v_cvt_pk_bf16_f32 v47, v68, v69
	v_cvt_pk_bf16_f32 v36, v40, v41
	v_cvt_pk_bf16_f32 v37, v42, v43
	v_cvt_pk_bf16_f32 v38, v38, v39
	v_cvt_pk_bf16_f32 v39, v48, v49
	global_store_dwordx4 v[130:131], v[44:47], off offset:2304
	global_store_dwordx4 v[132:133], v[36:39], off offset:2304
	global_load_dwordx4 v[40:43], v[134:135], off offset:2304
	global_load_dwordx4 v[48:51], v[136:137], off offset:2304
	v_lshlrev_b32_e32 v68, 16, v56
	v_and_b32_e32 v69, 0xffff0000, v56
	v_lshlrev_b32_e32 v56, 16, v57
	v_and_b32_e32 v57, 0xffff0000, v57
	v_lshlrev_b32_e32 v70, 16, v58
	v_and_b32_e32 v71, 0xffff0000, v58
	v_lshlrev_b32_e32 v58, 16, v59
	v_and_b32_e32 v59, 0xffff0000, v59
	v_lshlrev_b32_e32 v74, 16, v60
	v_and_b32_e32 v75, 0xffff0000, v60
	v_lshlrev_b32_e32 v82, 16, v62
	v_and_b32_e32 v83, 0xffff0000, v62
	v_lshlrev_b32_e32 v62, 16, v63
	v_and_b32_e32 v63, 0xffff0000, v63
	v_pk_fma_f32 v[32:33], v[32:33], v[158:159], v[68:69]
	v_lshlrev_b32_e32 v60, 16, v61
	v_and_b32_e32 v61, 0xffff0000, v61
	v_pk_fma_f32 v[34:35], v[34:35], v[160:161], v[56:57]
	v_pk_fma_f32 v[56:57], v[30:31], v[156:157], v[58:59]
	v_pk_fma_f32 v[30:31], v[28:29], v[154:155], v[70:71]
	v_cvt_pk_bf16_f32 v28, v32, v33
	v_pk_fma_f32 v[22:23], v[22:23], v[158:159], v[74:75]
	v_pk_fma_f32 v[32:33], v[20:21], v[156:157], v[62:63]
	v_pk_fma_f32 v[20:21], v[18:19], v[154:155], v[82:83]
	v_cvt_pk_bf16_f32 v29, v34, v35
	v_pk_fma_f32 v[24:25], v[24:25], v[160:161], v[60:61]
	v_cvt_pk_bf16_f32 v18, v22, v23
	v_cvt_pk_bf16_f32 v20, v20, v21
	v_cvt_pk_bf16_f32 v21, v32, v33
	v_cvt_pk_bf16_f32 v19, v24, v25
	v_cvt_pk_bf16_f32 v30, v30, v31
	v_cvt_pk_bf16_f32 v31, v56, v57
	global_store_dwordx4 v[96:97], v[28:31], off offset:2304
	global_store_dwordx4 v[88:89], v[18:21], off offset:2304
	s_waitcnt vmcnt(0)
	v_lshlrev_b32_e32 v22, 16, v40
	v_and_b32_e32 v23, 0xffff0000, v40
	v_lshlrev_b32_e32 v32, 16, v42
	v_and_b32_e32 v33, 0xffff0000, v42
	v_lshlrev_b32_e32 v34, 16, v43
	v_and_b32_e32 v35, 0xffff0000, v43
	v_lshlrev_b32_e32 v42, 16, v49
	v_and_b32_e32 v43, 0xffff0000, v49
	v_lshlrev_b32_e32 v24, 16, v41
	v_and_b32_e32 v25, 0xffff0000, v41
	v_lshlrev_b32_e32 v40, 16, v48
	v_and_b32_e32 v41, 0xffff0000, v48
	v_lshlrev_b32_e32 v48, 16, v50
	v_and_b32_e32 v49, 0xffff0000, v50
	v_lshlrev_b32_e32 v50, 16, v51
	v_and_b32_e32 v51, 0xffff0000, v51
	v_pk_fma_f32 v[14:15], v[14:15], v[158:159], v[22:23]
	v_pk_fma_f32 v[8:9], v[8:9], v[160:161], v[42:43]
	v_pk_fma_f32 v[22:23], v[12:13], v[156:157], v[34:35]
	v_pk_fma_f32 v[12:13], v[10:11], v[154:155], v[32:33]
	v_cvt_pk_bf16_f32 v10, v14, v15
	v_pk_fma_f32 v[14:15], v[4:5], v[156:157], v[50:51]
	v_pk_fma_f32 v[4:5], v[2:3], v[154:155], v[48:49]
	v_cvt_pk_bf16_f32 v3, v8, v9
	v_and_b32_e32 v9, 64, v227
	v_xor_b32_e32 v8, 16, v227
	v_add_u32_e32 v9, 64, v9
	v_cvt_pk_bf16_f32 v4, v4, v5
	v_cvt_pk_bf16_f32 v5, v14, v15
	v_cmp_lt_i32_e32 vcc, v8, v9
	v_xor_b32_e32 v14, 32, v227
	v_mul_f32_e32 v15, v195, v195
	v_cndmask_b32_e32 v8, v227, v8, vcc
	v_cmp_lt_i32_e32 vcc, v14, v9
	v_pk_fma_f32 v[16:17], v[16:17], v[160:161], v[24:25]
	v_fmac_f32_e32 v15, v191, v191
	v_cndmask_b32_e32 v9, v227, v14, vcc
	v_mul_f32_e32 v14, v196, v196
	v_fmac_f32_e32 v14, v193, v193
	v_cvt_pk_bf16_f32 v11, v16, v17
	v_add_f32_e32 v14, v14, v15
	v_mul_f32_e32 v15, v194, v194
	v_mul_f32_e32 v16, v192, v192
	v_fmac_f32_e32 v15, v190, v190
	v_fmac_f32_e32 v16, v189, v189
	v_add_f32_e32 v15, v15, v16
	v_add_f32_e32 v14, v14, v15
	v_mul_f32_e32 v15, v165, v165
	v_mul_f32_e32 v16, v167, v167
	v_fmac_f32_e32 v15, v164, v164
	v_fmac_f32_e32 v16, v166, v166
	v_add_f32_e32 v15, v15, v16
	v_add_f32_e32 v14, v14, v15
	v_mul_f32_e32 v15, v169, v169
	v_mul_f32_e32 v16, v173, v173
	v_fmac_f32_e32 v15, v168, v168
	v_fmac_f32_e32 v16, v172, v172
	v_add_f32_e32 v15, v15, v16
	v_lshlrev_b32_e32 v8, 2, v8
	v_add_f32_e32 v14, v15, v14
	ds_bpermute_b32 v15, v8, v14
	v_lshlrev_b32_e32 v9, 2, v9
	v_pk_fma_f32 v[6:7], v[6:7], v[158:159], v[40:41]
	v_cvt_pk_bf16_f32 v12, v12, v13
	v_cvt_pk_bf16_f32 v13, v22, v23
	s_waitcnt lgkmcnt(0)
	v_add_f32_e32 v14, v14, v15
	ds_bpermute_b32 v15, v9, v14
	v_cvt_pk_bf16_f32 v2, v6, v7
	v_lshl_add_u64 v[6:7], v[148:149], 0, s[22:23]
	global_store_dwordx4 v[80:81], v[10:13], off offset:2304
	global_store_dwordx4 v[72:73], v[2:5], off offset:2304
	s_and_saveexec_b64 s[22:23], s[38:39]
	s_cbranch_execz .LBB0_1125
	s_waitcnt lgkmcnt(0)
	v_add_f32_e32 v14, v14, v15
	global_atomic_add_f32 v[6:7], v14, off

.LBB0_1155:
	s_add_u32 s44, s28, 0x100
	v_mov_b32_e32 v2, 0
	s_addc_u32 s45, s29, 0
	s_mov_b32 s81, -2
	v_mov_b32_e32 v3, v2
	v_mov_b32_e32 v4, v2
	v_mov_b32_e32 v5, v2
	v_mov_b32_e32 v6, v2
	v_mov_b32_e32 v7, v2
	v_mov_b32_e32 v8, v2
	v_mov_b32_e32 v9, v2
	v_mov_b32_e32 v10, v2
	v_mov_b32_e32 v11, v2
	v_mov_b32_e32 v12, v2
	v_mov_b32_e32 v13, v2
	v_mov_b32_e32 v14, v2
	v_mov_b32_e32 v15, v2
	v_mov_b32_e32 v16, v2
	v_mov_b32_e32 v17, v2
	v_mov_b32_e32 v18, v2
	v_mov_b32_e32 v19, v2
	v_mov_b32_e32 v20, v2
	v_mov_b32_e32 v21, v2
	v_mov_b32_e32 v22, v2
	v_mov_b32_e32 v23, v2
	v_mov_b32_e32 v24, v2
	v_mov_b32_e32 v25, v2
	v_mov_b32_e32 v28, v2
	v_mov_b32_e32 v29, v2
	v_mov_b32_e32 v30, v2
	v_mov_b32_e32 v31, v2
	v_mov_b32_e32 v32, v2
	v_mov_b32_e32 v33, v2
	v_mov_b32_e32 v34, v2
	v_mov_b32_e32 v35, v2
	v_mov_b32_e32 v68, v2
	v_mov_b32_e32 v69, v2
	v_mov_b32_e32 v70, v2
	v_mov_b32_e32 v71, v2
	v_mov_b32_e32 v72, v2
	v_mov_b32_e32 v73, v2
	v_mov_b32_e32 v74, v2
	v_mov_b32_e32 v75, v2
	v_mov_b32_e32 v76, v2
	v_mov_b32_e32 v77, v2
	v_mov_b32_e32 v78, v2
	v_mov_b32_e32 v79, v2
	v_mov_b32_e32 v80, v2
	v_mov_b32_e32 v81, v2
	v_mov_b32_e32 v82, v2
	v_mov_b32_e32 v83, v2
	v_mov_b32_e32 v84, v2
	v_mov_b32_e32 v85, v2
	v_mov_b32_e32 v86, v2
	v_mov_b32_e32 v87, v2
	v_mov_b32_e32 v88, v2
	v_mov_b32_e32 v89, v2
	v_mov_b32_e32 v90, v2
	v_mov_b32_e32 v91, v2
	v_mov_b32_e32 v92, v2
	v_mov_b32_e32 v93, v2
	v_mov_b32_e32 v94, v2
	v_mov_b32_e32 v95, v2
	v_mov_b32_e32 v96, v2
	v_mov_b32_e32 v97, v2
	v_mov_b32_e32 v98, v2
	v_mov_b32_e32 v99, v2
	s_waitcnt vmcnt(0)
	v_mov_b32_e32 v36, v2
	v_mov_b32_e32 v37, v2
	v_mov_b32_e32 v38, v2
	v_mov_b32_e32 v39, v2
	v_mov_b32_e32 v40, v2
	v_mov_b32_e32 v41, v2
	v_mov_b32_e32 v42, v2
	v_mov_b32_e32 v43, v2
	v_mov_b32_e32 v44, v2
	v_mov_b32_e32 v45, v2
	v_mov_b32_e32 v46, v2
	v_mov_b32_e32 v47, v2
	v_mov_b32_e32 v48, v2
	v_mov_b32_e32 v49, v2
	v_mov_b32_e32 v50, v2
	v_mov_b32_e32 v51, v2
	v_mov_b32_e32 v52, v2
	v_mov_b32_e32 v53, v2
	v_mov_b32_e32 v54, v2
	v_mov_b32_e32 v55, v2
	v_mov_b32_e32 v56, v2
	v_mov_b32_e32 v57, v2
	v_mov_b32_e32 v58, v2
	v_mov_b32_e32 v59, v2
	v_mov_b32_e32 v60, v2
	v_mov_b32_e32 v61, v2
	v_mov_b32_e32 v62, v2
	v_mov_b32_e32 v63, v2
	v_mov_b32_e32 v64, v2
	v_mov_b32_e32 v65, v2
	v_mov_b32_e32 v66, v2
	v_mov_b32_e32 v67, v2
	v_mov_b32_e32 v100, v2
	v_mov_b32_e32 v101, v2
	v_mov_b32_e32 v102, v2
	v_mov_b32_e32 v103, v2
	v_mov_b32_e32 v104, v2
	v_mov_b32_e32 v105, v2
	v_mov_b32_e32 v106, v2
	v_mov_b32_e32 v107, v2
	v_mov_b32_e32 v108, v2
	v_mov_b32_e32 v109, v2
	v_mov_b32_e32 v110, v2
	v_mov_b32_e32 v111, v2
	v_mov_b32_e32 v112, v2
	v_mov_b32_e32 v113, v2
	v_mov_b32_e32 v114, v2
	v_mov_b32_e32 v115, v2
	v_mov_b32_e32 v116, v2
	v_mov_b32_e32 v117, v2
	v_mov_b32_e32 v118, v2
	v_mov_b32_e32 v119, v2
	v_mov_b32_e32 v120, v2
	v_mov_b32_e32 v121, v2
	v_mov_b32_e32 v122, v2
	v_mov_b32_e32 v123, v2
	v_mov_b32_e32 v124, v2
	v_mov_b32_e32 v125, v2
	v_mov_b32_e32 v126, v2
	v_mov_b32_e32 v127, v2
	v_mov_b32_e32 v128, v2
	v_mov_b32_e32 v129, v2
	v_mov_b32_e32 v130, v2
	v_mov_b32_e32 v131, v2
	v_add_u32_e32 v160, 0x10000, v222
	ds_read_b128 v[132:135], v160
	ds_read_b128 v[136:139], v160 offset:1024
	ds_read_b128 v[156:159], v160 offset:2048
	ds_read_b128 v[160:163], v160 offset:3072
.LBB0_1156:
	s_add_u32 s28, s26, 0x100
	s_addc_u32 s29, s27, 0
	s_add_i32 s0, 0, 0x10000
	s_cmp_eq_u32 s81, 40
	s_cselect_b32 s35, s43, s29
	s_cselect_b32 s34, s42, s28
	s_cselect_b32 s31, s23, s45
	s_cselect_b32 s30, s22, s44
	v_lshl_add_u64 v[164:165], s[26:27], 0, v[152:153]
	s_add_i32 m0, s52, 0xc000
	ds_read_b128 v[172:175], v224
	ds_read_b128 v[176:179], v224 offset:1024
	ds_read_b128 v[180:183], v224 offset:2048
	ds_read_b128 v[184:187], v224 offset:3072
	ds_read_b128 v[188:191], v224 offset:4096
	ds_read_b128 v[192:195], v224 offset:5120
	ds_read_b128 v[196:199], v224 offset:6144
	ds_read_b128 v[200:203], v224 offset:7168
	global_load_lds_dwordx4 v[164:165], off
	v_lshl_add_u64 v[164:165], s[26:27], 0, v[154:155]
	s_add_i32 m0, s52, 0xe000
	s_nop 0
	global_load_lds_dwordx4 v[164:165], off
	s_waitcnt vmcnt(10) lgkmcnt(8)
	s_setprio 1
	s_barrier
	s_waitcnt lgkmcnt(0)
	v_mfma_f32_16x16x32_bf16 v[128:131], v[132:135], v[172:175], v[128:131]
	v_mfma_f32_16x16x32_bf16 v[124:127], v[156:159], v[172:175], v[124:127]
	v_mfma_f32_16x16x32_bf16 v[120:123], v[132:135], v[180:183], v[120:123]
	v_mfma_f32_16x16x32_bf16 v[116:119], v[156:159], v[180:183], v[116:119]
	v_mfma_f32_16x16x32_bf16 v[112:115], v[132:135], v[188:191], v[112:115]
	v_mfma_f32_16x16x32_bf16 v[108:111], v[156:159], v[188:191], v[108:111]
	v_mfma_f32_16x16x32_bf16 v[104:107], v[132:135], v[196:199], v[104:107]
	v_mfma_f32_16x16x32_bf16 v[100:103], v[156:159], v[196:199], v[100:103]
	v_mfma_f32_16x16x32_bf16 v[128:131], v[136:139], v[176:179], v[128:131]
	v_mfma_f32_16x16x32_bf16 v[124:127], v[160:163], v[176:179], v[124:127]
	v_mfma_f32_16x16x32_bf16 v[120:123], v[136:139], v[184:187], v[120:123]
	v_mfma_f32_16x16x32_bf16 v[116:119], v[160:163], v[184:187], v[116:119]
	v_mfma_f32_16x16x32_bf16 v[112:115], v[136:139], v[192:195], v[112:115]
	v_mfma_f32_16x16x32_bf16 v[108:111], v[160:163], v[192:195], v[108:111]
	v_mfma_f32_16x16x32_bf16 v[104:107], v[136:139], v[200:203], v[104:107]
	v_mfma_f32_16x16x32_bf16 v[100:103], v[160:163], v[200:203], v[100:103]
	s_barrier
	s_setprio 0
	s_add_i32 s26, 0, 0x14000
	v_add_u32_e32 v164, s26, v222
	s_add_i32 s0, s0, s17
	ds_read_b128 v[204:207], v164
	ds_read_b128 v[208:211], v164 offset:1024
	ds_read_b128 v[212:215], v164 offset:2048
	ds_read_b128 v[216:219], v164 offset:3072
	v_lshl_add_u64 v[164:165], s[30:31], 0, v[26:27]
	s_mov_b32 m0, s0
	v_lshl_add_u64 v[166:167], s[30:31], 0, v[144:145]
	global_load_lds_dwordx4 v[164:165], off
	s_add_i32 m0, s0, 0x2000
	s_nop 0
	global_load_lds_dwordx4 v[166:167], off
	s_waitcnt vmcnt(10)
	s_setprio 1
	s_barrier
	s_waitcnt lgkmcnt(0)
	v_mfma_f32_16x16x32_bf16 v[64:67], v[204:207], v[172:175], v[64:67]
	v_mfma_f32_16x16x32_bf16 v[60:63], v[212:215], v[172:175], v[60:63]
	v_mfma_f32_16x16x32_bf16 v[56:59], v[204:207], v[180:183], v[56:59]
	v_mfma_f32_16x16x32_bf16 v[52:55], v[212:215], v[180:183], v[52:55]
	v_mfma_f32_16x16x32_bf16 v[48:51], v[204:207], v[188:191], v[48:51]
	v_mfma_f32_16x16x32_bf16 v[44:47], v[212:215], v[188:191], v[44:47]
	v_mfma_f32_16x16x32_bf16 v[40:43], v[204:207], v[196:199], v[40:43]
	v_mfma_f32_16x16x32_bf16 v[36:39], v[212:215], v[196:199], v[36:39]
	v_mfma_f32_16x16x32_bf16 v[64:67], v[208:211], v[176:179], v[64:67]
	v_mfma_f32_16x16x32_bf16 v[60:63], v[216:219], v[176:179], v[60:63]
	v_mfma_f32_16x16x32_bf16 v[56:59], v[208:211], v[184:187], v[56:59]
	v_mfma_f32_16x16x32_bf16 v[52:55], v[216:219], v[184:187], v[52:55]
	v_mfma_f32_16x16x32_bf16 v[48:51], v[208:211], v[192:195], v[48:51]
	v_mfma_f32_16x16x32_bf16 v[44:47], v[216:219], v[192:195], v[44:47]
	v_mfma_f32_16x16x32_bf16 v[40:43], v[208:211], v[200:203], v[40:43]
	v_mfma_f32_16x16x32_bf16 v[36:39], v[216:219], v[200:203], v[36:39]
	s_barrier
	s_setprio 0
	s_mov_b32 m0, s52
	v_lshl_add_u64 v[168:169], s[34:35], 0, v[140:141]
	ds_read_b128 v[172:175], v224 offset:16384
	ds_read_b128 v[176:179], v224 offset:17408
	ds_read_b128 v[180:183], v224 offset:18432
	ds_read_b128 v[184:187], v224 offset:19456
	ds_read_b128 v[188:191], v224 offset:20480
	ds_read_b128 v[192:195], v224 offset:21504
	ds_read_b128 v[196:199], v224 offset:22528
	ds_read_b128 v[200:203], v224 offset:23552
	global_load_lds_dwordx4 v[168:169], off
	v_lshl_add_u64 v[220:221], s[34:35], 0, v[142:143]
	s_mov_b32 m0, s54
	s_nop 0
	global_load_lds_dwordx4 v[220:221], off
	s_waitcnt vmcnt(10)
	s_setprio 1
	s_barrier
	s_waitcnt lgkmcnt(0)
	v_mfma_f32_16x16x32_bf16 v[96:99], v[132:135], v[172:175], v[96:99]
	v_mfma_f32_16x16x32_bf16 v[92:95], v[156:159], v[172:175], v[92:95]
	v_mfma_f32_16x16x32_bf16 v[88:91], v[132:135], v[180:183], v[88:91]
	v_mfma_f32_16x16x32_bf16 v[84:87], v[156:159], v[180:183], v[84:87]
	v_mfma_f32_16x16x32_bf16 v[80:83], v[132:135], v[188:191], v[80:83]
	v_mfma_f32_16x16x32_bf16 v[76:79], v[156:159], v[188:191], v[76:79]
	v_mfma_f32_16x16x32_bf16 v[72:75], v[132:135], v[196:199], v[72:75]
	v_mfma_f32_16x16x32_bf16 v[68:71], v[156:159], v[196:199], v[68:71]
	v_mfma_f32_16x16x32_bf16 v[96:99], v[136:139], v[176:179], v[96:99]
	v_mfma_f32_16x16x32_bf16 v[92:95], v[160:163], v[176:179], v[92:95]
	v_mfma_f32_16x16x32_bf16 v[88:91], v[136:139], v[184:187], v[88:91]
	v_mfma_f32_16x16x32_bf16 v[84:87], v[160:163], v[184:187], v[84:87]
	v_mfma_f32_16x16x32_bf16 v[80:83], v[136:139], v[192:195], v[80:83]
	v_mfma_f32_16x16x32_bf16 v[76:79], v[160:163], v[192:195], v[76:79]
	v_mfma_f32_16x16x32_bf16 v[72:75], v[136:139], v[200:203], v[72:75]
	v_mfma_f32_16x16x32_bf16 v[68:71], v[160:163], v[200:203], v[68:71]
	s_barrier
	s_setprio 0
	s_add_u32 s0, s30, 0xb0000
	s_addc_u32 s1, s31, 0
	s_add_i32 s26, s26, s17
	v_lshl_add_u64 v[132:133], s[0:1], 0, v[26:27]
	s_mov_b32 m0, s26
	s_nop 0
	global_load_lds_dwordx4 v[132:133], off
	v_lshl_add_u64 v[132:133], s[0:1], 0, v[144:145]
	s_add_i32 m0, s26, 0x2000
	s_nop 0
	global_load_lds_dwordx4 v[132:133], off
	v_add_u32_e32 v160, 0x18000, v222
	ds_read_b128 v[132:135], v160
	ds_read_b128 v[136:139], v160 offset:1024
	ds_read_b128 v[156:159], v160 offset:2048
	ds_read_b128 v[160:163], v160 offset:3072
	s_waitcnt vmcnt(10)
	s_setprio 1
	s_barrier
	v_mfma_f32_16x16x32_bf16 v[32:35], v[204:207], v[172:175], v[32:35]
	v_mfma_f32_16x16x32_bf16 v[28:31], v[212:215], v[172:175], v[28:31]
	v_mfma_f32_16x16x32_bf16 v[22:25], v[204:207], v[180:183], v[22:25]
	v_mfma_f32_16x16x32_bf16 v[18:21], v[212:215], v[180:183], v[18:21]
	v_mfma_f32_16x16x32_bf16 v[14:17], v[204:207], v[188:191], v[14:17]
	v_mfma_f32_16x16x32_bf16 v[10:13], v[212:215], v[188:191], v[10:13]
	v_mfma_f32_16x16x32_bf16 v[6:9], v[204:207], v[196:199], v[6:9]
	v_mfma_f32_16x16x32_bf16 v[2:5], v[212:215], v[196:199], v[2:5]
	v_mfma_f32_16x16x32_bf16 v[32:35], v[208:211], v[176:179], v[32:35]
	v_mfma_f32_16x16x32_bf16 v[28:31], v[216:219], v[176:179], v[28:31]
	v_mfma_f32_16x16x32_bf16 v[22:25], v[208:211], v[184:187], v[22:25]
	v_mfma_f32_16x16x32_bf16 v[18:21], v[216:219], v[184:187], v[18:21]
	v_mfma_f32_16x16x32_bf16 v[14:17], v[208:211], v[192:195], v[14:17]
	v_mfma_f32_16x16x32_bf16 v[10:13], v[216:219], v[192:195], v[10:13]
	v_mfma_f32_16x16x32_bf16 v[6:9], v[208:211], v[200:203], v[6:9]
	v_mfma_f32_16x16x32_bf16 v[2:5], v[216:219], v[200:203], v[2:5]
	s_barrier
	s_setprio 0
	s_add_i32 s26, 0, 0x18000
	s_add_u32 s0, s34, 0xb0000
	s_addc_u32 s1, s35, 0
	s_mov_b32 m0, s55
	v_lshl_add_u64 v[204:205], s[0:1], 0, v[140:141]
	ds_read_b128 v[172:175], v224 offset:32768
	ds_read_b128 v[176:179], v224 offset:33792
	ds_read_b128 v[180:183], v224 offset:34816
	ds_read_b128 v[184:187], v224 offset:35840
	ds_read_b128 v[188:191], v224 offset:36864
	ds_read_b128 v[192:195], v224 offset:37888
	ds_read_b128 v[196:199], v224 offset:38912
	ds_read_b128 v[200:203], v224 offset:39936
	global_load_lds_dwordx4 v[204:205], off
	v_lshl_add_u64 v[204:205], s[0:1], 0, v[142:143]
	s_mov_b32 m0, s56
	s_nop 0
	global_load_lds_dwordx4 v[204:205], off
	s_waitcnt vmcnt(10) lgkmcnt(8)
	s_setprio 1
	s_barrier
	s_waitcnt lgkmcnt(0)
	v_mfma_f32_16x16x32_bf16 v[128:131], v[132:135], v[172:175], v[128:131]
	v_mfma_f32_16x16x32_bf16 v[124:127], v[156:159], v[172:175], v[124:127]
	v_mfma_f32_16x16x32_bf16 v[120:123], v[132:135], v[180:183], v[120:123]
	v_mfma_f32_16x16x32_bf16 v[116:119], v[156:159], v[180:183], v[116:119]
	v_mfma_f32_16x16x32_bf16 v[112:115], v[132:135], v[188:191], v[112:115]
	v_mfma_f32_16x16x32_bf16 v[108:111], v[156:159], v[188:191], v[108:111]
	v_mfma_f32_16x16x32_bf16 v[104:107], v[132:135], v[196:199], v[104:107]
	v_mfma_f32_16x16x32_bf16 v[100:103], v[156:159], v[196:199], v[100:103]
	v_mfma_f32_16x16x32_bf16 v[128:131], v[136:139], v[176:179], v[128:131]
	v_mfma_f32_16x16x32_bf16 v[124:127], v[160:163], v[176:179], v[124:127]
	v_mfma_f32_16x16x32_bf16 v[120:123], v[136:139], v[184:187], v[120:123]
	v_mfma_f32_16x16x32_bf16 v[116:119], v[160:163], v[184:187], v[116:119]
	v_mfma_f32_16x16x32_bf16 v[112:115], v[136:139], v[192:195], v[112:115]
	v_mfma_f32_16x16x32_bf16 v[108:111], v[160:163], v[192:195], v[108:111]
	v_mfma_f32_16x16x32_bf16 v[104:107], v[136:139], v[200:203], v[104:107]
	v_mfma_f32_16x16x32_bf16 v[100:103], v[160:163], v[200:203], v[100:103]
	s_barrier
	s_setprio 0
	s_add_i32 s27, 0, 0x1c000
	s_add_i32 s0, s26, s17
	v_add_u32_e32 v216, s27, v222
	v_lshl_add_u64 v[164:165], v[164:165], 0, s[12:13]
	s_mov_b32 m0, s0
	ds_read_b128 v[204:207], v216
	ds_read_b128 v[208:211], v216 offset:1024
	ds_read_b128 v[212:215], v216 offset:2048
	ds_read_b128 v[216:219], v216 offset:3072
	global_load_lds_dwordx4 v[164:165], off
	v_lshl_add_u64 v[164:165], v[166:167], 0, s[12:13]
	s_add_i32 m0, s0, 0x2000
	s_nop 0
	global_load_lds_dwordx4 v[164:165], off
	s_waitcnt vmcnt(10)
	s_setprio 1
	s_barrier
	s_waitcnt lgkmcnt(0)
	v_mfma_f32_16x16x32_bf16 v[64:67], v[204:207], v[172:175], v[64:67]
	v_mfma_f32_16x16x32_bf16 v[60:63], v[212:215], v[172:175], v[60:63]
	v_mfma_f32_16x16x32_bf16 v[56:59], v[204:207], v[180:183], v[56:59]
	v_mfma_f32_16x16x32_bf16 v[52:55], v[212:215], v[180:183], v[52:55]
	v_mfma_f32_16x16x32_bf16 v[48:51], v[204:207], v[188:191], v[48:51]
	v_mfma_f32_16x16x32_bf16 v[44:47], v[212:215], v[188:191], v[44:47]
	v_mfma_f32_16x16x32_bf16 v[40:43], v[204:207], v[196:199], v[40:43]
	v_mfma_f32_16x16x32_bf16 v[36:39], v[212:215], v[196:199], v[36:39]
	v_mfma_f32_16x16x32_bf16 v[64:67], v[208:211], v[176:179], v[64:67]
	v_mfma_f32_16x16x32_bf16 v[60:63], v[216:219], v[176:179], v[60:63]
	v_mfma_f32_16x16x32_bf16 v[56:59], v[208:211], v[184:187], v[56:59]
	v_mfma_f32_16x16x32_bf16 v[52:55], v[216:219], v[184:187], v[52:55]
	v_mfma_f32_16x16x32_bf16 v[48:51], v[208:211], v[192:195], v[48:51]
	v_mfma_f32_16x16x32_bf16 v[44:47], v[216:219], v[192:195], v[44:47]
	v_mfma_f32_16x16x32_bf16 v[40:43], v[208:211], v[200:203], v[40:43]
	v_mfma_f32_16x16x32_bf16 v[36:39], v[216:219], v[200:203], v[36:39]
	s_barrier
	s_setprio 0
	s_mov_b32 m0, s59
	v_lshl_add_u64 v[164:165], v[168:169], 0, s[12:13]
	ds_read_b128 v[172:175], v224 offset:49152
	ds_read_b128 v[176:179], v224 offset:50176
	ds_read_b128 v[180:183], v224 offset:51200
	ds_read_b128 v[184:187], v224 offset:52224
	ds_read_b128 v[188:191], v224 offset:53248
	ds_read_b128 v[192:195], v224 offset:54272
	ds_read_b128 v[196:199], v224 offset:55296
	ds_read_b128 v[200:203], v224 offset:56320
	global_load_lds_dwordx4 v[164:165], off
	v_lshl_add_u64 v[164:165], v[220:221], 0, s[12:13]
	s_mov_b32 m0, s68
	s_nop 0
	global_load_lds_dwordx4 v[164:165], off
	s_waitcnt vmcnt(10)
	s_setprio 1
	s_barrier
	s_waitcnt lgkmcnt(0)
	v_mfma_f32_16x16x32_bf16 v[96:99], v[132:135], v[172:175], v[96:99]
	v_mfma_f32_16x16x32_bf16 v[92:95], v[156:159], v[172:175], v[92:95]
	v_mfma_f32_16x16x32_bf16 v[88:91], v[132:135], v[180:183], v[88:91]
	v_mfma_f32_16x16x32_bf16 v[84:87], v[156:159], v[180:183], v[84:87]
	v_mfma_f32_16x16x32_bf16 v[80:83], v[132:135], v[188:191], v[80:83]
	v_mfma_f32_16x16x32_bf16 v[76:79], v[156:159], v[188:191], v[76:79]
	v_mfma_f32_16x16x32_bf16 v[72:75], v[132:135], v[196:199], v[72:75]
	v_mfma_f32_16x16x32_bf16 v[68:71], v[156:159], v[196:199], v[68:71]
	v_mfma_f32_16x16x32_bf16 v[96:99], v[136:139], v[176:179], v[96:99]
	v_mfma_f32_16x16x32_bf16 v[92:95], v[160:163], v[176:179], v[92:95]
	v_mfma_f32_16x16x32_bf16 v[88:91], v[136:139], v[184:187], v[88:91]
	v_mfma_f32_16x16x32_bf16 v[84:87], v[160:163], v[184:187], v[84:87]
	v_mfma_f32_16x16x32_bf16 v[80:83], v[136:139], v[192:195], v[80:83]
	v_mfma_f32_16x16x32_bf16 v[76:79], v[160:163], v[192:195], v[76:79]
	v_mfma_f32_16x16x32_bf16 v[72:75], v[136:139], v[200:203], v[72:75]
	v_mfma_f32_16x16x32_bf16 v[68:71], v[160:163], v[200:203], v[68:71]
	s_barrier
	s_setprio 0
	s_add_u32 s0, s30, 0xb0080
	s_addc_u32 s1, s31, 0
	s_add_i32 s26, s27, s17
	v_lshl_add_u64 v[132:133], s[0:1], 0, v[26:27]
	s_mov_b32 m0, s26
	s_nop 0
	global_load_lds_dwordx4 v[132:133], off
	v_lshl_add_u64 v[132:133], s[0:1], 0, v[144:145]
	s_add_i32 m0, s26, 0x2000
	s_nop 0
	global_load_lds_dwordx4 v[132:133], off
	v_add_u32_e32 v160, 0x10000, v222
	ds_read_b128 v[132:135], v160
	ds_read_b128 v[136:139], v160 offset:1024
	ds_read_b128 v[156:159], v160 offset:2048
	ds_read_b128 v[160:163], v160 offset:3072
	s_waitcnt vmcnt(10)
	s_setprio 1
	s_barrier
	v_mfma_f32_16x16x32_bf16 v[32:35], v[204:207], v[172:175], v[32:35]
	v_mfma_f32_16x16x32_bf16 v[28:31], v[212:215], v[172:175], v[28:31]
	v_mfma_f32_16x16x32_bf16 v[22:25], v[204:207], v[180:183], v[22:25]
	v_mfma_f32_16x16x32_bf16 v[18:21], v[212:215], v[180:183], v[18:21]
	v_mfma_f32_16x16x32_bf16 v[14:17], v[204:207], v[188:191], v[14:17]
	v_mfma_f32_16x16x32_bf16 v[10:13], v[212:215], v[188:191], v[10:13]
	v_mfma_f32_16x16x32_bf16 v[6:9], v[204:207], v[196:199], v[6:9]
	v_mfma_f32_16x16x32_bf16 v[2:5], v[212:215], v[196:199], v[2:5]
	v_mfma_f32_16x16x32_bf16 v[32:35], v[208:211], v[176:179], v[32:35]
	v_mfma_f32_16x16x32_bf16 v[28:31], v[216:219], v[176:179], v[28:31]
	v_mfma_f32_16x16x32_bf16 v[22:25], v[208:211], v[184:187], v[22:25]
	v_mfma_f32_16x16x32_bf16 v[18:21], v[216:219], v[184:187], v[18:21]
	v_mfma_f32_16x16x32_bf16 v[14:17], v[208:211], v[192:195], v[14:17]
	v_mfma_f32_16x16x32_bf16 v[10:13], v[216:219], v[192:195], v[10:13]
	v_mfma_f32_16x16x32_bf16 v[6:9], v[208:211], v[200:203], v[6:9]
	v_mfma_f32_16x16x32_bf16 v[2:5], v[216:219], v[200:203], v[2:5]
	s_barrier
	s_setprio 0
	s_add_i32 s81, s81, 2
	s_add_u32 s44, s44, 0x100
	s_addc_u32 s45, s45, 0
	s_cmp_gt_u32 s81, 41
	s_mov_b64 s[26:27], s[28:29]
	s_cbranch_scc0 .LBB0_1156
	s_waitcnt lgkmcnt(0)
	s_min_i32 s0, s24, 0x100
	s_ashr_i32 s0, s0, 5
	s_ashr_i32 s1, s0, 31
	s_add_i32 s26, s24, 0xffffff00
	s_cmpk_lt_i32 s24, 0x100
	s_cselect_b32 s26, s24, s26
	s_cselect_b32 s28, 0, s51
	s_cselect_b32 s29, 0, s50
	s_ashr_i32 s27, s26, 31
	s_lshl_b64 s[26:27], s[26:27], 19
	v_lshl_add_u64 v[132:133], s[26:27], 0, v[146:147]
	s_add_u32 s26, s20, s29
	v_lshl_or_b32 v166, s25, 8, v223
	s_addc_u32 s27, s21, s28
	s_ashr_i32 s25, s24, 31
	s_lshl_b64 s[28:29], s[24:25], 19
	v_lshl_add_u64 v[178:179], v[148:149], 0, s[28:29]
	s_lshl_b64 s[24:25], s[24:25], 10
	s_mul_i32 s28, s0, 0x9000
	v_ashrrev_i32_e32 v167, 31, v166
	s_mul_hi_i32 s29, s0, 0x9000
	s_add_u32 s28, s36, s28
	s_addc_u32 s29, s37, s29
	v_lshlrev_b64 v[180:181], 2, v[166:167]
	v_lshl_add_u64 v[156:157], s[28:29], 0, v[180:181]
	v_lshl_add_u64 v[168:169], v[132:133], 0, v[166:167]
	v_lshl_add_u64 v[182:183], v[132:133], 1, s[26:27]
	global_load_dwordx4 v[132:135], v[156:157], off offset:16
	global_load_dwordx4 v[136:139], v[156:157], off
	s_lshl_b64 s[0:1], s[0:1], 12
	s_add_u32 s28, s57, s0
	s_addc_u32 s29, s58, s1
	v_lshl_add_u64 v[180:181], s[28:29], 0, v[180:181]
	v_lshl_add_u64 v[196:197], v[168:169], 1, s[26:27]
	v_add_co_u32_e32 v210, vcc, s65, v196
	s_mov_b32 s1, 0x20000
	s_nop 0
	v_addc_co_u32_e32 v211, vcc, 0, v197, vcc
	v_add_co_u32_e32 v184, vcc, s1, v196
	s_mov_b32 s26, 0x30000
	s_nop 0
	v_addc_co_u32_e32 v185, vcc, 0, v197, vcc
	v_add_co_u32_e32 v188, vcc, s26, v196
	v_lshlrev_b64 v[166:167], 1, v[166:167]
	s_nop 0
	v_addc_co_u32_e32 v189, vcc, 0, v197, vcc
	v_lshl_add_u64 v[178:179], v[178:179], 0, v[166:167]
	v_lshl_add_u64 v[182:183], v[182:183], 0, v[166:167]
	s_mov_b32 s0, 0x8000
	s_mov_b32 s27, 0x80000
	s_mov_b32 s28, 0x90000
	s_waitcnt vmcnt(0)
	v_pk_mul_f32 v[172:173], v[134:135], 0.5 op_sel_hi:[1,0]
	v_pk_mul_f32 v[176:177], v[138:139], 0.5 op_sel_hi:[1,0]
	v_pk_mul_f32 v[174:175], v[136:137], 0.5 op_sel_hi:[1,0]
	v_pk_mul_f32 v[164:165], v[132:133], 0.5 op_sel_hi:[1,0]
	global_load_dwordx4 v[132:135], v[156:157], off offset:528
	global_load_dwordx4 v[136:139], v[156:157], off offset:512
	s_waitcnt vmcnt(0)
	v_pk_mul_f32 v[158:159], v[134:135], 0.5 op_sel_hi:[1,0]
	v_pk_mul_f32 v[162:163], v[138:139], 0.5 op_sel_hi:[1,0]
	v_pk_mul_f32 v[160:161], v[136:137], 0.5 op_sel_hi:[1,0]
	v_pk_mul_f32 v[156:157], v[132:133], 0.5 op_sel_hi:[1,0]
	global_load_dwordx4 v[132:135], v[180:181], off offset:16
	global_load_dwordx4 v[136:139], v[180:181], off
	global_load_dwordx4 v[190:193], v[196:197], off offset:2048
	global_load_dwordx4 v[198:201], v[210:211], off offset:2048
	global_load_dwordx4 v[202:205], v[184:185], off offset:2048
	global_load_dwordx4 v[206:209], v[188:189], off offset:2048
	s_waitcnt vmcnt(0)
	v_lshlrev_b32_e32 v166, 16, v190
	v_and_b32_e32 v167, 0xffff0000, v190
	v_lshlrev_b32_e32 v168, 16, v191
	v_and_b32_e32 v169, 0xffff0000, v191
	v_lshlrev_b32_e32 v186, 16, v192
	v_and_b32_e32 v187, 0xffff0000, v192
	v_lshlrev_b32_e32 v190, 16, v193
	v_and_b32_e32 v191, 0xffff0000, v193
	v_pk_fma_f32 v[130:131], v[130:131], v[176:177], v[168:169]
	v_pk_fma_f32 v[128:129], v[128:129], v[174:175], v[166:167]
	v_pk_fma_f32 v[126:127], v[126:127], v[172:173], v[190:191]
	v_pk_fma_f32 v[124:125], v[124:125], v[164:165], v[186:187]
	v_cvt_pk_bf16_f32 v190, v128, v129
	v_cvt_pk_bf16_f32 v191, v130, v131
	v_cvt_pk_bf16_f32 v192, v124, v125
	v_cvt_pk_bf16_f32 v193, v126, v127
	v_lshlrev_b32_e32 v130, 16, v190
	v_and_b32_e32 v131, 0xffff0000, v190
	v_lshlrev_b32_e32 v128, 16, v191
	v_and_b32_e32 v129, 0xffff0000, v191
	v_lshlrev_b32_e32 v126, 16, v192
	v_and_b32_e32 v127, 0xffff0000, v192
	v_lshlrev_b32_e32 v124, 16, v193
	v_and_b32_e32 v125, 0xffff0000, v193
	v_lshlrev_b32_e32 v212, 16, v200
	v_and_b32_e32 v213, 0xffff0000, v200
	v_lshlrev_b32_e32 v200, 16, v201
	v_and_b32_e32 v201, 0xffff0000, v201
	global_store_dwordx4 v[182:183], v[190:193], off offset:2048
	v_pk_mul_f32 v[166:167], v[138:139], v[128:129]
	v_pk_mul_f32 v[168:169], v[136:137], v[130:131]
	v_pk_mul_f32 v[186:187], v[134:135], v[124:125]
	v_pk_mul_f32 v[192:193], v[132:133], v[126:127]
	v_lshlrev_b32_e32 v194, 16, v198
	v_and_b32_e32 v195, 0xffff0000, v198
	v_lshlrev_b32_e32 v198, 16, v199
	v_and_b32_e32 v199, 0xffff0000, v199
	v_cvt_pk_bf16_f32 v190, v168, v169
	v_cvt_pk_bf16_f32 v191, v166, v167
	v_cvt_pk_bf16_f32 v192, v192, v193
	v_cvt_pk_bf16_f32 v193, v186, v187
	v_pk_fma_f32 v[118:119], v[118:119], v[172:173], v[200:201]
	v_pk_fma_f32 v[116:117], v[116:117], v[164:165], v[212:213]
	global_store_dwordx4 v[178:179], v[190:193], off
	v_pk_fma_f32 v[122:123], v[122:123], v[176:177], v[198:199]
	v_pk_fma_f32 v[120:121], v[120:121], v[174:175], v[194:195]
	v_cvt_pk_bf16_f32 v192, v116, v117
	v_cvt_pk_bf16_f32 v193, v118, v119
	v_add_co_u32_e32 v186, vcc, s65, v182
	v_cvt_pk_bf16_f32 v190, v120, v121
	v_cvt_pk_bf16_f32 v191, v122, v123
	v_addc_co_u32_e32 v187, vcc, 0, v183, vcc
	v_lshlrev_b32_e32 v118, 16, v192
	v_and_b32_e32 v119, 0xffff0000, v192
	v_lshlrev_b32_e32 v116, 16, v193
	v_and_b32_e32 v117, 0xffff0000, v193
	global_store_dwordx4 v[186:187], v[190:193], off offset:2048
	v_lshlrev_b32_e32 v122, 16, v190
	v_and_b32_e32 v123, 0xffff0000, v190
	v_lshlrev_b32_e32 v120, 16, v191
	v_and_b32_e32 v121, 0xffff0000, v191
	v_pk_mul_f32 v[190:191], v[134:135], v[116:117]
	v_pk_mul_f32 v[194:195], v[132:133], v[118:119]
	v_pk_mul_f32 v[166:167], v[138:139], v[120:121]
	v_pk_mul_f32 v[168:169], v[136:137], v[122:123]
	v_cvt_pk_bf16_f32 v194, v194, v195
	v_cvt_pk_bf16_f32 v195, v190, v191
	v_add_co_u32_e32 v190, vcc, s0, v178
	v_cvt_pk_bf16_f32 v192, v168, v169
	v_cvt_pk_bf16_f32 v193, v166, v167
	v_addc_co_u32_e32 v191, vcc, 0, v179, vcc
	global_store_dwordx4 v[190:191], v[192:195], off
	v_lshlrev_b32_e32 v198, 16, v204
	v_and_b32_e32 v199, 0xffff0000, v204
	v_add_co_u32_e32 v192, vcc, s27, v196
	v_lshlrev_b32_e32 v200, 16, v205
	s_nop 0
	v_addc_co_u32_e32 v193, vcc, 0, v197, vcc
	v_add_co_u32_e32 v194, vcc, s28, v196
	v_and_b32_e32 v201, 0xffff0000, v205
	global_load_dwordx4 v[212:215], v[192:193], off offset:2048
	v_addc_co_u32_e32 v195, vcc, 0, v197, vcc
	v_lshlrev_b32_e32 v166, 16, v202
	v_and_b32_e32 v167, 0xffff0000, v202
	v_lshlrev_b32_e32 v168, 16, v203
	v_and_b32_e32 v169, 0xffff0000, v203
	v_pk_fma_f32 v[110:111], v[110:111], v[172:173], v[200:201]
	v_pk_fma_f32 v[108:109], v[108:109], v[164:165], v[198:199]
	v_pk_fma_f32 v[114:115], v[114:115], v[176:177], v[168:169]
	v_pk_fma_f32 v[112:113], v[112:113], v[174:175], v[166:167]
	v_cvt_pk_bf16_f32 v202, v108, v109
	v_cvt_pk_bf16_f32 v203, v110, v111
	v_add_co_u32_e32 v198, vcc, s1, v182
	global_load_dwordx4 v[216:219], v[194:195], off offset:2048
	v_cvt_pk_bf16_f32 v200, v112, v113
	v_cvt_pk_bf16_f32 v201, v114, v115
	v_addc_co_u32_e32 v199, vcc, 0, v183, vcc
	v_lshlrev_b32_e32 v110, 16, v202
	v_and_b32_e32 v111, 0xffff0000, v202
	v_lshlrev_b32_e32 v108, 16, v203
	v_and_b32_e32 v109, 0xffff0000, v203
	global_store_dwordx4 v[198:199], v[200:203], off offset:2048
	v_lshlrev_b32_e32 v114, 16, v200
	v_and_b32_e32 v115, 0xffff0000, v200
	v_lshlrev_b32_e32 v112, 16, v201
	v_and_b32_e32 v113, 0xffff0000, v201
	v_pk_mul_f32 v[200:201], v[134:135], v[108:109]
	v_pk_mul_f32 v[204:205], v[132:133], v[110:111]
	v_lshlrev_b32_e32 v234, 16, v208
	v_and_b32_e32 v235, 0xffff0000, v208
	v_lshlrev_b32_e32 v208, 16, v209
	v_and_b32_e32 v209, 0xffff0000, v209
	v_pk_mul_f32 v[166:167], v[138:139], v[112:113]
	v_pk_mul_f32 v[168:169], v[136:137], v[114:115]
	v_cvt_pk_bf16_f32 v204, v204, v205
	v_cvt_pk_bf16_f32 v205, v200, v201
	v_add_co_u32_e32 v200, vcc, s65, v178
	v_lshlrev_b32_e32 v220, 16, v206
	v_and_b32_e32 v221, 0xffff0000, v206
	v_lshlrev_b32_e32 v206, 16, v207
	v_and_b32_e32 v207, 0xffff0000, v207
	v_cvt_pk_bf16_f32 v202, v168, v169
	v_cvt_pk_bf16_f32 v203, v166, v167
	v_addc_co_u32_e32 v201, vcc, 0, v179, vcc
	v_pk_fma_f32 v[102:103], v[102:103], v[172:173], v[208:209]
	v_pk_fma_f32 v[100:101], v[100:101], v[164:165], v[234:235]
	global_store_dwordx4 v[200:201], v[202:205], off
	v_pk_fma_f32 v[106:107], v[106:107], v[176:177], v[206:207]
	v_pk_fma_f32 v[104:105], v[104:105], v[174:175], v[220:221]
	v_cvt_pk_bf16_f32 v206, v100, v101
	v_cvt_pk_bf16_f32 v207, v102, v103
	v_add_co_u32_e32 v202, vcc, s26, v182
	v_cvt_pk_bf16_f32 v204, v104, v105
	v_cvt_pk_bf16_f32 v205, v106, v107
	v_addc_co_u32_e32 v203, vcc, 0, v183, vcc
	v_lshlrev_b32_e32 v102, 16, v206
	v_and_b32_e32 v103, 0xffff0000, v206
	v_lshlrev_b32_e32 v100, 16, v207
	v_and_b32_e32 v101, 0xffff0000, v207
	global_store_dwordx4 v[202:203], v[204:207], off offset:2048
	v_lshlrev_b32_e32 v106, 16, v204
	v_and_b32_e32 v107, 0xffff0000, v204
	v_lshlrev_b32_e32 v104, 16, v205
	v_and_b32_e32 v105, 0xffff0000, v205
	v_pk_mul_f32 v[204:205], v[134:135], v[100:101]
	v_pk_mul_f32 v[208:209], v[132:133], v[102:103]
	s_mov_b32 s0, 0x18000
	v_pk_mul_f32 v[166:167], v[138:139], v[104:105]
	v_pk_mul_f32 v[168:169], v[136:137], v[106:107]
	v_cvt_pk_bf16_f32 v208, v208, v209
	v_cvt_pk_bf16_f32 v209, v204, v205
	v_add_co_u32_e32 v204, vcc, s0, v178
	v_cvt_pk_bf16_f32 v206, v168, v169
	v_cvt_pk_bf16_f32 v207, v166, v167
	v_addc_co_u32_e32 v205, vcc, 0, v179, vcc
	global_store_dwordx4 v[204:205], v[206:209], off
	s_mov_b32 s0, 0xb0000
	s_waitcnt vmcnt(0)
	v_lshlrev_b32_e32 v166, 16, v212
	v_add_co_u32_e32 v206, vcc, s76, v196
	v_and_b32_e32 v167, 0xffff0000, v212
	s_nop 0
	v_addc_co_u32_e32 v207, vcc, 0, v197, vcc
	global_load_dwordx4 v[238:241], v[206:207], off offset:2048
	v_add_co_u32_e32 v208, vcc, s0, v196
	v_lshlrev_b32_e32 v168, 16, v213
	s_nop 0
	v_addc_co_u32_e32 v209, vcc, 0, v197, vcc
	global_load_dwordx4 v[242:245], v[208:209], off offset:2048
	v_and_b32_e32 v169, 0xffff0000, v213
	v_lshlrev_b32_e32 v212, 16, v214
	v_and_b32_e32 v213, 0xffff0000, v214
	v_lshlrev_b32_e32 v214, 16, v215
	v_and_b32_e32 v215, 0xffff0000, v215
	v_pk_fma_f32 v[94:95], v[94:95], v[172:173], v[214:215]
	v_pk_fma_f32 v[92:93], v[92:93], v[164:165], v[212:213]
	v_lshlrev_b32_e32 v220, 16, v216
	v_and_b32_e32 v221, 0xffff0000, v216
	v_lshlrev_b32_e32 v234, 16, v217
	v_and_b32_e32 v235, 0xffff0000, v217
	v_pk_fma_f32 v[98:99], v[98:99], v[176:177], v[168:169]
	v_pk_fma_f32 v[96:97], v[96:97], v[174:175], v[166:167]
	v_cvt_pk_bf16_f32 v216, v92, v93
	v_cvt_pk_bf16_f32 v217, v94, v95
	v_add_co_u32_e32 v212, vcc, s27, v182
	v_cvt_pk_bf16_f32 v214, v96, v97
	v_cvt_pk_bf16_f32 v215, v98, v99
	v_addc_co_u32_e32 v213, vcc, 0, v183, vcc
	v_lshlrev_b32_e32 v94, 16, v216
	v_and_b32_e32 v95, 0xffff0000, v216
	v_lshlrev_b32_e32 v92, 16, v217
	v_and_b32_e32 v93, 0xffff0000, v217
	v_lshlrev_b32_e32 v246, 16, v218
	v_and_b32_e32 v247, 0xffff0000, v218
	v_lshlrev_b32_e32 v248, 16, v219
	v_and_b32_e32 v249, 0xffff0000, v219
	global_store_dwordx4 v[212:213], v[214:217], off offset:2048
	v_lshlrev_b32_e32 v98, 16, v214
	v_and_b32_e32 v99, 0xffff0000, v214
	v_lshlrev_b32_e32 v96, 16, v215
	v_and_b32_e32 v97, 0xffff0000, v215
	v_pk_mul_f32 v[214:215], v[134:135], v[92:93]
	v_pk_mul_f32 v[218:219], v[132:133], v[94:95]
	s_mov_b32 s1, 0x40000
	v_pk_mul_f32 v[166:167], v[138:139], v[96:97]
	v_pk_mul_f32 v[168:169], v[136:137], v[98:99]
	v_cvt_pk_bf16_f32 v218, v218, v219
	v_cvt_pk_bf16_f32 v219, v214, v215
	v_add_co_u32_e32 v214, vcc, s1, v178
	v_cvt_pk_bf16_f32 v216, v168, v169
	v_cvt_pk_bf16_f32 v217, v166, v167
	v_addc_co_u32_e32 v215, vcc, 0, v179, vcc
	v_pk_fma_f32 v[86:87], v[86:87], v[172:173], v[248:249]
	global_store_dwordx4 v[214:215], v[216:219], off
	v_pk_fma_f32 v[90:91], v[90:91], v[176:177], v[234:235]
	v_pk_fma_f32 v[88:89], v[88:89], v[174:175], v[220:221]
	v_pk_fma_f32 v[84:85], v[84:85], v[164:165], v[246:247]
	v_cvt_pk_bf16_f32 v221, v86, v87
	v_add_co_u32_e32 v216, vcc, s28, v182
	v_cvt_pk_bf16_f32 v218, v88, v89
	v_cvt_pk_bf16_f32 v219, v90, v91
	v_cvt_pk_bf16_f32 v220, v84, v85
	v_addc_co_u32_e32 v217, vcc, 0, v183, vcc
	v_lshlrev_b32_e32 v84, 16, v221
	v_and_b32_e32 v85, 0xffff0000, v221
	global_store_dwordx4 v[216:217], v[218:221], off offset:2048
	v_lshlrev_b32_e32 v90, 16, v218
	v_and_b32_e32 v91, 0xffff0000, v218
	v_lshlrev_b32_e32 v88, 16, v219
	v_and_b32_e32 v89, 0xffff0000, v219
	v_lshlrev_b32_e32 v86, 16, v220
	v_and_b32_e32 v87, 0xffff0000, v220
	v_pk_mul_f32 v[218:219], v[134:135], v[84:85]
	s_mov_b32 s1, 0x48000
	v_pk_mul_f32 v[166:167], v[138:139], v[88:89]
	v_pk_mul_f32 v[168:169], v[136:137], v[90:91]
	v_pk_mul_f32 v[220:221], v[132:133], v[86:87]
	v_cvt_pk_bf16_f32 v249, v218, v219
	v_add_co_u32_e32 v218, vcc, s1, v178
	v_cvt_pk_bf16_f32 v246, v168, v169
	v_cvt_pk_bf16_f32 v247, v166, v167
	v_cvt_pk_bf16_f32 v248, v220, v221
	v_addc_co_u32_e32 v219, vcc, 0, v179, vcc
	global_store_dwordx4 v[218:219], v[246:249], off
	global_load_dwordx4 v[246:249], v[196:197], off offset:2304
	s_nop 0
	global_load_dwordx4 v[250:253], v[210:211], off offset:2304
	s_waitcnt vmcnt(0)
	v_lshlrev_b32_e32 v196, 16, v240
	v_and_b32_e32 v197, 0xffff0000, v240
	v_lshlrev_b32_e32 v210, 16, v241
	v_and_b32_e32 v211, 0xffff0000, v241
	v_lshlrev_b32_e32 v166, 16, v238
	v_and_b32_e32 v167, 0xffff0000, v238
	v_lshlrev_b32_e32 v168, 16, v239
	v_and_b32_e32 v169, 0xffff0000, v239
	v_pk_fma_f32 v[78:79], v[78:79], v[172:173], v[210:211]
	v_pk_fma_f32 v[76:77], v[76:77], v[164:165], v[196:197]
	v_pk_fma_f32 v[82:83], v[82:83], v[176:177], v[168:169]
	v_pk_fma_f32 v[80:81], v[80:81], v[174:175], v[166:167]
	v_cvt_pk_bf16_f32 v240, v76, v77
	v_cvt_pk_bf16_f32 v241, v78, v79
	v_add_co_u32_e32 v196, vcc, s76, v182
	v_cvt_pk_bf16_f32 v238, v80, v81
	v_cvt_pk_bf16_f32 v239, v82, v83
	v_addc_co_u32_e32 v197, vcc, 0, v183, vcc
	v_lshlrev_b32_e32 v78, 16, v240
	v_and_b32_e32 v79, 0xffff0000, v240
	v_lshlrev_b32_e32 v76, 16, v241
	v_and_b32_e32 v77, 0xffff0000, v241
	global_store_dwordx4 v[196:197], v[238:241], off offset:2048
	v_lshlrev_b32_e32 v80, 16, v239
	v_and_b32_e32 v81, 0xffff0000, v239
	v_pk_mul_f32 v[210:211], v[134:135], v[76:77]
	v_pk_mul_f32 v[240:241], v[132:133], v[78:79]
	v_lshlrev_b32_e32 v220, 16, v242
	v_and_b32_e32 v221, 0xffff0000, v242
	v_lshlrev_b32_e32 v234, 16, v243
	v_and_b32_e32 v235, 0xffff0000, v243
	v_lshlrev_b32_e32 v242, 16, v244
	v_and_b32_e32 v243, 0xffff0000, v244
	v_lshlrev_b32_e32 v244, 16, v245
	v_and_b32_e32 v245, 0xffff0000, v245
	v_pk_mul_f32 v[166:167], v[138:139], v[80:81]
	v_cvt_pk_bf16_f32 v240, v240, v241
	v_cvt_pk_bf16_f32 v241, v210, v211
	v_add_co_u32_e32 v210, vcc, s77, v178
	v_lshlrev_b32_e32 v82, 16, v238
	v_and_b32_e32 v83, 0xffff0000, v238
	v_cvt_pk_bf16_f32 v239, v166, v167
	v_addc_co_u32_e32 v211, vcc, 0, v179, vcc
	v_pk_fma_f32 v[74:75], v[74:75], v[176:177], v[234:235]
	v_pk_fma_f32 v[72:73], v[72:73], v[174:175], v[220:221]
	v_pk_fma_f32 v[166:167], v[70:71], v[172:173], v[244:245]
	v_pk_fma_f32 v[70:71], v[68:69], v[164:165], v[242:243]
	v_pk_mul_f32 v[168:169], v[136:137], v[82:83]
	v_cvt_pk_bf16_f32 v68, v72, v73
	v_cvt_pk_bf16_f32 v69, v74, v75
	v_cvt_pk_bf16_f32 v70, v70, v71
	v_cvt_pk_bf16_f32 v71, v166, v167
	v_add_co_u32_e32 v220, vcc, s0, v182
	v_cvt_pk_bf16_f32 v238, v168, v169
	s_nop 0
	v_addc_co_u32_e32 v221, vcc, 0, v183, vcc
	v_lshlrev_b32_e32 v176, 16, v68
	v_and_b32_e32 v177, 0xffff0000, v68
	v_lshlrev_b32_e32 v174, 16, v69
	v_and_b32_e32 v175, 0xffff0000, v69
	v_lshlrev_b32_e32 v172, 16, v70
	v_and_b32_e32 v173, 0xffff0000, v70
	v_lshlrev_b32_e32 v164, 16, v71
	v_and_b32_e32 v165, 0xffff0000, v71
	s_mov_b32 s0, 0x58000
	global_store_dwordx4 v[210:211], v[238:241], off
	global_store_dwordx4 v[220:221], v[68:71], off offset:2048
	v_pk_mul_f32 v[72:73], v[134:135], v[164:165]
	v_pk_mul_f32 v[74:75], v[132:133], v[172:173]
	v_pk_mul_f32 v[70:71], v[138:139], v[174:175]
	v_pk_mul_f32 v[68:69], v[136:137], v[176:177]
	v_add_co_u32_e32 v132, vcc, s0, v178
	v_cvt_pk_bf16_f32 v68, v68, v69
	v_cvt_pk_bf16_f32 v69, v70, v71
	v_cvt_pk_bf16_f32 v70, v74, v75
	v_cvt_pk_bf16_f32 v71, v72, v73
	v_addc_co_u32_e32 v133, vcc, 0, v179, vcc
	global_store_dwordx4 v[132:133], v[68:71], off
	global_load_dwordx4 v[134:137], v[184:185], off offset:2304
	global_load_dwordx4 v[238:241], v[188:189], off offset:2304
	s_nop 0
	global_load_dwordx4 v[68:71], v[180:181], off offset:528
	global_load_dwordx4 v[72:75], v[180:181], off offset:512
	v_lshlrev_b32_e32 v138, 16, v246
	v_and_b32_e32 v139, 0xffff0000, v246
	v_lshlrev_b32_e32 v166, 16, v247
	v_and_b32_e32 v167, 0xffff0000, v247
	v_lshlrev_b32_e32 v168, 16, v248
	v_and_b32_e32 v169, 0xffff0000, v248
	v_lshlrev_b32_e32 v180, 16, v249
	v_and_b32_e32 v181, 0xffff0000, v249
	v_pk_fma_f32 v[66:67], v[66:67], v[162:163], v[166:167]
	v_pk_fma_f32 v[64:65], v[64:65], v[160:161], v[138:139]
	v_pk_fma_f32 v[62:63], v[62:63], v[158:159], v[180:181]
	v_pk_fma_f32 v[60:61], v[60:61], v[156:157], v[168:169]
	v_cvt_pk_bf16_f32 v242, v64, v65
	v_cvt_pk_bf16_f32 v243, v66, v67
	v_cvt_pk_bf16_f32 v244, v60, v61
	v_cvt_pk_bf16_f32 v245, v62, v63
	v_lshlrev_b32_e32 v66, 16, v242
	v_and_b32_e32 v67, 0xffff0000, v242
	v_lshlrev_b32_e32 v64, 16, v243
	v_and_b32_e32 v65, 0xffff0000, v243
	v_lshlrev_b32_e32 v62, 16, v244
	v_and_b32_e32 v63, 0xffff0000, v244
	v_lshlrev_b32_e32 v60, 16, v245
	v_and_b32_e32 v61, 0xffff0000, v245
	v_lshlrev_b32_e32 v184, 16, v250
	v_and_b32_e32 v185, 0xffff0000, v250
	v_lshlrev_b32_e32 v188, 16, v251
	v_and_b32_e32 v189, 0xffff0000, v251
	v_lshlrev_b32_e32 v234, 16, v252
	v_and_b32_e32 v235, 0xffff0000, v252
	v_lshlrev_b32_e32 v246, 16, v253
	v_and_b32_e32 v247, 0xffff0000, v253
	global_store_dwordx4 v[182:183], v[242:245], off offset:2304
	v_pk_fma_f32 v[58:59], v[58:59], v[162:163], v[188:189]
	v_pk_fma_f32 v[56:57], v[56:57], v[160:161], v[184:185]
	v_pk_fma_f32 v[54:55], v[54:55], v[158:159], v[246:247]
	v_pk_fma_f32 v[52:53], v[52:53], v[156:157], v[234:235]
	s_waitcnt vmcnt(0)
	v_lshlrev_b32_e32 v188, 16, v240
	v_pk_mul_f32 v[168:169], v[70:71], v[60:61]
	v_pk_mul_f32 v[138:139], v[74:75], v[64:65]
	v_pk_mul_f32 v[166:167], v[72:73], v[66:67]
	v_pk_mul_f32 v[182:183], v[68:69], v[62:63]
	v_cvt_pk_bf16_f32 v180, v166, v167
	v_cvt_pk_bf16_f32 v181, v138, v139
	v_cvt_pk_bf16_f32 v182, v182, v183
	v_cvt_pk_bf16_f32 v183, v168, v169
	global_store_dwordx4 v[178:179], v[180:183], off offset:256
	v_cvt_pk_bf16_f32 v178, v56, v57
	v_cvt_pk_bf16_f32 v179, v58, v59
	v_cvt_pk_bf16_f32 v180, v52, v53
	v_cvt_pk_bf16_f32 v181, v54, v55
	v_lshlrev_b32_e32 v58, 16, v178
	v_and_b32_e32 v59, 0xffff0000, v178
	v_lshlrev_b32_e32 v56, 16, v179
	v_and_b32_e32 v57, 0xffff0000, v179
	v_lshlrev_b32_e32 v54, 16, v180
	v_and_b32_e32 v55, 0xffff0000, v180
	v_lshlrev_b32_e32 v52, 16, v181
	v_and_b32_e32 v53, 0xffff0000, v181
	global_store_dwordx4 v[186:187], v[178:181], off offset:2304
	v_pk_mul_f32 v[138:139], v[74:75], v[56:57]
	v_pk_mul_f32 v[166:167], v[72:73], v[58:59]
	v_pk_mul_f32 v[168:169], v[70:71], v[52:53]
	v_pk_mul_f32 v[180:181], v[68:69], v[54:55]
	v_cvt_pk_bf16_f32 v178, v166, v167
	v_cvt_pk_bf16_f32 v179, v138, v139
	v_cvt_pk_bf16_f32 v180, v180, v181
	v_cvt_pk_bf16_f32 v181, v168, v169
	v_lshlrev_b32_e32 v138, 16, v134
	v_and_b32_e32 v139, 0xffff0000, v134
	v_lshlrev_b32_e32 v134, 16, v135
	v_and_b32_e32 v135, 0xffff0000, v135
	v_lshlrev_b32_e32 v166, 16, v136
	v_and_b32_e32 v167, 0xffff0000, v136
	v_lshlrev_b32_e32 v136, 16, v137
	v_and_b32_e32 v137, 0xffff0000, v137
	global_store_dwordx4 v[190:191], v[178:181], off offset:256
	v_pk_fma_f32 v[50:51], v[50:51], v[162:163], v[134:135]
	v_pk_fma_f32 v[48:49], v[48:49], v[160:161], v[138:139]
	v_pk_fma_f32 v[46:47], v[46:47], v[158:159], v[136:137]
	v_pk_fma_f32 v[44:45], v[44:45], v[156:157], v[166:167]
	global_load_dwordx4 v[178:181], v[192:193], off offset:2304
	global_load_dwordx4 v[182:185], v[194:195], off offset:2304
	v_cvt_pk_bf16_f32 v134, v48, v49
	v_cvt_pk_bf16_f32 v135, v50, v51
	v_cvt_pk_bf16_f32 v136, v44, v45
	v_cvt_pk_bf16_f32 v137, v46, v47
	v_lshlrev_b32_e32 v50, 16, v134
	v_and_b32_e32 v51, 0xffff0000, v134
	v_lshlrev_b32_e32 v48, 16, v135
	v_and_b32_e32 v49, 0xffff0000, v135
	v_lshlrev_b32_e32 v46, 16, v136
	v_and_b32_e32 v47, 0xffff0000, v136
	v_lshlrev_b32_e32 v44, 16, v137
	v_and_b32_e32 v45, 0xffff0000, v137
	v_lshlrev_b32_e32 v168, 16, v238
	v_and_b32_e32 v169, 0xffff0000, v238
	v_lshlrev_b32_e32 v186, 16, v239
	v_and_b32_e32 v187, 0xffff0000, v239
	v_and_b32_e32 v189, 0xffff0000, v240
	v_lshlrev_b32_e32 v190, 16, v241
	v_and_b32_e32 v191, 0xffff0000, v241
	global_store_dwordx4 v[198:199], v[134:137], off offset:2304
	v_pk_mul_f32 v[138:139], v[70:71], v[44:45]
	v_pk_mul_f32 v[166:167], v[68:69], v[46:47]
	v_pk_mul_f32 v[136:137], v[74:75], v[48:49]
	v_pk_mul_f32 v[134:135], v[72:73], v[50:51]
	v_pk_fma_f32 v[42:43], v[42:43], v[162:163], v[186:187]
	v_cvt_pk_bf16_f32 v134, v134, v135
	v_cvt_pk_bf16_f32 v135, v136, v137
	v_cvt_pk_bf16_f32 v136, v166, v167
	v_cvt_pk_bf16_f32 v137, v138, v139
	v_pk_fma_f32 v[40:41], v[40:41], v[160:161], v[168:169]
	v_pk_fma_f32 v[38:39], v[38:39], v[158:159], v[190:191]
	v_pk_fma_f32 v[36:37], v[36:37], v[156:157], v[188:189]
	global_store_dwordx4 v[200:201], v[134:137], off offset:256
	v_mul_f32_e32 v67, v67, v67
	v_mul_f32_e32 v65, v65, v65
	v_cvt_pk_bf16_f32 v134, v40, v41
	v_cvt_pk_bf16_f32 v135, v42, v43
	v_cvt_pk_bf16_f32 v136, v36, v37
	v_cvt_pk_bf16_f32 v137, v38, v39
	v_lshlrev_b32_e32 v42, 16, v134
	v_and_b32_e32 v43, 0xffff0000, v134
	v_lshlrev_b32_e32 v40, 16, v135
	v_and_b32_e32 v41, 0xffff0000, v135
	v_lshlrev_b32_e32 v38, 16, v136
	v_and_b32_e32 v39, 0xffff0000, v136
	v_lshlrev_b32_e32 v36, 16, v137
	v_and_b32_e32 v37, 0xffff0000, v137
	global_store_dwordx4 v[202:203], v[134:137], off offset:2304
	v_pk_mul_f32 v[138:139], v[70:71], v[36:37]
	v_pk_mul_f32 v[166:167], v[68:69], v[38:39]
	v_pk_mul_f32 v[136:137], v[74:75], v[40:41]
	v_pk_mul_f32 v[134:135], v[72:73], v[42:43]
	v_fmac_f32_e32 v67, v66, v66
	v_cvt_pk_bf16_f32 v134, v134, v135
	v_cvt_pk_bf16_f32 v135, v136, v137
	v_cvt_pk_bf16_f32 v136, v166, v167
	v_cvt_pk_bf16_f32 v137, v138, v139
	global_store_dwordx4 v[204:205], v[134:137], off offset:256
	global_load_dwordx4 v[134:137], v[206:207], off offset:2304
	s_nop 0
	global_load_dwordx4 v[186:189], v[208:209], off offset:2304
	v_fmac_f32_e32 v65, v64, v64
	v_mul_f32_e32 v63, v63, v63
	v_mul_f32_e32 v61, v61, v61
	v_add_f32_e32 v64, v67, v65
	v_fmac_f32_e32 v63, v62, v62
	v_fmac_f32_e32 v61, v60, v60
	v_add_f32_e32 v60, v63, v61
	s_waitcnt vmcnt(0)
	v_lshlrev_b32_e32 v138, 16, v178
	v_and_b32_e32 v139, 0xffff0000, v178
	v_lshlrev_b32_e32 v166, 16, v179
	v_and_b32_e32 v167, 0xffff0000, v179
	v_lshlrev_b32_e32 v168, 16, v180
	v_and_b32_e32 v169, 0xffff0000, v180
	v_lshlrev_b32_e32 v178, 16, v181
	v_and_b32_e32 v179, 0xffff0000, v181
	v_pk_fma_f32 v[34:35], v[34:35], v[162:163], v[166:167]
	v_pk_fma_f32 v[32:33], v[32:33], v[160:161], v[138:139]
	v_pk_fma_f32 v[30:31], v[30:31], v[158:159], v[178:179]
	v_pk_fma_f32 v[28:29], v[28:29], v[156:157], v[168:169]
	v_cvt_pk_bf16_f32 v178, v32, v33
	v_cvt_pk_bf16_f32 v179, v34, v35
	v_cvt_pk_bf16_f32 v180, v28, v29
	v_cvt_pk_bf16_f32 v181, v30, v31
	v_lshlrev_b32_e32 v34, 16, v178
	v_and_b32_e32 v35, 0xffff0000, v178
	v_lshlrev_b32_e32 v32, 16, v179
	v_and_b32_e32 v33, 0xffff0000, v179
	v_lshlrev_b32_e32 v30, 16, v180
	v_and_b32_e32 v31, 0xffff0000, v180
	v_lshlrev_b32_e32 v28, 16, v181
	v_and_b32_e32 v29, 0xffff0000, v181
	v_lshlrev_b32_e32 v190, 16, v182
	v_and_b32_e32 v191, 0xffff0000, v182
	v_lshlrev_b32_e32 v182, 16, v183
	v_and_b32_e32 v183, 0xffff0000, v183
	global_store_dwordx4 v[212:213], v[178:181], off offset:2304
	v_pk_mul_f32 v[138:139], v[74:75], v[32:33]
	v_pk_mul_f32 v[166:167], v[72:73], v[34:35]
	v_pk_mul_f32 v[168:169], v[70:71], v[28:29]
	v_pk_mul_f32 v[180:181], v[68:69], v[30:31]
	v_cvt_pk_bf16_f32 v178, v166, v167
	v_cvt_pk_bf16_f32 v179, v138, v139
	v_cvt_pk_bf16_f32 v180, v180, v181
	v_cvt_pk_bf16_f32 v181, v168, v169
	v_pk_fma_f32 v[24:25], v[24:25], v[162:163], v[182:183]
	v_pk_fma_f32 v[22:23], v[22:23], v[160:161], v[190:191]
	v_lshlrev_b32_e32 v192, 16, v184
	v_and_b32_e32 v193, 0xffff0000, v184
	v_lshlrev_b32_e32 v184, 16, v185
	v_and_b32_e32 v185, 0xffff0000, v185
	global_store_dwordx4 v[214:215], v[178:181], off offset:256
	v_pk_fma_f32 v[20:21], v[20:21], v[158:159], v[184:185]
	v_pk_fma_f32 v[18:19], v[18:19], v[156:157], v[192:193]
	v_cvt_pk_bf16_f32 v178, v22, v23
	v_cvt_pk_bf16_f32 v179, v24, v25
	v_lshlrev_b32_e32 v24, 16, v178
	v_and_b32_e32 v25, 0xffff0000, v178
	v_lshlrev_b32_e32 v22, 16, v179
	v_and_b32_e32 v23, 0xffff0000, v179
	v_cvt_pk_bf16_f32 v180, v18, v19
	v_cvt_pk_bf16_f32 v181, v20, v21
	v_pk_mul_f32 v[138:139], v[74:75], v[22:23]
	v_pk_mul_f32 v[166:167], v[72:73], v[24:25]
	global_store_dwordx4 v[216:217], v[178:181], off offset:2304
	v_lshlrev_b32_e32 v20, 16, v180
	v_and_b32_e32 v21, 0xffff0000, v180
	v_cvt_pk_bf16_f32 v178, v166, v167
	v_cvt_pk_bf16_f32 v179, v138, v139
	v_lshlrev_b32_e32 v138, 16, v134
	v_and_b32_e32 v139, 0xffff0000, v134
	v_lshlrev_b32_e32 v134, 16, v135
	v_and_b32_e32 v135, 0xffff0000, v135
	v_lshlrev_b32_e32 v166, 16, v136
	v_and_b32_e32 v167, 0xffff0000, v136
	v_lshlrev_b32_e32 v136, 16, v137
	v_and_b32_e32 v137, 0xffff0000, v137
	v_lshlrev_b32_e32 v18, 16, v181
	v_and_b32_e32 v19, 0xffff0000, v181
	v_pk_fma_f32 v[16:17], v[16:17], v[162:163], v[134:135]
	v_pk_fma_f32 v[14:15], v[14:15], v[160:161], v[138:139]
	v_pk_fma_f32 v[12:13], v[12:13], v[158:159], v[136:137]
	v_pk_fma_f32 v[10:11], v[10:11], v[156:157], v[166:167]
	v_pk_mul_f32 v[168:169], v[70:71], v[18:19]
	v_pk_mul_f32 v[180:181], v[68:69], v[20:21]
	v_cvt_pk_bf16_f32 v134, v14, v15
	v_cvt_pk_bf16_f32 v135, v16, v17
	v_cvt_pk_bf16_f32 v136, v10, v11
	v_cvt_pk_bf16_f32 v137, v12, v13
	v_cvt_pk_bf16_f32 v180, v180, v181
	v_cvt_pk_bf16_f32 v181, v168, v169
	v_lshlrev_b32_e32 v16, 16, v134
	v_and_b32_e32 v17, 0xffff0000, v134
	v_lshlrev_b32_e32 v14, 16, v135
	v_and_b32_e32 v15, 0xffff0000, v135
	v_lshlrev_b32_e32 v12, 16, v136
	v_and_b32_e32 v13, 0xffff0000, v136
	v_lshlrev_b32_e32 v10, 16, v137
	v_and_b32_e32 v11, 0xffff0000, v137
	global_store_dwordx4 v[218:219], v[178:181], off offset:256
	v_lshlrev_b32_e32 v168, 16, v186
	v_and_b32_e32 v169, 0xffff0000, v186
	v_lshlrev_b32_e32 v178, 16, v187
	v_and_b32_e32 v179, 0xffff0000, v187
	v_lshlrev_b32_e32 v180, 16, v188
	v_and_b32_e32 v181, 0xffff0000, v188
	v_lshlrev_b32_e32 v182, 16, v189
	v_and_b32_e32 v183, 0xffff0000, v189
	global_store_dwordx4 v[196:197], v[134:137], off offset:2304
	v_pk_mul_f32 v[138:139], v[70:71], v[10:11]
	v_pk_mul_f32 v[166:167], v[68:69], v[12:13]
	v_pk_mul_f32 v[136:137], v[74:75], v[14:15]
	v_pk_mul_f32 v[134:135], v[72:73], v[16:17]
	v_pk_fma_f32 v[8:9], v[8:9], v[162:163], v[178:179]
	v_cvt_pk_bf16_f32 v134, v134, v135
	v_cvt_pk_bf16_f32 v135, v136, v137
	v_cvt_pk_bf16_f32 v136, v166, v167
	v_cvt_pk_bf16_f32 v137, v138, v139
	v_pk_fma_f32 v[6:7], v[6:7], v[160:161], v[168:169]
	v_pk_fma_f32 v[4:5], v[4:5], v[158:159], v[182:183]
	v_pk_fma_f32 v[2:3], v[2:3], v[156:157], v[180:181]
	global_store_dwordx4 v[210:211], v[134:137], off offset:256
	s_nop 1
	v_cvt_pk_bf16_f32 v134, v6, v7
	v_cvt_pk_bf16_f32 v135, v8, v9
	v_cvt_pk_bf16_f32 v136, v2, v3
	v_cvt_pk_bf16_f32 v137, v4, v5
	v_lshlrev_b32_e32 v8, 16, v134
	v_and_b32_e32 v9, 0xffff0000, v134
	v_lshlrev_b32_e32 v6, 16, v135
	v_and_b32_e32 v7, 0xffff0000, v135
	v_lshlrev_b32_e32 v4, 16, v136
	v_and_b32_e32 v5, 0xffff0000, v136
	v_lshlrev_b32_e32 v2, 16, v137
	v_and_b32_e32 v3, 0xffff0000, v137
	global_store_dwordx4 v[220:221], v[134:137], off offset:2304
	v_pk_mul_f32 v[74:75], v[74:75], v[6:7]
	v_pk_mul_f32 v[72:73], v[72:73], v[8:9]
	v_pk_mul_f32 v[134:135], v[70:71], v[2:3]
	v_pk_mul_f32 v[70:71], v[68:69], v[4:5]
	v_cvt_pk_bf16_f32 v68, v72, v73
	v_cvt_pk_bf16_f32 v69, v74, v75
	v_cvt_pk_bf16_f32 v70, v70, v71
	v_cvt_pk_bf16_f32 v71, v134, v135
	global_store_dwordx4 v[132:133], v[68:71], off offset:256
	v_xor_b32_e32 v72, 32, v227
	v_mul_f32_e32 v73, v129, v129
	v_and_b32_e32 v71, 64, v227
	v_xor_b32_e32 v70, 16, v227
	v_add_u32_e32 v71, 64, v71
	v_cmp_lt_i32_e32 vcc, v70, v71
	v_fmac_f32_e32 v73, v128, v128
	v_mul_f32_e32 v74, v125, v125
	v_cndmask_b32_e32 v70, v227, v70, vcc
	v_cmp_lt_i32_e32 vcc, v72, v71
	v_fmac_f32_e32 v74, v124, v124
	v_lshlrev_b32_e32 v70, 2, v70
	v_cndmask_b32_e32 v71, v227, v72, vcc
	v_mul_f32_e32 v72, v131, v131
	v_fmac_f32_e32 v72, v130, v130
	v_add_f32_e32 v72, v72, v73
	v_mul_f32_e32 v73, v127, v127
	v_fmac_f32_e32 v73, v126, v126
	v_add_f32_e32 v73, v73, v74
	v_add_f32_e32 v72, v72, v73
	v_add_f32_e32 v64, v72, v64
	v_add_f32_e32 v60, v60, v64
	ds_bpermute_b32 v61, v70, v60
	v_lshlrev_b32_e32 v71, 2, v71
	v_lshl_add_u64 v[68:69], v[150:151], 0, s[24:25]
	s_waitcnt lgkmcnt(0)
	v_add_f32_e32 v60, v60, v61
	ds_bpermute_b32 v61, v71, v60
	s_and_saveexec_b64 s[24:25], s[38:39]
	s_cbranch_execz .LBB0_1159
	s_waitcnt lgkmcnt(0)
	v_add_f32_e32 v60, v60, v61
	global_atomic_add_f32 v[68:69], v60, off
